# x-update rows assigned XCD-locally (rows 2048*(bx%8)+256k+j: the panels whose GEMM tiles the same XCD writes/reads) + rs hoist
# baseline (speedup 1.0000x reference)
.LBB0_446:
	s_waitcnt lgkmcnt(0)
	v_cndmask_b32_e64 v0, 0, 1, s[24:25]
	v_cmp_ne_u32_e64 s[0:1], 1, v0
	s_andn2_b64 vcc, exec, s[24:25]
	s_nop 0
	v_writelane_b32 v235, s0, 52
	s_barrier
	s_nop 0
	v_writelane_b32 v235, s1, 53
	v_mbcnt_lo_u32_b32 v0, -1, 0
	v_mbcnt_hi_u32_b32 v0, -1, v0
	s_cbranch_vccnz .LBB0_465
	v_lshlrev_b32_e32 v2, 3, v0
	v_ashrrev_i32_e32 v3, 31, v2
	v_readlane_b32 s4, v235, 4
	v_lshlrev_b64 v[4:5], 1, v[2:3]
	v_lshlrev_b64 v[2:3], 2, v[2:3]
	v_readlane_b32 s5, v235, 5
	v_readlane_b32 s6, v235, 6
	v_readlane_b32 s7, v235, 7
	v_readlane_b32 s8, v235, 8
	v_readlane_b32 s9, v235, 9
	v_readlane_b32 s10, v235, 10
	v_readlane_b32 s11, v235, 11
	v_readlane_b32 s12, v235, 12
	v_readlane_b32 s13, v235, 13
	v_readlane_b32 s14, v235, 14
	v_readlane_b32 s15, v235, 15
	v_readlane_b32 s16, v235, 16
	v_readlane_b32 s17, v235, 17
	v_readlane_b32 s18, v235, 18
	v_readlane_b32 s19, v235, 19
	v_lshl_add_u64 v[60:61], s[86:87], 0, v[4:5]
	v_lshl_add_u64 v[62:63], s[90:91], 0, v[2:3]
	v_lshl_add_u64 v[64:65], s[54:55], 0, v[4:5]
	v_lshl_add_u64 v[66:67], s[14:15], 0, v[2:3]
	s_mov_b32 s1, 0
	v_cmp_eq_u32_e64 s[4:5], 0, v0
	s_mov_b64 s[6:7], 0x200000
	s_mov_b64 s[8:9], 0x200800
	s_mov_b64 s[10:11], 0x400000
	s_mov_b64 s[12:13], 0x400800
	s_mov_b64 s[14:15], 0x600000
	s_mov_b64 s[16:17], 0x600800
	s_mov_b64 s[18:19], 0x800000
	s_mov_b32 s48, 0x800000
	s_mov_b64 s[20:21], 0x800800
	s_mov_b64 s[22:23], 0xa00000
	s_mov_b64 s[24:25], 0xa00800
	s_mov_b64 s[26:27], 0xc00000
	s_mov_b64 s[28:29], 0xc00800
	s_mov_b64 s[34:35], 0xe00000
	s_mov_b64 s[36:37], 0xe00800
	v_mov_b32_e32 v104, 0
	v_mov_b32_e32 v105, 0x358637bd
	s_mov_b32 s40, s80
	v_mbcnt_lo_u32_b32 v176, -1, 0
	v_mbcnt_hi_u32_b32 v176, -1, v176
	v_readlane_b32 s98, v235, 49
	v_readlane_b32 s99, v235, 20
	v_readlane_b32 s100, v235, 14
	v_readlane_b32 s101, v235, 15
	s_nop 3
	s_lshr_b32 vcc_lo, s98, 3
	s_and_b32 vcc_hi, vcc_lo, 7
	s_lshr_b32 vcc_lo, vcc_lo, 3
	s_lshl_b32 vcc_lo, vcc_lo, 3
	s_add_i32 vcc_lo, vcc_lo, s99
	s_lshl_b32 s98, vcc_hi, 8
	s_add_i32 s98, s98, vcc_lo
	s_lshl_b32 s99, vcc_hi, 11
	s_add_i32 s99, s99, vcc_lo
	v_mov_b32_e32 v183, s99
	v_lshlrev_b32_e32 v177, 4, v176
	s_lshl_b32 s99, s99, 11
	v_add_u32_e32 v177, s99, v177
	v_add_u32_e32 v178, 0x1800000, v177
	v_add_u32_e32 v179, 0x9e00000, v177
	v_lshlrev_b32_e32 v180, 5, v176
	global_load_dwordx4 v[128:131], v180, s[100:101]
	global_load_dwordx4 v[132:135], v180, s[100:101] offset:16
	global_load_dwordx4 v[136:139], v180, s[100:101] offset:2048
	global_load_dwordx4 v[140:143], v180, s[100:101] offset:2064
	v_mov_b32_e32 v182, 0x358637bd
	global_load_dwordx4 v[0:3], v178, s[78:79]
	global_load_dwordx4 v[4:7], v178, s[78:79] offset:1024
	global_load_dwordx4 v[8:11], v179, s[78:79]
	global_load_dwordx4 v[12:15], v179, s[78:79] offset:1024
	v_add_u32_e32 v178, 0x80000, v178
	v_add_u32_e32 v179, 0x80000, v179
	global_load_dwordx4 v[16:19], v178, s[78:79]
	global_load_dwordx4 v[20:23], v178, s[78:79] offset:1024
	global_load_dwordx4 v[24:27], v179, s[78:79]
	global_load_dwordx4 v[28:31], v179, s[78:79] offset:1024
	v_add_u32_e32 v178, 0x80000, v178
	v_add_u32_e32 v179, 0x80000, v179
	global_load_dwordx4 v[32:35], v178, s[78:79]
	global_load_dwordx4 v[36:39], v178, s[78:79] offset:1024
	global_load_dwordx4 v[40:43], v179, s[78:79]
	global_load_dwordx4 v[44:47], v179, s[78:79] offset:1024
	v_add_u32_e32 v178, 0x80000, v178
	v_add_u32_e32 v179, 0x80000, v179
	global_load_dwordx4 v[48:51], v178, s[78:79]
	global_load_dwordx4 v[52:55], v178, s[78:79] offset:1024
	global_load_dwordx4 v[56:59], v179, s[78:79]
	global_load_dwordx4 v[60:63], v179, s[78:79] offset:1024
	v_add_u32_e32 v178, 0x80000, v178
	v_add_u32_e32 v179, 0x80000, v179
	global_load_dwordx4 v[64:67], v178, s[78:79]
	global_load_dwordx4 v[68:71], v178, s[78:79] offset:1024
	global_load_dwordx4 v[72:75], v179, s[78:79]
	global_load_dwordx4 v[76:79], v179, s[78:79] offset:1024
	v_add_u32_e32 v178, 0x80000, v178
	v_add_u32_e32 v179, 0x80000, v179
	global_load_dwordx4 v[80:83], v178, s[78:79]
	global_load_dwordx4 v[84:87], v178, s[78:79] offset:1024
	global_load_dwordx4 v[88:91], v179, s[78:79]
	global_load_dwordx4 v[92:95], v179, s[78:79] offset:1024
	v_add_u32_e32 v178, 0x80000, v178
	v_add_u32_e32 v179, 0x80000, v179
	global_load_dwordx4 v[96:99], v178, s[78:79]
	global_load_dwordx4 v[100:103], v178, s[78:79] offset:1024
	global_load_dwordx4 v[104:107], v179, s[78:79]
	global_load_dwordx4 v[108:111], v179, s[78:79] offset:1024
	v_add_u32_e32 v178, 0x80000, v178
	v_add_u32_e32 v179, 0x80000, v179
	global_load_dwordx4 v[112:115], v178, s[78:79]
	global_load_dwordx4 v[116:119], v178, s[78:79] offset:1024
	global_load_dwordx4 v[120:123], v179, s[78:79]
	global_load_dwordx4 v[124:127], v179, s[78:79] offset:1024
	v_lshlrev_b32_e32 v237, 2, v183
	v_add_u32_e32 v237, 0x10000, v237
	v_mov_b32_e32 v179, s98
	s_waitcnt vmcnt(28)
	v_lshlrev_b32_e32 v144, 16, v0
	v_and_b32_e32 v145, 0xffff0000, v0
	v_lshlrev_b32_e32 v146, 16, v1
	v_and_b32_e32 v147, 0xffff0000, v1
	v_lshlrev_b32_e32 v148, 16, v2
	v_and_b32_e32 v149, 0xffff0000, v2
	v_lshlrev_b32_e32 v150, 16, v3
	v_and_b32_e32 v151, 0xffff0000, v3
	v_lshlrev_b32_e32 v152, 16, v4
	v_and_b32_e32 v153, 0xffff0000, v4
	v_lshlrev_b32_e32 v154, 16, v5
	v_and_b32_e32 v155, 0xffff0000, v5
	v_lshlrev_b32_e32 v156, 16, v6
	v_and_b32_e32 v157, 0xffff0000, v6
	v_lshlrev_b32_e32 v158, 16, v7
	v_and_b32_e32 v159, 0xffff0000, v7
	v_lshlrev_b32_e32 v160, 16, v8
	v_and_b32_e32 v161, 0xffff0000, v8
	v_lshlrev_b32_e32 v162, 16, v9
	v_and_b32_e32 v163, 0xffff0000, v9
	v_lshlrev_b32_e32 v164, 16, v10
	v_and_b32_e32 v165, 0xffff0000, v10
	v_lshlrev_b32_e32 v166, 16, v11
	v_and_b32_e32 v167, 0xffff0000, v11
	v_lshlrev_b32_e32 v168, 16, v12
	v_and_b32_e32 v169, 0xffff0000, v12
	v_lshlrev_b32_e32 v170, 16, v13
	v_and_b32_e32 v171, 0xffff0000, v13
	v_lshlrev_b32_e32 v172, 16, v14
	v_and_b32_e32 v173, 0xffff0000, v14
	v_lshlrev_b32_e32 v174, 16, v15
	v_and_b32_e32 v175, 0xffff0000, v15
	v_pk_mul_f32 v[252:253], v[160:161], v[160:161]
	v_pk_mul_f32 v[254:255], v[162:163], v[162:163]
	v_pk_fma_f32 v[252:253], v[164:165], v[164:165], v[252:253]
	v_pk_fma_f32 v[254:255], v[166:167], v[166:167], v[254:255]
	v_pk_fma_f32 v[252:253], v[168:169], v[168:169], v[252:253]
	v_pk_fma_f32 v[254:255], v[170:171], v[170:171], v[254:255]
	v_pk_fma_f32 v[252:253], v[172:173], v[172:173], v[252:253]
	v_pk_fma_f32 v[254:255], v[174:175], v[174:175], v[254:255]
	v_pk_add_f32 v[252:253], v[252:253], v[254:255]
	s_nop 0
	v_add_f32_e32 v183, v252, v253
	s_nop 1
	v_add_f32_dpp v183, v183, v183 quad_perm:[1,0,3,2] row_mask:0xf bank_mask:0xf bound_ctrl:1
	s_nop 1
	v_add_f32_dpp v183, v183, v183 quad_perm:[2,3,0,1] row_mask:0xf bank_mask:0xf bound_ctrl:1
	s_nop 1
	v_add_f32_dpp v183, v183, v183 row_half_mirror row_mask:0xf bank_mask:0xf bound_ctrl:1
	s_nop 1
	v_add_f32_dpp v183, v183, v183 row_mirror row_mask:0xf bank_mask:0xf bound_ctrl:1
	s_nop 1
	v_readlane_b32 s98, v183, 0
	v_readlane_b32 s99, v183, 16
	v_readlane_b32 s100, v183, 32
	v_readlane_b32 s101, v183, 48
	s_nop 1
	v_mov_b32_e32 v183, s98
	v_add_f32_e32 v183, s99, v183
	v_add_f32_e32 v183, s100, v183
	v_add_f32_e32 v183, s101, v183
	v_fmamk_f32 v183, v183, 0x3a800000, v182
	v_cmp_gt_f32_e32 vcc, 0x800000, v183
	v_mul_f32_e32 v181, 0x4b800000, v183
	s_nop 1
	v_cndmask_b32_e32 v183, v183, v181, vcc
	v_rsq_f32_e32 v183, v183
	s_nop 0
	v_mul_f32_e32 v181, 0x45800000, v183
	v_cndmask_b32_e32 v184, v183, v181, vcc
	v_mov_b32_e32 v185, v184
	v_pk_mul_f32 v[160:161], v[160:161], v[184:185]
	v_pk_mul_f32 v[162:163], v[162:163], v[184:185]
	v_pk_mul_f32 v[164:165], v[164:165], v[184:185]
	v_pk_mul_f32 v[166:167], v[166:167], v[184:185]
	v_pk_mul_f32 v[168:169], v[168:169], v[184:185]
	v_pk_mul_f32 v[170:171], v[170:171], v[184:185]
	v_pk_mul_f32 v[172:173], v[172:173], v[184:185]
	v_pk_mul_f32 v[174:175], v[174:175], v[184:185]
	v_pk_fma_f32 v[144:145], v[160:161], v[128:129], v[144:145]
	v_pk_fma_f32 v[146:147], v[162:163], v[130:131], v[146:147]
	v_pk_fma_f32 v[148:149], v[164:165], v[132:133], v[148:149]
	v_pk_fma_f32 v[150:151], v[166:167], v[134:135], v[150:151]
	v_pk_fma_f32 v[152:153], v[168:169], v[136:137], v[152:153]
	v_pk_fma_f32 v[154:155], v[170:171], v[138:139], v[154:155]
	v_pk_fma_f32 v[156:157], v[172:173], v[140:141], v[156:157]
	v_pk_fma_f32 v[158:159], v[174:175], v[142:143], v[158:159]
	v_pk_mul_f32 v[252:253], v[144:145], v[144:145]
	v_pk_mul_f32 v[254:255], v[146:147], v[146:147]
	v_pk_fma_f32 v[252:253], v[148:149], v[148:149], v[252:253]
	v_pk_fma_f32 v[254:255], v[150:151], v[150:151], v[254:255]
	v_pk_fma_f32 v[252:253], v[152:153], v[152:153], v[252:253]
	v_pk_fma_f32 v[254:255], v[154:155], v[154:155], v[254:255]
	v_pk_fma_f32 v[252:253], v[156:157], v[156:157], v[252:253]
	v_pk_fma_f32 v[254:255], v[158:159], v[158:159], v[254:255]
	v_pk_add_f32 v[252:253], v[252:253], v[254:255]
	s_nop 0
	v_add_f32_e32 v183, v252, v253
	s_nop 1
	v_add_f32_dpp v183, v183, v183 quad_perm:[1,0,3,2] row_mask:0xf bank_mask:0xf bound_ctrl:1
	s_nop 1
	v_add_f32_dpp v183, v183, v183 quad_perm:[2,3,0,1] row_mask:0xf bank_mask:0xf bound_ctrl:1
	s_nop 1
	v_add_f32_dpp v183, v183, v183 row_half_mirror row_mask:0xf bank_mask:0xf bound_ctrl:1
	s_nop 1
	v_add_f32_dpp v183, v183, v183 row_mirror row_mask:0xf bank_mask:0xf bound_ctrl:1
	s_nop 1
	v_readlane_b32 s98, v183, 0
	v_readlane_b32 s99, v183, 16
	v_readlane_b32 s100, v183, 32
	v_readlane_b32 s101, v183, 48
	s_nop 1
	v_mov_b32_e32 v183, s98
	v_add_f32_e32 v183, s99, v183
	v_add_f32_e32 v183, s100, v183
	v_add_f32_e32 v183, s101, v183
	v_fmamk_f32 v183, v183, 0x3a800000, v182
	v_cmp_gt_f32_e32 vcc, 0x800000, v183
	v_mul_f32_e32 v181, 0x4b800000, v183
	s_nop 1
	v_cndmask_b32_e32 v183, v183, v181, vcc
	v_rsq_f32_e32 v183, v183
	s_nop 0
	v_mul_f32_e32 v181, 0x45800000, v183
	v_cndmask_b32_e32 v184, v183, v181, vcc
	v_mov_b32_e32 v185, v184
	v_cvt_pk_bf16_f32 v0, v144, v145
	v_cvt_pk_bf16_f32 v1, v146, v147
	v_cvt_pk_bf16_f32 v2, v148, v149
	v_cvt_pk_bf16_f32 v3, v150, v151
	v_cvt_pk_bf16_f32 v4, v152, v153
	v_cvt_pk_bf16_f32 v5, v154, v155
	v_cvt_pk_bf16_f32 v6, v156, v157
	v_cvt_pk_bf16_f32 v7, v158, v159
	v_add_u32_e32 v181, 0x1800000, v177
	global_store_dwordx4 v181, v[0:3], s[78:79]
	global_store_dwordx4 v181, v[4:7], s[78:79] offset:1024
	v_add_u32_e32 v236, 0x0, v237
	s_mov_b64 exec, 1
	global_store_dword v236, v184, s[78:79]
	s_mov_b64 exec, -1
	s_waitcnt vmcnt(24)
	v_lshlrev_b32_e32 v144, 16, v16
	v_and_b32_e32 v145, 0xffff0000, v16
	v_lshlrev_b32_e32 v146, 16, v17
	v_and_b32_e32 v147, 0xffff0000, v17
	v_lshlrev_b32_e32 v148, 16, v18
	v_and_b32_e32 v149, 0xffff0000, v18
	v_lshlrev_b32_e32 v150, 16, v19
	v_and_b32_e32 v151, 0xffff0000, v19
	v_lshlrev_b32_e32 v152, 16, v20
	v_and_b32_e32 v153, 0xffff0000, v20
	v_lshlrev_b32_e32 v154, 16, v21
	v_and_b32_e32 v155, 0xffff0000, v21
	v_lshlrev_b32_e32 v156, 16, v22
	v_and_b32_e32 v157, 0xffff0000, v22
	v_lshlrev_b32_e32 v158, 16, v23
	v_and_b32_e32 v159, 0xffff0000, v23
	v_lshlrev_b32_e32 v160, 16, v24
	v_and_b32_e32 v161, 0xffff0000, v24
	v_lshlrev_b32_e32 v162, 16, v25
	v_and_b32_e32 v163, 0xffff0000, v25
	v_lshlrev_b32_e32 v164, 16, v26
	v_and_b32_e32 v165, 0xffff0000, v26
	v_lshlrev_b32_e32 v166, 16, v27
	v_and_b32_e32 v167, 0xffff0000, v27
	v_lshlrev_b32_e32 v168, 16, v28
	v_and_b32_e32 v169, 0xffff0000, v28
	v_lshlrev_b32_e32 v170, 16, v29
	v_and_b32_e32 v171, 0xffff0000, v29
	v_lshlrev_b32_e32 v172, 16, v30
	v_and_b32_e32 v173, 0xffff0000, v30
	v_lshlrev_b32_e32 v174, 16, v31
	v_and_b32_e32 v175, 0xffff0000, v31
	v_pk_mul_f32 v[252:253], v[160:161], v[160:161]
	v_pk_mul_f32 v[254:255], v[162:163], v[162:163]
	v_pk_fma_f32 v[252:253], v[164:165], v[164:165], v[252:253]
	v_pk_fma_f32 v[254:255], v[166:167], v[166:167], v[254:255]
	v_pk_fma_f32 v[252:253], v[168:169], v[168:169], v[252:253]
	v_pk_fma_f32 v[254:255], v[170:171], v[170:171], v[254:255]
	v_pk_fma_f32 v[252:253], v[172:173], v[172:173], v[252:253]
	v_pk_fma_f32 v[254:255], v[174:175], v[174:175], v[254:255]
	v_pk_add_f32 v[252:253], v[252:253], v[254:255]
	s_nop 0
	v_add_f32_e32 v183, v252, v253
	s_nop 1
	v_add_f32_dpp v183, v183, v183 quad_perm:[1,0,3,2] row_mask:0xf bank_mask:0xf bound_ctrl:1
	s_nop 1
	v_add_f32_dpp v183, v183, v183 quad_perm:[2,3,0,1] row_mask:0xf bank_mask:0xf bound_ctrl:1
	s_nop 1
	v_add_f32_dpp v183, v183, v183 row_half_mirror row_mask:0xf bank_mask:0xf bound_ctrl:1
	s_nop 1
	v_add_f32_dpp v183, v183, v183 row_mirror row_mask:0xf bank_mask:0xf bound_ctrl:1
	s_nop 1
	v_readlane_b32 s98, v183, 0
	v_readlane_b32 s99, v183, 16
	v_readlane_b32 s100, v183, 32
	v_readlane_b32 s101, v183, 48
	s_nop 1
	v_mov_b32_e32 v183, s98
	v_add_f32_e32 v183, s99, v183
	v_add_f32_e32 v183, s100, v183
	v_add_f32_e32 v183, s101, v183
	v_fmamk_f32 v183, v183, 0x3a800000, v182
	v_cmp_gt_f32_e32 vcc, 0x800000, v183
	v_mul_f32_e32 v181, 0x4b800000, v183
	s_nop 1
	v_cndmask_b32_e32 v183, v183, v181, vcc
	v_rsq_f32_e32 v183, v183
	s_nop 0
	v_mul_f32_e32 v181, 0x45800000, v183
	v_cndmask_b32_e32 v184, v183, v181, vcc
	v_mov_b32_e32 v185, v184
	v_pk_mul_f32 v[160:161], v[160:161], v[184:185]
	v_pk_mul_f32 v[162:163], v[162:163], v[184:185]
	v_pk_mul_f32 v[164:165], v[164:165], v[184:185]
	v_pk_mul_f32 v[166:167], v[166:167], v[184:185]
	v_pk_mul_f32 v[168:169], v[168:169], v[184:185]
	v_pk_mul_f32 v[170:171], v[170:171], v[184:185]
	v_pk_mul_f32 v[172:173], v[172:173], v[184:185]
	v_pk_mul_f32 v[174:175], v[174:175], v[184:185]
	v_pk_fma_f32 v[144:145], v[160:161], v[128:129], v[144:145]
	v_pk_fma_f32 v[146:147], v[162:163], v[130:131], v[146:147]
	v_pk_fma_f32 v[148:149], v[164:165], v[132:133], v[148:149]
	v_pk_fma_f32 v[150:151], v[166:167], v[134:135], v[150:151]
	v_pk_fma_f32 v[152:153], v[168:169], v[136:137], v[152:153]
	v_pk_fma_f32 v[154:155], v[170:171], v[138:139], v[154:155]
	v_pk_fma_f32 v[156:157], v[172:173], v[140:141], v[156:157]
	v_pk_fma_f32 v[158:159], v[174:175], v[142:143], v[158:159]
	v_pk_mul_f32 v[252:253], v[144:145], v[144:145]
	v_pk_mul_f32 v[254:255], v[146:147], v[146:147]
	v_pk_fma_f32 v[252:253], v[148:149], v[148:149], v[252:253]
	v_pk_fma_f32 v[254:255], v[150:151], v[150:151], v[254:255]
	v_pk_fma_f32 v[252:253], v[152:153], v[152:153], v[252:253]
	v_pk_fma_f32 v[254:255], v[154:155], v[154:155], v[254:255]
	v_pk_fma_f32 v[252:253], v[156:157], v[156:157], v[252:253]
	v_pk_fma_f32 v[254:255], v[158:159], v[158:159], v[254:255]
	v_pk_add_f32 v[252:253], v[252:253], v[254:255]
	s_nop 0
	v_add_f32_e32 v183, v252, v253
	s_nop 1
	v_add_f32_dpp v183, v183, v183 quad_perm:[1,0,3,2] row_mask:0xf bank_mask:0xf bound_ctrl:1
	s_nop 1
	v_add_f32_dpp v183, v183, v183 quad_perm:[2,3,0,1] row_mask:0xf bank_mask:0xf bound_ctrl:1
	s_nop 1
	v_add_f32_dpp v183, v183, v183 row_half_mirror row_mask:0xf bank_mask:0xf bound_ctrl:1
	s_nop 1
	v_add_f32_dpp v183, v183, v183 row_mirror row_mask:0xf bank_mask:0xf bound_ctrl:1
	s_nop 1
	v_readlane_b32 s98, v183, 0
	v_readlane_b32 s99, v183, 16
	v_readlane_b32 s100, v183, 32
	v_readlane_b32 s101, v183, 48
	s_nop 1
	v_mov_b32_e32 v183, s98
	v_add_f32_e32 v183, s99, v183
	v_add_f32_e32 v183, s100, v183
	v_add_f32_e32 v183, s101, v183
	v_fmamk_f32 v183, v183, 0x3a800000, v182
	v_cmp_gt_f32_e32 vcc, 0x800000, v183
	v_mul_f32_e32 v181, 0x4b800000, v183
	s_nop 1
	v_cndmask_b32_e32 v183, v183, v181, vcc
	v_rsq_f32_e32 v183, v183
	s_nop 0
	v_mul_f32_e32 v181, 0x45800000, v183
	v_cndmask_b32_e32 v184, v183, v181, vcc
	v_mov_b32_e32 v185, v184
	v_cvt_pk_bf16_f32 v16, v144, v145
	v_cvt_pk_bf16_f32 v17, v146, v147
	v_cvt_pk_bf16_f32 v18, v148, v149
	v_cvt_pk_bf16_f32 v19, v150, v151
	v_cvt_pk_bf16_f32 v20, v152, v153
	v_cvt_pk_bf16_f32 v21, v154, v155
	v_cvt_pk_bf16_f32 v22, v156, v157
	v_cvt_pk_bf16_f32 v23, v158, v159
	v_add_u32_e32 v181, 0x1880000, v177
	global_store_dwordx4 v181, v[16:19], s[78:79]
	global_store_dwordx4 v181, v[20:23], s[78:79] offset:1024
	v_add_u32_e32 v236, 0x400, v237
	s_mov_b64 exec, 1
	global_store_dword v236, v184, s[78:79]
	s_mov_b64 exec, -1
	s_waitcnt vmcnt(20)
	v_lshlrev_b32_e32 v144, 16, v32
	v_and_b32_e32 v145, 0xffff0000, v32
	v_lshlrev_b32_e32 v146, 16, v33
	v_and_b32_e32 v147, 0xffff0000, v33
	v_lshlrev_b32_e32 v148, 16, v34
	v_and_b32_e32 v149, 0xffff0000, v34
	v_lshlrev_b32_e32 v150, 16, v35
	v_and_b32_e32 v151, 0xffff0000, v35
	v_lshlrev_b32_e32 v152, 16, v36
	v_and_b32_e32 v153, 0xffff0000, v36
	v_lshlrev_b32_e32 v154, 16, v37
	v_and_b32_e32 v155, 0xffff0000, v37
	v_lshlrev_b32_e32 v156, 16, v38
	v_and_b32_e32 v157, 0xffff0000, v38
	v_lshlrev_b32_e32 v158, 16, v39
	v_and_b32_e32 v159, 0xffff0000, v39
	v_lshlrev_b32_e32 v160, 16, v40
	v_and_b32_e32 v161, 0xffff0000, v40
	v_lshlrev_b32_e32 v162, 16, v41
	v_and_b32_e32 v163, 0xffff0000, v41
	v_lshlrev_b32_e32 v164, 16, v42
	v_and_b32_e32 v165, 0xffff0000, v42
	v_lshlrev_b32_e32 v166, 16, v43
	v_and_b32_e32 v167, 0xffff0000, v43
	v_lshlrev_b32_e32 v168, 16, v44
	v_and_b32_e32 v169, 0xffff0000, v44
	v_lshlrev_b32_e32 v170, 16, v45
	v_and_b32_e32 v171, 0xffff0000, v45
	v_lshlrev_b32_e32 v172, 16, v46
	v_and_b32_e32 v173, 0xffff0000, v46
	v_lshlrev_b32_e32 v174, 16, v47
	v_and_b32_e32 v175, 0xffff0000, v47
	v_pk_mul_f32 v[252:253], v[160:161], v[160:161]
	v_pk_mul_f32 v[254:255], v[162:163], v[162:163]
	v_pk_fma_f32 v[252:253], v[164:165], v[164:165], v[252:253]
	v_pk_fma_f32 v[254:255], v[166:167], v[166:167], v[254:255]
	v_pk_fma_f32 v[252:253], v[168:169], v[168:169], v[252:253]
	v_pk_fma_f32 v[254:255], v[170:171], v[170:171], v[254:255]
	v_pk_fma_f32 v[252:253], v[172:173], v[172:173], v[252:253]
	v_pk_fma_f32 v[254:255], v[174:175], v[174:175], v[254:255]
	v_pk_add_f32 v[252:253], v[252:253], v[254:255]
	s_nop 0
	v_add_f32_e32 v183, v252, v253
	s_nop 1
	v_add_f32_dpp v183, v183, v183 quad_perm:[1,0,3,2] row_mask:0xf bank_mask:0xf bound_ctrl:1
	s_nop 1
	v_add_f32_dpp v183, v183, v183 quad_perm:[2,3,0,1] row_mask:0xf bank_mask:0xf bound_ctrl:1
	s_nop 1
	v_add_f32_dpp v183, v183, v183 row_half_mirror row_mask:0xf bank_mask:0xf bound_ctrl:1
	s_nop 1
	v_add_f32_dpp v183, v183, v183 row_mirror row_mask:0xf bank_mask:0xf bound_ctrl:1
	s_nop 1
	v_readlane_b32 s98, v183, 0
	v_readlane_b32 s99, v183, 16
	v_readlane_b32 s100, v183, 32
	v_readlane_b32 s101, v183, 48
	s_nop 1
	v_mov_b32_e32 v183, s98
	v_add_f32_e32 v183, s99, v183
	v_add_f32_e32 v183, s100, v183
	v_add_f32_e32 v183, s101, v183
	v_fmamk_f32 v183, v183, 0x3a800000, v182
	v_cmp_gt_f32_e32 vcc, 0x800000, v183
	v_mul_f32_e32 v181, 0x4b800000, v183
	s_nop 1
	v_cndmask_b32_e32 v183, v183, v181, vcc
	v_rsq_f32_e32 v183, v183
	s_nop 0
	v_mul_f32_e32 v181, 0x45800000, v183
	v_cndmask_b32_e32 v184, v183, v181, vcc
	v_mov_b32_e32 v185, v184
	v_pk_mul_f32 v[160:161], v[160:161], v[184:185]
	v_pk_mul_f32 v[162:163], v[162:163], v[184:185]
	v_pk_mul_f32 v[164:165], v[164:165], v[184:185]
	v_pk_mul_f32 v[166:167], v[166:167], v[184:185]
	v_pk_mul_f32 v[168:169], v[168:169], v[184:185]
	v_pk_mul_f32 v[170:171], v[170:171], v[184:185]
	v_pk_mul_f32 v[172:173], v[172:173], v[184:185]
	v_pk_mul_f32 v[174:175], v[174:175], v[184:185]
	v_pk_fma_f32 v[144:145], v[160:161], v[128:129], v[144:145]
	v_pk_fma_f32 v[146:147], v[162:163], v[130:131], v[146:147]
	v_pk_fma_f32 v[148:149], v[164:165], v[132:133], v[148:149]
	v_pk_fma_f32 v[150:151], v[166:167], v[134:135], v[150:151]
	v_pk_fma_f32 v[152:153], v[168:169], v[136:137], v[152:153]
	v_pk_fma_f32 v[154:155], v[170:171], v[138:139], v[154:155]
	v_pk_fma_f32 v[156:157], v[172:173], v[140:141], v[156:157]
	v_pk_fma_f32 v[158:159], v[174:175], v[142:143], v[158:159]
	v_pk_mul_f32 v[252:253], v[144:145], v[144:145]
	v_pk_mul_f32 v[254:255], v[146:147], v[146:147]
	v_pk_fma_f32 v[252:253], v[148:149], v[148:149], v[252:253]
	v_pk_fma_f32 v[254:255], v[150:151], v[150:151], v[254:255]
	v_pk_fma_f32 v[252:253], v[152:153], v[152:153], v[252:253]
	v_pk_fma_f32 v[254:255], v[154:155], v[154:155], v[254:255]
	v_pk_fma_f32 v[252:253], v[156:157], v[156:157], v[252:253]
	v_pk_fma_f32 v[254:255], v[158:159], v[158:159], v[254:255]
	v_pk_add_f32 v[252:253], v[252:253], v[254:255]
	s_nop 0
	v_add_f32_e32 v183, v252, v253
	s_nop 1
	v_add_f32_dpp v183, v183, v183 quad_perm:[1,0,3,2] row_mask:0xf bank_mask:0xf bound_ctrl:1
	s_nop 1
	v_add_f32_dpp v183, v183, v183 quad_perm:[2,3,0,1] row_mask:0xf bank_mask:0xf bound_ctrl:1
	s_nop 1
	v_add_f32_dpp v183, v183, v183 row_half_mirror row_mask:0xf bank_mask:0xf bound_ctrl:1
	s_nop 1
	v_add_f32_dpp v183, v183, v183 row_mirror row_mask:0xf bank_mask:0xf bound_ctrl:1
	s_nop 1
	v_readlane_b32 s98, v183, 0
	v_readlane_b32 s99, v183, 16
	v_readlane_b32 s100, v183, 32
	v_readlane_b32 s101, v183, 48
	s_nop 1
	v_mov_b32_e32 v183, s98
	v_add_f32_e32 v183, s99, v183
	v_add_f32_e32 v183, s100, v183
	v_add_f32_e32 v183, s101, v183
	v_fmamk_f32 v183, v183, 0x3a800000, v182
	v_cmp_gt_f32_e32 vcc, 0x800000, v183
	v_mul_f32_e32 v181, 0x4b800000, v183
	s_nop 1
	v_cndmask_b32_e32 v183, v183, v181, vcc
	v_rsq_f32_e32 v183, v183
	s_nop 0
	v_mul_f32_e32 v181, 0x45800000, v183
	v_cndmask_b32_e32 v184, v183, v181, vcc
	v_mov_b32_e32 v185, v184
	v_cvt_pk_bf16_f32 v32, v144, v145
	v_cvt_pk_bf16_f32 v33, v146, v147
	v_cvt_pk_bf16_f32 v34, v148, v149
	v_cvt_pk_bf16_f32 v35, v150, v151
	v_cvt_pk_bf16_f32 v36, v152, v153
	v_cvt_pk_bf16_f32 v37, v154, v155
	v_cvt_pk_bf16_f32 v38, v156, v157
	v_cvt_pk_bf16_f32 v39, v158, v159
	v_add_u32_e32 v181, 0x1900000, v177
	global_store_dwordx4 v181, v[32:35], s[78:79]
	global_store_dwordx4 v181, v[36:39], s[78:79] offset:1024
	v_add_u32_e32 v236, 0x800, v237
	s_mov_b64 exec, 1
	global_store_dword v236, v184, s[78:79]
	s_mov_b64 exec, -1
	s_waitcnt vmcnt(16)
	v_lshlrev_b32_e32 v144, 16, v48
	v_and_b32_e32 v145, 0xffff0000, v48
	v_lshlrev_b32_e32 v146, 16, v49
	v_and_b32_e32 v147, 0xffff0000, v49
	v_lshlrev_b32_e32 v148, 16, v50
	v_and_b32_e32 v149, 0xffff0000, v50
	v_lshlrev_b32_e32 v150, 16, v51
	v_and_b32_e32 v151, 0xffff0000, v51
	v_lshlrev_b32_e32 v152, 16, v52
	v_and_b32_e32 v153, 0xffff0000, v52
	v_lshlrev_b32_e32 v154, 16, v53
	v_and_b32_e32 v155, 0xffff0000, v53
	v_lshlrev_b32_e32 v156, 16, v54
	v_and_b32_e32 v157, 0xffff0000, v54
	v_lshlrev_b32_e32 v158, 16, v55
	v_and_b32_e32 v159, 0xffff0000, v55
	v_lshlrev_b32_e32 v160, 16, v56
	v_and_b32_e32 v161, 0xffff0000, v56
	v_lshlrev_b32_e32 v162, 16, v57
	v_and_b32_e32 v163, 0xffff0000, v57
	v_lshlrev_b32_e32 v164, 16, v58
	v_and_b32_e32 v165, 0xffff0000, v58
	v_lshlrev_b32_e32 v166, 16, v59
	v_and_b32_e32 v167, 0xffff0000, v59
	v_lshlrev_b32_e32 v168, 16, v60
	v_and_b32_e32 v169, 0xffff0000, v60
	v_lshlrev_b32_e32 v170, 16, v61
	v_and_b32_e32 v171, 0xffff0000, v61
	v_lshlrev_b32_e32 v172, 16, v62
	v_and_b32_e32 v173, 0xffff0000, v62
	v_lshlrev_b32_e32 v174, 16, v63
	v_and_b32_e32 v175, 0xffff0000, v63
	v_pk_mul_f32 v[252:253], v[160:161], v[160:161]
	v_pk_mul_f32 v[254:255], v[162:163], v[162:163]
	v_pk_fma_f32 v[252:253], v[164:165], v[164:165], v[252:253]
	v_pk_fma_f32 v[254:255], v[166:167], v[166:167], v[254:255]
	v_pk_fma_f32 v[252:253], v[168:169], v[168:169], v[252:253]
	v_pk_fma_f32 v[254:255], v[170:171], v[170:171], v[254:255]
	v_pk_fma_f32 v[252:253], v[172:173], v[172:173], v[252:253]
	v_pk_fma_f32 v[254:255], v[174:175], v[174:175], v[254:255]
	v_pk_add_f32 v[252:253], v[252:253], v[254:255]
	s_nop 0
	v_add_f32_e32 v183, v252, v253
	s_nop 1
	v_add_f32_dpp v183, v183, v183 quad_perm:[1,0,3,2] row_mask:0xf bank_mask:0xf bound_ctrl:1
	s_nop 1
	v_add_f32_dpp v183, v183, v183 quad_perm:[2,3,0,1] row_mask:0xf bank_mask:0xf bound_ctrl:1
	s_nop 1
	v_add_f32_dpp v183, v183, v183 row_half_mirror row_mask:0xf bank_mask:0xf bound_ctrl:1
	s_nop 1
	v_add_f32_dpp v183, v183, v183 row_mirror row_mask:0xf bank_mask:0xf bound_ctrl:1
	s_nop 1
	v_readlane_b32 s98, v183, 0
	v_readlane_b32 s99, v183, 16
	v_readlane_b32 s100, v183, 32
	v_readlane_b32 s101, v183, 48
	s_nop 1
	v_mov_b32_e32 v183, s98
	v_add_f32_e32 v183, s99, v183
	v_add_f32_e32 v183, s100, v183
	v_add_f32_e32 v183, s101, v183
	v_fmamk_f32 v183, v183, 0x3a800000, v182
	v_cmp_gt_f32_e32 vcc, 0x800000, v183
	v_mul_f32_e32 v181, 0x4b800000, v183
	s_nop 1
	v_cndmask_b32_e32 v183, v183, v181, vcc
	v_rsq_f32_e32 v183, v183
	s_nop 0
	v_mul_f32_e32 v181, 0x45800000, v183
	v_cndmask_b32_e32 v184, v183, v181, vcc
	v_mov_b32_e32 v185, v184
	v_pk_mul_f32 v[160:161], v[160:161], v[184:185]
	v_pk_mul_f32 v[162:163], v[162:163], v[184:185]
	v_pk_mul_f32 v[164:165], v[164:165], v[184:185]
	v_pk_mul_f32 v[166:167], v[166:167], v[184:185]
	v_pk_mul_f32 v[168:169], v[168:169], v[184:185]
	v_pk_mul_f32 v[170:171], v[170:171], v[184:185]
	v_pk_mul_f32 v[172:173], v[172:173], v[184:185]
	v_pk_mul_f32 v[174:175], v[174:175], v[184:185]
	v_pk_fma_f32 v[144:145], v[160:161], v[128:129], v[144:145]
	v_pk_fma_f32 v[146:147], v[162:163], v[130:131], v[146:147]
	v_pk_fma_f32 v[148:149], v[164:165], v[132:133], v[148:149]
	v_pk_fma_f32 v[150:151], v[166:167], v[134:135], v[150:151]
	v_pk_fma_f32 v[152:153], v[168:169], v[136:137], v[152:153]
	v_pk_fma_f32 v[154:155], v[170:171], v[138:139], v[154:155]
	v_pk_fma_f32 v[156:157], v[172:173], v[140:141], v[156:157]
	v_pk_fma_f32 v[158:159], v[174:175], v[142:143], v[158:159]
	v_pk_mul_f32 v[252:253], v[144:145], v[144:145]
	v_pk_mul_f32 v[254:255], v[146:147], v[146:147]
	v_pk_fma_f32 v[252:253], v[148:149], v[148:149], v[252:253]
	v_pk_fma_f32 v[254:255], v[150:151], v[150:151], v[254:255]
	v_pk_fma_f32 v[252:253], v[152:153], v[152:153], v[252:253]
	v_pk_fma_f32 v[254:255], v[154:155], v[154:155], v[254:255]
	v_pk_fma_f32 v[252:253], v[156:157], v[156:157], v[252:253]
	v_pk_fma_f32 v[254:255], v[158:159], v[158:159], v[254:255]
	v_pk_add_f32 v[252:253], v[252:253], v[254:255]
	s_nop 0
	v_add_f32_e32 v183, v252, v253
	s_nop 1
	v_add_f32_dpp v183, v183, v183 quad_perm:[1,0,3,2] row_mask:0xf bank_mask:0xf bound_ctrl:1
	s_nop 1
	v_add_f32_dpp v183, v183, v183 quad_perm:[2,3,0,1] row_mask:0xf bank_mask:0xf bound_ctrl:1
	s_nop 1
	v_add_f32_dpp v183, v183, v183 row_half_mirror row_mask:0xf bank_mask:0xf bound_ctrl:1
	s_nop 1
	v_add_f32_dpp v183, v183, v183 row_mirror row_mask:0xf bank_mask:0xf bound_ctrl:1
	s_nop 1
	v_readlane_b32 s98, v183, 0
	v_readlane_b32 s99, v183, 16
	v_readlane_b32 s100, v183, 32
	v_readlane_b32 s101, v183, 48
	s_nop 1
	v_mov_b32_e32 v183, s98
	v_add_f32_e32 v183, s99, v183
	v_add_f32_e32 v183, s100, v183
	v_add_f32_e32 v183, s101, v183
	v_fmamk_f32 v183, v183, 0x3a800000, v182
	v_cmp_gt_f32_e32 vcc, 0x800000, v183
	v_mul_f32_e32 v181, 0x4b800000, v183
	s_nop 1
	v_cndmask_b32_e32 v183, v183, v181, vcc
	v_rsq_f32_e32 v183, v183
	s_nop 0
	v_mul_f32_e32 v181, 0x45800000, v183
	v_cndmask_b32_e32 v184, v183, v181, vcc
	v_mov_b32_e32 v185, v184
	v_cvt_pk_bf16_f32 v48, v144, v145
	v_cvt_pk_bf16_f32 v49, v146, v147
	v_cvt_pk_bf16_f32 v50, v148, v149
	v_cvt_pk_bf16_f32 v51, v150, v151
	v_cvt_pk_bf16_f32 v52, v152, v153
	v_cvt_pk_bf16_f32 v53, v154, v155
	v_cvt_pk_bf16_f32 v54, v156, v157
	v_cvt_pk_bf16_f32 v55, v158, v159
	v_add_u32_e32 v181, 0x1980000, v177
	global_store_dwordx4 v181, v[48:51], s[78:79]
	global_store_dwordx4 v181, v[52:55], s[78:79] offset:1024
	v_add_u32_e32 v236, 0xc00, v237
	s_mov_b64 exec, 1
	global_store_dword v236, v184, s[78:79]
	s_mov_b64 exec, -1
	s_waitcnt vmcnt(12)
	v_lshlrev_b32_e32 v144, 16, v64
	v_and_b32_e32 v145, 0xffff0000, v64
	v_lshlrev_b32_e32 v146, 16, v65
	v_and_b32_e32 v147, 0xffff0000, v65
	v_lshlrev_b32_e32 v148, 16, v66
	v_and_b32_e32 v149, 0xffff0000, v66
	v_lshlrev_b32_e32 v150, 16, v67
	v_and_b32_e32 v151, 0xffff0000, v67
	v_lshlrev_b32_e32 v152, 16, v68
	v_and_b32_e32 v153, 0xffff0000, v68
	v_lshlrev_b32_e32 v154, 16, v69
	v_and_b32_e32 v155, 0xffff0000, v69
	v_lshlrev_b32_e32 v156, 16, v70
	v_and_b32_e32 v157, 0xffff0000, v70
	v_lshlrev_b32_e32 v158, 16, v71
	v_and_b32_e32 v159, 0xffff0000, v71
	v_lshlrev_b32_e32 v160, 16, v72
	v_and_b32_e32 v161, 0xffff0000, v72
	v_lshlrev_b32_e32 v162, 16, v73
	v_and_b32_e32 v163, 0xffff0000, v73
	v_lshlrev_b32_e32 v164, 16, v74
	v_and_b32_e32 v165, 0xffff0000, v74
	v_lshlrev_b32_e32 v166, 16, v75
	v_and_b32_e32 v167, 0xffff0000, v75
	v_lshlrev_b32_e32 v168, 16, v76
	v_and_b32_e32 v169, 0xffff0000, v76
	v_lshlrev_b32_e32 v170, 16, v77
	v_and_b32_e32 v171, 0xffff0000, v77
	v_lshlrev_b32_e32 v172, 16, v78
	v_and_b32_e32 v173, 0xffff0000, v78
	v_lshlrev_b32_e32 v174, 16, v79
	v_and_b32_e32 v175, 0xffff0000, v79
	v_pk_mul_f32 v[252:253], v[160:161], v[160:161]
	v_pk_mul_f32 v[254:255], v[162:163], v[162:163]
	v_pk_fma_f32 v[252:253], v[164:165], v[164:165], v[252:253]
	v_pk_fma_f32 v[254:255], v[166:167], v[166:167], v[254:255]
	v_pk_fma_f32 v[252:253], v[168:169], v[168:169], v[252:253]
	v_pk_fma_f32 v[254:255], v[170:171], v[170:171], v[254:255]
	v_pk_fma_f32 v[252:253], v[172:173], v[172:173], v[252:253]
	v_pk_fma_f32 v[254:255], v[174:175], v[174:175], v[254:255]
	v_pk_add_f32 v[252:253], v[252:253], v[254:255]
	s_nop 0
	v_add_f32_e32 v183, v252, v253
	s_nop 1
	v_add_f32_dpp v183, v183, v183 quad_perm:[1,0,3,2] row_mask:0xf bank_mask:0xf bound_ctrl:1
	s_nop 1
	v_add_f32_dpp v183, v183, v183 quad_perm:[2,3,0,1] row_mask:0xf bank_mask:0xf bound_ctrl:1
	s_nop 1
	v_add_f32_dpp v183, v183, v183 row_half_mirror row_mask:0xf bank_mask:0xf bound_ctrl:1
	s_nop 1
	v_add_f32_dpp v183, v183, v183 row_mirror row_mask:0xf bank_mask:0xf bound_ctrl:1
	s_nop 1
	v_readlane_b32 s98, v183, 0
	v_readlane_b32 s99, v183, 16
	v_readlane_b32 s100, v183, 32
	v_readlane_b32 s101, v183, 48
	s_nop 1
	v_mov_b32_e32 v183, s98
	v_add_f32_e32 v183, s99, v183
	v_add_f32_e32 v183, s100, v183
	v_add_f32_e32 v183, s101, v183
	v_fmamk_f32 v183, v183, 0x3a800000, v182
	v_cmp_gt_f32_e32 vcc, 0x800000, v183
	v_mul_f32_e32 v181, 0x4b800000, v183
	s_nop 1
	v_cndmask_b32_e32 v183, v183, v181, vcc
	v_rsq_f32_e32 v183, v183
	s_nop 0
	v_mul_f32_e32 v181, 0x45800000, v183
	v_cndmask_b32_e32 v184, v183, v181, vcc
	v_mov_b32_e32 v185, v184
	v_pk_mul_f32 v[160:161], v[160:161], v[184:185]
	v_pk_mul_f32 v[162:163], v[162:163], v[184:185]
	v_pk_mul_f32 v[164:165], v[164:165], v[184:185]
	v_pk_mul_f32 v[166:167], v[166:167], v[184:185]
	v_pk_mul_f32 v[168:169], v[168:169], v[184:185]
	v_pk_mul_f32 v[170:171], v[170:171], v[184:185]
	v_pk_mul_f32 v[172:173], v[172:173], v[184:185]
	v_pk_mul_f32 v[174:175], v[174:175], v[184:185]
	v_pk_fma_f32 v[144:145], v[160:161], v[128:129], v[144:145]
	v_pk_fma_f32 v[146:147], v[162:163], v[130:131], v[146:147]
	v_pk_fma_f32 v[148:149], v[164:165], v[132:133], v[148:149]
	v_pk_fma_f32 v[150:151], v[166:167], v[134:135], v[150:151]
	v_pk_fma_f32 v[152:153], v[168:169], v[136:137], v[152:153]
	v_pk_fma_f32 v[154:155], v[170:171], v[138:139], v[154:155]
	v_pk_fma_f32 v[156:157], v[172:173], v[140:141], v[156:157]
	v_pk_fma_f32 v[158:159], v[174:175], v[142:143], v[158:159]
	v_pk_mul_f32 v[252:253], v[144:145], v[144:145]
	v_pk_mul_f32 v[254:255], v[146:147], v[146:147]
	v_pk_fma_f32 v[252:253], v[148:149], v[148:149], v[252:253]
	v_pk_fma_f32 v[254:255], v[150:151], v[150:151], v[254:255]
	v_pk_fma_f32 v[252:253], v[152:153], v[152:153], v[252:253]
	v_pk_fma_f32 v[254:255], v[154:155], v[154:155], v[254:255]
	v_pk_fma_f32 v[252:253], v[156:157], v[156:157], v[252:253]
	v_pk_fma_f32 v[254:255], v[158:159], v[158:159], v[254:255]
	v_pk_add_f32 v[252:253], v[252:253], v[254:255]
	s_nop 0
	v_add_f32_e32 v183, v252, v253
	s_nop 1
	v_add_f32_dpp v183, v183, v183 quad_perm:[1,0,3,2] row_mask:0xf bank_mask:0xf bound_ctrl:1
	s_nop 1
	v_add_f32_dpp v183, v183, v183 quad_perm:[2,3,0,1] row_mask:0xf bank_mask:0xf bound_ctrl:1
	s_nop 1
	v_add_f32_dpp v183, v183, v183 row_half_mirror row_mask:0xf bank_mask:0xf bound_ctrl:1
	s_nop 1
	v_add_f32_dpp v183, v183, v183 row_mirror row_mask:0xf bank_mask:0xf bound_ctrl:1
	s_nop 1
	v_readlane_b32 s98, v183, 0
	v_readlane_b32 s99, v183, 16
	v_readlane_b32 s100, v183, 32
	v_readlane_b32 s101, v183, 48
	s_nop 1
	v_mov_b32_e32 v183, s98
	v_add_f32_e32 v183, s99, v183
	v_add_f32_e32 v183, s100, v183
	v_add_f32_e32 v183, s101, v183
	v_fmamk_f32 v183, v183, 0x3a800000, v182
	v_cmp_gt_f32_e32 vcc, 0x800000, v183
	v_mul_f32_e32 v181, 0x4b800000, v183
	s_nop 1
	v_cndmask_b32_e32 v183, v183, v181, vcc
	v_rsq_f32_e32 v183, v183
	s_nop 0
	v_mul_f32_e32 v181, 0x45800000, v183
	v_cndmask_b32_e32 v184, v183, v181, vcc
	v_mov_b32_e32 v185, v184
	v_cvt_pk_bf16_f32 v64, v144, v145
	v_cvt_pk_bf16_f32 v65, v146, v147
	v_cvt_pk_bf16_f32 v66, v148, v149
	v_cvt_pk_bf16_f32 v67, v150, v151
	v_cvt_pk_bf16_f32 v68, v152, v153
	v_cvt_pk_bf16_f32 v69, v154, v155
	v_cvt_pk_bf16_f32 v70, v156, v157
	v_cvt_pk_bf16_f32 v71, v158, v159
	v_add_u32_e32 v181, 0x1a00000, v177
	global_store_dwordx4 v181, v[64:67], s[78:79]
	global_store_dwordx4 v181, v[68:71], s[78:79] offset:1024
	v_add_u32_e32 v236, 0x1000, v237
	s_mov_b64 exec, 1
	global_store_dword v236, v184, s[78:79]
	s_mov_b64 exec, -1
	s_waitcnt vmcnt(8)
	v_lshlrev_b32_e32 v144, 16, v80
	v_and_b32_e32 v145, 0xffff0000, v80
	v_lshlrev_b32_e32 v146, 16, v81
	v_and_b32_e32 v147, 0xffff0000, v81
	v_lshlrev_b32_e32 v148, 16, v82
	v_and_b32_e32 v149, 0xffff0000, v82
	v_lshlrev_b32_e32 v150, 16, v83
	v_and_b32_e32 v151, 0xffff0000, v83
	v_lshlrev_b32_e32 v152, 16, v84
	v_and_b32_e32 v153, 0xffff0000, v84
	v_lshlrev_b32_e32 v154, 16, v85
	v_and_b32_e32 v155, 0xffff0000, v85
	v_lshlrev_b32_e32 v156, 16, v86
	v_and_b32_e32 v157, 0xffff0000, v86
	v_lshlrev_b32_e32 v158, 16, v87
	v_and_b32_e32 v159, 0xffff0000, v87
	v_lshlrev_b32_e32 v160, 16, v88
	v_and_b32_e32 v161, 0xffff0000, v88
	v_lshlrev_b32_e32 v162, 16, v89
	v_and_b32_e32 v163, 0xffff0000, v89
	v_lshlrev_b32_e32 v164, 16, v90
	v_and_b32_e32 v165, 0xffff0000, v90
	v_lshlrev_b32_e32 v166, 16, v91
	v_and_b32_e32 v167, 0xffff0000, v91
	v_lshlrev_b32_e32 v168, 16, v92
	v_and_b32_e32 v169, 0xffff0000, v92
	v_lshlrev_b32_e32 v170, 16, v93
	v_and_b32_e32 v171, 0xffff0000, v93
	v_lshlrev_b32_e32 v172, 16, v94
	v_and_b32_e32 v173, 0xffff0000, v94
	v_lshlrev_b32_e32 v174, 16, v95
	v_and_b32_e32 v175, 0xffff0000, v95
	v_pk_mul_f32 v[252:253], v[160:161], v[160:161]
	v_pk_mul_f32 v[254:255], v[162:163], v[162:163]
	v_pk_fma_f32 v[252:253], v[164:165], v[164:165], v[252:253]
	v_pk_fma_f32 v[254:255], v[166:167], v[166:167], v[254:255]
	v_pk_fma_f32 v[252:253], v[168:169], v[168:169], v[252:253]
	v_pk_fma_f32 v[254:255], v[170:171], v[170:171], v[254:255]
	v_pk_fma_f32 v[252:253], v[172:173], v[172:173], v[252:253]
	v_pk_fma_f32 v[254:255], v[174:175], v[174:175], v[254:255]
	v_pk_add_f32 v[252:253], v[252:253], v[254:255]
	s_nop 0
	v_add_f32_e32 v183, v252, v253
	s_nop 1
	v_add_f32_dpp v183, v183, v183 quad_perm:[1,0,3,2] row_mask:0xf bank_mask:0xf bound_ctrl:1
	s_nop 1
	v_add_f32_dpp v183, v183, v183 quad_perm:[2,3,0,1] row_mask:0xf bank_mask:0xf bound_ctrl:1
	s_nop 1
	v_add_f32_dpp v183, v183, v183 row_half_mirror row_mask:0xf bank_mask:0xf bound_ctrl:1
	s_nop 1
	v_add_f32_dpp v183, v183, v183 row_mirror row_mask:0xf bank_mask:0xf bound_ctrl:1
	s_nop 1
	v_readlane_b32 s98, v183, 0
	v_readlane_b32 s99, v183, 16
	v_readlane_b32 s100, v183, 32
	v_readlane_b32 s101, v183, 48
	s_nop 1
	v_mov_b32_e32 v183, s98
	v_add_f32_e32 v183, s99, v183
	v_add_f32_e32 v183, s100, v183
	v_add_f32_e32 v183, s101, v183
	v_fmamk_f32 v183, v183, 0x3a800000, v182
	v_cmp_gt_f32_e32 vcc, 0x800000, v183
	v_mul_f32_e32 v181, 0x4b800000, v183
	s_nop 1
	v_cndmask_b32_e32 v183, v183, v181, vcc
	v_rsq_f32_e32 v183, v183
	s_nop 0
	v_mul_f32_e32 v181, 0x45800000, v183
	v_cndmask_b32_e32 v184, v183, v181, vcc
	v_mov_b32_e32 v185, v184
	v_pk_mul_f32 v[160:161], v[160:161], v[184:185]
	v_pk_mul_f32 v[162:163], v[162:163], v[184:185]
	v_pk_mul_f32 v[164:165], v[164:165], v[184:185]
	v_pk_mul_f32 v[166:167], v[166:167], v[184:185]
	v_pk_mul_f32 v[168:169], v[168:169], v[184:185]
	v_pk_mul_f32 v[170:171], v[170:171], v[184:185]
	v_pk_mul_f32 v[172:173], v[172:173], v[184:185]
	v_pk_mul_f32 v[174:175], v[174:175], v[184:185]
	v_pk_fma_f32 v[144:145], v[160:161], v[128:129], v[144:145]
	v_pk_fma_f32 v[146:147], v[162:163], v[130:131], v[146:147]
	v_pk_fma_f32 v[148:149], v[164:165], v[132:133], v[148:149]
	v_pk_fma_f32 v[150:151], v[166:167], v[134:135], v[150:151]
	v_pk_fma_f32 v[152:153], v[168:169], v[136:137], v[152:153]
	v_pk_fma_f32 v[154:155], v[170:171], v[138:139], v[154:155]
	v_pk_fma_f32 v[156:157], v[172:173], v[140:141], v[156:157]
	v_pk_fma_f32 v[158:159], v[174:175], v[142:143], v[158:159]
	v_pk_mul_f32 v[252:253], v[144:145], v[144:145]
	v_pk_mul_f32 v[254:255], v[146:147], v[146:147]
	v_pk_fma_f32 v[252:253], v[148:149], v[148:149], v[252:253]
	v_pk_fma_f32 v[254:255], v[150:151], v[150:151], v[254:255]
	v_pk_fma_f32 v[252:253], v[152:153], v[152:153], v[252:253]
	v_pk_fma_f32 v[254:255], v[154:155], v[154:155], v[254:255]
	v_pk_fma_f32 v[252:253], v[156:157], v[156:157], v[252:253]
	v_pk_fma_f32 v[254:255], v[158:159], v[158:159], v[254:255]
	v_pk_add_f32 v[252:253], v[252:253], v[254:255]
	s_nop 0
	v_add_f32_e32 v183, v252, v253
	s_nop 1
	v_add_f32_dpp v183, v183, v183 quad_perm:[1,0,3,2] row_mask:0xf bank_mask:0xf bound_ctrl:1
	s_nop 1
	v_add_f32_dpp v183, v183, v183 quad_perm:[2,3,0,1] row_mask:0xf bank_mask:0xf bound_ctrl:1
	s_nop 1
	v_add_f32_dpp v183, v183, v183 row_half_mirror row_mask:0xf bank_mask:0xf bound_ctrl:1
	s_nop 1
	v_add_f32_dpp v183, v183, v183 row_mirror row_mask:0xf bank_mask:0xf bound_ctrl:1
	s_nop 1
	v_readlane_b32 s98, v183, 0
	v_readlane_b32 s99, v183, 16
	v_readlane_b32 s100, v183, 32
	v_readlane_b32 s101, v183, 48
	s_nop 1
	v_mov_b32_e32 v183, s98
	v_add_f32_e32 v183, s99, v183
	v_add_f32_e32 v183, s100, v183
	v_add_f32_e32 v183, s101, v183
	v_fmamk_f32 v183, v183, 0x3a800000, v182
	v_cmp_gt_f32_e32 vcc, 0x800000, v183
	v_mul_f32_e32 v181, 0x4b800000, v183
	s_nop 1
	v_cndmask_b32_e32 v183, v183, v181, vcc
	v_rsq_f32_e32 v183, v183
	s_nop 0
	v_mul_f32_e32 v181, 0x45800000, v183
	v_cndmask_b32_e32 v184, v183, v181, vcc
	v_mov_b32_e32 v185, v184
	v_cvt_pk_bf16_f32 v80, v144, v145
	v_cvt_pk_bf16_f32 v81, v146, v147
	v_cvt_pk_bf16_f32 v82, v148, v149
	v_cvt_pk_bf16_f32 v83, v150, v151
	v_cvt_pk_bf16_f32 v84, v152, v153
	v_cvt_pk_bf16_f32 v85, v154, v155
	v_cvt_pk_bf16_f32 v86, v156, v157
	v_cvt_pk_bf16_f32 v87, v158, v159
	v_add_u32_e32 v181, 0x1a80000, v177
	global_store_dwordx4 v181, v[80:83], s[78:79]
	global_store_dwordx4 v181, v[84:87], s[78:79] offset:1024
	v_add_u32_e32 v236, 0x1400, v237
	s_mov_b64 exec, 1
	global_store_dword v236, v184, s[78:79]
	s_mov_b64 exec, -1
	s_waitcnt vmcnt(4)
	v_lshlrev_b32_e32 v144, 16, v96
	v_and_b32_e32 v145, 0xffff0000, v96
	v_lshlrev_b32_e32 v146, 16, v97
	v_and_b32_e32 v147, 0xffff0000, v97
	v_lshlrev_b32_e32 v148, 16, v98
	v_and_b32_e32 v149, 0xffff0000, v98
	v_lshlrev_b32_e32 v150, 16, v99
	v_and_b32_e32 v151, 0xffff0000, v99
	v_lshlrev_b32_e32 v152, 16, v100
	v_and_b32_e32 v153, 0xffff0000, v100
	v_lshlrev_b32_e32 v154, 16, v101
	v_and_b32_e32 v155, 0xffff0000, v101
	v_lshlrev_b32_e32 v156, 16, v102
	v_and_b32_e32 v157, 0xffff0000, v102
	v_lshlrev_b32_e32 v158, 16, v103
	v_and_b32_e32 v159, 0xffff0000, v103
	v_lshlrev_b32_e32 v160, 16, v104
	v_and_b32_e32 v161, 0xffff0000, v104
	v_lshlrev_b32_e32 v162, 16, v105
	v_and_b32_e32 v163, 0xffff0000, v105
	v_lshlrev_b32_e32 v164, 16, v106
	v_and_b32_e32 v165, 0xffff0000, v106
	v_lshlrev_b32_e32 v166, 16, v107
	v_and_b32_e32 v167, 0xffff0000, v107
	v_lshlrev_b32_e32 v168, 16, v108
	v_and_b32_e32 v169, 0xffff0000, v108
	v_lshlrev_b32_e32 v170, 16, v109
	v_and_b32_e32 v171, 0xffff0000, v109
	v_lshlrev_b32_e32 v172, 16, v110
	v_and_b32_e32 v173, 0xffff0000, v110
	v_lshlrev_b32_e32 v174, 16, v111
	v_and_b32_e32 v175, 0xffff0000, v111
	v_pk_mul_f32 v[252:253], v[160:161], v[160:161]
	v_pk_mul_f32 v[254:255], v[162:163], v[162:163]
	v_pk_fma_f32 v[252:253], v[164:165], v[164:165], v[252:253]
	v_pk_fma_f32 v[254:255], v[166:167], v[166:167], v[254:255]
	v_pk_fma_f32 v[252:253], v[168:169], v[168:169], v[252:253]
	v_pk_fma_f32 v[254:255], v[170:171], v[170:171], v[254:255]
	v_pk_fma_f32 v[252:253], v[172:173], v[172:173], v[252:253]
	v_pk_fma_f32 v[254:255], v[174:175], v[174:175], v[254:255]
	v_pk_add_f32 v[252:253], v[252:253], v[254:255]
	s_nop 0
	v_add_f32_e32 v183, v252, v253
	s_nop 1
	v_add_f32_dpp v183, v183, v183 quad_perm:[1,0,3,2] row_mask:0xf bank_mask:0xf bound_ctrl:1
	s_nop 1
	v_add_f32_dpp v183, v183, v183 quad_perm:[2,3,0,1] row_mask:0xf bank_mask:0xf bound_ctrl:1
	s_nop 1
	v_add_f32_dpp v183, v183, v183 row_half_mirror row_mask:0xf bank_mask:0xf bound_ctrl:1
	s_nop 1
	v_add_f32_dpp v183, v183, v183 row_mirror row_mask:0xf bank_mask:0xf bound_ctrl:1
	s_nop 1
	v_readlane_b32 s98, v183, 0
	v_readlane_b32 s99, v183, 16
	v_readlane_b32 s100, v183, 32
	v_readlane_b32 s101, v183, 48
	s_nop 1
	v_mov_b32_e32 v183, s98
	v_add_f32_e32 v183, s99, v183
	v_add_f32_e32 v183, s100, v183
	v_add_f32_e32 v183, s101, v183
	v_fmamk_f32 v183, v183, 0x3a800000, v182
	v_cmp_gt_f32_e32 vcc, 0x800000, v183
	v_mul_f32_e32 v181, 0x4b800000, v183
	s_nop 1
	v_cndmask_b32_e32 v183, v183, v181, vcc
	v_rsq_f32_e32 v183, v183
	s_nop 0
	v_mul_f32_e32 v181, 0x45800000, v183
	v_cndmask_b32_e32 v184, v183, v181, vcc
	v_mov_b32_e32 v185, v184
	v_pk_mul_f32 v[160:161], v[160:161], v[184:185]
	v_pk_mul_f32 v[162:163], v[162:163], v[184:185]
	v_pk_mul_f32 v[164:165], v[164:165], v[184:185]
	v_pk_mul_f32 v[166:167], v[166:167], v[184:185]
	v_pk_mul_f32 v[168:169], v[168:169], v[184:185]
	v_pk_mul_f32 v[170:171], v[170:171], v[184:185]
	v_pk_mul_f32 v[172:173], v[172:173], v[184:185]
	v_pk_mul_f32 v[174:175], v[174:175], v[184:185]
	v_pk_fma_f32 v[144:145], v[160:161], v[128:129], v[144:145]
	v_pk_fma_f32 v[146:147], v[162:163], v[130:131], v[146:147]
	v_pk_fma_f32 v[148:149], v[164:165], v[132:133], v[148:149]
	v_pk_fma_f32 v[150:151], v[166:167], v[134:135], v[150:151]
	v_pk_fma_f32 v[152:153], v[168:169], v[136:137], v[152:153]
	v_pk_fma_f32 v[154:155], v[170:171], v[138:139], v[154:155]
	v_pk_fma_f32 v[156:157], v[172:173], v[140:141], v[156:157]
	v_pk_fma_f32 v[158:159], v[174:175], v[142:143], v[158:159]
	v_pk_mul_f32 v[252:253], v[144:145], v[144:145]
	v_pk_mul_f32 v[254:255], v[146:147], v[146:147]
	v_pk_fma_f32 v[252:253], v[148:149], v[148:149], v[252:253]
	v_pk_fma_f32 v[254:255], v[150:151], v[150:151], v[254:255]
	v_pk_fma_f32 v[252:253], v[152:153], v[152:153], v[252:253]
	v_pk_fma_f32 v[254:255], v[154:155], v[154:155], v[254:255]
	v_pk_fma_f32 v[252:253], v[156:157], v[156:157], v[252:253]
	v_pk_fma_f32 v[254:255], v[158:159], v[158:159], v[254:255]
	v_pk_add_f32 v[252:253], v[252:253], v[254:255]
	s_nop 0
	v_add_f32_e32 v183, v252, v253
	s_nop 1
	v_add_f32_dpp v183, v183, v183 quad_perm:[1,0,3,2] row_mask:0xf bank_mask:0xf bound_ctrl:1
	s_nop 1
	v_add_f32_dpp v183, v183, v183 quad_perm:[2,3,0,1] row_mask:0xf bank_mask:0xf bound_ctrl:1
	s_nop 1
	v_add_f32_dpp v183, v183, v183 row_half_mirror row_mask:0xf bank_mask:0xf bound_ctrl:1
	s_nop 1
	v_add_f32_dpp v183, v183, v183 row_mirror row_mask:0xf bank_mask:0xf bound_ctrl:1
	s_nop 1
	v_readlane_b32 s98, v183, 0
	v_readlane_b32 s99, v183, 16
	v_readlane_b32 s100, v183, 32
	v_readlane_b32 s101, v183, 48
	s_nop 1
	v_mov_b32_e32 v183, s98
	v_add_f32_e32 v183, s99, v183
	v_add_f32_e32 v183, s100, v183
	v_add_f32_e32 v183, s101, v183
	v_fmamk_f32 v183, v183, 0x3a800000, v182
	v_cmp_gt_f32_e32 vcc, 0x800000, v183
	v_mul_f32_e32 v181, 0x4b800000, v183
	s_nop 1
	v_cndmask_b32_e32 v183, v183, v181, vcc
	v_rsq_f32_e32 v183, v183
	s_nop 0
	v_mul_f32_e32 v181, 0x45800000, v183
	v_cndmask_b32_e32 v184, v183, v181, vcc
	v_mov_b32_e32 v185, v184
	v_cvt_pk_bf16_f32 v96, v144, v145
	v_cvt_pk_bf16_f32 v97, v146, v147
	v_cvt_pk_bf16_f32 v98, v148, v149
	v_cvt_pk_bf16_f32 v99, v150, v151
	v_cvt_pk_bf16_f32 v100, v152, v153
	v_cvt_pk_bf16_f32 v101, v154, v155
	v_cvt_pk_bf16_f32 v102, v156, v157
	v_cvt_pk_bf16_f32 v103, v158, v159
	v_add_u32_e32 v181, 0x1b00000, v177
	global_store_dwordx4 v181, v[96:99], s[78:79]
	global_store_dwordx4 v181, v[100:103], s[78:79] offset:1024
	v_add_u32_e32 v236, 0x1800, v237
	s_mov_b64 exec, 1
	global_store_dword v236, v184, s[78:79]
	s_mov_b64 exec, -1
	s_waitcnt vmcnt(0)
	v_lshlrev_b32_e32 v144, 16, v112
	v_and_b32_e32 v145, 0xffff0000, v112
	v_lshlrev_b32_e32 v146, 16, v113
	v_and_b32_e32 v147, 0xffff0000, v113
	v_lshlrev_b32_e32 v148, 16, v114
	v_and_b32_e32 v149, 0xffff0000, v114
	v_lshlrev_b32_e32 v150, 16, v115
	v_and_b32_e32 v151, 0xffff0000, v115
	v_lshlrev_b32_e32 v152, 16, v116
	v_and_b32_e32 v153, 0xffff0000, v116
	v_lshlrev_b32_e32 v154, 16, v117
	v_and_b32_e32 v155, 0xffff0000, v117
	v_lshlrev_b32_e32 v156, 16, v118
	v_and_b32_e32 v157, 0xffff0000, v118
	v_lshlrev_b32_e32 v158, 16, v119
	v_and_b32_e32 v159, 0xffff0000, v119
	v_lshlrev_b32_e32 v160, 16, v120
	v_and_b32_e32 v161, 0xffff0000, v120
	v_lshlrev_b32_e32 v162, 16, v121
	v_and_b32_e32 v163, 0xffff0000, v121
	v_lshlrev_b32_e32 v164, 16, v122
	v_and_b32_e32 v165, 0xffff0000, v122
	v_lshlrev_b32_e32 v166, 16, v123
	v_and_b32_e32 v167, 0xffff0000, v123
	v_lshlrev_b32_e32 v168, 16, v124
	v_and_b32_e32 v169, 0xffff0000, v124
	v_lshlrev_b32_e32 v170, 16, v125
	v_and_b32_e32 v171, 0xffff0000, v125
	v_lshlrev_b32_e32 v172, 16, v126
	v_and_b32_e32 v173, 0xffff0000, v126
	v_lshlrev_b32_e32 v174, 16, v127
	v_and_b32_e32 v175, 0xffff0000, v127
	v_pk_mul_f32 v[252:253], v[160:161], v[160:161]
	v_pk_mul_f32 v[254:255], v[162:163], v[162:163]
	v_pk_fma_f32 v[252:253], v[164:165], v[164:165], v[252:253]
	v_pk_fma_f32 v[254:255], v[166:167], v[166:167], v[254:255]
	v_pk_fma_f32 v[252:253], v[168:169], v[168:169], v[252:253]
	v_pk_fma_f32 v[254:255], v[170:171], v[170:171], v[254:255]
	v_pk_fma_f32 v[252:253], v[172:173], v[172:173], v[252:253]
	v_pk_fma_f32 v[254:255], v[174:175], v[174:175], v[254:255]
	v_pk_add_f32 v[252:253], v[252:253], v[254:255]
	s_nop 0
	v_add_f32_e32 v183, v252, v253
	s_nop 1
	v_add_f32_dpp v183, v183, v183 quad_perm:[1,0,3,2] row_mask:0xf bank_mask:0xf bound_ctrl:1
	s_nop 1
	v_add_f32_dpp v183, v183, v183 quad_perm:[2,3,0,1] row_mask:0xf bank_mask:0xf bound_ctrl:1
	s_nop 1
	v_add_f32_dpp v183, v183, v183 row_half_mirror row_mask:0xf bank_mask:0xf bound_ctrl:1
	s_nop 1
	v_add_f32_dpp v183, v183, v183 row_mirror row_mask:0xf bank_mask:0xf bound_ctrl:1
	s_nop 1
	v_readlane_b32 s98, v183, 0
	v_readlane_b32 s99, v183, 16
	v_readlane_b32 s100, v183, 32
	v_readlane_b32 s101, v183, 48
	s_nop 1
	v_mov_b32_e32 v183, s98
	v_add_f32_e32 v183, s99, v183
	v_add_f32_e32 v183, s100, v183
	v_add_f32_e32 v183, s101, v183
	v_fmamk_f32 v183, v183, 0x3a800000, v182
	v_cmp_gt_f32_e32 vcc, 0x800000, v183
	v_mul_f32_e32 v181, 0x4b800000, v183
	s_nop 1
	v_cndmask_b32_e32 v183, v183, v181, vcc
	v_rsq_f32_e32 v183, v183
	s_nop 0
	v_mul_f32_e32 v181, 0x45800000, v183
	v_cndmask_b32_e32 v184, v183, v181, vcc
	v_mov_b32_e32 v185, v184
	v_pk_mul_f32 v[160:161], v[160:161], v[184:185]
	v_pk_mul_f32 v[162:163], v[162:163], v[184:185]
	v_pk_mul_f32 v[164:165], v[164:165], v[184:185]
	v_pk_mul_f32 v[166:167], v[166:167], v[184:185]
	v_pk_mul_f32 v[168:169], v[168:169], v[184:185]
	v_pk_mul_f32 v[170:171], v[170:171], v[184:185]
	v_pk_mul_f32 v[172:173], v[172:173], v[184:185]
	v_pk_mul_f32 v[174:175], v[174:175], v[184:185]
	v_pk_fma_f32 v[144:145], v[160:161], v[128:129], v[144:145]
	v_pk_fma_f32 v[146:147], v[162:163], v[130:131], v[146:147]
	v_pk_fma_f32 v[148:149], v[164:165], v[132:133], v[148:149]
	v_pk_fma_f32 v[150:151], v[166:167], v[134:135], v[150:151]
	v_pk_fma_f32 v[152:153], v[168:169], v[136:137], v[152:153]
	v_pk_fma_f32 v[154:155], v[170:171], v[138:139], v[154:155]
	v_pk_fma_f32 v[156:157], v[172:173], v[140:141], v[156:157]
	v_pk_fma_f32 v[158:159], v[174:175], v[142:143], v[158:159]
	v_pk_mul_f32 v[252:253], v[144:145], v[144:145]
	v_pk_mul_f32 v[254:255], v[146:147], v[146:147]
	v_pk_fma_f32 v[252:253], v[148:149], v[148:149], v[252:253]
	v_pk_fma_f32 v[254:255], v[150:151], v[150:151], v[254:255]
	v_pk_fma_f32 v[252:253], v[152:153], v[152:153], v[252:253]
	v_pk_fma_f32 v[254:255], v[154:155], v[154:155], v[254:255]
	v_pk_fma_f32 v[252:253], v[156:157], v[156:157], v[252:253]
	v_pk_fma_f32 v[254:255], v[158:159], v[158:159], v[254:255]
	v_pk_add_f32 v[252:253], v[252:253], v[254:255]
	s_nop 0
	v_add_f32_e32 v183, v252, v253
	s_nop 1
	v_add_f32_dpp v183, v183, v183 quad_perm:[1,0,3,2] row_mask:0xf bank_mask:0xf bound_ctrl:1
	s_nop 1
	v_add_f32_dpp v183, v183, v183 quad_perm:[2,3,0,1] row_mask:0xf bank_mask:0xf bound_ctrl:1
	s_nop 1
	v_add_f32_dpp v183, v183, v183 row_half_mirror row_mask:0xf bank_mask:0xf bound_ctrl:1
	s_nop 1
	v_add_f32_dpp v183, v183, v183 row_mirror row_mask:0xf bank_mask:0xf bound_ctrl:1
	s_nop 1
	v_readlane_b32 s98, v183, 0
	v_readlane_b32 s99, v183, 16
	v_readlane_b32 s100, v183, 32
	v_readlane_b32 s101, v183, 48
	s_nop 1
	v_mov_b32_e32 v183, s98
	v_add_f32_e32 v183, s99, v183
	v_add_f32_e32 v183, s100, v183
	v_add_f32_e32 v183, s101, v183
	v_fmamk_f32 v183, v183, 0x3a800000, v182
	v_cmp_gt_f32_e32 vcc, 0x800000, v183
	v_mul_f32_e32 v181, 0x4b800000, v183
	s_nop 1
	v_cndmask_b32_e32 v183, v183, v181, vcc
	v_rsq_f32_e32 v183, v183
	s_nop 0
	v_mul_f32_e32 v181, 0x45800000, v183
	v_cndmask_b32_e32 v184, v183, v181, vcc
	v_mov_b32_e32 v185, v184
	v_cvt_pk_bf16_f32 v112, v144, v145
	v_cvt_pk_bf16_f32 v113, v146, v147
	v_cvt_pk_bf16_f32 v114, v148, v149
	v_cvt_pk_bf16_f32 v115, v150, v151
	v_cvt_pk_bf16_f32 v116, v152, v153
	v_cvt_pk_bf16_f32 v117, v154, v155
	v_cvt_pk_bf16_f32 v118, v156, v157
	v_cvt_pk_bf16_f32 v119, v158, v159
	v_add_u32_e32 v181, 0x1b80000, v177
	global_store_dwordx4 v181, v[112:115], s[78:79]
	global_store_dwordx4 v181, v[116:119], s[78:79] offset:1024
	v_add_u32_e32 v236, 0x1c00, v237
	s_mov_b64 exec, 1
	global_store_dword v236, v184, s[78:79]
	s_mov_b64 exec, -1
	v_readfirstlane_b32 s98, v179
	s_nop 3
	s_cmp_ge_u32 s98, 512
	s_cbranch_scc1 .Lmyxupd_done_0
	v_lshlrev_b32_e32 v177, 4, v176
	v_lshl_add_u32 v177, v179, 11, v177
	v_lshlrev_b32_e32 v237, 2, v179
	v_add_u32_e32 v237, 0x10000, v237
	v_add_u32_e32 v181, 0x3800000, v177
	global_load_dwordx4 v[0:3], v181, s[78:79]
	global_load_dwordx4 v[4:7], v181, s[78:79] offset:1024
	v_lshl_add_u32 v183, v179, 12, v180
	v_add_u32_e32 v183, 0xbf00000, v183
	v_add_u32_e32 v181, 0x0, v183
	global_load_dwordx4 v[8:11], v181, s[78:79]
	global_load_dwordx4 v[12:15], v181, s[78:79] offset:16
	global_load_dwordx4 v[16:19], v181, s[78:79] offset:2048
	global_load_dwordx4 v[20:23], v181, s[78:79] offset:2064
	v_add_u32_e32 v181, 0x200000, v183
	global_load_dwordx4 v[24:27], v181, s[78:79]
	global_load_dwordx4 v[28:31], v181, s[78:79] offset:16
	global_load_dwordx4 v[32:35], v181, s[78:79] offset:2048
	global_load_dwordx4 v[36:39], v181, s[78:79] offset:2064
	v_add_u32_e32 v181, 0x400000, v183
	global_load_dwordx4 v[40:43], v181, s[78:79]
	global_load_dwordx4 v[44:47], v181, s[78:79] offset:16
	global_load_dwordx4 v[48:51], v181, s[78:79] offset:2048
	global_load_dwordx4 v[52:55], v181, s[78:79] offset:2064
	v_add_u32_e32 v181, 0x600000, v183
	global_load_dwordx4 v[56:59], v181, s[78:79]
	global_load_dwordx4 v[60:63], v181, s[78:79] offset:16
	global_load_dwordx4 v[64:67], v181, s[78:79] offset:2048
	global_load_dwordx4 v[68:71], v181, s[78:79] offset:2064
	v_add_u32_e32 v181, 0x800000, v183
	global_load_dwordx4 v[72:75], v181, s[78:79]
	global_load_dwordx4 v[76:79], v181, s[78:79] offset:16
	global_load_dwordx4 v[80:83], v181, s[78:79] offset:2048
	global_load_dwordx4 v[84:87], v181, s[78:79] offset:2064
	v_add_u32_e32 v181, 0xa00000, v183
	global_load_dwordx4 v[88:91], v181, s[78:79]
	global_load_dwordx4 v[92:95], v181, s[78:79] offset:16
	global_load_dwordx4 v[96:99], v181, s[78:79] offset:2048
	global_load_dwordx4 v[100:103], v181, s[78:79] offset:2064
	s_waitcnt vmcnt(20)
	v_pk_add_f32 v[160:161], v[8:9], 0 op_sel_hi:[1,0]
	v_pk_add_f32 v[162:163], v[10:11], 0 op_sel_hi:[1,0]
	v_pk_add_f32 v[164:165], v[12:13], 0 op_sel_hi:[1,0]
	v_pk_add_f32 v[166:167], v[14:15], 0 op_sel_hi:[1,0]
	v_pk_add_f32 v[168:169], v[16:17], 0 op_sel_hi:[1,0]
	v_pk_add_f32 v[170:171], v[18:19], 0 op_sel_hi:[1,0]
	v_pk_add_f32 v[172:173], v[20:21], 0 op_sel_hi:[1,0]
	v_pk_add_f32 v[174:175], v[22:23], 0 op_sel_hi:[1,0]
	s_waitcnt vmcnt(16)
	v_pk_add_f32 v[160:161], v[160:161], v[24:25]
	v_pk_add_f32 v[162:163], v[162:163], v[26:27]
	v_pk_add_f32 v[164:165], v[164:165], v[28:29]
	v_pk_add_f32 v[166:167], v[166:167], v[30:31]
	v_pk_add_f32 v[168:169], v[168:169], v[32:33]
	v_pk_add_f32 v[170:171], v[170:171], v[34:35]
	v_pk_add_f32 v[172:173], v[172:173], v[36:37]
	v_pk_add_f32 v[174:175], v[174:175], v[38:39]
	s_waitcnt vmcnt(12)
	v_pk_add_f32 v[160:161], v[160:161], v[40:41]
	v_pk_add_f32 v[162:163], v[162:163], v[42:43]
	v_pk_add_f32 v[164:165], v[164:165], v[44:45]
	v_pk_add_f32 v[166:167], v[166:167], v[46:47]
	v_pk_add_f32 v[168:169], v[168:169], v[48:49]
	v_pk_add_f32 v[170:171], v[170:171], v[50:51]
	v_pk_add_f32 v[172:173], v[172:173], v[52:53]
	v_pk_add_f32 v[174:175], v[174:175], v[54:55]
	s_waitcnt vmcnt(8)
	v_pk_add_f32 v[160:161], v[160:161], v[56:57]
	v_pk_add_f32 v[162:163], v[162:163], v[58:59]
	v_pk_add_f32 v[164:165], v[164:165], v[60:61]
	v_pk_add_f32 v[166:167], v[166:167], v[62:63]
	v_pk_add_f32 v[168:169], v[168:169], v[64:65]
	v_pk_add_f32 v[170:171], v[170:171], v[66:67]
	v_pk_add_f32 v[172:173], v[172:173], v[68:69]
	v_pk_add_f32 v[174:175], v[174:175], v[70:71]
	s_waitcnt vmcnt(4)
	v_pk_add_f32 v[160:161], v[160:161], v[72:73]
	v_pk_add_f32 v[162:163], v[162:163], v[74:75]
	v_pk_add_f32 v[164:165], v[164:165], v[76:77]
	v_pk_add_f32 v[166:167], v[166:167], v[78:79]
	v_pk_add_f32 v[168:169], v[168:169], v[80:81]
	v_pk_add_f32 v[170:171], v[170:171], v[82:83]
	v_pk_add_f32 v[172:173], v[172:173], v[84:85]
	v_pk_add_f32 v[174:175], v[174:175], v[86:87]
	s_waitcnt vmcnt(0)
	v_pk_add_f32 v[160:161], v[160:161], v[88:89]
	v_pk_add_f32 v[162:163], v[162:163], v[90:91]
	v_pk_add_f32 v[164:165], v[164:165], v[92:93]
	v_pk_add_f32 v[166:167], v[166:167], v[94:95]
	v_pk_add_f32 v[168:169], v[168:169], v[96:97]
	v_pk_add_f32 v[170:171], v[170:171], v[98:99]
	v_pk_add_f32 v[172:173], v[172:173], v[100:101]
	v_pk_add_f32 v[174:175], v[174:175], v[102:103]
	v_lshlrev_b32_e32 v144, 16, v0
	v_and_b32_e32 v145, 0xffff0000, v0
	v_lshlrev_b32_e32 v146, 16, v1
	v_and_b32_e32 v147, 0xffff0000, v1
	v_lshlrev_b32_e32 v148, 16, v2
	v_and_b32_e32 v149, 0xffff0000, v2
	v_lshlrev_b32_e32 v150, 16, v3
	v_and_b32_e32 v151, 0xffff0000, v3
	v_lshlrev_b32_e32 v152, 16, v4
	v_and_b32_e32 v153, 0xffff0000, v4
	v_lshlrev_b32_e32 v154, 16, v5
	v_and_b32_e32 v155, 0xffff0000, v5
	v_lshlrev_b32_e32 v156, 16, v6
	v_and_b32_e32 v157, 0xffff0000, v6
	v_lshlrev_b32_e32 v158, 16, v7
	v_and_b32_e32 v159, 0xffff0000, v7
	v_add_u32_e32 v181, 0xc00000, v183
	global_load_dwordx4 v[8:11], v181, s[78:79]
	global_load_dwordx4 v[12:15], v181, s[78:79] offset:16
	global_load_dwordx4 v[16:19], v181, s[78:79] offset:2048
	global_load_dwordx4 v[20:23], v181, s[78:79] offset:2064
	v_add_u32_e32 v181, 0xe00000, v183
	global_load_dwordx4 v[24:27], v181, s[78:79]
	global_load_dwordx4 v[28:31], v181, s[78:79] offset:16
	global_load_dwordx4 v[32:35], v181, s[78:79] offset:2048
	global_load_dwordx4 v[36:39], v181, s[78:79] offset:2064
	s_waitcnt vmcnt(4)
	v_pk_add_f32 v[160:161], v[160:161], v[8:9]
	v_pk_add_f32 v[162:163], v[162:163], v[10:11]
	v_pk_add_f32 v[164:165], v[164:165], v[12:13]
	v_pk_add_f32 v[166:167], v[166:167], v[14:15]
	v_pk_add_f32 v[168:169], v[168:169], v[16:17]
	v_pk_add_f32 v[170:171], v[170:171], v[18:19]
	v_pk_add_f32 v[172:173], v[172:173], v[20:21]
	v_pk_add_f32 v[174:175], v[174:175], v[22:23]
	s_waitcnt vmcnt(0)
	v_pk_add_f32 v[160:161], v[160:161], v[24:25]
	v_pk_add_f32 v[162:163], v[162:163], v[26:27]
	v_pk_add_f32 v[164:165], v[164:165], v[28:29]
	v_pk_add_f32 v[166:167], v[166:167], v[30:31]
	v_pk_add_f32 v[168:169], v[168:169], v[32:33]
	v_pk_add_f32 v[170:171], v[170:171], v[34:35]
	v_pk_add_f32 v[172:173], v[172:173], v[36:37]
	v_pk_add_f32 v[174:175], v[174:175], v[38:39]
	v_pk_mul_f32 v[252:253], v[160:161], v[160:161]
	v_pk_mul_f32 v[254:255], v[162:163], v[162:163]
	v_pk_fma_f32 v[252:253], v[164:165], v[164:165], v[252:253]
	v_pk_fma_f32 v[254:255], v[166:167], v[166:167], v[254:255]
	v_pk_fma_f32 v[252:253], v[168:169], v[168:169], v[252:253]
	v_pk_fma_f32 v[254:255], v[170:171], v[170:171], v[254:255]
	v_pk_fma_f32 v[252:253], v[172:173], v[172:173], v[252:253]
	v_pk_fma_f32 v[254:255], v[174:175], v[174:175], v[254:255]
	v_pk_add_f32 v[252:253], v[252:253], v[254:255]
	s_nop 0
	v_add_f32_e32 v183, v252, v253
	s_nop 1
	v_add_f32_dpp v183, v183, v183 quad_perm:[1,0,3,2] row_mask:0xf bank_mask:0xf bound_ctrl:1
	s_nop 1
	v_add_f32_dpp v183, v183, v183 quad_perm:[2,3,0,1] row_mask:0xf bank_mask:0xf bound_ctrl:1
	s_nop 1
	v_add_f32_dpp v183, v183, v183 row_half_mirror row_mask:0xf bank_mask:0xf bound_ctrl:1
	s_nop 1
	v_add_f32_dpp v183, v183, v183 row_mirror row_mask:0xf bank_mask:0xf bound_ctrl:1
	s_nop 1
	v_readlane_b32 s98, v183, 0
	v_readlane_b32 s99, v183, 16
	v_readlane_b32 s100, v183, 32
	v_readlane_b32 s101, v183, 48
	s_nop 1
	v_mov_b32_e32 v183, s98
	v_add_f32_e32 v183, s99, v183
	v_add_f32_e32 v183, s100, v183
	v_add_f32_e32 v183, s101, v183
	v_fmamk_f32 v183, v183, 0x3a800000, v182
	v_cmp_gt_f32_e32 vcc, 0x800000, v183
	v_mul_f32_e32 v181, 0x4b800000, v183
	s_nop 1
	v_cndmask_b32_e32 v183, v183, v181, vcc
	v_rsq_f32_e32 v183, v183
	s_nop 0
	v_mul_f32_e32 v181, 0x45800000, v183
	v_cndmask_b32_e32 v184, v183, v181, vcc
	v_mov_b32_e32 v185, v184
	v_pk_mul_f32 v[160:161], v[160:161], v[184:185]
	v_pk_mul_f32 v[162:163], v[162:163], v[184:185]
	v_pk_mul_f32 v[164:165], v[164:165], v[184:185]
	v_pk_mul_f32 v[166:167], v[166:167], v[184:185]
	v_pk_mul_f32 v[168:169], v[168:169], v[184:185]
	v_pk_mul_f32 v[170:171], v[170:171], v[184:185]
	v_pk_mul_f32 v[172:173], v[172:173], v[184:185]
	v_pk_mul_f32 v[174:175], v[174:175], v[184:185]
	v_pk_fma_f32 v[144:145], v[160:161], v[128:129], v[144:145]
	v_pk_fma_f32 v[146:147], v[162:163], v[130:131], v[146:147]
	v_pk_fma_f32 v[148:149], v[164:165], v[132:133], v[148:149]
	v_pk_fma_f32 v[150:151], v[166:167], v[134:135], v[150:151]
	v_pk_fma_f32 v[152:153], v[168:169], v[136:137], v[152:153]
	v_pk_fma_f32 v[154:155], v[170:171], v[138:139], v[154:155]
	v_pk_fma_f32 v[156:157], v[172:173], v[140:141], v[156:157]
	v_pk_fma_f32 v[158:159], v[174:175], v[142:143], v[158:159]
	v_pk_mul_f32 v[252:253], v[144:145], v[144:145]
	v_pk_mul_f32 v[254:255], v[146:147], v[146:147]
	v_pk_fma_f32 v[252:253], v[148:149], v[148:149], v[252:253]
	v_pk_fma_f32 v[254:255], v[150:151], v[150:151], v[254:255]
	v_pk_fma_f32 v[252:253], v[152:153], v[152:153], v[252:253]
	v_pk_fma_f32 v[254:255], v[154:155], v[154:155], v[254:255]
	v_pk_fma_f32 v[252:253], v[156:157], v[156:157], v[252:253]
	v_pk_fma_f32 v[254:255], v[158:159], v[158:159], v[254:255]
	v_pk_add_f32 v[252:253], v[252:253], v[254:255]
	s_nop 0
	v_add_f32_e32 v183, v252, v253
	s_nop 1
	v_add_f32_dpp v183, v183, v183 quad_perm:[1,0,3,2] row_mask:0xf bank_mask:0xf bound_ctrl:1
	s_nop 1
	v_add_f32_dpp v183, v183, v183 quad_perm:[2,3,0,1] row_mask:0xf bank_mask:0xf bound_ctrl:1
	s_nop 1
	v_add_f32_dpp v183, v183, v183 row_half_mirror row_mask:0xf bank_mask:0xf bound_ctrl:1
	s_nop 1
	v_add_f32_dpp v183, v183, v183 row_mirror row_mask:0xf bank_mask:0xf bound_ctrl:1
	s_nop 1
	v_readlane_b32 s98, v183, 0
	v_readlane_b32 s99, v183, 16
	v_readlane_b32 s100, v183, 32
	v_readlane_b32 s101, v183, 48
	s_nop 1
	v_mov_b32_e32 v183, s98
	v_add_f32_e32 v183, s99, v183
	v_add_f32_e32 v183, s100, v183
	v_add_f32_e32 v183, s101, v183
	v_fmamk_f32 v183, v183, 0x3a800000, v182
	v_cmp_gt_f32_e32 vcc, 0x800000, v183
	v_mul_f32_e32 v181, 0x4b800000, v183
	s_nop 1
	v_cndmask_b32_e32 v183, v183, v181, vcc
	v_rsq_f32_e32 v183, v183
	s_nop 0
	v_mul_f32_e32 v181, 0x45800000, v183
	v_cndmask_b32_e32 v184, v183, v181, vcc
	v_mov_b32_e32 v185, v184
	v_cvt_pk_bf16_f32 v0, v144, v145
	v_cvt_pk_bf16_f32 v1, v146, v147
	v_cvt_pk_bf16_f32 v2, v148, v149
	v_cvt_pk_bf16_f32 v3, v150, v151
	v_cvt_pk_bf16_f32 v4, v152, v153
	v_cvt_pk_bf16_f32 v5, v154, v155
	v_cvt_pk_bf16_f32 v6, v156, v157
	v_cvt_pk_bf16_f32 v7, v158, v159
	v_add_u32_e32 v181, 0x3800000, v177
	global_store_dwordx4 v181, v[0:3], s[78:79]
	global_store_dwordx4 v181, v[4:7], s[78:79] offset:1024
	v_add_u32_e32 v236, 0x10000, v237
	s_mov_b64 exec, 1
	global_store_dword v236, v184, s[78:79]
	s_mov_b64 exec, -1

.LBB0_721:
	v_readlane_b32 s0, v235, 52
	v_readlane_b32 s1, v235, 53
	s_and_b64 vcc, exec, s[0:1]
	s_waitcnt lgkmcnt(0)
	s_barrier
	v_mbcnt_lo_u32_b32 v0, -1, 0
	v_mbcnt_hi_u32_b32 v0, -1, v0
	v_writelane_b32 v234, s93, 4
	s_cbranch_vccnz .LBB0_741
	v_readlane_b32 s4, v235, 4
	v_readlane_b32 s8, v235, 8
	v_readlane_b32 s9, v235, 9
	v_readlane_b32 s6, v235, 6
	v_readlane_b32 s7, v235, 7
	v_readlane_b32 s12, v235, 12
	v_readlane_b32 s13, v235, 13
	v_readlane_b32 s8, v235, 61
	v_readlane_b32 s10, v235, 10
	v_readlane_b32 s6, v235, 0
	v_readlane_b32 s9, v235, 62
	s_mov_b32 s12, s8
	s_ashr_i32 s13, s8, 31
	v_lshlrev_b32_e32 v2, 3, v0
	v_readlane_b32 s11, v235, 11
	s_lshl_b32 s6, s6, 4
	s_add_i32 s0, s8, 0xffffc000
	s_lshl_b64 s[8:9], s[12:13], 2
	s_mov_b32 s10, s12
	v_ashrrev_i32_e32 v3, 31, v2
	v_readlane_b32 s5, v235, 5
	v_readlane_b32 s14, v235, 14
	v_readlane_b32 s15, v235, 15
	v_readlane_b32 s16, v235, 16
	v_readlane_b32 s17, v235, 17
	v_readlane_b32 s18, v235, 18
	v_readlane_b32 s19, v235, 19
	v_readlane_b32 s7, v235, 1
	s_add_u32 s80, s8, 0x10000
	v_writelane_b32 v235, s10, 61
	v_lshlrev_b64 v[4:5], 1, v[2:3]
	v_lshlrev_b64 v[2:3], 2, v[2:3]
	s_addc_u32 s14, s9, 0
	s_ashr_i32 s7, s6, 31
	v_writelane_b32 v235, s11, 62
	s_lshl_b64 s[10:11], s[12:13], 11
	v_lshl_add_u64 v[152:153], s[86:87], 0, v[4:5]
	v_lshl_add_u64 v[154:155], s[90:91], 0, v[2:3]
	v_lshl_add_u64 v[156:157], s[54:55], 0, v[4:5]
	v_lshl_add_u64 v[158:159], s[18:19], 0, v[2:3]
	s_mov_b32 s1, 0
	v_cmp_eq_u32_e64 s[4:5], 0, v0
	s_lshl_b64 s[8:9], s[6:7], 2
	v_lshl_add_u64 v[160:161], s[10:11], 0, v[4:5]
	s_lshl_b64 s[10:11], s[6:7], 11
	s_mov_b64 s[24:25], 0x600000
	s_mov_b64 s[26:27], 0x600800
	s_mov_b64 s[28:29], 0x800000
	s_mov_b32 s7, 0x800000
	s_mov_b64 s[36:37], 0x800800
	s_mov_b64 s[38:39], 0xa00000
	s_mov_b64 s[40:41], 0xa00800
	s_mov_b64 s[42:43], 0xc00000
	s_mov_b64 s[44:45], 0xc00800
	s_mov_b64 s[46:47], 0xe00000
	s_mov_b64 s[48:49], 0xe00800
	s_mov_b64 s[50:51], 0x1000000
	s_mov_b32 s15, 0x1000000
	s_mov_b64 s[12:13], 0x1000800
	s_mov_b64 s[82:83], 0x1200000
	s_mov_b32 s16, 0x1200000
	s_mov_b64 s[90:91], 0x1200800
	s_mov_b64 s[20:21], 0x1400000
	s_mov_b32 s17, 0x1400000
	s_mov_b64 s[22:23], 0x1400800
	v_mov_b32_e32 v215, 0
	v_mov_b32_e32 v216, 0x358637bd
	v_mbcnt_lo_u32_b32 v176, -1, 0
	v_mbcnt_hi_u32_b32 v176, -1, v176
	v_readlane_b32 s98, v235, 49
	v_readlane_b32 s99, v235, 20
	v_readlane_b32 s100, v235, 18
	v_readlane_b32 s101, v235, 19
	s_nop 3
	s_lshr_b32 vcc_lo, s98, 3
	s_and_b32 vcc_hi, vcc_lo, 7
	s_lshr_b32 vcc_lo, vcc_lo, 3
	s_lshl_b32 vcc_lo, vcc_lo, 3
	s_add_i32 vcc_lo, vcc_lo, s99
	s_lshl_b32 s98, vcc_hi, 8
	s_add_i32 s98, s98, vcc_lo
	s_lshl_b32 s99, vcc_hi, 11
	s_add_i32 s99, s99, vcc_lo
	v_mov_b32_e32 v183, s99
	v_lshlrev_b32_e32 v177, 4, v176
	s_lshl_b32 s99, s99, 11
	v_add_u32_e32 v177, s99, v177
	v_add_u32_e32 v178, 0x1800000, v177
	v_add_u32_e32 v179, 0x9e00000, v177
	v_lshlrev_b32_e32 v180, 5, v176
	global_load_dwordx4 v[128:131], v180, s[100:101]
	global_load_dwordx4 v[132:135], v180, s[100:101] offset:16
	global_load_dwordx4 v[136:139], v180, s[100:101] offset:2048
	global_load_dwordx4 v[140:143], v180, s[100:101] offset:2064
	v_mov_b32_e32 v182, 0x358637bd
	global_load_dwordx4 v[0:3], v178, s[78:79]
	global_load_dwordx4 v[4:7], v178, s[78:79] offset:1024
	global_load_dwordx4 v[8:11], v179, s[78:79]
	global_load_dwordx4 v[12:15], v179, s[78:79] offset:1024
	v_add_u32_e32 v178, 0x80000, v178
	v_add_u32_e32 v179, 0x80000, v179
	global_load_dwordx4 v[16:19], v178, s[78:79]
	global_load_dwordx4 v[20:23], v178, s[78:79] offset:1024
	global_load_dwordx4 v[24:27], v179, s[78:79]
	global_load_dwordx4 v[28:31], v179, s[78:79] offset:1024
	v_add_u32_e32 v178, 0x80000, v178
	v_add_u32_e32 v179, 0x80000, v179
	global_load_dwordx4 v[32:35], v178, s[78:79]
	global_load_dwordx4 v[36:39], v178, s[78:79] offset:1024
	global_load_dwordx4 v[40:43], v179, s[78:79]
	global_load_dwordx4 v[44:47], v179, s[78:79] offset:1024
	v_add_u32_e32 v178, 0x80000, v178
	v_add_u32_e32 v179, 0x80000, v179
	global_load_dwordx4 v[48:51], v178, s[78:79]
	global_load_dwordx4 v[52:55], v178, s[78:79] offset:1024
	global_load_dwordx4 v[56:59], v179, s[78:79]
	global_load_dwordx4 v[60:63], v179, s[78:79] offset:1024
	v_add_u32_e32 v178, 0x80000, v178
	v_add_u32_e32 v179, 0x80000, v179
	global_load_dwordx4 v[64:67], v178, s[78:79]
	global_load_dwordx4 v[68:71], v178, s[78:79] offset:1024
	global_load_dwordx4 v[72:75], v179, s[78:79]
	global_load_dwordx4 v[76:79], v179, s[78:79] offset:1024
	v_add_u32_e32 v178, 0x80000, v178
	v_add_u32_e32 v179, 0x80000, v179
	global_load_dwordx4 v[80:83], v178, s[78:79]
	global_load_dwordx4 v[84:87], v178, s[78:79] offset:1024
	global_load_dwordx4 v[88:91], v179, s[78:79]
	global_load_dwordx4 v[92:95], v179, s[78:79] offset:1024
	v_add_u32_e32 v178, 0x80000, v178
	v_add_u32_e32 v179, 0x80000, v179
	global_load_dwordx4 v[96:99], v178, s[78:79]
	global_load_dwordx4 v[100:103], v178, s[78:79] offset:1024
	global_load_dwordx4 v[104:107], v179, s[78:79]
	global_load_dwordx4 v[108:111], v179, s[78:79] offset:1024
	v_add_u32_e32 v178, 0x80000, v178
	v_add_u32_e32 v179, 0x80000, v179
	global_load_dwordx4 v[112:115], v178, s[78:79]
	global_load_dwordx4 v[116:119], v178, s[78:79] offset:1024
	global_load_dwordx4 v[120:123], v179, s[78:79]
	global_load_dwordx4 v[124:127], v179, s[78:79] offset:1024
	v_lshlrev_b32_e32 v237, 2, v183
	v_add_u32_e32 v237, 0x10000, v237
	v_mov_b32_e32 v179, s98
	s_waitcnt vmcnt(28)
	v_lshlrev_b32_e32 v144, 16, v0
	v_and_b32_e32 v145, 0xffff0000, v0
	v_lshlrev_b32_e32 v146, 16, v1
	v_and_b32_e32 v147, 0xffff0000, v1
	v_lshlrev_b32_e32 v148, 16, v2
	v_and_b32_e32 v149, 0xffff0000, v2
	v_lshlrev_b32_e32 v150, 16, v3
	v_and_b32_e32 v151, 0xffff0000, v3
	v_lshlrev_b32_e32 v152, 16, v4
	v_and_b32_e32 v153, 0xffff0000, v4
	v_lshlrev_b32_e32 v154, 16, v5
	v_and_b32_e32 v155, 0xffff0000, v5
	v_lshlrev_b32_e32 v156, 16, v6
	v_and_b32_e32 v157, 0xffff0000, v6
	v_lshlrev_b32_e32 v158, 16, v7
	v_and_b32_e32 v159, 0xffff0000, v7
	v_lshlrev_b32_e32 v160, 16, v8
	v_and_b32_e32 v161, 0xffff0000, v8
	v_lshlrev_b32_e32 v162, 16, v9
	v_and_b32_e32 v163, 0xffff0000, v9
	v_lshlrev_b32_e32 v164, 16, v10
	v_and_b32_e32 v165, 0xffff0000, v10
	v_lshlrev_b32_e32 v166, 16, v11
	v_and_b32_e32 v167, 0xffff0000, v11
	v_lshlrev_b32_e32 v168, 16, v12
	v_and_b32_e32 v169, 0xffff0000, v12
	v_lshlrev_b32_e32 v170, 16, v13
	v_and_b32_e32 v171, 0xffff0000, v13
	v_lshlrev_b32_e32 v172, 16, v14
	v_and_b32_e32 v173, 0xffff0000, v14
	v_lshlrev_b32_e32 v174, 16, v15
	v_and_b32_e32 v175, 0xffff0000, v15
	v_pk_mul_f32 v[252:253], v[160:161], v[160:161]
	v_pk_mul_f32 v[254:255], v[162:163], v[162:163]
	v_pk_fma_f32 v[252:253], v[164:165], v[164:165], v[252:253]
	v_pk_fma_f32 v[254:255], v[166:167], v[166:167], v[254:255]
	v_pk_fma_f32 v[252:253], v[168:169], v[168:169], v[252:253]
	v_pk_fma_f32 v[254:255], v[170:171], v[170:171], v[254:255]
	v_pk_fma_f32 v[252:253], v[172:173], v[172:173], v[252:253]
	v_pk_fma_f32 v[254:255], v[174:175], v[174:175], v[254:255]
	v_pk_add_f32 v[252:253], v[252:253], v[254:255]
	s_nop 0
	v_add_f32_e32 v183, v252, v253
	s_nop 1
	v_add_f32_dpp v183, v183, v183 quad_perm:[1,0,3,2] row_mask:0xf bank_mask:0xf bound_ctrl:1
	s_nop 1
	v_add_f32_dpp v183, v183, v183 quad_perm:[2,3,0,1] row_mask:0xf bank_mask:0xf bound_ctrl:1
	s_nop 1
	v_add_f32_dpp v183, v183, v183 row_half_mirror row_mask:0xf bank_mask:0xf bound_ctrl:1
	s_nop 1
	v_add_f32_dpp v183, v183, v183 row_mirror row_mask:0xf bank_mask:0xf bound_ctrl:1
	s_nop 1
	v_readlane_b32 s98, v183, 0
	v_readlane_b32 s99, v183, 16
	v_readlane_b32 s100, v183, 32
	v_readlane_b32 s101, v183, 48
	s_nop 1
	v_mov_b32_e32 v183, s98
	v_add_f32_e32 v183, s99, v183
	v_add_f32_e32 v183, s100, v183
	v_add_f32_e32 v183, s101, v183
	v_fmamk_f32 v183, v183, 0x3a800000, v182
	v_cmp_gt_f32_e32 vcc, 0x800000, v183
	v_mul_f32_e32 v181, 0x4b800000, v183
	s_nop 1
	v_cndmask_b32_e32 v183, v183, v181, vcc
	v_rsq_f32_e32 v183, v183
	s_nop 0
	v_mul_f32_e32 v181, 0x45800000, v183
	v_cndmask_b32_e32 v184, v183, v181, vcc
	v_mov_b32_e32 v185, v184
	v_pk_mul_f32 v[160:161], v[160:161], v[184:185]
	v_pk_mul_f32 v[162:163], v[162:163], v[184:185]
	v_pk_mul_f32 v[164:165], v[164:165], v[184:185]
	v_pk_mul_f32 v[166:167], v[166:167], v[184:185]
	v_pk_mul_f32 v[168:169], v[168:169], v[184:185]
	v_pk_mul_f32 v[170:171], v[170:171], v[184:185]
	v_pk_mul_f32 v[172:173], v[172:173], v[184:185]
	v_pk_mul_f32 v[174:175], v[174:175], v[184:185]
	v_pk_fma_f32 v[144:145], v[160:161], v[128:129], v[144:145]
	v_pk_fma_f32 v[146:147], v[162:163], v[130:131], v[146:147]
	v_pk_fma_f32 v[148:149], v[164:165], v[132:133], v[148:149]
	v_pk_fma_f32 v[150:151], v[166:167], v[134:135], v[150:151]
	v_pk_fma_f32 v[152:153], v[168:169], v[136:137], v[152:153]
	v_pk_fma_f32 v[154:155], v[170:171], v[138:139], v[154:155]
	v_pk_fma_f32 v[156:157], v[172:173], v[140:141], v[156:157]
	v_pk_fma_f32 v[158:159], v[174:175], v[142:143], v[158:159]
	v_pk_mul_f32 v[252:253], v[144:145], v[144:145]
	v_pk_mul_f32 v[254:255], v[146:147], v[146:147]
	v_pk_fma_f32 v[252:253], v[148:149], v[148:149], v[252:253]
	v_pk_fma_f32 v[254:255], v[150:151], v[150:151], v[254:255]
	v_pk_fma_f32 v[252:253], v[152:153], v[152:153], v[252:253]
	v_pk_fma_f32 v[254:255], v[154:155], v[154:155], v[254:255]
	v_pk_fma_f32 v[252:253], v[156:157], v[156:157], v[252:253]
	v_pk_fma_f32 v[254:255], v[158:159], v[158:159], v[254:255]
	v_pk_add_f32 v[252:253], v[252:253], v[254:255]
	s_nop 0
	v_add_f32_e32 v183, v252, v253
	s_nop 1
	v_add_f32_dpp v183, v183, v183 quad_perm:[1,0,3,2] row_mask:0xf bank_mask:0xf bound_ctrl:1
	s_nop 1
	v_add_f32_dpp v183, v183, v183 quad_perm:[2,3,0,1] row_mask:0xf bank_mask:0xf bound_ctrl:1
	s_nop 1
	v_add_f32_dpp v183, v183, v183 row_half_mirror row_mask:0xf bank_mask:0xf bound_ctrl:1
	s_nop 1
	v_add_f32_dpp v183, v183, v183 row_mirror row_mask:0xf bank_mask:0xf bound_ctrl:1
	s_nop 1
	v_readlane_b32 s98, v183, 0
	v_readlane_b32 s99, v183, 16
	v_readlane_b32 s100, v183, 32
	v_readlane_b32 s101, v183, 48
	s_nop 1
	v_mov_b32_e32 v183, s98
	v_add_f32_e32 v183, s99, v183
	v_add_f32_e32 v183, s100, v183
	v_add_f32_e32 v183, s101, v183
	v_fmamk_f32 v183, v183, 0x3a800000, v182
	v_cmp_gt_f32_e32 vcc, 0x800000, v183
	v_mul_f32_e32 v181, 0x4b800000, v183
	s_nop 1
	v_cndmask_b32_e32 v183, v183, v181, vcc
	v_rsq_f32_e32 v183, v183
	s_nop 0
	v_mul_f32_e32 v181, 0x45800000, v183
	v_cndmask_b32_e32 v184, v183, v181, vcc
	v_mov_b32_e32 v185, v184
	v_cvt_pk_bf16_f32 v0, v144, v145
	v_cvt_pk_bf16_f32 v1, v146, v147
	v_cvt_pk_bf16_f32 v2, v148, v149
	v_cvt_pk_bf16_f32 v3, v150, v151
	v_cvt_pk_bf16_f32 v4, v152, v153
	v_cvt_pk_bf16_f32 v5, v154, v155
	v_cvt_pk_bf16_f32 v6, v156, v157
	v_cvt_pk_bf16_f32 v7, v158, v159
	v_add_u32_e32 v181, 0x1800000, v177
	global_store_dwordx4 v181, v[0:3], s[78:79]
	global_store_dwordx4 v181, v[4:7], s[78:79] offset:1024
	v_add_u32_e32 v236, 0x0, v237
	s_mov_b64 exec, 1
	global_store_dword v236, v184, s[78:79]
	s_mov_b64 exec, -1
	s_waitcnt vmcnt(24)
	v_lshlrev_b32_e32 v144, 16, v16
	v_and_b32_e32 v145, 0xffff0000, v16
	v_lshlrev_b32_e32 v146, 16, v17
	v_and_b32_e32 v147, 0xffff0000, v17
	v_lshlrev_b32_e32 v148, 16, v18
	v_and_b32_e32 v149, 0xffff0000, v18
	v_lshlrev_b32_e32 v150, 16, v19
	v_and_b32_e32 v151, 0xffff0000, v19
	v_lshlrev_b32_e32 v152, 16, v20
	v_and_b32_e32 v153, 0xffff0000, v20
	v_lshlrev_b32_e32 v154, 16, v21
	v_and_b32_e32 v155, 0xffff0000, v21
	v_lshlrev_b32_e32 v156, 16, v22
	v_and_b32_e32 v157, 0xffff0000, v22
	v_lshlrev_b32_e32 v158, 16, v23
	v_and_b32_e32 v159, 0xffff0000, v23
	v_lshlrev_b32_e32 v160, 16, v24
	v_and_b32_e32 v161, 0xffff0000, v24
	v_lshlrev_b32_e32 v162, 16, v25
	v_and_b32_e32 v163, 0xffff0000, v25
	v_lshlrev_b32_e32 v164, 16, v26
	v_and_b32_e32 v165, 0xffff0000, v26
	v_lshlrev_b32_e32 v166, 16, v27
	v_and_b32_e32 v167, 0xffff0000, v27
	v_lshlrev_b32_e32 v168, 16, v28
	v_and_b32_e32 v169, 0xffff0000, v28
	v_lshlrev_b32_e32 v170, 16, v29
	v_and_b32_e32 v171, 0xffff0000, v29
	v_lshlrev_b32_e32 v172, 16, v30
	v_and_b32_e32 v173, 0xffff0000, v30
	v_lshlrev_b32_e32 v174, 16, v31
	v_and_b32_e32 v175, 0xffff0000, v31
	v_pk_mul_f32 v[252:253], v[160:161], v[160:161]
	v_pk_mul_f32 v[254:255], v[162:163], v[162:163]
	v_pk_fma_f32 v[252:253], v[164:165], v[164:165], v[252:253]
	v_pk_fma_f32 v[254:255], v[166:167], v[166:167], v[254:255]
	v_pk_fma_f32 v[252:253], v[168:169], v[168:169], v[252:253]
	v_pk_fma_f32 v[254:255], v[170:171], v[170:171], v[254:255]
	v_pk_fma_f32 v[252:253], v[172:173], v[172:173], v[252:253]
	v_pk_fma_f32 v[254:255], v[174:175], v[174:175], v[254:255]
	v_pk_add_f32 v[252:253], v[252:253], v[254:255]
	s_nop 0
	v_add_f32_e32 v183, v252, v253
	s_nop 1
	v_add_f32_dpp v183, v183, v183 quad_perm:[1,0,3,2] row_mask:0xf bank_mask:0xf bound_ctrl:1
	s_nop 1
	v_add_f32_dpp v183, v183, v183 quad_perm:[2,3,0,1] row_mask:0xf bank_mask:0xf bound_ctrl:1
	s_nop 1
	v_add_f32_dpp v183, v183, v183 row_half_mirror row_mask:0xf bank_mask:0xf bound_ctrl:1
	s_nop 1
	v_add_f32_dpp v183, v183, v183 row_mirror row_mask:0xf bank_mask:0xf bound_ctrl:1
	s_nop 1
	v_readlane_b32 s98, v183, 0
	v_readlane_b32 s99, v183, 16
	v_readlane_b32 s100, v183, 32
	v_readlane_b32 s101, v183, 48
	s_nop 1
	v_mov_b32_e32 v183, s98
	v_add_f32_e32 v183, s99, v183
	v_add_f32_e32 v183, s100, v183
	v_add_f32_e32 v183, s101, v183
	v_fmamk_f32 v183, v183, 0x3a800000, v182
	v_cmp_gt_f32_e32 vcc, 0x800000, v183
	v_mul_f32_e32 v181, 0x4b800000, v183
	s_nop 1
	v_cndmask_b32_e32 v183, v183, v181, vcc
	v_rsq_f32_e32 v183, v183
	s_nop 0
	v_mul_f32_e32 v181, 0x45800000, v183
	v_cndmask_b32_e32 v184, v183, v181, vcc
	v_mov_b32_e32 v185, v184
	v_pk_mul_f32 v[160:161], v[160:161], v[184:185]
	v_pk_mul_f32 v[162:163], v[162:163], v[184:185]
	v_pk_mul_f32 v[164:165], v[164:165], v[184:185]
	v_pk_mul_f32 v[166:167], v[166:167], v[184:185]
	v_pk_mul_f32 v[168:169], v[168:169], v[184:185]
	v_pk_mul_f32 v[170:171], v[170:171], v[184:185]
	v_pk_mul_f32 v[172:173], v[172:173], v[184:185]
	v_pk_mul_f32 v[174:175], v[174:175], v[184:185]
	v_pk_fma_f32 v[144:145], v[160:161], v[128:129], v[144:145]
	v_pk_fma_f32 v[146:147], v[162:163], v[130:131], v[146:147]
	v_pk_fma_f32 v[148:149], v[164:165], v[132:133], v[148:149]
	v_pk_fma_f32 v[150:151], v[166:167], v[134:135], v[150:151]
	v_pk_fma_f32 v[152:153], v[168:169], v[136:137], v[152:153]
	v_pk_fma_f32 v[154:155], v[170:171], v[138:139], v[154:155]
	v_pk_fma_f32 v[156:157], v[172:173], v[140:141], v[156:157]
	v_pk_fma_f32 v[158:159], v[174:175], v[142:143], v[158:159]
	v_pk_mul_f32 v[252:253], v[144:145], v[144:145]
	v_pk_mul_f32 v[254:255], v[146:147], v[146:147]
	v_pk_fma_f32 v[252:253], v[148:149], v[148:149], v[252:253]
	v_pk_fma_f32 v[254:255], v[150:151], v[150:151], v[254:255]
	v_pk_fma_f32 v[252:253], v[152:153], v[152:153], v[252:253]
	v_pk_fma_f32 v[254:255], v[154:155], v[154:155], v[254:255]
	v_pk_fma_f32 v[252:253], v[156:157], v[156:157], v[252:253]
	v_pk_fma_f32 v[254:255], v[158:159], v[158:159], v[254:255]
	v_pk_add_f32 v[252:253], v[252:253], v[254:255]
	s_nop 0
	v_add_f32_e32 v183, v252, v253
	s_nop 1
	v_add_f32_dpp v183, v183, v183 quad_perm:[1,0,3,2] row_mask:0xf bank_mask:0xf bound_ctrl:1
	s_nop 1
	v_add_f32_dpp v183, v183, v183 quad_perm:[2,3,0,1] row_mask:0xf bank_mask:0xf bound_ctrl:1
	s_nop 1
	v_add_f32_dpp v183, v183, v183 row_half_mirror row_mask:0xf bank_mask:0xf bound_ctrl:1
	s_nop 1
	v_add_f32_dpp v183, v183, v183 row_mirror row_mask:0xf bank_mask:0xf bound_ctrl:1
	s_nop 1
	v_readlane_b32 s98, v183, 0
	v_readlane_b32 s99, v183, 16
	v_readlane_b32 s100, v183, 32
	v_readlane_b32 s101, v183, 48
	s_nop 1
	v_mov_b32_e32 v183, s98
	v_add_f32_e32 v183, s99, v183
	v_add_f32_e32 v183, s100, v183
	v_add_f32_e32 v183, s101, v183
	v_fmamk_f32 v183, v183, 0x3a800000, v182
	v_cmp_gt_f32_e32 vcc, 0x800000, v183
	v_mul_f32_e32 v181, 0x4b800000, v183
	s_nop 1
	v_cndmask_b32_e32 v183, v183, v181, vcc
	v_rsq_f32_e32 v183, v183
	s_nop 0
	v_mul_f32_e32 v181, 0x45800000, v183
	v_cndmask_b32_e32 v184, v183, v181, vcc
	v_mov_b32_e32 v185, v184
	v_cvt_pk_bf16_f32 v16, v144, v145
	v_cvt_pk_bf16_f32 v17, v146, v147
	v_cvt_pk_bf16_f32 v18, v148, v149
	v_cvt_pk_bf16_f32 v19, v150, v151
	v_cvt_pk_bf16_f32 v20, v152, v153
	v_cvt_pk_bf16_f32 v21, v154, v155
	v_cvt_pk_bf16_f32 v22, v156, v157
	v_cvt_pk_bf16_f32 v23, v158, v159
	v_add_u32_e32 v181, 0x1880000, v177
	global_store_dwordx4 v181, v[16:19], s[78:79]
	global_store_dwordx4 v181, v[20:23], s[78:79] offset:1024
	v_add_u32_e32 v236, 0x400, v237
	s_mov_b64 exec, 1
	global_store_dword v236, v184, s[78:79]
	s_mov_b64 exec, -1
	s_waitcnt vmcnt(20)
	v_lshlrev_b32_e32 v144, 16, v32
	v_and_b32_e32 v145, 0xffff0000, v32
	v_lshlrev_b32_e32 v146, 16, v33
	v_and_b32_e32 v147, 0xffff0000, v33
	v_lshlrev_b32_e32 v148, 16, v34
	v_and_b32_e32 v149, 0xffff0000, v34
	v_lshlrev_b32_e32 v150, 16, v35
	v_and_b32_e32 v151, 0xffff0000, v35
	v_lshlrev_b32_e32 v152, 16, v36
	v_and_b32_e32 v153, 0xffff0000, v36
	v_lshlrev_b32_e32 v154, 16, v37
	v_and_b32_e32 v155, 0xffff0000, v37
	v_lshlrev_b32_e32 v156, 16, v38
	v_and_b32_e32 v157, 0xffff0000, v38
	v_lshlrev_b32_e32 v158, 16, v39
	v_and_b32_e32 v159, 0xffff0000, v39
	v_lshlrev_b32_e32 v160, 16, v40
	v_and_b32_e32 v161, 0xffff0000, v40
	v_lshlrev_b32_e32 v162, 16, v41
	v_and_b32_e32 v163, 0xffff0000, v41
	v_lshlrev_b32_e32 v164, 16, v42
	v_and_b32_e32 v165, 0xffff0000, v42
	v_lshlrev_b32_e32 v166, 16, v43
	v_and_b32_e32 v167, 0xffff0000, v43
	v_lshlrev_b32_e32 v168, 16, v44
	v_and_b32_e32 v169, 0xffff0000, v44
	v_lshlrev_b32_e32 v170, 16, v45
	v_and_b32_e32 v171, 0xffff0000, v45
	v_lshlrev_b32_e32 v172, 16, v46
	v_and_b32_e32 v173, 0xffff0000, v46
	v_lshlrev_b32_e32 v174, 16, v47
	v_and_b32_e32 v175, 0xffff0000, v47
	v_pk_mul_f32 v[252:253], v[160:161], v[160:161]
	v_pk_mul_f32 v[254:255], v[162:163], v[162:163]
	v_pk_fma_f32 v[252:253], v[164:165], v[164:165], v[252:253]
	v_pk_fma_f32 v[254:255], v[166:167], v[166:167], v[254:255]
	v_pk_fma_f32 v[252:253], v[168:169], v[168:169], v[252:253]
	v_pk_fma_f32 v[254:255], v[170:171], v[170:171], v[254:255]
	v_pk_fma_f32 v[252:253], v[172:173], v[172:173], v[252:253]
	v_pk_fma_f32 v[254:255], v[174:175], v[174:175], v[254:255]
	v_pk_add_f32 v[252:253], v[252:253], v[254:255]
	s_nop 0
	v_add_f32_e32 v183, v252, v253
	s_nop 1
	v_add_f32_dpp v183, v183, v183 quad_perm:[1,0,3,2] row_mask:0xf bank_mask:0xf bound_ctrl:1
	s_nop 1
	v_add_f32_dpp v183, v183, v183 quad_perm:[2,3,0,1] row_mask:0xf bank_mask:0xf bound_ctrl:1
	s_nop 1
	v_add_f32_dpp v183, v183, v183 row_half_mirror row_mask:0xf bank_mask:0xf bound_ctrl:1
	s_nop 1
	v_add_f32_dpp v183, v183, v183 row_mirror row_mask:0xf bank_mask:0xf bound_ctrl:1
	s_nop 1
	v_readlane_b32 s98, v183, 0
	v_readlane_b32 s99, v183, 16
	v_readlane_b32 s100, v183, 32
	v_readlane_b32 s101, v183, 48
	s_nop 1
	v_mov_b32_e32 v183, s98
	v_add_f32_e32 v183, s99, v183
	v_add_f32_e32 v183, s100, v183
	v_add_f32_e32 v183, s101, v183
	v_fmamk_f32 v183, v183, 0x3a800000, v182
	v_cmp_gt_f32_e32 vcc, 0x800000, v183
	v_mul_f32_e32 v181, 0x4b800000, v183
	s_nop 1
	v_cndmask_b32_e32 v183, v183, v181, vcc
	v_rsq_f32_e32 v183, v183
	s_nop 0
	v_mul_f32_e32 v181, 0x45800000, v183
	v_cndmask_b32_e32 v184, v183, v181, vcc
	v_mov_b32_e32 v185, v184
	v_pk_mul_f32 v[160:161], v[160:161], v[184:185]
	v_pk_mul_f32 v[162:163], v[162:163], v[184:185]
	v_pk_mul_f32 v[164:165], v[164:165], v[184:185]
	v_pk_mul_f32 v[166:167], v[166:167], v[184:185]
	v_pk_mul_f32 v[168:169], v[168:169], v[184:185]
	v_pk_mul_f32 v[170:171], v[170:171], v[184:185]
	v_pk_mul_f32 v[172:173], v[172:173], v[184:185]
	v_pk_mul_f32 v[174:175], v[174:175], v[184:185]
	v_pk_fma_f32 v[144:145], v[160:161], v[128:129], v[144:145]
	v_pk_fma_f32 v[146:147], v[162:163], v[130:131], v[146:147]
	v_pk_fma_f32 v[148:149], v[164:165], v[132:133], v[148:149]
	v_pk_fma_f32 v[150:151], v[166:167], v[134:135], v[150:151]
	v_pk_fma_f32 v[152:153], v[168:169], v[136:137], v[152:153]
	v_pk_fma_f32 v[154:155], v[170:171], v[138:139], v[154:155]
	v_pk_fma_f32 v[156:157], v[172:173], v[140:141], v[156:157]
	v_pk_fma_f32 v[158:159], v[174:175], v[142:143], v[158:159]
	v_pk_mul_f32 v[252:253], v[144:145], v[144:145]
	v_pk_mul_f32 v[254:255], v[146:147], v[146:147]
	v_pk_fma_f32 v[252:253], v[148:149], v[148:149], v[252:253]
	v_pk_fma_f32 v[254:255], v[150:151], v[150:151], v[254:255]
	v_pk_fma_f32 v[252:253], v[152:153], v[152:153], v[252:253]
	v_pk_fma_f32 v[254:255], v[154:155], v[154:155], v[254:255]
	v_pk_fma_f32 v[252:253], v[156:157], v[156:157], v[252:253]
	v_pk_fma_f32 v[254:255], v[158:159], v[158:159], v[254:255]
	v_pk_add_f32 v[252:253], v[252:253], v[254:255]
	s_nop 0
	v_add_f32_e32 v183, v252, v253
	s_nop 1
	v_add_f32_dpp v183, v183, v183 quad_perm:[1,0,3,2] row_mask:0xf bank_mask:0xf bound_ctrl:1
	s_nop 1
	v_add_f32_dpp v183, v183, v183 quad_perm:[2,3,0,1] row_mask:0xf bank_mask:0xf bound_ctrl:1
	s_nop 1
	v_add_f32_dpp v183, v183, v183 row_half_mirror row_mask:0xf bank_mask:0xf bound_ctrl:1
	s_nop 1
	v_add_f32_dpp v183, v183, v183 row_mirror row_mask:0xf bank_mask:0xf bound_ctrl:1
	s_nop 1
	v_readlane_b32 s98, v183, 0
	v_readlane_b32 s99, v183, 16
	v_readlane_b32 s100, v183, 32
	v_readlane_b32 s101, v183, 48
	s_nop 1
	v_mov_b32_e32 v183, s98
	v_add_f32_e32 v183, s99, v183
	v_add_f32_e32 v183, s100, v183
	v_add_f32_e32 v183, s101, v183
	v_fmamk_f32 v183, v183, 0x3a800000, v182
	v_cmp_gt_f32_e32 vcc, 0x800000, v183
	v_mul_f32_e32 v181, 0x4b800000, v183
	s_nop 1
	v_cndmask_b32_e32 v183, v183, v181, vcc
	v_rsq_f32_e32 v183, v183
	s_nop 0
	v_mul_f32_e32 v181, 0x45800000, v183
	v_cndmask_b32_e32 v184, v183, v181, vcc
	v_mov_b32_e32 v185, v184
	v_cvt_pk_bf16_f32 v32, v144, v145
	v_cvt_pk_bf16_f32 v33, v146, v147
	v_cvt_pk_bf16_f32 v34, v148, v149
	v_cvt_pk_bf16_f32 v35, v150, v151
	v_cvt_pk_bf16_f32 v36, v152, v153
	v_cvt_pk_bf16_f32 v37, v154, v155
	v_cvt_pk_bf16_f32 v38, v156, v157
	v_cvt_pk_bf16_f32 v39, v158, v159
	v_add_u32_e32 v181, 0x1900000, v177
	global_store_dwordx4 v181, v[32:35], s[78:79]
	global_store_dwordx4 v181, v[36:39], s[78:79] offset:1024
	v_add_u32_e32 v236, 0x800, v237
	s_mov_b64 exec, 1
	global_store_dword v236, v184, s[78:79]
	s_mov_b64 exec, -1
	s_waitcnt vmcnt(16)
	v_lshlrev_b32_e32 v144, 16, v48
	v_and_b32_e32 v145, 0xffff0000, v48
	v_lshlrev_b32_e32 v146, 16, v49
	v_and_b32_e32 v147, 0xffff0000, v49
	v_lshlrev_b32_e32 v148, 16, v50
	v_and_b32_e32 v149, 0xffff0000, v50
	v_lshlrev_b32_e32 v150, 16, v51
	v_and_b32_e32 v151, 0xffff0000, v51
	v_lshlrev_b32_e32 v152, 16, v52
	v_and_b32_e32 v153, 0xffff0000, v52
	v_lshlrev_b32_e32 v154, 16, v53
	v_and_b32_e32 v155, 0xffff0000, v53
	v_lshlrev_b32_e32 v156, 16, v54
	v_and_b32_e32 v157, 0xffff0000, v54
	v_lshlrev_b32_e32 v158, 16, v55
	v_and_b32_e32 v159, 0xffff0000, v55
	v_lshlrev_b32_e32 v160, 16, v56
	v_and_b32_e32 v161, 0xffff0000, v56
	v_lshlrev_b32_e32 v162, 16, v57
	v_and_b32_e32 v163, 0xffff0000, v57
	v_lshlrev_b32_e32 v164, 16, v58
	v_and_b32_e32 v165, 0xffff0000, v58
	v_lshlrev_b32_e32 v166, 16, v59
	v_and_b32_e32 v167, 0xffff0000, v59
	v_lshlrev_b32_e32 v168, 16, v60
	v_and_b32_e32 v169, 0xffff0000, v60
	v_lshlrev_b32_e32 v170, 16, v61
	v_and_b32_e32 v171, 0xffff0000, v61
	v_lshlrev_b32_e32 v172, 16, v62
	v_and_b32_e32 v173, 0xffff0000, v62
	v_lshlrev_b32_e32 v174, 16, v63
	v_and_b32_e32 v175, 0xffff0000, v63
	v_pk_mul_f32 v[252:253], v[160:161], v[160:161]
	v_pk_mul_f32 v[254:255], v[162:163], v[162:163]
	v_pk_fma_f32 v[252:253], v[164:165], v[164:165], v[252:253]
	v_pk_fma_f32 v[254:255], v[166:167], v[166:167], v[254:255]
	v_pk_fma_f32 v[252:253], v[168:169], v[168:169], v[252:253]
	v_pk_fma_f32 v[254:255], v[170:171], v[170:171], v[254:255]
	v_pk_fma_f32 v[252:253], v[172:173], v[172:173], v[252:253]
	v_pk_fma_f32 v[254:255], v[174:175], v[174:175], v[254:255]
	v_pk_add_f32 v[252:253], v[252:253], v[254:255]
	s_nop 0
	v_add_f32_e32 v183, v252, v253
	s_nop 1
	v_add_f32_dpp v183, v183, v183 quad_perm:[1,0,3,2] row_mask:0xf bank_mask:0xf bound_ctrl:1
	s_nop 1
	v_add_f32_dpp v183, v183, v183 quad_perm:[2,3,0,1] row_mask:0xf bank_mask:0xf bound_ctrl:1
	s_nop 1
	v_add_f32_dpp v183, v183, v183 row_half_mirror row_mask:0xf bank_mask:0xf bound_ctrl:1
	s_nop 1
	v_add_f32_dpp v183, v183, v183 row_mirror row_mask:0xf bank_mask:0xf bound_ctrl:1
	s_nop 1
	v_readlane_b32 s98, v183, 0
	v_readlane_b32 s99, v183, 16
	v_readlane_b32 s100, v183, 32
	v_readlane_b32 s101, v183, 48
	s_nop 1
	v_mov_b32_e32 v183, s98
	v_add_f32_e32 v183, s99, v183
	v_add_f32_e32 v183, s100, v183
	v_add_f32_e32 v183, s101, v183
	v_fmamk_f32 v183, v183, 0x3a800000, v182
	v_cmp_gt_f32_e32 vcc, 0x800000, v183
	v_mul_f32_e32 v181, 0x4b800000, v183
	s_nop 1
	v_cndmask_b32_e32 v183, v183, v181, vcc
	v_rsq_f32_e32 v183, v183
	s_nop 0
	v_mul_f32_e32 v181, 0x45800000, v183
	v_cndmask_b32_e32 v184, v183, v181, vcc
	v_mov_b32_e32 v185, v184
	v_pk_mul_f32 v[160:161], v[160:161], v[184:185]
	v_pk_mul_f32 v[162:163], v[162:163], v[184:185]
	v_pk_mul_f32 v[164:165], v[164:165], v[184:185]
	v_pk_mul_f32 v[166:167], v[166:167], v[184:185]
	v_pk_mul_f32 v[168:169], v[168:169], v[184:185]
	v_pk_mul_f32 v[170:171], v[170:171], v[184:185]
	v_pk_mul_f32 v[172:173], v[172:173], v[184:185]
	v_pk_mul_f32 v[174:175], v[174:175], v[184:185]
	v_pk_fma_f32 v[144:145], v[160:161], v[128:129], v[144:145]
	v_pk_fma_f32 v[146:147], v[162:163], v[130:131], v[146:147]
	v_pk_fma_f32 v[148:149], v[164:165], v[132:133], v[148:149]
	v_pk_fma_f32 v[150:151], v[166:167], v[134:135], v[150:151]
	v_pk_fma_f32 v[152:153], v[168:169], v[136:137], v[152:153]
	v_pk_fma_f32 v[154:155], v[170:171], v[138:139], v[154:155]
	v_pk_fma_f32 v[156:157], v[172:173], v[140:141], v[156:157]
	v_pk_fma_f32 v[158:159], v[174:175], v[142:143], v[158:159]
	v_pk_mul_f32 v[252:253], v[144:145], v[144:145]
	v_pk_mul_f32 v[254:255], v[146:147], v[146:147]
	v_pk_fma_f32 v[252:253], v[148:149], v[148:149], v[252:253]
	v_pk_fma_f32 v[254:255], v[150:151], v[150:151], v[254:255]
	v_pk_fma_f32 v[252:253], v[152:153], v[152:153], v[252:253]
	v_pk_fma_f32 v[254:255], v[154:155], v[154:155], v[254:255]
	v_pk_fma_f32 v[252:253], v[156:157], v[156:157], v[252:253]
	v_pk_fma_f32 v[254:255], v[158:159], v[158:159], v[254:255]
	v_pk_add_f32 v[252:253], v[252:253], v[254:255]
	s_nop 0
	v_add_f32_e32 v183, v252, v253
	s_nop 1
	v_add_f32_dpp v183, v183, v183 quad_perm:[1,0,3,2] row_mask:0xf bank_mask:0xf bound_ctrl:1
	s_nop 1
	v_add_f32_dpp v183, v183, v183 quad_perm:[2,3,0,1] row_mask:0xf bank_mask:0xf bound_ctrl:1
	s_nop 1
	v_add_f32_dpp v183, v183, v183 row_half_mirror row_mask:0xf bank_mask:0xf bound_ctrl:1
	s_nop 1
	v_add_f32_dpp v183, v183, v183 row_mirror row_mask:0xf bank_mask:0xf bound_ctrl:1
	s_nop 1
	v_readlane_b32 s98, v183, 0
	v_readlane_b32 s99, v183, 16
	v_readlane_b32 s100, v183, 32
	v_readlane_b32 s101, v183, 48
	s_nop 1
	v_mov_b32_e32 v183, s98
	v_add_f32_e32 v183, s99, v183
	v_add_f32_e32 v183, s100, v183
	v_add_f32_e32 v183, s101, v183
	v_fmamk_f32 v183, v183, 0x3a800000, v182
	v_cmp_gt_f32_e32 vcc, 0x800000, v183
	v_mul_f32_e32 v181, 0x4b800000, v183
	s_nop 1
	v_cndmask_b32_e32 v183, v183, v181, vcc
	v_rsq_f32_e32 v183, v183
	s_nop 0
	v_mul_f32_e32 v181, 0x45800000, v183
	v_cndmask_b32_e32 v184, v183, v181, vcc
	v_mov_b32_e32 v185, v184
	v_cvt_pk_bf16_f32 v48, v144, v145
	v_cvt_pk_bf16_f32 v49, v146, v147
	v_cvt_pk_bf16_f32 v50, v148, v149
	v_cvt_pk_bf16_f32 v51, v150, v151
	v_cvt_pk_bf16_f32 v52, v152, v153
	v_cvt_pk_bf16_f32 v53, v154, v155
	v_cvt_pk_bf16_f32 v54, v156, v157
	v_cvt_pk_bf16_f32 v55, v158, v159
	v_add_u32_e32 v181, 0x1980000, v177
	global_store_dwordx4 v181, v[48:51], s[78:79]
	global_store_dwordx4 v181, v[52:55], s[78:79] offset:1024
	v_add_u32_e32 v236, 0xc00, v237
	s_mov_b64 exec, 1
	global_store_dword v236, v184, s[78:79]
	s_mov_b64 exec, -1
	s_waitcnt vmcnt(12)
	v_lshlrev_b32_e32 v144, 16, v64
	v_and_b32_e32 v145, 0xffff0000, v64
	v_lshlrev_b32_e32 v146, 16, v65
	v_and_b32_e32 v147, 0xffff0000, v65
	v_lshlrev_b32_e32 v148, 16, v66
	v_and_b32_e32 v149, 0xffff0000, v66
	v_lshlrev_b32_e32 v150, 16, v67
	v_and_b32_e32 v151, 0xffff0000, v67
	v_lshlrev_b32_e32 v152, 16, v68
	v_and_b32_e32 v153, 0xffff0000, v68
	v_lshlrev_b32_e32 v154, 16, v69
	v_and_b32_e32 v155, 0xffff0000, v69
	v_lshlrev_b32_e32 v156, 16, v70
	v_and_b32_e32 v157, 0xffff0000, v70
	v_lshlrev_b32_e32 v158, 16, v71
	v_and_b32_e32 v159, 0xffff0000, v71
	v_lshlrev_b32_e32 v160, 16, v72
	v_and_b32_e32 v161, 0xffff0000, v72
	v_lshlrev_b32_e32 v162, 16, v73
	v_and_b32_e32 v163, 0xffff0000, v73
	v_lshlrev_b32_e32 v164, 16, v74
	v_and_b32_e32 v165, 0xffff0000, v74
	v_lshlrev_b32_e32 v166, 16, v75
	v_and_b32_e32 v167, 0xffff0000, v75
	v_lshlrev_b32_e32 v168, 16, v76
	v_and_b32_e32 v169, 0xffff0000, v76
	v_lshlrev_b32_e32 v170, 16, v77
	v_and_b32_e32 v171, 0xffff0000, v77
	v_lshlrev_b32_e32 v172, 16, v78
	v_and_b32_e32 v173, 0xffff0000, v78
	v_lshlrev_b32_e32 v174, 16, v79
	v_and_b32_e32 v175, 0xffff0000, v79
	v_pk_mul_f32 v[252:253], v[160:161], v[160:161]
	v_pk_mul_f32 v[254:255], v[162:163], v[162:163]
	v_pk_fma_f32 v[252:253], v[164:165], v[164:165], v[252:253]
	v_pk_fma_f32 v[254:255], v[166:167], v[166:167], v[254:255]
	v_pk_fma_f32 v[252:253], v[168:169], v[168:169], v[252:253]
	v_pk_fma_f32 v[254:255], v[170:171], v[170:171], v[254:255]
	v_pk_fma_f32 v[252:253], v[172:173], v[172:173], v[252:253]
	v_pk_fma_f32 v[254:255], v[174:175], v[174:175], v[254:255]
	v_pk_add_f32 v[252:253], v[252:253], v[254:255]
	s_nop 0
	v_add_f32_e32 v183, v252, v253
	s_nop 1
	v_add_f32_dpp v183, v183, v183 quad_perm:[1,0,3,2] row_mask:0xf bank_mask:0xf bound_ctrl:1
	s_nop 1
	v_add_f32_dpp v183, v183, v183 quad_perm:[2,3,0,1] row_mask:0xf bank_mask:0xf bound_ctrl:1
	s_nop 1
	v_add_f32_dpp v183, v183, v183 row_half_mirror row_mask:0xf bank_mask:0xf bound_ctrl:1
	s_nop 1
	v_add_f32_dpp v183, v183, v183 row_mirror row_mask:0xf bank_mask:0xf bound_ctrl:1
	s_nop 1
	v_readlane_b32 s98, v183, 0
	v_readlane_b32 s99, v183, 16
	v_readlane_b32 s100, v183, 32
	v_readlane_b32 s101, v183, 48
	s_nop 1
	v_mov_b32_e32 v183, s98
	v_add_f32_e32 v183, s99, v183
	v_add_f32_e32 v183, s100, v183
	v_add_f32_e32 v183, s101, v183
	v_fmamk_f32 v183, v183, 0x3a800000, v182
	v_cmp_gt_f32_e32 vcc, 0x800000, v183
	v_mul_f32_e32 v181, 0x4b800000, v183
	s_nop 1
	v_cndmask_b32_e32 v183, v183, v181, vcc
	v_rsq_f32_e32 v183, v183
	s_nop 0
	v_mul_f32_e32 v181, 0x45800000, v183
	v_cndmask_b32_e32 v184, v183, v181, vcc
	v_mov_b32_e32 v185, v184
	v_pk_mul_f32 v[160:161], v[160:161], v[184:185]
	v_pk_mul_f32 v[162:163], v[162:163], v[184:185]
	v_pk_mul_f32 v[164:165], v[164:165], v[184:185]
	v_pk_mul_f32 v[166:167], v[166:167], v[184:185]
	v_pk_mul_f32 v[168:169], v[168:169], v[184:185]
	v_pk_mul_f32 v[170:171], v[170:171], v[184:185]
	v_pk_mul_f32 v[172:173], v[172:173], v[184:185]
	v_pk_mul_f32 v[174:175], v[174:175], v[184:185]
	v_pk_fma_f32 v[144:145], v[160:161], v[128:129], v[144:145]
	v_pk_fma_f32 v[146:147], v[162:163], v[130:131], v[146:147]
	v_pk_fma_f32 v[148:149], v[164:165], v[132:133], v[148:149]
	v_pk_fma_f32 v[150:151], v[166:167], v[134:135], v[150:151]
	v_pk_fma_f32 v[152:153], v[168:169], v[136:137], v[152:153]
	v_pk_fma_f32 v[154:155], v[170:171], v[138:139], v[154:155]
	v_pk_fma_f32 v[156:157], v[172:173], v[140:141], v[156:157]
	v_pk_fma_f32 v[158:159], v[174:175], v[142:143], v[158:159]
	v_pk_mul_f32 v[252:253], v[144:145], v[144:145]
	v_pk_mul_f32 v[254:255], v[146:147], v[146:147]
	v_pk_fma_f32 v[252:253], v[148:149], v[148:149], v[252:253]
	v_pk_fma_f32 v[254:255], v[150:151], v[150:151], v[254:255]
	v_pk_fma_f32 v[252:253], v[152:153], v[152:153], v[252:253]
	v_pk_fma_f32 v[254:255], v[154:155], v[154:155], v[254:255]
	v_pk_fma_f32 v[252:253], v[156:157], v[156:157], v[252:253]
	v_pk_fma_f32 v[254:255], v[158:159], v[158:159], v[254:255]
	v_pk_add_f32 v[252:253], v[252:253], v[254:255]
	s_nop 0
	v_add_f32_e32 v183, v252, v253
	s_nop 1
	v_add_f32_dpp v183, v183, v183 quad_perm:[1,0,3,2] row_mask:0xf bank_mask:0xf bound_ctrl:1
	s_nop 1
	v_add_f32_dpp v183, v183, v183 quad_perm:[2,3,0,1] row_mask:0xf bank_mask:0xf bound_ctrl:1
	s_nop 1
	v_add_f32_dpp v183, v183, v183 row_half_mirror row_mask:0xf bank_mask:0xf bound_ctrl:1
	s_nop 1
	v_add_f32_dpp v183, v183, v183 row_mirror row_mask:0xf bank_mask:0xf bound_ctrl:1
	s_nop 1
	v_readlane_b32 s98, v183, 0
	v_readlane_b32 s99, v183, 16
	v_readlane_b32 s100, v183, 32
	v_readlane_b32 s101, v183, 48
	s_nop 1
	v_mov_b32_e32 v183, s98
	v_add_f32_e32 v183, s99, v183
	v_add_f32_e32 v183, s100, v183
	v_add_f32_e32 v183, s101, v183
	v_fmamk_f32 v183, v183, 0x3a800000, v182
	v_cmp_gt_f32_e32 vcc, 0x800000, v183
	v_mul_f32_e32 v181, 0x4b800000, v183
	s_nop 1
	v_cndmask_b32_e32 v183, v183, v181, vcc
	v_rsq_f32_e32 v183, v183
	s_nop 0
	v_mul_f32_e32 v181, 0x45800000, v183
	v_cndmask_b32_e32 v184, v183, v181, vcc
	v_mov_b32_e32 v185, v184
	v_cvt_pk_bf16_f32 v64, v144, v145
	v_cvt_pk_bf16_f32 v65, v146, v147
	v_cvt_pk_bf16_f32 v66, v148, v149
	v_cvt_pk_bf16_f32 v67, v150, v151
	v_cvt_pk_bf16_f32 v68, v152, v153
	v_cvt_pk_bf16_f32 v69, v154, v155
	v_cvt_pk_bf16_f32 v70, v156, v157
	v_cvt_pk_bf16_f32 v71, v158, v159
	v_add_u32_e32 v181, 0x1a00000, v177
	global_store_dwordx4 v181, v[64:67], s[78:79]
	global_store_dwordx4 v181, v[68:71], s[78:79] offset:1024
	v_add_u32_e32 v236, 0x1000, v237
	s_mov_b64 exec, 1
	global_store_dword v236, v184, s[78:79]
	s_mov_b64 exec, -1
	s_waitcnt vmcnt(8)
	v_lshlrev_b32_e32 v144, 16, v80
	v_and_b32_e32 v145, 0xffff0000, v80
	v_lshlrev_b32_e32 v146, 16, v81
	v_and_b32_e32 v147, 0xffff0000, v81
	v_lshlrev_b32_e32 v148, 16, v82
	v_and_b32_e32 v149, 0xffff0000, v82
	v_lshlrev_b32_e32 v150, 16, v83
	v_and_b32_e32 v151, 0xffff0000, v83
	v_lshlrev_b32_e32 v152, 16, v84
	v_and_b32_e32 v153, 0xffff0000, v84
	v_lshlrev_b32_e32 v154, 16, v85
	v_and_b32_e32 v155, 0xffff0000, v85
	v_lshlrev_b32_e32 v156, 16, v86
	v_and_b32_e32 v157, 0xffff0000, v86
	v_lshlrev_b32_e32 v158, 16, v87
	v_and_b32_e32 v159, 0xffff0000, v87
	v_lshlrev_b32_e32 v160, 16, v88
	v_and_b32_e32 v161, 0xffff0000, v88
	v_lshlrev_b32_e32 v162, 16, v89
	v_and_b32_e32 v163, 0xffff0000, v89
	v_lshlrev_b32_e32 v164, 16, v90
	v_and_b32_e32 v165, 0xffff0000, v90
	v_lshlrev_b32_e32 v166, 16, v91
	v_and_b32_e32 v167, 0xffff0000, v91
	v_lshlrev_b32_e32 v168, 16, v92
	v_and_b32_e32 v169, 0xffff0000, v92
	v_lshlrev_b32_e32 v170, 16, v93
	v_and_b32_e32 v171, 0xffff0000, v93
	v_lshlrev_b32_e32 v172, 16, v94
	v_and_b32_e32 v173, 0xffff0000, v94
	v_lshlrev_b32_e32 v174, 16, v95
	v_and_b32_e32 v175, 0xffff0000, v95
	v_pk_mul_f32 v[252:253], v[160:161], v[160:161]
	v_pk_mul_f32 v[254:255], v[162:163], v[162:163]
	v_pk_fma_f32 v[252:253], v[164:165], v[164:165], v[252:253]
	v_pk_fma_f32 v[254:255], v[166:167], v[166:167], v[254:255]
	v_pk_fma_f32 v[252:253], v[168:169], v[168:169], v[252:253]
	v_pk_fma_f32 v[254:255], v[170:171], v[170:171], v[254:255]
	v_pk_fma_f32 v[252:253], v[172:173], v[172:173], v[252:253]
	v_pk_fma_f32 v[254:255], v[174:175], v[174:175], v[254:255]
	v_pk_add_f32 v[252:253], v[252:253], v[254:255]
	s_nop 0
	v_add_f32_e32 v183, v252, v253
	s_nop 1
	v_add_f32_dpp v183, v183, v183 quad_perm:[1,0,3,2] row_mask:0xf bank_mask:0xf bound_ctrl:1
	s_nop 1
	v_add_f32_dpp v183, v183, v183 quad_perm:[2,3,0,1] row_mask:0xf bank_mask:0xf bound_ctrl:1
	s_nop 1
	v_add_f32_dpp v183, v183, v183 row_half_mirror row_mask:0xf bank_mask:0xf bound_ctrl:1
	s_nop 1
	v_add_f32_dpp v183, v183, v183 row_mirror row_mask:0xf bank_mask:0xf bound_ctrl:1
	s_nop 1
	v_readlane_b32 s98, v183, 0
	v_readlane_b32 s99, v183, 16
	v_readlane_b32 s100, v183, 32
	v_readlane_b32 s101, v183, 48
	s_nop 1
	v_mov_b32_e32 v183, s98
	v_add_f32_e32 v183, s99, v183
	v_add_f32_e32 v183, s100, v183
	v_add_f32_e32 v183, s101, v183
	v_fmamk_f32 v183, v183, 0x3a800000, v182
	v_cmp_gt_f32_e32 vcc, 0x800000, v183
	v_mul_f32_e32 v181, 0x4b800000, v183
	s_nop 1
	v_cndmask_b32_e32 v183, v183, v181, vcc
	v_rsq_f32_e32 v183, v183
	s_nop 0
	v_mul_f32_e32 v181, 0x45800000, v183
	v_cndmask_b32_e32 v184, v183, v181, vcc
	v_mov_b32_e32 v185, v184
	v_pk_mul_f32 v[160:161], v[160:161], v[184:185]
	v_pk_mul_f32 v[162:163], v[162:163], v[184:185]
	v_pk_mul_f32 v[164:165], v[164:165], v[184:185]
	v_pk_mul_f32 v[166:167], v[166:167], v[184:185]
	v_pk_mul_f32 v[168:169], v[168:169], v[184:185]
	v_pk_mul_f32 v[170:171], v[170:171], v[184:185]
	v_pk_mul_f32 v[172:173], v[172:173], v[184:185]
	v_pk_mul_f32 v[174:175], v[174:175], v[184:185]
	v_pk_fma_f32 v[144:145], v[160:161], v[128:129], v[144:145]
	v_pk_fma_f32 v[146:147], v[162:163], v[130:131], v[146:147]
	v_pk_fma_f32 v[148:149], v[164:165], v[132:133], v[148:149]
	v_pk_fma_f32 v[150:151], v[166:167], v[134:135], v[150:151]
	v_pk_fma_f32 v[152:153], v[168:169], v[136:137], v[152:153]
	v_pk_fma_f32 v[154:155], v[170:171], v[138:139], v[154:155]
	v_pk_fma_f32 v[156:157], v[172:173], v[140:141], v[156:157]
	v_pk_fma_f32 v[158:159], v[174:175], v[142:143], v[158:159]
	v_pk_mul_f32 v[252:253], v[144:145], v[144:145]
	v_pk_mul_f32 v[254:255], v[146:147], v[146:147]
	v_pk_fma_f32 v[252:253], v[148:149], v[148:149], v[252:253]
	v_pk_fma_f32 v[254:255], v[150:151], v[150:151], v[254:255]
	v_pk_fma_f32 v[252:253], v[152:153], v[152:153], v[252:253]
	v_pk_fma_f32 v[254:255], v[154:155], v[154:155], v[254:255]
	v_pk_fma_f32 v[252:253], v[156:157], v[156:157], v[252:253]
	v_pk_fma_f32 v[254:255], v[158:159], v[158:159], v[254:255]
	v_pk_add_f32 v[252:253], v[252:253], v[254:255]
	s_nop 0
	v_add_f32_e32 v183, v252, v253
	s_nop 1
	v_add_f32_dpp v183, v183, v183 quad_perm:[1,0,3,2] row_mask:0xf bank_mask:0xf bound_ctrl:1
	s_nop 1
	v_add_f32_dpp v183, v183, v183 quad_perm:[2,3,0,1] row_mask:0xf bank_mask:0xf bound_ctrl:1
	s_nop 1
	v_add_f32_dpp v183, v183, v183 row_half_mirror row_mask:0xf bank_mask:0xf bound_ctrl:1
	s_nop 1
	v_add_f32_dpp v183, v183, v183 row_mirror row_mask:0xf bank_mask:0xf bound_ctrl:1
	s_nop 1
	v_readlane_b32 s98, v183, 0
	v_readlane_b32 s99, v183, 16
	v_readlane_b32 s100, v183, 32
	v_readlane_b32 s101, v183, 48
	s_nop 1
	v_mov_b32_e32 v183, s98
	v_add_f32_e32 v183, s99, v183
	v_add_f32_e32 v183, s100, v183
	v_add_f32_e32 v183, s101, v183
	v_fmamk_f32 v183, v183, 0x3a800000, v182
	v_cmp_gt_f32_e32 vcc, 0x800000, v183
	v_mul_f32_e32 v181, 0x4b800000, v183
	s_nop 1
	v_cndmask_b32_e32 v183, v183, v181, vcc
	v_rsq_f32_e32 v183, v183
	s_nop 0
	v_mul_f32_e32 v181, 0x45800000, v183
	v_cndmask_b32_e32 v184, v183, v181, vcc
	v_mov_b32_e32 v185, v184
	v_cvt_pk_bf16_f32 v80, v144, v145
	v_cvt_pk_bf16_f32 v81, v146, v147
	v_cvt_pk_bf16_f32 v82, v148, v149
	v_cvt_pk_bf16_f32 v83, v150, v151
	v_cvt_pk_bf16_f32 v84, v152, v153
	v_cvt_pk_bf16_f32 v85, v154, v155
	v_cvt_pk_bf16_f32 v86, v156, v157
	v_cvt_pk_bf16_f32 v87, v158, v159
	v_add_u32_e32 v181, 0x1a80000, v177
	global_store_dwordx4 v181, v[80:83], s[78:79]
	global_store_dwordx4 v181, v[84:87], s[78:79] offset:1024
	v_add_u32_e32 v236, 0x1400, v237
	s_mov_b64 exec, 1
	global_store_dword v236, v184, s[78:79]
	s_mov_b64 exec, -1
	s_waitcnt vmcnt(4)
	v_lshlrev_b32_e32 v144, 16, v96
	v_and_b32_e32 v145, 0xffff0000, v96
	v_lshlrev_b32_e32 v146, 16, v97
	v_and_b32_e32 v147, 0xffff0000, v97
	v_lshlrev_b32_e32 v148, 16, v98
	v_and_b32_e32 v149, 0xffff0000, v98
	v_lshlrev_b32_e32 v150, 16, v99
	v_and_b32_e32 v151, 0xffff0000, v99
	v_lshlrev_b32_e32 v152, 16, v100
	v_and_b32_e32 v153, 0xffff0000, v100
	v_lshlrev_b32_e32 v154, 16, v101
	v_and_b32_e32 v155, 0xffff0000, v101
	v_lshlrev_b32_e32 v156, 16, v102
	v_and_b32_e32 v157, 0xffff0000, v102
	v_lshlrev_b32_e32 v158, 16, v103
	v_and_b32_e32 v159, 0xffff0000, v103
	v_lshlrev_b32_e32 v160, 16, v104
	v_and_b32_e32 v161, 0xffff0000, v104
	v_lshlrev_b32_e32 v162, 16, v105
	v_and_b32_e32 v163, 0xffff0000, v105
	v_lshlrev_b32_e32 v164, 16, v106
	v_and_b32_e32 v165, 0xffff0000, v106
	v_lshlrev_b32_e32 v166, 16, v107
	v_and_b32_e32 v167, 0xffff0000, v107
	v_lshlrev_b32_e32 v168, 16, v108
	v_and_b32_e32 v169, 0xffff0000, v108
	v_lshlrev_b32_e32 v170, 16, v109
	v_and_b32_e32 v171, 0xffff0000, v109
	v_lshlrev_b32_e32 v172, 16, v110
	v_and_b32_e32 v173, 0xffff0000, v110
	v_lshlrev_b32_e32 v174, 16, v111
	v_and_b32_e32 v175, 0xffff0000, v111
	v_pk_mul_f32 v[252:253], v[160:161], v[160:161]
	v_pk_mul_f32 v[254:255], v[162:163], v[162:163]
	v_pk_fma_f32 v[252:253], v[164:165], v[164:165], v[252:253]
	v_pk_fma_f32 v[254:255], v[166:167], v[166:167], v[254:255]
	v_pk_fma_f32 v[252:253], v[168:169], v[168:169], v[252:253]
	v_pk_fma_f32 v[254:255], v[170:171], v[170:171], v[254:255]
	v_pk_fma_f32 v[252:253], v[172:173], v[172:173], v[252:253]
	v_pk_fma_f32 v[254:255], v[174:175], v[174:175], v[254:255]
	v_pk_add_f32 v[252:253], v[252:253], v[254:255]
	s_nop 0
	v_add_f32_e32 v183, v252, v253
	s_nop 1
	v_add_f32_dpp v183, v183, v183 quad_perm:[1,0,3,2] row_mask:0xf bank_mask:0xf bound_ctrl:1
	s_nop 1
	v_add_f32_dpp v183, v183, v183 quad_perm:[2,3,0,1] row_mask:0xf bank_mask:0xf bound_ctrl:1
	s_nop 1
	v_add_f32_dpp v183, v183, v183 row_half_mirror row_mask:0xf bank_mask:0xf bound_ctrl:1
	s_nop 1
	v_add_f32_dpp v183, v183, v183 row_mirror row_mask:0xf bank_mask:0xf bound_ctrl:1
	s_nop 1
	v_readlane_b32 s98, v183, 0
	v_readlane_b32 s99, v183, 16
	v_readlane_b32 s100, v183, 32
	v_readlane_b32 s101, v183, 48
	s_nop 1
	v_mov_b32_e32 v183, s98
	v_add_f32_e32 v183, s99, v183
	v_add_f32_e32 v183, s100, v183
	v_add_f32_e32 v183, s101, v183
	v_fmamk_f32 v183, v183, 0x3a800000, v182
	v_cmp_gt_f32_e32 vcc, 0x800000, v183
	v_mul_f32_e32 v181, 0x4b800000, v183
	s_nop 1
	v_cndmask_b32_e32 v183, v183, v181, vcc
	v_rsq_f32_e32 v183, v183
	s_nop 0
	v_mul_f32_e32 v181, 0x45800000, v183
	v_cndmask_b32_e32 v184, v183, v181, vcc
	v_mov_b32_e32 v185, v184
	v_pk_mul_f32 v[160:161], v[160:161], v[184:185]
	v_pk_mul_f32 v[162:163], v[162:163], v[184:185]
	v_pk_mul_f32 v[164:165], v[164:165], v[184:185]
	v_pk_mul_f32 v[166:167], v[166:167], v[184:185]
	v_pk_mul_f32 v[168:169], v[168:169], v[184:185]
	v_pk_mul_f32 v[170:171], v[170:171], v[184:185]
	v_pk_mul_f32 v[172:173], v[172:173], v[184:185]
	v_pk_mul_f32 v[174:175], v[174:175], v[184:185]
	v_pk_fma_f32 v[144:145], v[160:161], v[128:129], v[144:145]
	v_pk_fma_f32 v[146:147], v[162:163], v[130:131], v[146:147]
	v_pk_fma_f32 v[148:149], v[164:165], v[132:133], v[148:149]
	v_pk_fma_f32 v[150:151], v[166:167], v[134:135], v[150:151]
	v_pk_fma_f32 v[152:153], v[168:169], v[136:137], v[152:153]
	v_pk_fma_f32 v[154:155], v[170:171], v[138:139], v[154:155]
	v_pk_fma_f32 v[156:157], v[172:173], v[140:141], v[156:157]
	v_pk_fma_f32 v[158:159], v[174:175], v[142:143], v[158:159]
	v_pk_mul_f32 v[252:253], v[144:145], v[144:145]
	v_pk_mul_f32 v[254:255], v[146:147], v[146:147]
	v_pk_fma_f32 v[252:253], v[148:149], v[148:149], v[252:253]
	v_pk_fma_f32 v[254:255], v[150:151], v[150:151], v[254:255]
	v_pk_fma_f32 v[252:253], v[152:153], v[152:153], v[252:253]
	v_pk_fma_f32 v[254:255], v[154:155], v[154:155], v[254:255]
	v_pk_fma_f32 v[252:253], v[156:157], v[156:157], v[252:253]
	v_pk_fma_f32 v[254:255], v[158:159], v[158:159], v[254:255]
	v_pk_add_f32 v[252:253], v[252:253], v[254:255]
	s_nop 0
	v_add_f32_e32 v183, v252, v253
	s_nop 1
	v_add_f32_dpp v183, v183, v183 quad_perm:[1,0,3,2] row_mask:0xf bank_mask:0xf bound_ctrl:1
	s_nop 1
	v_add_f32_dpp v183, v183, v183 quad_perm:[2,3,0,1] row_mask:0xf bank_mask:0xf bound_ctrl:1
	s_nop 1
	v_add_f32_dpp v183, v183, v183 row_half_mirror row_mask:0xf bank_mask:0xf bound_ctrl:1
	s_nop 1
	v_add_f32_dpp v183, v183, v183 row_mirror row_mask:0xf bank_mask:0xf bound_ctrl:1
	s_nop 1
	v_readlane_b32 s98, v183, 0
	v_readlane_b32 s99, v183, 16
	v_readlane_b32 s100, v183, 32
	v_readlane_b32 s101, v183, 48
	s_nop 1
	v_mov_b32_e32 v183, s98
	v_add_f32_e32 v183, s99, v183
	v_add_f32_e32 v183, s100, v183
	v_add_f32_e32 v183, s101, v183
	v_fmamk_f32 v183, v183, 0x3a800000, v182
	v_cmp_gt_f32_e32 vcc, 0x800000, v183
	v_mul_f32_e32 v181, 0x4b800000, v183
	s_nop 1
	v_cndmask_b32_e32 v183, v183, v181, vcc
	v_rsq_f32_e32 v183, v183
	s_nop 0
	v_mul_f32_e32 v181, 0x45800000, v183
	v_cndmask_b32_e32 v184, v183, v181, vcc
	v_mov_b32_e32 v185, v184
	v_cvt_pk_bf16_f32 v96, v144, v145
	v_cvt_pk_bf16_f32 v97, v146, v147
	v_cvt_pk_bf16_f32 v98, v148, v149
	v_cvt_pk_bf16_f32 v99, v150, v151
	v_cvt_pk_bf16_f32 v100, v152, v153
	v_cvt_pk_bf16_f32 v101, v154, v155
	v_cvt_pk_bf16_f32 v102, v156, v157
	v_cvt_pk_bf16_f32 v103, v158, v159
	v_add_u32_e32 v181, 0x1b00000, v177
	global_store_dwordx4 v181, v[96:99], s[78:79]
	global_store_dwordx4 v181, v[100:103], s[78:79] offset:1024
	v_add_u32_e32 v236, 0x1800, v237
	s_mov_b64 exec, 1
	global_store_dword v236, v184, s[78:79]
	s_mov_b64 exec, -1
	s_waitcnt vmcnt(0)
	v_lshlrev_b32_e32 v144, 16, v112
	v_and_b32_e32 v145, 0xffff0000, v112
	v_lshlrev_b32_e32 v146, 16, v113
	v_and_b32_e32 v147, 0xffff0000, v113
	v_lshlrev_b32_e32 v148, 16, v114
	v_and_b32_e32 v149, 0xffff0000, v114
	v_lshlrev_b32_e32 v150, 16, v115
	v_and_b32_e32 v151, 0xffff0000, v115
	v_lshlrev_b32_e32 v152, 16, v116
	v_and_b32_e32 v153, 0xffff0000, v116
	v_lshlrev_b32_e32 v154, 16, v117
	v_and_b32_e32 v155, 0xffff0000, v117
	v_lshlrev_b32_e32 v156, 16, v118
	v_and_b32_e32 v157, 0xffff0000, v118
	v_lshlrev_b32_e32 v158, 16, v119
	v_and_b32_e32 v159, 0xffff0000, v119
	v_lshlrev_b32_e32 v160, 16, v120
	v_and_b32_e32 v161, 0xffff0000, v120
	v_lshlrev_b32_e32 v162, 16, v121
	v_and_b32_e32 v163, 0xffff0000, v121
	v_lshlrev_b32_e32 v164, 16, v122
	v_and_b32_e32 v165, 0xffff0000, v122
	v_lshlrev_b32_e32 v166, 16, v123
	v_and_b32_e32 v167, 0xffff0000, v123
	v_lshlrev_b32_e32 v168, 16, v124
	v_and_b32_e32 v169, 0xffff0000, v124
	v_lshlrev_b32_e32 v170, 16, v125
	v_and_b32_e32 v171, 0xffff0000, v125
	v_lshlrev_b32_e32 v172, 16, v126
	v_and_b32_e32 v173, 0xffff0000, v126
	v_lshlrev_b32_e32 v174, 16, v127
	v_and_b32_e32 v175, 0xffff0000, v127
	v_pk_mul_f32 v[252:253], v[160:161], v[160:161]
	v_pk_mul_f32 v[254:255], v[162:163], v[162:163]
	v_pk_fma_f32 v[252:253], v[164:165], v[164:165], v[252:253]
	v_pk_fma_f32 v[254:255], v[166:167], v[166:167], v[254:255]
	v_pk_fma_f32 v[252:253], v[168:169], v[168:169], v[252:253]
	v_pk_fma_f32 v[254:255], v[170:171], v[170:171], v[254:255]
	v_pk_fma_f32 v[252:253], v[172:173], v[172:173], v[252:253]
	v_pk_fma_f32 v[254:255], v[174:175], v[174:175], v[254:255]
	v_pk_add_f32 v[252:253], v[252:253], v[254:255]
	s_nop 0
	v_add_f32_e32 v183, v252, v253
	s_nop 1
	v_add_f32_dpp v183, v183, v183 quad_perm:[1,0,3,2] row_mask:0xf bank_mask:0xf bound_ctrl:1
	s_nop 1
	v_add_f32_dpp v183, v183, v183 quad_perm:[2,3,0,1] row_mask:0xf bank_mask:0xf bound_ctrl:1
	s_nop 1
	v_add_f32_dpp v183, v183, v183 row_half_mirror row_mask:0xf bank_mask:0xf bound_ctrl:1
	s_nop 1
	v_add_f32_dpp v183, v183, v183 row_mirror row_mask:0xf bank_mask:0xf bound_ctrl:1
	s_nop 1
	v_readlane_b32 s98, v183, 0
	v_readlane_b32 s99, v183, 16
	v_readlane_b32 s100, v183, 32
	v_readlane_b32 s101, v183, 48
	s_nop 1
	v_mov_b32_e32 v183, s98
	v_add_f32_e32 v183, s99, v183
	v_add_f32_e32 v183, s100, v183
	v_add_f32_e32 v183, s101, v183
	v_fmamk_f32 v183, v183, 0x3a800000, v182
	v_cmp_gt_f32_e32 vcc, 0x800000, v183
	v_mul_f32_e32 v181, 0x4b800000, v183
	s_nop 1
	v_cndmask_b32_e32 v183, v183, v181, vcc
	v_rsq_f32_e32 v183, v183
	s_nop 0
	v_mul_f32_e32 v181, 0x45800000, v183
	v_cndmask_b32_e32 v184, v183, v181, vcc
	v_mov_b32_e32 v185, v184
	v_pk_mul_f32 v[160:161], v[160:161], v[184:185]
	v_pk_mul_f32 v[162:163], v[162:163], v[184:185]
	v_pk_mul_f32 v[164:165], v[164:165], v[184:185]
	v_pk_mul_f32 v[166:167], v[166:167], v[184:185]
	v_pk_mul_f32 v[168:169], v[168:169], v[184:185]
	v_pk_mul_f32 v[170:171], v[170:171], v[184:185]
	v_pk_mul_f32 v[172:173], v[172:173], v[184:185]
	v_pk_mul_f32 v[174:175], v[174:175], v[184:185]
	v_pk_fma_f32 v[144:145], v[160:161], v[128:129], v[144:145]
	v_pk_fma_f32 v[146:147], v[162:163], v[130:131], v[146:147]
	v_pk_fma_f32 v[148:149], v[164:165], v[132:133], v[148:149]
	v_pk_fma_f32 v[150:151], v[166:167], v[134:135], v[150:151]
	v_pk_fma_f32 v[152:153], v[168:169], v[136:137], v[152:153]
	v_pk_fma_f32 v[154:155], v[170:171], v[138:139], v[154:155]
	v_pk_fma_f32 v[156:157], v[172:173], v[140:141], v[156:157]
	v_pk_fma_f32 v[158:159], v[174:175], v[142:143], v[158:159]
	v_pk_mul_f32 v[252:253], v[144:145], v[144:145]
	v_pk_mul_f32 v[254:255], v[146:147], v[146:147]
	v_pk_fma_f32 v[252:253], v[148:149], v[148:149], v[252:253]
	v_pk_fma_f32 v[254:255], v[150:151], v[150:151], v[254:255]
	v_pk_fma_f32 v[252:253], v[152:153], v[152:153], v[252:253]
	v_pk_fma_f32 v[254:255], v[154:155], v[154:155], v[254:255]
	v_pk_fma_f32 v[252:253], v[156:157], v[156:157], v[252:253]
	v_pk_fma_f32 v[254:255], v[158:159], v[158:159], v[254:255]
	v_pk_add_f32 v[252:253], v[252:253], v[254:255]
	s_nop 0
	v_add_f32_e32 v183, v252, v253
	s_nop 1
	v_add_f32_dpp v183, v183, v183 quad_perm:[1,0,3,2] row_mask:0xf bank_mask:0xf bound_ctrl:1
	s_nop 1
	v_add_f32_dpp v183, v183, v183 quad_perm:[2,3,0,1] row_mask:0xf bank_mask:0xf bound_ctrl:1
	s_nop 1
	v_add_f32_dpp v183, v183, v183 row_half_mirror row_mask:0xf bank_mask:0xf bound_ctrl:1
	s_nop 1
	v_add_f32_dpp v183, v183, v183 row_mirror row_mask:0xf bank_mask:0xf bound_ctrl:1
	s_nop 1
	v_readlane_b32 s98, v183, 0
	v_readlane_b32 s99, v183, 16
	v_readlane_b32 s100, v183, 32
	v_readlane_b32 s101, v183, 48
	s_nop 1
	v_mov_b32_e32 v183, s98
	v_add_f32_e32 v183, s99, v183
	v_add_f32_e32 v183, s100, v183
	v_add_f32_e32 v183, s101, v183
	v_fmamk_f32 v183, v183, 0x3a800000, v182
	v_cmp_gt_f32_e32 vcc, 0x800000, v183
	v_mul_f32_e32 v181, 0x4b800000, v183
	s_nop 1
	v_cndmask_b32_e32 v183, v183, v181, vcc
	v_rsq_f32_e32 v183, v183
	s_nop 0
	v_mul_f32_e32 v181, 0x45800000, v183
	v_cndmask_b32_e32 v184, v183, v181, vcc
	v_mov_b32_e32 v185, v184
	v_cvt_pk_bf16_f32 v112, v144, v145
	v_cvt_pk_bf16_f32 v113, v146, v147
	v_cvt_pk_bf16_f32 v114, v148, v149
	v_cvt_pk_bf16_f32 v115, v150, v151
	v_cvt_pk_bf16_f32 v116, v152, v153
	v_cvt_pk_bf16_f32 v117, v154, v155
	v_cvt_pk_bf16_f32 v118, v156, v157
	v_cvt_pk_bf16_f32 v119, v158, v159
	v_add_u32_e32 v181, 0x1b80000, v177
	global_store_dwordx4 v181, v[112:115], s[78:79]
	global_store_dwordx4 v181, v[116:119], s[78:79] offset:1024
	v_add_u32_e32 v236, 0x1c00, v237
	s_mov_b64 exec, 1
	global_store_dword v236, v184, s[78:79]
	s_mov_b64 exec, -1
	v_readfirstlane_b32 s98, v179
	s_nop 3
	s_cmp_ge_u32 s98, 512
	s_cbranch_scc1 .Lmyxupd_done_1
	v_lshlrev_b32_e32 v177, 4, v176
	v_lshl_add_u32 v177, v179, 11, v177
	v_lshlrev_b32_e32 v237, 2, v179
	v_add_u32_e32 v237, 0x10000, v237
	v_add_u32_e32 v181, 0x3800000, v177
	global_load_dwordx4 v[0:3], v181, s[78:79]
	global_load_dwordx4 v[4:7], v181, s[78:79] offset:1024
	v_lshl_add_u32 v183, v179, 12, v180
	v_add_u32_e32 v183, 0xbf00000, v183
	v_add_u32_e32 v181, 0x0, v183
	global_load_dwordx4 v[8:11], v181, s[78:79]
	global_load_dwordx4 v[12:15], v181, s[78:79] offset:16
	global_load_dwordx4 v[16:19], v181, s[78:79] offset:2048
	global_load_dwordx4 v[20:23], v181, s[78:79] offset:2064
	v_add_u32_e32 v181, 0x200000, v183
	global_load_dwordx4 v[24:27], v181, s[78:79]
	global_load_dwordx4 v[28:31], v181, s[78:79] offset:16
	global_load_dwordx4 v[32:35], v181, s[78:79] offset:2048
	global_load_dwordx4 v[36:39], v181, s[78:79] offset:2064
	v_add_u32_e32 v181, 0x400000, v183
	global_load_dwordx4 v[40:43], v181, s[78:79]
	global_load_dwordx4 v[44:47], v181, s[78:79] offset:16
	global_load_dwordx4 v[48:51], v181, s[78:79] offset:2048
	global_load_dwordx4 v[52:55], v181, s[78:79] offset:2064
	v_add_u32_e32 v181, 0x600000, v183
	global_load_dwordx4 v[56:59], v181, s[78:79]
	global_load_dwordx4 v[60:63], v181, s[78:79] offset:16
	global_load_dwordx4 v[64:67], v181, s[78:79] offset:2048
	global_load_dwordx4 v[68:71], v181, s[78:79] offset:2064
	v_add_u32_e32 v181, 0x800000, v183
	global_load_dwordx4 v[72:75], v181, s[78:79]
	global_load_dwordx4 v[76:79], v181, s[78:79] offset:16
	global_load_dwordx4 v[80:83], v181, s[78:79] offset:2048
	global_load_dwordx4 v[84:87], v181, s[78:79] offset:2064
	v_add_u32_e32 v181, 0xa00000, v183
	global_load_dwordx4 v[88:91], v181, s[78:79]
	global_load_dwordx4 v[92:95], v181, s[78:79] offset:16
	global_load_dwordx4 v[96:99], v181, s[78:79] offset:2048
	global_load_dwordx4 v[100:103], v181, s[78:79] offset:2064
	s_waitcnt vmcnt(20)
	v_pk_add_f32 v[160:161], v[8:9], 0 op_sel_hi:[1,0]
	v_pk_add_f32 v[162:163], v[10:11], 0 op_sel_hi:[1,0]
	v_pk_add_f32 v[164:165], v[12:13], 0 op_sel_hi:[1,0]
	v_pk_add_f32 v[166:167], v[14:15], 0 op_sel_hi:[1,0]
	v_pk_add_f32 v[168:169], v[16:17], 0 op_sel_hi:[1,0]
	v_pk_add_f32 v[170:171], v[18:19], 0 op_sel_hi:[1,0]
	v_pk_add_f32 v[172:173], v[20:21], 0 op_sel_hi:[1,0]
	v_pk_add_f32 v[174:175], v[22:23], 0 op_sel_hi:[1,0]
	s_waitcnt vmcnt(16)
	v_pk_add_f32 v[160:161], v[160:161], v[24:25]
	v_pk_add_f32 v[162:163], v[162:163], v[26:27]
	v_pk_add_f32 v[164:165], v[164:165], v[28:29]
	v_pk_add_f32 v[166:167], v[166:167], v[30:31]
	v_pk_add_f32 v[168:169], v[168:169], v[32:33]
	v_pk_add_f32 v[170:171], v[170:171], v[34:35]
	v_pk_add_f32 v[172:173], v[172:173], v[36:37]
	v_pk_add_f32 v[174:175], v[174:175], v[38:39]
	s_waitcnt vmcnt(12)
	v_pk_add_f32 v[160:161], v[160:161], v[40:41]
	v_pk_add_f32 v[162:163], v[162:163], v[42:43]
	v_pk_add_f32 v[164:165], v[164:165], v[44:45]
	v_pk_add_f32 v[166:167], v[166:167], v[46:47]
	v_pk_add_f32 v[168:169], v[168:169], v[48:49]
	v_pk_add_f32 v[170:171], v[170:171], v[50:51]
	v_pk_add_f32 v[172:173], v[172:173], v[52:53]
	v_pk_add_f32 v[174:175], v[174:175], v[54:55]
	s_waitcnt vmcnt(8)
	v_pk_add_f32 v[160:161], v[160:161], v[56:57]
	v_pk_add_f32 v[162:163], v[162:163], v[58:59]
	v_pk_add_f32 v[164:165], v[164:165], v[60:61]
	v_pk_add_f32 v[166:167], v[166:167], v[62:63]
	v_pk_add_f32 v[168:169], v[168:169], v[64:65]
	v_pk_add_f32 v[170:171], v[170:171], v[66:67]
	v_pk_add_f32 v[172:173], v[172:173], v[68:69]
	v_pk_add_f32 v[174:175], v[174:175], v[70:71]
	s_waitcnt vmcnt(4)
	v_pk_add_f32 v[160:161], v[160:161], v[72:73]
	v_pk_add_f32 v[162:163], v[162:163], v[74:75]
	v_pk_add_f32 v[164:165], v[164:165], v[76:77]
	v_pk_add_f32 v[166:167], v[166:167], v[78:79]
	v_pk_add_f32 v[168:169], v[168:169], v[80:81]
	v_pk_add_f32 v[170:171], v[170:171], v[82:83]
	v_pk_add_f32 v[172:173], v[172:173], v[84:85]
	v_pk_add_f32 v[174:175], v[174:175], v[86:87]
	s_waitcnt vmcnt(0)
	v_pk_add_f32 v[160:161], v[160:161], v[88:89]
	v_pk_add_f32 v[162:163], v[162:163], v[90:91]
	v_pk_add_f32 v[164:165], v[164:165], v[92:93]
	v_pk_add_f32 v[166:167], v[166:167], v[94:95]
	v_pk_add_f32 v[168:169], v[168:169], v[96:97]
	v_pk_add_f32 v[170:171], v[170:171], v[98:99]
	v_pk_add_f32 v[172:173], v[172:173], v[100:101]
	v_pk_add_f32 v[174:175], v[174:175], v[102:103]
	v_lshlrev_b32_e32 v144, 16, v0
	v_and_b32_e32 v145, 0xffff0000, v0
	v_lshlrev_b32_e32 v146, 16, v1
	v_and_b32_e32 v147, 0xffff0000, v1
	v_lshlrev_b32_e32 v148, 16, v2
	v_and_b32_e32 v149, 0xffff0000, v2
	v_lshlrev_b32_e32 v150, 16, v3
	v_and_b32_e32 v151, 0xffff0000, v3
	v_lshlrev_b32_e32 v152, 16, v4
	v_and_b32_e32 v153, 0xffff0000, v4
	v_lshlrev_b32_e32 v154, 16, v5
	v_and_b32_e32 v155, 0xffff0000, v5
	v_lshlrev_b32_e32 v156, 16, v6
	v_and_b32_e32 v157, 0xffff0000, v6
	v_lshlrev_b32_e32 v158, 16, v7
	v_and_b32_e32 v159, 0xffff0000, v7
	v_add_u32_e32 v181, 0xc00000, v183
	global_load_dwordx4 v[8:11], v181, s[78:79]
	global_load_dwordx4 v[12:15], v181, s[78:79] offset:16
	global_load_dwordx4 v[16:19], v181, s[78:79] offset:2048
	global_load_dwordx4 v[20:23], v181, s[78:79] offset:2064
	v_add_u32_e32 v181, 0xe00000, v183
	global_load_dwordx4 v[24:27], v181, s[78:79]
	global_load_dwordx4 v[28:31], v181, s[78:79] offset:16
	global_load_dwordx4 v[32:35], v181, s[78:79] offset:2048
	global_load_dwordx4 v[36:39], v181, s[78:79] offset:2064
	v_add_u32_e32 v181, 0x1000000, v183
	global_load_dwordx4 v[40:43], v181, s[78:79]
	global_load_dwordx4 v[44:47], v181, s[78:79] offset:16
	global_load_dwordx4 v[48:51], v181, s[78:79] offset:2048
	global_load_dwordx4 v[52:55], v181, s[78:79] offset:2064
	v_add_u32_e32 v181, 0x1200000, v183
	global_load_dwordx4 v[56:59], v181, s[78:79]
	global_load_dwordx4 v[60:63], v181, s[78:79] offset:16
	global_load_dwordx4 v[64:67], v181, s[78:79] offset:2048
	global_load_dwordx4 v[68:71], v181, s[78:79] offset:2064
	v_add_u32_e32 v181, 0x1400000, v183
	global_load_dwordx4 v[72:75], v181, s[78:79]
	global_load_dwordx4 v[76:79], v181, s[78:79] offset:16
	global_load_dwordx4 v[80:83], v181, s[78:79] offset:2048
	global_load_dwordx4 v[84:87], v181, s[78:79] offset:2064
	s_waitcnt vmcnt(16)
	v_pk_add_f32 v[160:161], v[160:161], v[8:9]
	v_pk_add_f32 v[162:163], v[162:163], v[10:11]
	v_pk_add_f32 v[164:165], v[164:165], v[12:13]
	v_pk_add_f32 v[166:167], v[166:167], v[14:15]
	v_pk_add_f32 v[168:169], v[168:169], v[16:17]
	v_pk_add_f32 v[170:171], v[170:171], v[18:19]
	v_pk_add_f32 v[172:173], v[172:173], v[20:21]
	v_pk_add_f32 v[174:175], v[174:175], v[22:23]
	s_waitcnt vmcnt(12)
	v_pk_add_f32 v[160:161], v[160:161], v[24:25]
	v_pk_add_f32 v[162:163], v[162:163], v[26:27]
	v_pk_add_f32 v[164:165], v[164:165], v[28:29]
	v_pk_add_f32 v[166:167], v[166:167], v[30:31]
	v_pk_add_f32 v[168:169], v[168:169], v[32:33]
	v_pk_add_f32 v[170:171], v[170:171], v[34:35]
	v_pk_add_f32 v[172:173], v[172:173], v[36:37]
	v_pk_add_f32 v[174:175], v[174:175], v[38:39]
	s_waitcnt vmcnt(8)
	v_pk_add_f32 v[160:161], v[160:161], v[40:41]
	v_pk_add_f32 v[162:163], v[162:163], v[42:43]
	v_pk_add_f32 v[164:165], v[164:165], v[44:45]
	v_pk_add_f32 v[166:167], v[166:167], v[46:47]
	v_pk_add_f32 v[168:169], v[168:169], v[48:49]
	v_pk_add_f32 v[170:171], v[170:171], v[50:51]
	v_pk_add_f32 v[172:173], v[172:173], v[52:53]
	v_pk_add_f32 v[174:175], v[174:175], v[54:55]
	s_waitcnt vmcnt(4)
	v_pk_add_f32 v[160:161], v[160:161], v[56:57]
	v_pk_add_f32 v[162:163], v[162:163], v[58:59]
	v_pk_add_f32 v[164:165], v[164:165], v[60:61]
	v_pk_add_f32 v[166:167], v[166:167], v[62:63]
	v_pk_add_f32 v[168:169], v[168:169], v[64:65]
	v_pk_add_f32 v[170:171], v[170:171], v[66:67]
	v_pk_add_f32 v[172:173], v[172:173], v[68:69]
	v_pk_add_f32 v[174:175], v[174:175], v[70:71]
	s_waitcnt vmcnt(0)
	v_pk_add_f32 v[160:161], v[160:161], v[72:73]
	v_pk_add_f32 v[162:163], v[162:163], v[74:75]
	v_pk_add_f32 v[164:165], v[164:165], v[76:77]
	v_pk_add_f32 v[166:167], v[166:167], v[78:79]
	v_pk_add_f32 v[168:169], v[168:169], v[80:81]
	v_pk_add_f32 v[170:171], v[170:171], v[82:83]
	v_pk_add_f32 v[172:173], v[172:173], v[84:85]
	v_pk_add_f32 v[174:175], v[174:175], v[86:87]
	v_pk_mul_f32 v[252:253], v[160:161], v[160:161]
	v_pk_mul_f32 v[254:255], v[162:163], v[162:163]
	v_pk_fma_f32 v[252:253], v[164:165], v[164:165], v[252:253]
	v_pk_fma_f32 v[254:255], v[166:167], v[166:167], v[254:255]
	v_pk_fma_f32 v[252:253], v[168:169], v[168:169], v[252:253]
	v_pk_fma_f32 v[254:255], v[170:171], v[170:171], v[254:255]
	v_pk_fma_f32 v[252:253], v[172:173], v[172:173], v[252:253]
	v_pk_fma_f32 v[254:255], v[174:175], v[174:175], v[254:255]
	v_pk_add_f32 v[252:253], v[252:253], v[254:255]
	s_nop 0
	v_add_f32_e32 v183, v252, v253
	s_nop 1
	v_add_f32_dpp v183, v183, v183 quad_perm:[1,0,3,2] row_mask:0xf bank_mask:0xf bound_ctrl:1
	s_nop 1
	v_add_f32_dpp v183, v183, v183 quad_perm:[2,3,0,1] row_mask:0xf bank_mask:0xf bound_ctrl:1
	s_nop 1
	v_add_f32_dpp v183, v183, v183 row_half_mirror row_mask:0xf bank_mask:0xf bound_ctrl:1
	s_nop 1
	v_add_f32_dpp v183, v183, v183 row_mirror row_mask:0xf bank_mask:0xf bound_ctrl:1
	s_nop 1
	v_readlane_b32 s98, v183, 0
	v_readlane_b32 s99, v183, 16
	v_readlane_b32 s100, v183, 32
	v_readlane_b32 s101, v183, 48
	s_nop 1
	v_mov_b32_e32 v183, s98
	v_add_f32_e32 v183, s99, v183
	v_add_f32_e32 v183, s100, v183
	v_add_f32_e32 v183, s101, v183
	v_fmamk_f32 v183, v183, 0x3a800000, v182
	v_cmp_gt_f32_e32 vcc, 0x800000, v183
	v_mul_f32_e32 v181, 0x4b800000, v183
	s_nop 1
	v_cndmask_b32_e32 v183, v183, v181, vcc
	v_rsq_f32_e32 v183, v183
	s_nop 0
	v_mul_f32_e32 v181, 0x45800000, v183
	v_cndmask_b32_e32 v184, v183, v181, vcc
	v_mov_b32_e32 v185, v184
	v_pk_mul_f32 v[160:161], v[160:161], v[184:185]
	v_pk_mul_f32 v[162:163], v[162:163], v[184:185]
	v_pk_mul_f32 v[164:165], v[164:165], v[184:185]
	v_pk_mul_f32 v[166:167], v[166:167], v[184:185]
	v_pk_mul_f32 v[168:169], v[168:169], v[184:185]
	v_pk_mul_f32 v[170:171], v[170:171], v[184:185]
	v_pk_mul_f32 v[172:173], v[172:173], v[184:185]
	v_pk_mul_f32 v[174:175], v[174:175], v[184:185]
	v_pk_fma_f32 v[144:145], v[160:161], v[128:129], v[144:145]
	v_pk_fma_f32 v[146:147], v[162:163], v[130:131], v[146:147]
	v_pk_fma_f32 v[148:149], v[164:165], v[132:133], v[148:149]
	v_pk_fma_f32 v[150:151], v[166:167], v[134:135], v[150:151]
	v_pk_fma_f32 v[152:153], v[168:169], v[136:137], v[152:153]
	v_pk_fma_f32 v[154:155], v[170:171], v[138:139], v[154:155]
	v_pk_fma_f32 v[156:157], v[172:173], v[140:141], v[156:157]
	v_pk_fma_f32 v[158:159], v[174:175], v[142:143], v[158:159]
	v_pk_mul_f32 v[252:253], v[144:145], v[144:145]
	v_pk_mul_f32 v[254:255], v[146:147], v[146:147]
	v_pk_fma_f32 v[252:253], v[148:149], v[148:149], v[252:253]
	v_pk_fma_f32 v[254:255], v[150:151], v[150:151], v[254:255]
	v_pk_fma_f32 v[252:253], v[152:153], v[152:153], v[252:253]
	v_pk_fma_f32 v[254:255], v[154:155], v[154:155], v[254:255]
	v_pk_fma_f32 v[252:253], v[156:157], v[156:157], v[252:253]
	v_pk_fma_f32 v[254:255], v[158:159], v[158:159], v[254:255]
	v_pk_add_f32 v[252:253], v[252:253], v[254:255]
	s_nop 0
	v_add_f32_e32 v183, v252, v253
	s_nop 1
	v_add_f32_dpp v183, v183, v183 quad_perm:[1,0,3,2] row_mask:0xf bank_mask:0xf bound_ctrl:1
	s_nop 1
	v_add_f32_dpp v183, v183, v183 quad_perm:[2,3,0,1] row_mask:0xf bank_mask:0xf bound_ctrl:1
	s_nop 1
	v_add_f32_dpp v183, v183, v183 row_half_mirror row_mask:0xf bank_mask:0xf bound_ctrl:1
	s_nop 1
	v_add_f32_dpp v183, v183, v183 row_mirror row_mask:0xf bank_mask:0xf bound_ctrl:1
	s_nop 1
	v_readlane_b32 s98, v183, 0
	v_readlane_b32 s99, v183, 16
	v_readlane_b32 s100, v183, 32
	v_readlane_b32 s101, v183, 48
	s_nop 1
	v_mov_b32_e32 v183, s98
	v_add_f32_e32 v183, s99, v183
	v_add_f32_e32 v183, s100, v183
	v_add_f32_e32 v183, s101, v183
	v_fmamk_f32 v183, v183, 0x3a800000, v182
	v_cmp_gt_f32_e32 vcc, 0x800000, v183
	v_mul_f32_e32 v181, 0x4b800000, v183
	s_nop 1
	v_cndmask_b32_e32 v183, v183, v181, vcc
	v_rsq_f32_e32 v183, v183
	s_nop 0
	v_mul_f32_e32 v181, 0x45800000, v183
	v_cndmask_b32_e32 v184, v183, v181, vcc
	v_mov_b32_e32 v185, v184
	v_cvt_pk_bf16_f32 v0, v144, v145
	v_cvt_pk_bf16_f32 v1, v146, v147
	v_cvt_pk_bf16_f32 v2, v148, v149
	v_cvt_pk_bf16_f32 v3, v150, v151
	v_cvt_pk_bf16_f32 v4, v152, v153
	v_cvt_pk_bf16_f32 v5, v154, v155
	v_cvt_pk_bf16_f32 v6, v156, v157
	v_cvt_pk_bf16_f32 v7, v158, v159
	v_add_u32_e32 v181, 0x3800000, v177
	global_store_dwordx4 v181, v[0:3], s[78:79]
	global_store_dwordx4 v181, v[4:7], s[78:79] offset:1024
	v_add_u32_e32 v236, 0x10000, v237
	s_mov_b64 exec, 1
	global_store_dword v236, v184, s[78:79]
	s_mov_b64 exec, -1

.LBB0_1154:
	v_readlane_b32 s0, v235, 52
	v_readlane_b32 s1, v235, 53
	s_and_b64 vcc, exec, s[0:1]
	s_waitcnt lgkmcnt(0)
	s_barrier
	v_mbcnt_lo_u32_b32 v0, -1, 0
	v_mbcnt_hi_u32_b32 v0, -1, v0
	s_cbranch_vccnz .LBB0_1174
	v_lshlrev_b32_e32 v2, 3, v0
	v_ashrrev_i32_e32 v3, 31, v2
	v_readlane_b32 s4, v235, 4
	v_lshlrev_b64 v[4:5], 1, v[2:3]
	v_lshlrev_b64 v[2:3], 2, v[2:3]
	v_readlane_b32 s14, v235, 14
	v_readlane_b32 s15, v235, 15
	v_lshl_add_u64 v[62:63], s[90:91], 0, v[2:3]
	v_readlane_b32 s5, v235, 5
	v_readlane_b32 s6, v235, 6
	v_readlane_b32 s7, v235, 7
	v_readlane_b32 s8, v235, 8
	v_readlane_b32 s9, v235, 9
	v_readlane_b32 s10, v235, 10
	v_readlane_b32 s11, v235, 11
	v_readlane_b32 s12, v235, 12
	v_readlane_b32 s13, v235, 13
	v_readlane_b32 s16, v235, 16
	v_readlane_b32 s17, v235, 17
	v_readlane_b32 s18, v235, 18
	v_readlane_b32 s19, v235, 19
	v_lshl_add_u64 v[2:3], s[14:15], 0, v[2:3]
	s_mov_b64 s[0:1], 0x1000
	v_lshl_add_u64 v[60:61], s[86:87], 0, v[4:5]
	v_lshl_add_u64 v[64:65], s[54:55], 0, v[4:5]
	v_lshl_add_u64 v[66:67], v[2:3], 0, s[0:1]
	s_mov_b32 s1, 0
	v_cmp_eq_u32_e64 s[12:13], 0, v0
	s_mov_b64 s[4:5], 0x200000
	s_mov_b64 s[6:7], 0x200800
	s_mov_b64 s[8:9], 0x400000
	s_mov_b64 s[10:11], 0x400800
	s_mov_b64 s[14:15], 0x600000
	s_mov_b64 s[16:17], 0x600800
	s_mov_b64 s[18:19], 0x800000
	s_mov_b32 s48, 0x800000
	s_mov_b64 s[20:21], 0x800800
	s_mov_b64 s[22:23], 0xa00000
	s_mov_b64 s[24:25], 0xa00800
	s_mov_b64 s[26:27], 0xc00000
	s_mov_b64 s[28:29], 0xc00800
	s_mov_b64 s[36:37], 0xe00000
	s_mov_b64 s[38:39], 0xe00800
	v_mov_b32_e32 v104, 0
	v_mov_b32_e32 v105, 0x358637bd
	v_readlane_b32 s42, v235, 61
	v_readlane_b32 s43, v235, 62
	v_mbcnt_lo_u32_b32 v176, -1, 0
	v_mbcnt_hi_u32_b32 v176, -1, v176
	v_readlane_b32 s98, v235, 49
	v_readlane_b32 s99, v235, 20
	v_readlane_b32 s100, v235, 14
	v_readlane_b32 s101, v235, 15
	s_nop 3
	s_lshr_b32 vcc_lo, s98, 3
	s_and_b32 vcc_hi, vcc_lo, 7
	s_lshr_b32 vcc_lo, vcc_lo, 3
	s_lshl_b32 vcc_lo, vcc_lo, 3
	s_add_i32 vcc_lo, vcc_lo, s99
	s_lshl_b32 s98, vcc_hi, 8
	s_add_i32 s98, s98, vcc_lo
	s_lshl_b32 s99, vcc_hi, 11
	s_add_i32 s99, s99, vcc_lo
	v_mov_b32_e32 v183, s99
	v_lshlrev_b32_e32 v177, 4, v176
	s_lshl_b32 s99, s99, 11
	v_add_u32_e32 v177, s99, v177
	v_add_u32_e32 v178, 0x1800000, v177
	v_add_u32_e32 v179, 0x9e00000, v177
	v_lshlrev_b32_e32 v180, 5, v176
	v_add_u32_e32 v181, 0x1000, v180
	global_load_dwordx4 v[128:131], v181, s[100:101]
	global_load_dwordx4 v[132:135], v181, s[100:101] offset:16
	global_load_dwordx4 v[136:139], v181, s[100:101] offset:2048
	global_load_dwordx4 v[140:143], v181, s[100:101] offset:2064
	v_mov_b32_e32 v182, 0x358637bd
	global_load_dwordx4 v[0:3], v178, s[78:79]
	global_load_dwordx4 v[4:7], v178, s[78:79] offset:1024
	global_load_dwordx4 v[8:11], v179, s[78:79]
	global_load_dwordx4 v[12:15], v179, s[78:79] offset:1024
	v_add_u32_e32 v178, 0x80000, v178
	v_add_u32_e32 v179, 0x80000, v179
	global_load_dwordx4 v[16:19], v178, s[78:79]
	global_load_dwordx4 v[20:23], v178, s[78:79] offset:1024
	global_load_dwordx4 v[24:27], v179, s[78:79]
	global_load_dwordx4 v[28:31], v179, s[78:79] offset:1024
	v_add_u32_e32 v178, 0x80000, v178
	v_add_u32_e32 v179, 0x80000, v179
	global_load_dwordx4 v[32:35], v178, s[78:79]
	global_load_dwordx4 v[36:39], v178, s[78:79] offset:1024
	global_load_dwordx4 v[40:43], v179, s[78:79]
	global_load_dwordx4 v[44:47], v179, s[78:79] offset:1024
	v_add_u32_e32 v178, 0x80000, v178
	v_add_u32_e32 v179, 0x80000, v179
	global_load_dwordx4 v[48:51], v178, s[78:79]
	global_load_dwordx4 v[52:55], v178, s[78:79] offset:1024
	global_load_dwordx4 v[56:59], v179, s[78:79]
	global_load_dwordx4 v[60:63], v179, s[78:79] offset:1024
	v_add_u32_e32 v178, 0x80000, v178
	v_add_u32_e32 v179, 0x80000, v179
	global_load_dwordx4 v[64:67], v178, s[78:79]
	global_load_dwordx4 v[68:71], v178, s[78:79] offset:1024
	global_load_dwordx4 v[72:75], v179, s[78:79]
	global_load_dwordx4 v[76:79], v179, s[78:79] offset:1024
	v_add_u32_e32 v178, 0x80000, v178
	v_add_u32_e32 v179, 0x80000, v179
	global_load_dwordx4 v[80:83], v178, s[78:79]
	global_load_dwordx4 v[84:87], v178, s[78:79] offset:1024
	global_load_dwordx4 v[88:91], v179, s[78:79]
	global_load_dwordx4 v[92:95], v179, s[78:79] offset:1024
	v_add_u32_e32 v178, 0x80000, v178
	v_add_u32_e32 v179, 0x80000, v179
	global_load_dwordx4 v[96:99], v178, s[78:79]
	global_load_dwordx4 v[100:103], v178, s[78:79] offset:1024
	global_load_dwordx4 v[104:107], v179, s[78:79]
	global_load_dwordx4 v[108:111], v179, s[78:79] offset:1024
	v_add_u32_e32 v178, 0x80000, v178
	v_add_u32_e32 v179, 0x80000, v179
	global_load_dwordx4 v[112:115], v178, s[78:79]
	global_load_dwordx4 v[116:119], v178, s[78:79] offset:1024
	global_load_dwordx4 v[120:123], v179, s[78:79]
	global_load_dwordx4 v[124:127], v179, s[78:79] offset:1024
	v_lshlrev_b32_e32 v237, 2, v183
	v_add_u32_e32 v237, 0x10000, v237
	v_mov_b32_e32 v179, s98
	s_waitcnt vmcnt(28)
	v_lshlrev_b32_e32 v144, 16, v0
	v_and_b32_e32 v145, 0xffff0000, v0
	v_lshlrev_b32_e32 v146, 16, v1
	v_and_b32_e32 v147, 0xffff0000, v1
	v_lshlrev_b32_e32 v148, 16, v2
	v_and_b32_e32 v149, 0xffff0000, v2
	v_lshlrev_b32_e32 v150, 16, v3
	v_and_b32_e32 v151, 0xffff0000, v3
	v_lshlrev_b32_e32 v152, 16, v4
	v_and_b32_e32 v153, 0xffff0000, v4
	v_lshlrev_b32_e32 v154, 16, v5
	v_and_b32_e32 v155, 0xffff0000, v5
	v_lshlrev_b32_e32 v156, 16, v6
	v_and_b32_e32 v157, 0xffff0000, v6
	v_lshlrev_b32_e32 v158, 16, v7
	v_and_b32_e32 v159, 0xffff0000, v7
	v_lshlrev_b32_e32 v160, 16, v8
	v_and_b32_e32 v161, 0xffff0000, v8
	v_lshlrev_b32_e32 v162, 16, v9
	v_and_b32_e32 v163, 0xffff0000, v9
	v_lshlrev_b32_e32 v164, 16, v10
	v_and_b32_e32 v165, 0xffff0000, v10
	v_lshlrev_b32_e32 v166, 16, v11
	v_and_b32_e32 v167, 0xffff0000, v11
	v_lshlrev_b32_e32 v168, 16, v12
	v_and_b32_e32 v169, 0xffff0000, v12
	v_lshlrev_b32_e32 v170, 16, v13
	v_and_b32_e32 v171, 0xffff0000, v13
	v_lshlrev_b32_e32 v172, 16, v14
	v_and_b32_e32 v173, 0xffff0000, v14
	v_lshlrev_b32_e32 v174, 16, v15
	v_and_b32_e32 v175, 0xffff0000, v15
	v_pk_mul_f32 v[252:253], v[160:161], v[160:161]
	v_pk_mul_f32 v[254:255], v[162:163], v[162:163]
	v_pk_fma_f32 v[252:253], v[164:165], v[164:165], v[252:253]
	v_pk_fma_f32 v[254:255], v[166:167], v[166:167], v[254:255]
	v_pk_fma_f32 v[252:253], v[168:169], v[168:169], v[252:253]
	v_pk_fma_f32 v[254:255], v[170:171], v[170:171], v[254:255]
	v_pk_fma_f32 v[252:253], v[172:173], v[172:173], v[252:253]
	v_pk_fma_f32 v[254:255], v[174:175], v[174:175], v[254:255]
	v_pk_add_f32 v[252:253], v[252:253], v[254:255]
	s_nop 0
	v_add_f32_e32 v183, v252, v253
	s_nop 1
	v_add_f32_dpp v183, v183, v183 quad_perm:[1,0,3,2] row_mask:0xf bank_mask:0xf bound_ctrl:1
	s_nop 1
	v_add_f32_dpp v183, v183, v183 quad_perm:[2,3,0,1] row_mask:0xf bank_mask:0xf bound_ctrl:1
	s_nop 1
	v_add_f32_dpp v183, v183, v183 row_half_mirror row_mask:0xf bank_mask:0xf bound_ctrl:1
	s_nop 1
	v_add_f32_dpp v183, v183, v183 row_mirror row_mask:0xf bank_mask:0xf bound_ctrl:1
	s_nop 1
	v_readlane_b32 s98, v183, 0
	v_readlane_b32 s99, v183, 16
	v_readlane_b32 s100, v183, 32
	v_readlane_b32 s101, v183, 48
	s_nop 1
	v_mov_b32_e32 v183, s98
	v_add_f32_e32 v183, s99, v183
	v_add_f32_e32 v183, s100, v183
	v_add_f32_e32 v183, s101, v183
	v_fmamk_f32 v183, v183, 0x3a800000, v182
	v_cmp_gt_f32_e32 vcc, 0x800000, v183
	v_mul_f32_e32 v181, 0x4b800000, v183
	s_nop 1
	v_cndmask_b32_e32 v183, v183, v181, vcc
	v_rsq_f32_e32 v183, v183
	s_nop 0
	v_mul_f32_e32 v181, 0x45800000, v183
	v_cndmask_b32_e32 v184, v183, v181, vcc
	v_mov_b32_e32 v185, v184
	v_pk_mul_f32 v[160:161], v[160:161], v[184:185]
	v_pk_mul_f32 v[162:163], v[162:163], v[184:185]
	v_pk_mul_f32 v[164:165], v[164:165], v[184:185]
	v_pk_mul_f32 v[166:167], v[166:167], v[184:185]
	v_pk_mul_f32 v[168:169], v[168:169], v[184:185]
	v_pk_mul_f32 v[170:171], v[170:171], v[184:185]
	v_pk_mul_f32 v[172:173], v[172:173], v[184:185]
	v_pk_mul_f32 v[174:175], v[174:175], v[184:185]
	v_pk_fma_f32 v[144:145], v[160:161], v[128:129], v[144:145]
	v_pk_fma_f32 v[146:147], v[162:163], v[130:131], v[146:147]
	v_pk_fma_f32 v[148:149], v[164:165], v[132:133], v[148:149]
	v_pk_fma_f32 v[150:151], v[166:167], v[134:135], v[150:151]
	v_pk_fma_f32 v[152:153], v[168:169], v[136:137], v[152:153]
	v_pk_fma_f32 v[154:155], v[170:171], v[138:139], v[154:155]
	v_pk_fma_f32 v[156:157], v[172:173], v[140:141], v[156:157]
	v_pk_fma_f32 v[158:159], v[174:175], v[142:143], v[158:159]
	v_pk_mul_f32 v[252:253], v[144:145], v[144:145]
	v_pk_mul_f32 v[254:255], v[146:147], v[146:147]
	v_pk_fma_f32 v[252:253], v[148:149], v[148:149], v[252:253]
	v_pk_fma_f32 v[254:255], v[150:151], v[150:151], v[254:255]
	v_pk_fma_f32 v[252:253], v[152:153], v[152:153], v[252:253]
	v_pk_fma_f32 v[254:255], v[154:155], v[154:155], v[254:255]
	v_pk_fma_f32 v[252:253], v[156:157], v[156:157], v[252:253]
	v_pk_fma_f32 v[254:255], v[158:159], v[158:159], v[254:255]
	v_pk_add_f32 v[252:253], v[252:253], v[254:255]
	s_nop 0
	v_add_f32_e32 v183, v252, v253
	s_nop 1
	v_add_f32_dpp v183, v183, v183 quad_perm:[1,0,3,2] row_mask:0xf bank_mask:0xf bound_ctrl:1
	s_nop 1
	v_add_f32_dpp v183, v183, v183 quad_perm:[2,3,0,1] row_mask:0xf bank_mask:0xf bound_ctrl:1
	s_nop 1
	v_add_f32_dpp v183, v183, v183 row_half_mirror row_mask:0xf bank_mask:0xf bound_ctrl:1
	s_nop 1
	v_add_f32_dpp v183, v183, v183 row_mirror row_mask:0xf bank_mask:0xf bound_ctrl:1
	s_nop 1
	v_readlane_b32 s98, v183, 0
	v_readlane_b32 s99, v183, 16
	v_readlane_b32 s100, v183, 32
	v_readlane_b32 s101, v183, 48
	s_nop 1
	v_mov_b32_e32 v183, s98
	v_add_f32_e32 v183, s99, v183
	v_add_f32_e32 v183, s100, v183
	v_add_f32_e32 v183, s101, v183
	v_fmamk_f32 v183, v183, 0x3a800000, v182
	v_cmp_gt_f32_e32 vcc, 0x800000, v183
	v_mul_f32_e32 v181, 0x4b800000, v183
	s_nop 1
	v_cndmask_b32_e32 v183, v183, v181, vcc
	v_rsq_f32_e32 v183, v183
	s_nop 0
	v_mul_f32_e32 v181, 0x45800000, v183
	v_cndmask_b32_e32 v184, v183, v181, vcc
	v_mov_b32_e32 v185, v184
	v_cvt_pk_bf16_f32 v0, v144, v145
	v_cvt_pk_bf16_f32 v1, v146, v147
	v_cvt_pk_bf16_f32 v2, v148, v149
	v_cvt_pk_bf16_f32 v3, v150, v151
	v_cvt_pk_bf16_f32 v4, v152, v153
	v_cvt_pk_bf16_f32 v5, v154, v155
	v_cvt_pk_bf16_f32 v6, v156, v157
	v_cvt_pk_bf16_f32 v7, v158, v159
	v_add_u32_e32 v181, 0x1800000, v177
	global_store_dwordx4 v181, v[0:3], s[78:79]
	global_store_dwordx4 v181, v[4:7], s[78:79] offset:1024
	v_add_u32_e32 v236, 0x0, v237
	s_mov_b64 exec, 1
	global_store_dword v236, v184, s[78:79]
	s_mov_b64 exec, -1
	s_waitcnt vmcnt(24)
	v_lshlrev_b32_e32 v144, 16, v16
	v_and_b32_e32 v145, 0xffff0000, v16
	v_lshlrev_b32_e32 v146, 16, v17
	v_and_b32_e32 v147, 0xffff0000, v17
	v_lshlrev_b32_e32 v148, 16, v18
	v_and_b32_e32 v149, 0xffff0000, v18
	v_lshlrev_b32_e32 v150, 16, v19
	v_and_b32_e32 v151, 0xffff0000, v19
	v_lshlrev_b32_e32 v152, 16, v20
	v_and_b32_e32 v153, 0xffff0000, v20
	v_lshlrev_b32_e32 v154, 16, v21
	v_and_b32_e32 v155, 0xffff0000, v21
	v_lshlrev_b32_e32 v156, 16, v22
	v_and_b32_e32 v157, 0xffff0000, v22
	v_lshlrev_b32_e32 v158, 16, v23
	v_and_b32_e32 v159, 0xffff0000, v23
	v_lshlrev_b32_e32 v160, 16, v24
	v_and_b32_e32 v161, 0xffff0000, v24
	v_lshlrev_b32_e32 v162, 16, v25
	v_and_b32_e32 v163, 0xffff0000, v25
	v_lshlrev_b32_e32 v164, 16, v26
	v_and_b32_e32 v165, 0xffff0000, v26
	v_lshlrev_b32_e32 v166, 16, v27
	v_and_b32_e32 v167, 0xffff0000, v27
	v_lshlrev_b32_e32 v168, 16, v28
	v_and_b32_e32 v169, 0xffff0000, v28
	v_lshlrev_b32_e32 v170, 16, v29
	v_and_b32_e32 v171, 0xffff0000, v29
	v_lshlrev_b32_e32 v172, 16, v30
	v_and_b32_e32 v173, 0xffff0000, v30
	v_lshlrev_b32_e32 v174, 16, v31
	v_and_b32_e32 v175, 0xffff0000, v31
	v_pk_mul_f32 v[252:253], v[160:161], v[160:161]
	v_pk_mul_f32 v[254:255], v[162:163], v[162:163]
	v_pk_fma_f32 v[252:253], v[164:165], v[164:165], v[252:253]
	v_pk_fma_f32 v[254:255], v[166:167], v[166:167], v[254:255]
	v_pk_fma_f32 v[252:253], v[168:169], v[168:169], v[252:253]
	v_pk_fma_f32 v[254:255], v[170:171], v[170:171], v[254:255]
	v_pk_fma_f32 v[252:253], v[172:173], v[172:173], v[252:253]
	v_pk_fma_f32 v[254:255], v[174:175], v[174:175], v[254:255]
	v_pk_add_f32 v[252:253], v[252:253], v[254:255]
	s_nop 0
	v_add_f32_e32 v183, v252, v253
	s_nop 1
	v_add_f32_dpp v183, v183, v183 quad_perm:[1,0,3,2] row_mask:0xf bank_mask:0xf bound_ctrl:1
	s_nop 1
	v_add_f32_dpp v183, v183, v183 quad_perm:[2,3,0,1] row_mask:0xf bank_mask:0xf bound_ctrl:1
	s_nop 1
	v_add_f32_dpp v183, v183, v183 row_half_mirror row_mask:0xf bank_mask:0xf bound_ctrl:1
	s_nop 1
	v_add_f32_dpp v183, v183, v183 row_mirror row_mask:0xf bank_mask:0xf bound_ctrl:1
	s_nop 1
	v_readlane_b32 s98, v183, 0
	v_readlane_b32 s99, v183, 16
	v_readlane_b32 s100, v183, 32
	v_readlane_b32 s101, v183, 48
	s_nop 1
	v_mov_b32_e32 v183, s98
	v_add_f32_e32 v183, s99, v183
	v_add_f32_e32 v183, s100, v183
	v_add_f32_e32 v183, s101, v183
	v_fmamk_f32 v183, v183, 0x3a800000, v182
	v_cmp_gt_f32_e32 vcc, 0x800000, v183
	v_mul_f32_e32 v181, 0x4b800000, v183
	s_nop 1
	v_cndmask_b32_e32 v183, v183, v181, vcc
	v_rsq_f32_e32 v183, v183
	s_nop 0
	v_mul_f32_e32 v181, 0x45800000, v183
	v_cndmask_b32_e32 v184, v183, v181, vcc
	v_mov_b32_e32 v185, v184
	v_pk_mul_f32 v[160:161], v[160:161], v[184:185]
	v_pk_mul_f32 v[162:163], v[162:163], v[184:185]
	v_pk_mul_f32 v[164:165], v[164:165], v[184:185]
	v_pk_mul_f32 v[166:167], v[166:167], v[184:185]
	v_pk_mul_f32 v[168:169], v[168:169], v[184:185]
	v_pk_mul_f32 v[170:171], v[170:171], v[184:185]
	v_pk_mul_f32 v[172:173], v[172:173], v[184:185]
	v_pk_mul_f32 v[174:175], v[174:175], v[184:185]
	v_pk_fma_f32 v[144:145], v[160:161], v[128:129], v[144:145]
	v_pk_fma_f32 v[146:147], v[162:163], v[130:131], v[146:147]
	v_pk_fma_f32 v[148:149], v[164:165], v[132:133], v[148:149]
	v_pk_fma_f32 v[150:151], v[166:167], v[134:135], v[150:151]
	v_pk_fma_f32 v[152:153], v[168:169], v[136:137], v[152:153]
	v_pk_fma_f32 v[154:155], v[170:171], v[138:139], v[154:155]
	v_pk_fma_f32 v[156:157], v[172:173], v[140:141], v[156:157]
	v_pk_fma_f32 v[158:159], v[174:175], v[142:143], v[158:159]
	v_pk_mul_f32 v[252:253], v[144:145], v[144:145]
	v_pk_mul_f32 v[254:255], v[146:147], v[146:147]
	v_pk_fma_f32 v[252:253], v[148:149], v[148:149], v[252:253]
	v_pk_fma_f32 v[254:255], v[150:151], v[150:151], v[254:255]
	v_pk_fma_f32 v[252:253], v[152:153], v[152:153], v[252:253]
	v_pk_fma_f32 v[254:255], v[154:155], v[154:155], v[254:255]
	v_pk_fma_f32 v[252:253], v[156:157], v[156:157], v[252:253]
	v_pk_fma_f32 v[254:255], v[158:159], v[158:159], v[254:255]
	v_pk_add_f32 v[252:253], v[252:253], v[254:255]
	s_nop 0
	v_add_f32_e32 v183, v252, v253
	s_nop 1
	v_add_f32_dpp v183, v183, v183 quad_perm:[1,0,3,2] row_mask:0xf bank_mask:0xf bound_ctrl:1
	s_nop 1
	v_add_f32_dpp v183, v183, v183 quad_perm:[2,3,0,1] row_mask:0xf bank_mask:0xf bound_ctrl:1
	s_nop 1
	v_add_f32_dpp v183, v183, v183 row_half_mirror row_mask:0xf bank_mask:0xf bound_ctrl:1
	s_nop 1
	v_add_f32_dpp v183, v183, v183 row_mirror row_mask:0xf bank_mask:0xf bound_ctrl:1
	s_nop 1
	v_readlane_b32 s98, v183, 0
	v_readlane_b32 s99, v183, 16
	v_readlane_b32 s100, v183, 32
	v_readlane_b32 s101, v183, 48
	s_nop 1
	v_mov_b32_e32 v183, s98
	v_add_f32_e32 v183, s99, v183
	v_add_f32_e32 v183, s100, v183
	v_add_f32_e32 v183, s101, v183
	v_fmamk_f32 v183, v183, 0x3a800000, v182
	v_cmp_gt_f32_e32 vcc, 0x800000, v183
	v_mul_f32_e32 v181, 0x4b800000, v183
	s_nop 1
	v_cndmask_b32_e32 v183, v183, v181, vcc
	v_rsq_f32_e32 v183, v183
	s_nop 0
	v_mul_f32_e32 v181, 0x45800000, v183
	v_cndmask_b32_e32 v184, v183, v181, vcc
	v_mov_b32_e32 v185, v184
	v_cvt_pk_bf16_f32 v16, v144, v145
	v_cvt_pk_bf16_f32 v17, v146, v147
	v_cvt_pk_bf16_f32 v18, v148, v149
	v_cvt_pk_bf16_f32 v19, v150, v151
	v_cvt_pk_bf16_f32 v20, v152, v153
	v_cvt_pk_bf16_f32 v21, v154, v155
	v_cvt_pk_bf16_f32 v22, v156, v157
	v_cvt_pk_bf16_f32 v23, v158, v159
	v_add_u32_e32 v181, 0x1880000, v177
	global_store_dwordx4 v181, v[16:19], s[78:79]
	global_store_dwordx4 v181, v[20:23], s[78:79] offset:1024
	v_add_u32_e32 v236, 0x400, v237
	s_mov_b64 exec, 1
	global_store_dword v236, v184, s[78:79]
	s_mov_b64 exec, -1
	s_waitcnt vmcnt(20)
	v_lshlrev_b32_e32 v144, 16, v32
	v_and_b32_e32 v145, 0xffff0000, v32
	v_lshlrev_b32_e32 v146, 16, v33
	v_and_b32_e32 v147, 0xffff0000, v33
	v_lshlrev_b32_e32 v148, 16, v34
	v_and_b32_e32 v149, 0xffff0000, v34
	v_lshlrev_b32_e32 v150, 16, v35
	v_and_b32_e32 v151, 0xffff0000, v35
	v_lshlrev_b32_e32 v152, 16, v36
	v_and_b32_e32 v153, 0xffff0000, v36
	v_lshlrev_b32_e32 v154, 16, v37
	v_and_b32_e32 v155, 0xffff0000, v37
	v_lshlrev_b32_e32 v156, 16, v38
	v_and_b32_e32 v157, 0xffff0000, v38
	v_lshlrev_b32_e32 v158, 16, v39
	v_and_b32_e32 v159, 0xffff0000, v39
	v_lshlrev_b32_e32 v160, 16, v40
	v_and_b32_e32 v161, 0xffff0000, v40
	v_lshlrev_b32_e32 v162, 16, v41
	v_and_b32_e32 v163, 0xffff0000, v41
	v_lshlrev_b32_e32 v164, 16, v42
	v_and_b32_e32 v165, 0xffff0000, v42
	v_lshlrev_b32_e32 v166, 16, v43
	v_and_b32_e32 v167, 0xffff0000, v43
	v_lshlrev_b32_e32 v168, 16, v44
	v_and_b32_e32 v169, 0xffff0000, v44
	v_lshlrev_b32_e32 v170, 16, v45
	v_and_b32_e32 v171, 0xffff0000, v45
	v_lshlrev_b32_e32 v172, 16, v46
	v_and_b32_e32 v173, 0xffff0000, v46
	v_lshlrev_b32_e32 v174, 16, v47
	v_and_b32_e32 v175, 0xffff0000, v47
	v_pk_mul_f32 v[252:253], v[160:161], v[160:161]
	v_pk_mul_f32 v[254:255], v[162:163], v[162:163]
	v_pk_fma_f32 v[252:253], v[164:165], v[164:165], v[252:253]
	v_pk_fma_f32 v[254:255], v[166:167], v[166:167], v[254:255]
	v_pk_fma_f32 v[252:253], v[168:169], v[168:169], v[252:253]
	v_pk_fma_f32 v[254:255], v[170:171], v[170:171], v[254:255]
	v_pk_fma_f32 v[252:253], v[172:173], v[172:173], v[252:253]
	v_pk_fma_f32 v[254:255], v[174:175], v[174:175], v[254:255]
	v_pk_add_f32 v[252:253], v[252:253], v[254:255]
	s_nop 0
	v_add_f32_e32 v183, v252, v253
	s_nop 1
	v_add_f32_dpp v183, v183, v183 quad_perm:[1,0,3,2] row_mask:0xf bank_mask:0xf bound_ctrl:1
	s_nop 1
	v_add_f32_dpp v183, v183, v183 quad_perm:[2,3,0,1] row_mask:0xf bank_mask:0xf bound_ctrl:1
	s_nop 1
	v_add_f32_dpp v183, v183, v183 row_half_mirror row_mask:0xf bank_mask:0xf bound_ctrl:1
	s_nop 1
	v_add_f32_dpp v183, v183, v183 row_mirror row_mask:0xf bank_mask:0xf bound_ctrl:1
	s_nop 1
	v_readlane_b32 s98, v183, 0
	v_readlane_b32 s99, v183, 16
	v_readlane_b32 s100, v183, 32
	v_readlane_b32 s101, v183, 48
	s_nop 1
	v_mov_b32_e32 v183, s98
	v_add_f32_e32 v183, s99, v183
	v_add_f32_e32 v183, s100, v183
	v_add_f32_e32 v183, s101, v183
	v_fmamk_f32 v183, v183, 0x3a800000, v182
	v_cmp_gt_f32_e32 vcc, 0x800000, v183
	v_mul_f32_e32 v181, 0x4b800000, v183
	s_nop 1
	v_cndmask_b32_e32 v183, v183, v181, vcc
	v_rsq_f32_e32 v183, v183
	s_nop 0
	v_mul_f32_e32 v181, 0x45800000, v183
	v_cndmask_b32_e32 v184, v183, v181, vcc
	v_mov_b32_e32 v185, v184
	v_pk_mul_f32 v[160:161], v[160:161], v[184:185]
	v_pk_mul_f32 v[162:163], v[162:163], v[184:185]
	v_pk_mul_f32 v[164:165], v[164:165], v[184:185]
	v_pk_mul_f32 v[166:167], v[166:167], v[184:185]
	v_pk_mul_f32 v[168:169], v[168:169], v[184:185]
	v_pk_mul_f32 v[170:171], v[170:171], v[184:185]
	v_pk_mul_f32 v[172:173], v[172:173], v[184:185]
	v_pk_mul_f32 v[174:175], v[174:175], v[184:185]
	v_pk_fma_f32 v[144:145], v[160:161], v[128:129], v[144:145]
	v_pk_fma_f32 v[146:147], v[162:163], v[130:131], v[146:147]
	v_pk_fma_f32 v[148:149], v[164:165], v[132:133], v[148:149]
	v_pk_fma_f32 v[150:151], v[166:167], v[134:135], v[150:151]
	v_pk_fma_f32 v[152:153], v[168:169], v[136:137], v[152:153]
	v_pk_fma_f32 v[154:155], v[170:171], v[138:139], v[154:155]
	v_pk_fma_f32 v[156:157], v[172:173], v[140:141], v[156:157]
	v_pk_fma_f32 v[158:159], v[174:175], v[142:143], v[158:159]
	v_pk_mul_f32 v[252:253], v[144:145], v[144:145]
	v_pk_mul_f32 v[254:255], v[146:147], v[146:147]
	v_pk_fma_f32 v[252:253], v[148:149], v[148:149], v[252:253]
	v_pk_fma_f32 v[254:255], v[150:151], v[150:151], v[254:255]
	v_pk_fma_f32 v[252:253], v[152:153], v[152:153], v[252:253]
	v_pk_fma_f32 v[254:255], v[154:155], v[154:155], v[254:255]
	v_pk_fma_f32 v[252:253], v[156:157], v[156:157], v[252:253]
	v_pk_fma_f32 v[254:255], v[158:159], v[158:159], v[254:255]
	v_pk_add_f32 v[252:253], v[252:253], v[254:255]
	s_nop 0
	v_add_f32_e32 v183, v252, v253
	s_nop 1
	v_add_f32_dpp v183, v183, v183 quad_perm:[1,0,3,2] row_mask:0xf bank_mask:0xf bound_ctrl:1
	s_nop 1
	v_add_f32_dpp v183, v183, v183 quad_perm:[2,3,0,1] row_mask:0xf bank_mask:0xf bound_ctrl:1
	s_nop 1
	v_add_f32_dpp v183, v183, v183 row_half_mirror row_mask:0xf bank_mask:0xf bound_ctrl:1
	s_nop 1
	v_add_f32_dpp v183, v183, v183 row_mirror row_mask:0xf bank_mask:0xf bound_ctrl:1
	s_nop 1
	v_readlane_b32 s98, v183, 0
	v_readlane_b32 s99, v183, 16
	v_readlane_b32 s100, v183, 32
	v_readlane_b32 s101, v183, 48
	s_nop 1
	v_mov_b32_e32 v183, s98
	v_add_f32_e32 v183, s99, v183
	v_add_f32_e32 v183, s100, v183
	v_add_f32_e32 v183, s101, v183
	v_fmamk_f32 v183, v183, 0x3a800000, v182
	v_cmp_gt_f32_e32 vcc, 0x800000, v183
	v_mul_f32_e32 v181, 0x4b800000, v183
	s_nop 1
	v_cndmask_b32_e32 v183, v183, v181, vcc
	v_rsq_f32_e32 v183, v183
	s_nop 0
	v_mul_f32_e32 v181, 0x45800000, v183
	v_cndmask_b32_e32 v184, v183, v181, vcc
	v_mov_b32_e32 v185, v184
	v_cvt_pk_bf16_f32 v32, v144, v145
	v_cvt_pk_bf16_f32 v33, v146, v147
	v_cvt_pk_bf16_f32 v34, v148, v149
	v_cvt_pk_bf16_f32 v35, v150, v151
	v_cvt_pk_bf16_f32 v36, v152, v153
	v_cvt_pk_bf16_f32 v37, v154, v155
	v_cvt_pk_bf16_f32 v38, v156, v157
	v_cvt_pk_bf16_f32 v39, v158, v159
	v_add_u32_e32 v181, 0x1900000, v177
	global_store_dwordx4 v181, v[32:35], s[78:79]
	global_store_dwordx4 v181, v[36:39], s[78:79] offset:1024
	v_add_u32_e32 v236, 0x800, v237
	s_mov_b64 exec, 1
	global_store_dword v236, v184, s[78:79]
	s_mov_b64 exec, -1
	s_waitcnt vmcnt(16)
	v_lshlrev_b32_e32 v144, 16, v48
	v_and_b32_e32 v145, 0xffff0000, v48
	v_lshlrev_b32_e32 v146, 16, v49
	v_and_b32_e32 v147, 0xffff0000, v49
	v_lshlrev_b32_e32 v148, 16, v50
	v_and_b32_e32 v149, 0xffff0000, v50
	v_lshlrev_b32_e32 v150, 16, v51
	v_and_b32_e32 v151, 0xffff0000, v51
	v_lshlrev_b32_e32 v152, 16, v52
	v_and_b32_e32 v153, 0xffff0000, v52
	v_lshlrev_b32_e32 v154, 16, v53
	v_and_b32_e32 v155, 0xffff0000, v53
	v_lshlrev_b32_e32 v156, 16, v54
	v_and_b32_e32 v157, 0xffff0000, v54
	v_lshlrev_b32_e32 v158, 16, v55
	v_and_b32_e32 v159, 0xffff0000, v55
	v_lshlrev_b32_e32 v160, 16, v56
	v_and_b32_e32 v161, 0xffff0000, v56
	v_lshlrev_b32_e32 v162, 16, v57
	v_and_b32_e32 v163, 0xffff0000, v57
	v_lshlrev_b32_e32 v164, 16, v58
	v_and_b32_e32 v165, 0xffff0000, v58
	v_lshlrev_b32_e32 v166, 16, v59
	v_and_b32_e32 v167, 0xffff0000, v59
	v_lshlrev_b32_e32 v168, 16, v60
	v_and_b32_e32 v169, 0xffff0000, v60
	v_lshlrev_b32_e32 v170, 16, v61
	v_and_b32_e32 v171, 0xffff0000, v61
	v_lshlrev_b32_e32 v172, 16, v62
	v_and_b32_e32 v173, 0xffff0000, v62
	v_lshlrev_b32_e32 v174, 16, v63
	v_and_b32_e32 v175, 0xffff0000, v63
	v_pk_mul_f32 v[252:253], v[160:161], v[160:161]
	v_pk_mul_f32 v[254:255], v[162:163], v[162:163]
	v_pk_fma_f32 v[252:253], v[164:165], v[164:165], v[252:253]
	v_pk_fma_f32 v[254:255], v[166:167], v[166:167], v[254:255]
	v_pk_fma_f32 v[252:253], v[168:169], v[168:169], v[252:253]
	v_pk_fma_f32 v[254:255], v[170:171], v[170:171], v[254:255]
	v_pk_fma_f32 v[252:253], v[172:173], v[172:173], v[252:253]
	v_pk_fma_f32 v[254:255], v[174:175], v[174:175], v[254:255]
	v_pk_add_f32 v[252:253], v[252:253], v[254:255]
	s_nop 0
	v_add_f32_e32 v183, v252, v253
	s_nop 1
	v_add_f32_dpp v183, v183, v183 quad_perm:[1,0,3,2] row_mask:0xf bank_mask:0xf bound_ctrl:1
	s_nop 1
	v_add_f32_dpp v183, v183, v183 quad_perm:[2,3,0,1] row_mask:0xf bank_mask:0xf bound_ctrl:1
	s_nop 1
	v_add_f32_dpp v183, v183, v183 row_half_mirror row_mask:0xf bank_mask:0xf bound_ctrl:1
	s_nop 1
	v_add_f32_dpp v183, v183, v183 row_mirror row_mask:0xf bank_mask:0xf bound_ctrl:1
	s_nop 1
	v_readlane_b32 s98, v183, 0
	v_readlane_b32 s99, v183, 16
	v_readlane_b32 s100, v183, 32
	v_readlane_b32 s101, v183, 48
	s_nop 1
	v_mov_b32_e32 v183, s98
	v_add_f32_e32 v183, s99, v183
	v_add_f32_e32 v183, s100, v183
	v_add_f32_e32 v183, s101, v183
	v_fmamk_f32 v183, v183, 0x3a800000, v182
	v_cmp_gt_f32_e32 vcc, 0x800000, v183
	v_mul_f32_e32 v181, 0x4b800000, v183
	s_nop 1
	v_cndmask_b32_e32 v183, v183, v181, vcc
	v_rsq_f32_e32 v183, v183
	s_nop 0
	v_mul_f32_e32 v181, 0x45800000, v183
	v_cndmask_b32_e32 v184, v183, v181, vcc
	v_mov_b32_e32 v185, v184
	v_pk_mul_f32 v[160:161], v[160:161], v[184:185]
	v_pk_mul_f32 v[162:163], v[162:163], v[184:185]
	v_pk_mul_f32 v[164:165], v[164:165], v[184:185]
	v_pk_mul_f32 v[166:167], v[166:167], v[184:185]
	v_pk_mul_f32 v[168:169], v[168:169], v[184:185]
	v_pk_mul_f32 v[170:171], v[170:171], v[184:185]
	v_pk_mul_f32 v[172:173], v[172:173], v[184:185]
	v_pk_mul_f32 v[174:175], v[174:175], v[184:185]
	v_pk_fma_f32 v[144:145], v[160:161], v[128:129], v[144:145]
	v_pk_fma_f32 v[146:147], v[162:163], v[130:131], v[146:147]
	v_pk_fma_f32 v[148:149], v[164:165], v[132:133], v[148:149]
	v_pk_fma_f32 v[150:151], v[166:167], v[134:135], v[150:151]
	v_pk_fma_f32 v[152:153], v[168:169], v[136:137], v[152:153]
	v_pk_fma_f32 v[154:155], v[170:171], v[138:139], v[154:155]
	v_pk_fma_f32 v[156:157], v[172:173], v[140:141], v[156:157]
	v_pk_fma_f32 v[158:159], v[174:175], v[142:143], v[158:159]
	v_pk_mul_f32 v[252:253], v[144:145], v[144:145]
	v_pk_mul_f32 v[254:255], v[146:147], v[146:147]
	v_pk_fma_f32 v[252:253], v[148:149], v[148:149], v[252:253]
	v_pk_fma_f32 v[254:255], v[150:151], v[150:151], v[254:255]
	v_pk_fma_f32 v[252:253], v[152:153], v[152:153], v[252:253]
	v_pk_fma_f32 v[254:255], v[154:155], v[154:155], v[254:255]
	v_pk_fma_f32 v[252:253], v[156:157], v[156:157], v[252:253]
	v_pk_fma_f32 v[254:255], v[158:159], v[158:159], v[254:255]
	v_pk_add_f32 v[252:253], v[252:253], v[254:255]
	s_nop 0
	v_add_f32_e32 v183, v252, v253
	s_nop 1
	v_add_f32_dpp v183, v183, v183 quad_perm:[1,0,3,2] row_mask:0xf bank_mask:0xf bound_ctrl:1
	s_nop 1
	v_add_f32_dpp v183, v183, v183 quad_perm:[2,3,0,1] row_mask:0xf bank_mask:0xf bound_ctrl:1
	s_nop 1
	v_add_f32_dpp v183, v183, v183 row_half_mirror row_mask:0xf bank_mask:0xf bound_ctrl:1
	s_nop 1
	v_add_f32_dpp v183, v183, v183 row_mirror row_mask:0xf bank_mask:0xf bound_ctrl:1
	s_nop 1
	v_readlane_b32 s98, v183, 0
	v_readlane_b32 s99, v183, 16
	v_readlane_b32 s100, v183, 32
	v_readlane_b32 s101, v183, 48
	s_nop 1
	v_mov_b32_e32 v183, s98
	v_add_f32_e32 v183, s99, v183
	v_add_f32_e32 v183, s100, v183
	v_add_f32_e32 v183, s101, v183
	v_fmamk_f32 v183, v183, 0x3a800000, v182
	v_cmp_gt_f32_e32 vcc, 0x800000, v183
	v_mul_f32_e32 v181, 0x4b800000, v183
	s_nop 1
	v_cndmask_b32_e32 v183, v183, v181, vcc
	v_rsq_f32_e32 v183, v183
	s_nop 0
	v_mul_f32_e32 v181, 0x45800000, v183
	v_cndmask_b32_e32 v184, v183, v181, vcc
	v_mov_b32_e32 v185, v184
	v_cvt_pk_bf16_f32 v48, v144, v145
	v_cvt_pk_bf16_f32 v49, v146, v147
	v_cvt_pk_bf16_f32 v50, v148, v149
	v_cvt_pk_bf16_f32 v51, v150, v151
	v_cvt_pk_bf16_f32 v52, v152, v153
	v_cvt_pk_bf16_f32 v53, v154, v155
	v_cvt_pk_bf16_f32 v54, v156, v157
	v_cvt_pk_bf16_f32 v55, v158, v159
	v_add_u32_e32 v181, 0x1980000, v177
	global_store_dwordx4 v181, v[48:51], s[78:79]
	global_store_dwordx4 v181, v[52:55], s[78:79] offset:1024
	v_add_u32_e32 v236, 0xc00, v237
	s_mov_b64 exec, 1
	global_store_dword v236, v184, s[78:79]
	s_mov_b64 exec, -1
	s_waitcnt vmcnt(12)
	v_lshlrev_b32_e32 v144, 16, v64
	v_and_b32_e32 v145, 0xffff0000, v64
	v_lshlrev_b32_e32 v146, 16, v65
	v_and_b32_e32 v147, 0xffff0000, v65
	v_lshlrev_b32_e32 v148, 16, v66
	v_and_b32_e32 v149, 0xffff0000, v66
	v_lshlrev_b32_e32 v150, 16, v67
	v_and_b32_e32 v151, 0xffff0000, v67
	v_lshlrev_b32_e32 v152, 16, v68
	v_and_b32_e32 v153, 0xffff0000, v68
	v_lshlrev_b32_e32 v154, 16, v69
	v_and_b32_e32 v155, 0xffff0000, v69
	v_lshlrev_b32_e32 v156, 16, v70
	v_and_b32_e32 v157, 0xffff0000, v70
	v_lshlrev_b32_e32 v158, 16, v71
	v_and_b32_e32 v159, 0xffff0000, v71
	v_lshlrev_b32_e32 v160, 16, v72
	v_and_b32_e32 v161, 0xffff0000, v72
	v_lshlrev_b32_e32 v162, 16, v73
	v_and_b32_e32 v163, 0xffff0000, v73
	v_lshlrev_b32_e32 v164, 16, v74
	v_and_b32_e32 v165, 0xffff0000, v74
	v_lshlrev_b32_e32 v166, 16, v75
	v_and_b32_e32 v167, 0xffff0000, v75
	v_lshlrev_b32_e32 v168, 16, v76
	v_and_b32_e32 v169, 0xffff0000, v76
	v_lshlrev_b32_e32 v170, 16, v77
	v_and_b32_e32 v171, 0xffff0000, v77
	v_lshlrev_b32_e32 v172, 16, v78
	v_and_b32_e32 v173, 0xffff0000, v78
	v_lshlrev_b32_e32 v174, 16, v79
	v_and_b32_e32 v175, 0xffff0000, v79
	v_pk_mul_f32 v[252:253], v[160:161], v[160:161]
	v_pk_mul_f32 v[254:255], v[162:163], v[162:163]
	v_pk_fma_f32 v[252:253], v[164:165], v[164:165], v[252:253]
	v_pk_fma_f32 v[254:255], v[166:167], v[166:167], v[254:255]
	v_pk_fma_f32 v[252:253], v[168:169], v[168:169], v[252:253]
	v_pk_fma_f32 v[254:255], v[170:171], v[170:171], v[254:255]
	v_pk_fma_f32 v[252:253], v[172:173], v[172:173], v[252:253]
	v_pk_fma_f32 v[254:255], v[174:175], v[174:175], v[254:255]
	v_pk_add_f32 v[252:253], v[252:253], v[254:255]
	s_nop 0
	v_add_f32_e32 v183, v252, v253
	s_nop 1
	v_add_f32_dpp v183, v183, v183 quad_perm:[1,0,3,2] row_mask:0xf bank_mask:0xf bound_ctrl:1
	s_nop 1
	v_add_f32_dpp v183, v183, v183 quad_perm:[2,3,0,1] row_mask:0xf bank_mask:0xf bound_ctrl:1
	s_nop 1
	v_add_f32_dpp v183, v183, v183 row_half_mirror row_mask:0xf bank_mask:0xf bound_ctrl:1
	s_nop 1
	v_add_f32_dpp v183, v183, v183 row_mirror row_mask:0xf bank_mask:0xf bound_ctrl:1
	s_nop 1
	v_readlane_b32 s98, v183, 0
	v_readlane_b32 s99, v183, 16
	v_readlane_b32 s100, v183, 32
	v_readlane_b32 s101, v183, 48
	s_nop 1
	v_mov_b32_e32 v183, s98
	v_add_f32_e32 v183, s99, v183
	v_add_f32_e32 v183, s100, v183
	v_add_f32_e32 v183, s101, v183
	v_fmamk_f32 v183, v183, 0x3a800000, v182
	v_cmp_gt_f32_e32 vcc, 0x800000, v183
	v_mul_f32_e32 v181, 0x4b800000, v183
	s_nop 1
	v_cndmask_b32_e32 v183, v183, v181, vcc
	v_rsq_f32_e32 v183, v183
	s_nop 0
	v_mul_f32_e32 v181, 0x45800000, v183
	v_cndmask_b32_e32 v184, v183, v181, vcc
	v_mov_b32_e32 v185, v184
	v_pk_mul_f32 v[160:161], v[160:161], v[184:185]
	v_pk_mul_f32 v[162:163], v[162:163], v[184:185]
	v_pk_mul_f32 v[164:165], v[164:165], v[184:185]
	v_pk_mul_f32 v[166:167], v[166:167], v[184:185]
	v_pk_mul_f32 v[168:169], v[168:169], v[184:185]
	v_pk_mul_f32 v[170:171], v[170:171], v[184:185]
	v_pk_mul_f32 v[172:173], v[172:173], v[184:185]
	v_pk_mul_f32 v[174:175], v[174:175], v[184:185]
	v_pk_fma_f32 v[144:145], v[160:161], v[128:129], v[144:145]
	v_pk_fma_f32 v[146:147], v[162:163], v[130:131], v[146:147]
	v_pk_fma_f32 v[148:149], v[164:165], v[132:133], v[148:149]
	v_pk_fma_f32 v[150:151], v[166:167], v[134:135], v[150:151]
	v_pk_fma_f32 v[152:153], v[168:169], v[136:137], v[152:153]
	v_pk_fma_f32 v[154:155], v[170:171], v[138:139], v[154:155]
	v_pk_fma_f32 v[156:157], v[172:173], v[140:141], v[156:157]
	v_pk_fma_f32 v[158:159], v[174:175], v[142:143], v[158:159]
	v_pk_mul_f32 v[252:253], v[144:145], v[144:145]
	v_pk_mul_f32 v[254:255], v[146:147], v[146:147]
	v_pk_fma_f32 v[252:253], v[148:149], v[148:149], v[252:253]
	v_pk_fma_f32 v[254:255], v[150:151], v[150:151], v[254:255]
	v_pk_fma_f32 v[252:253], v[152:153], v[152:153], v[252:253]
	v_pk_fma_f32 v[254:255], v[154:155], v[154:155], v[254:255]
	v_pk_fma_f32 v[252:253], v[156:157], v[156:157], v[252:253]
	v_pk_fma_f32 v[254:255], v[158:159], v[158:159], v[254:255]
	v_pk_add_f32 v[252:253], v[252:253], v[254:255]
	s_nop 0
	v_add_f32_e32 v183, v252, v253
	s_nop 1
	v_add_f32_dpp v183, v183, v183 quad_perm:[1,0,3,2] row_mask:0xf bank_mask:0xf bound_ctrl:1
	s_nop 1
	v_add_f32_dpp v183, v183, v183 quad_perm:[2,3,0,1] row_mask:0xf bank_mask:0xf bound_ctrl:1
	s_nop 1
	v_add_f32_dpp v183, v183, v183 row_half_mirror row_mask:0xf bank_mask:0xf bound_ctrl:1
	s_nop 1
	v_add_f32_dpp v183, v183, v183 row_mirror row_mask:0xf bank_mask:0xf bound_ctrl:1
	s_nop 1
	v_readlane_b32 s98, v183, 0
	v_readlane_b32 s99, v183, 16
	v_readlane_b32 s100, v183, 32
	v_readlane_b32 s101, v183, 48
	s_nop 1
	v_mov_b32_e32 v183, s98
	v_add_f32_e32 v183, s99, v183
	v_add_f32_e32 v183, s100, v183
	v_add_f32_e32 v183, s101, v183
	v_fmamk_f32 v183, v183, 0x3a800000, v182
	v_cmp_gt_f32_e32 vcc, 0x800000, v183
	v_mul_f32_e32 v181, 0x4b800000, v183
	s_nop 1
	v_cndmask_b32_e32 v183, v183, v181, vcc
	v_rsq_f32_e32 v183, v183
	s_nop 0
	v_mul_f32_e32 v181, 0x45800000, v183
	v_cndmask_b32_e32 v184, v183, v181, vcc
	v_mov_b32_e32 v185, v184
	v_cvt_pk_bf16_f32 v64, v144, v145
	v_cvt_pk_bf16_f32 v65, v146, v147
	v_cvt_pk_bf16_f32 v66, v148, v149
	v_cvt_pk_bf16_f32 v67, v150, v151
	v_cvt_pk_bf16_f32 v68, v152, v153
	v_cvt_pk_bf16_f32 v69, v154, v155
	v_cvt_pk_bf16_f32 v70, v156, v157
	v_cvt_pk_bf16_f32 v71, v158, v159
	v_add_u32_e32 v181, 0x1a00000, v177
	global_store_dwordx4 v181, v[64:67], s[78:79]
	global_store_dwordx4 v181, v[68:71], s[78:79] offset:1024
	v_add_u32_e32 v236, 0x1000, v237
	s_mov_b64 exec, 1
	global_store_dword v236, v184, s[78:79]
	s_mov_b64 exec, -1
	s_waitcnt vmcnt(8)
	v_lshlrev_b32_e32 v144, 16, v80
	v_and_b32_e32 v145, 0xffff0000, v80
	v_lshlrev_b32_e32 v146, 16, v81
	v_and_b32_e32 v147, 0xffff0000, v81
	v_lshlrev_b32_e32 v148, 16, v82
	v_and_b32_e32 v149, 0xffff0000, v82
	v_lshlrev_b32_e32 v150, 16, v83
	v_and_b32_e32 v151, 0xffff0000, v83
	v_lshlrev_b32_e32 v152, 16, v84
	v_and_b32_e32 v153, 0xffff0000, v84
	v_lshlrev_b32_e32 v154, 16, v85
	v_and_b32_e32 v155, 0xffff0000, v85
	v_lshlrev_b32_e32 v156, 16, v86
	v_and_b32_e32 v157, 0xffff0000, v86
	v_lshlrev_b32_e32 v158, 16, v87
	v_and_b32_e32 v159, 0xffff0000, v87
	v_lshlrev_b32_e32 v160, 16, v88
	v_and_b32_e32 v161, 0xffff0000, v88
	v_lshlrev_b32_e32 v162, 16, v89
	v_and_b32_e32 v163, 0xffff0000, v89
	v_lshlrev_b32_e32 v164, 16, v90
	v_and_b32_e32 v165, 0xffff0000, v90
	v_lshlrev_b32_e32 v166, 16, v91
	v_and_b32_e32 v167, 0xffff0000, v91
	v_lshlrev_b32_e32 v168, 16, v92
	v_and_b32_e32 v169, 0xffff0000, v92
	v_lshlrev_b32_e32 v170, 16, v93
	v_and_b32_e32 v171, 0xffff0000, v93
	v_lshlrev_b32_e32 v172, 16, v94
	v_and_b32_e32 v173, 0xffff0000, v94
	v_lshlrev_b32_e32 v174, 16, v95
	v_and_b32_e32 v175, 0xffff0000, v95
	v_pk_mul_f32 v[252:253], v[160:161], v[160:161]
	v_pk_mul_f32 v[254:255], v[162:163], v[162:163]
	v_pk_fma_f32 v[252:253], v[164:165], v[164:165], v[252:253]
	v_pk_fma_f32 v[254:255], v[166:167], v[166:167], v[254:255]
	v_pk_fma_f32 v[252:253], v[168:169], v[168:169], v[252:253]
	v_pk_fma_f32 v[254:255], v[170:171], v[170:171], v[254:255]
	v_pk_fma_f32 v[252:253], v[172:173], v[172:173], v[252:253]
	v_pk_fma_f32 v[254:255], v[174:175], v[174:175], v[254:255]
	v_pk_add_f32 v[252:253], v[252:253], v[254:255]
	s_nop 0
	v_add_f32_e32 v183, v252, v253
	s_nop 1
	v_add_f32_dpp v183, v183, v183 quad_perm:[1,0,3,2] row_mask:0xf bank_mask:0xf bound_ctrl:1
	s_nop 1
	v_add_f32_dpp v183, v183, v183 quad_perm:[2,3,0,1] row_mask:0xf bank_mask:0xf bound_ctrl:1
	s_nop 1
	v_add_f32_dpp v183, v183, v183 row_half_mirror row_mask:0xf bank_mask:0xf bound_ctrl:1
	s_nop 1
	v_add_f32_dpp v183, v183, v183 row_mirror row_mask:0xf bank_mask:0xf bound_ctrl:1
	s_nop 1
	v_readlane_b32 s98, v183, 0
	v_readlane_b32 s99, v183, 16
	v_readlane_b32 s100, v183, 32
	v_readlane_b32 s101, v183, 48
	s_nop 1
	v_mov_b32_e32 v183, s98
	v_add_f32_e32 v183, s99, v183
	v_add_f32_e32 v183, s100, v183
	v_add_f32_e32 v183, s101, v183
	v_fmamk_f32 v183, v183, 0x3a800000, v182
	v_cmp_gt_f32_e32 vcc, 0x800000, v183
	v_mul_f32_e32 v181, 0x4b800000, v183
	s_nop 1
	v_cndmask_b32_e32 v183, v183, v181, vcc
	v_rsq_f32_e32 v183, v183
	s_nop 0
	v_mul_f32_e32 v181, 0x45800000, v183
	v_cndmask_b32_e32 v184, v183, v181, vcc
	v_mov_b32_e32 v185, v184
	v_pk_mul_f32 v[160:161], v[160:161], v[184:185]
	v_pk_mul_f32 v[162:163], v[162:163], v[184:185]
	v_pk_mul_f32 v[164:165], v[164:165], v[184:185]
	v_pk_mul_f32 v[166:167], v[166:167], v[184:185]
	v_pk_mul_f32 v[168:169], v[168:169], v[184:185]
	v_pk_mul_f32 v[170:171], v[170:171], v[184:185]
	v_pk_mul_f32 v[172:173], v[172:173], v[184:185]
	v_pk_mul_f32 v[174:175], v[174:175], v[184:185]
	v_pk_fma_f32 v[144:145], v[160:161], v[128:129], v[144:145]
	v_pk_fma_f32 v[146:147], v[162:163], v[130:131], v[146:147]
	v_pk_fma_f32 v[148:149], v[164:165], v[132:133], v[148:149]
	v_pk_fma_f32 v[150:151], v[166:167], v[134:135], v[150:151]
	v_pk_fma_f32 v[152:153], v[168:169], v[136:137], v[152:153]
	v_pk_fma_f32 v[154:155], v[170:171], v[138:139], v[154:155]
	v_pk_fma_f32 v[156:157], v[172:173], v[140:141], v[156:157]
	v_pk_fma_f32 v[158:159], v[174:175], v[142:143], v[158:159]
	v_pk_mul_f32 v[252:253], v[144:145], v[144:145]
	v_pk_mul_f32 v[254:255], v[146:147], v[146:147]
	v_pk_fma_f32 v[252:253], v[148:149], v[148:149], v[252:253]
	v_pk_fma_f32 v[254:255], v[150:151], v[150:151], v[254:255]
	v_pk_fma_f32 v[252:253], v[152:153], v[152:153], v[252:253]
	v_pk_fma_f32 v[254:255], v[154:155], v[154:155], v[254:255]
	v_pk_fma_f32 v[252:253], v[156:157], v[156:157], v[252:253]
	v_pk_fma_f32 v[254:255], v[158:159], v[158:159], v[254:255]
	v_pk_add_f32 v[252:253], v[252:253], v[254:255]
	s_nop 0
	v_add_f32_e32 v183, v252, v253
	s_nop 1
	v_add_f32_dpp v183, v183, v183 quad_perm:[1,0,3,2] row_mask:0xf bank_mask:0xf bound_ctrl:1
	s_nop 1
	v_add_f32_dpp v183, v183, v183 quad_perm:[2,3,0,1] row_mask:0xf bank_mask:0xf bound_ctrl:1
	s_nop 1
	v_add_f32_dpp v183, v183, v183 row_half_mirror row_mask:0xf bank_mask:0xf bound_ctrl:1
	s_nop 1
	v_add_f32_dpp v183, v183, v183 row_mirror row_mask:0xf bank_mask:0xf bound_ctrl:1
	s_nop 1
	v_readlane_b32 s98, v183, 0
	v_readlane_b32 s99, v183, 16
	v_readlane_b32 s100, v183, 32
	v_readlane_b32 s101, v183, 48
	s_nop 1
	v_mov_b32_e32 v183, s98
	v_add_f32_e32 v183, s99, v183
	v_add_f32_e32 v183, s100, v183
	v_add_f32_e32 v183, s101, v183
	v_fmamk_f32 v183, v183, 0x3a800000, v182
	v_cmp_gt_f32_e32 vcc, 0x800000, v183
	v_mul_f32_e32 v181, 0x4b800000, v183
	s_nop 1
	v_cndmask_b32_e32 v183, v183, v181, vcc
	v_rsq_f32_e32 v183, v183
	s_nop 0
	v_mul_f32_e32 v181, 0x45800000, v183
	v_cndmask_b32_e32 v184, v183, v181, vcc
	v_mov_b32_e32 v185, v184
	v_cvt_pk_bf16_f32 v80, v144, v145
	v_cvt_pk_bf16_f32 v81, v146, v147
	v_cvt_pk_bf16_f32 v82, v148, v149
	v_cvt_pk_bf16_f32 v83, v150, v151
	v_cvt_pk_bf16_f32 v84, v152, v153
	v_cvt_pk_bf16_f32 v85, v154, v155
	v_cvt_pk_bf16_f32 v86, v156, v157
	v_cvt_pk_bf16_f32 v87, v158, v159
	v_add_u32_e32 v181, 0x1a80000, v177
	global_store_dwordx4 v181, v[80:83], s[78:79]
	global_store_dwordx4 v181, v[84:87], s[78:79] offset:1024
	v_add_u32_e32 v236, 0x1400, v237
	s_mov_b64 exec, 1
	global_store_dword v236, v184, s[78:79]
	s_mov_b64 exec, -1
	s_waitcnt vmcnt(4)
	v_lshlrev_b32_e32 v144, 16, v96
	v_and_b32_e32 v145, 0xffff0000, v96
	v_lshlrev_b32_e32 v146, 16, v97
	v_and_b32_e32 v147, 0xffff0000, v97
	v_lshlrev_b32_e32 v148, 16, v98
	v_and_b32_e32 v149, 0xffff0000, v98
	v_lshlrev_b32_e32 v150, 16, v99
	v_and_b32_e32 v151, 0xffff0000, v99
	v_lshlrev_b32_e32 v152, 16, v100
	v_and_b32_e32 v153, 0xffff0000, v100
	v_lshlrev_b32_e32 v154, 16, v101
	v_and_b32_e32 v155, 0xffff0000, v101
	v_lshlrev_b32_e32 v156, 16, v102
	v_and_b32_e32 v157, 0xffff0000, v102
	v_lshlrev_b32_e32 v158, 16, v103
	v_and_b32_e32 v159, 0xffff0000, v103
	v_lshlrev_b32_e32 v160, 16, v104
	v_and_b32_e32 v161, 0xffff0000, v104
	v_lshlrev_b32_e32 v162, 16, v105
	v_and_b32_e32 v163, 0xffff0000, v105
	v_lshlrev_b32_e32 v164, 16, v106
	v_and_b32_e32 v165, 0xffff0000, v106
	v_lshlrev_b32_e32 v166, 16, v107
	v_and_b32_e32 v167, 0xffff0000, v107
	v_lshlrev_b32_e32 v168, 16, v108
	v_and_b32_e32 v169, 0xffff0000, v108
	v_lshlrev_b32_e32 v170, 16, v109
	v_and_b32_e32 v171, 0xffff0000, v109
	v_lshlrev_b32_e32 v172, 16, v110
	v_and_b32_e32 v173, 0xffff0000, v110
	v_lshlrev_b32_e32 v174, 16, v111
	v_and_b32_e32 v175, 0xffff0000, v111
	v_pk_mul_f32 v[252:253], v[160:161], v[160:161]
	v_pk_mul_f32 v[254:255], v[162:163], v[162:163]
	v_pk_fma_f32 v[252:253], v[164:165], v[164:165], v[252:253]
	v_pk_fma_f32 v[254:255], v[166:167], v[166:167], v[254:255]
	v_pk_fma_f32 v[252:253], v[168:169], v[168:169], v[252:253]
	v_pk_fma_f32 v[254:255], v[170:171], v[170:171], v[254:255]
	v_pk_fma_f32 v[252:253], v[172:173], v[172:173], v[252:253]
	v_pk_fma_f32 v[254:255], v[174:175], v[174:175], v[254:255]
	v_pk_add_f32 v[252:253], v[252:253], v[254:255]
	s_nop 0
	v_add_f32_e32 v183, v252, v253
	s_nop 1
	v_add_f32_dpp v183, v183, v183 quad_perm:[1,0,3,2] row_mask:0xf bank_mask:0xf bound_ctrl:1
	s_nop 1
	v_add_f32_dpp v183, v183, v183 quad_perm:[2,3,0,1] row_mask:0xf bank_mask:0xf bound_ctrl:1
	s_nop 1
	v_add_f32_dpp v183, v183, v183 row_half_mirror row_mask:0xf bank_mask:0xf bound_ctrl:1
	s_nop 1
	v_add_f32_dpp v183, v183, v183 row_mirror row_mask:0xf bank_mask:0xf bound_ctrl:1
	s_nop 1
	v_readlane_b32 s98, v183, 0
	v_readlane_b32 s99, v183, 16
	v_readlane_b32 s100, v183, 32
	v_readlane_b32 s101, v183, 48
	s_nop 1
	v_mov_b32_e32 v183, s98
	v_add_f32_e32 v183, s99, v183
	v_add_f32_e32 v183, s100, v183
	v_add_f32_e32 v183, s101, v183
	v_fmamk_f32 v183, v183, 0x3a800000, v182
	v_cmp_gt_f32_e32 vcc, 0x800000, v183
	v_mul_f32_e32 v181, 0x4b800000, v183
	s_nop 1
	v_cndmask_b32_e32 v183, v183, v181, vcc
	v_rsq_f32_e32 v183, v183
	s_nop 0
	v_mul_f32_e32 v181, 0x45800000, v183
	v_cndmask_b32_e32 v184, v183, v181, vcc
	v_mov_b32_e32 v185, v184
	v_pk_mul_f32 v[160:161], v[160:161], v[184:185]
	v_pk_mul_f32 v[162:163], v[162:163], v[184:185]
	v_pk_mul_f32 v[164:165], v[164:165], v[184:185]
	v_pk_mul_f32 v[166:167], v[166:167], v[184:185]
	v_pk_mul_f32 v[168:169], v[168:169], v[184:185]
	v_pk_mul_f32 v[170:171], v[170:171], v[184:185]
	v_pk_mul_f32 v[172:173], v[172:173], v[184:185]
	v_pk_mul_f32 v[174:175], v[174:175], v[184:185]
	v_pk_fma_f32 v[144:145], v[160:161], v[128:129], v[144:145]
	v_pk_fma_f32 v[146:147], v[162:163], v[130:131], v[146:147]
	v_pk_fma_f32 v[148:149], v[164:165], v[132:133], v[148:149]
	v_pk_fma_f32 v[150:151], v[166:167], v[134:135], v[150:151]
	v_pk_fma_f32 v[152:153], v[168:169], v[136:137], v[152:153]
	v_pk_fma_f32 v[154:155], v[170:171], v[138:139], v[154:155]
	v_pk_fma_f32 v[156:157], v[172:173], v[140:141], v[156:157]
	v_pk_fma_f32 v[158:159], v[174:175], v[142:143], v[158:159]
	v_pk_mul_f32 v[252:253], v[144:145], v[144:145]
	v_pk_mul_f32 v[254:255], v[146:147], v[146:147]
	v_pk_fma_f32 v[252:253], v[148:149], v[148:149], v[252:253]
	v_pk_fma_f32 v[254:255], v[150:151], v[150:151], v[254:255]
	v_pk_fma_f32 v[252:253], v[152:153], v[152:153], v[252:253]
	v_pk_fma_f32 v[254:255], v[154:155], v[154:155], v[254:255]
	v_pk_fma_f32 v[252:253], v[156:157], v[156:157], v[252:253]
	v_pk_fma_f32 v[254:255], v[158:159], v[158:159], v[254:255]
	v_pk_add_f32 v[252:253], v[252:253], v[254:255]
	s_nop 0
	v_add_f32_e32 v183, v252, v253
	s_nop 1
	v_add_f32_dpp v183, v183, v183 quad_perm:[1,0,3,2] row_mask:0xf bank_mask:0xf bound_ctrl:1
	s_nop 1
	v_add_f32_dpp v183, v183, v183 quad_perm:[2,3,0,1] row_mask:0xf bank_mask:0xf bound_ctrl:1
	s_nop 1
	v_add_f32_dpp v183, v183, v183 row_half_mirror row_mask:0xf bank_mask:0xf bound_ctrl:1
	s_nop 1
	v_add_f32_dpp v183, v183, v183 row_mirror row_mask:0xf bank_mask:0xf bound_ctrl:1
	s_nop 1
	v_readlane_b32 s98, v183, 0
	v_readlane_b32 s99, v183, 16
	v_readlane_b32 s100, v183, 32
	v_readlane_b32 s101, v183, 48
	s_nop 1
	v_mov_b32_e32 v183, s98
	v_add_f32_e32 v183, s99, v183
	v_add_f32_e32 v183, s100, v183
	v_add_f32_e32 v183, s101, v183
	v_fmamk_f32 v183, v183, 0x3a800000, v182
	v_cmp_gt_f32_e32 vcc, 0x800000, v183
	v_mul_f32_e32 v181, 0x4b800000, v183
	s_nop 1
	v_cndmask_b32_e32 v183, v183, v181, vcc
	v_rsq_f32_e32 v183, v183
	s_nop 0
	v_mul_f32_e32 v181, 0x45800000, v183
	v_cndmask_b32_e32 v184, v183, v181, vcc
	v_mov_b32_e32 v185, v184
	v_cvt_pk_bf16_f32 v96, v144, v145
	v_cvt_pk_bf16_f32 v97, v146, v147
	v_cvt_pk_bf16_f32 v98, v148, v149
	v_cvt_pk_bf16_f32 v99, v150, v151
	v_cvt_pk_bf16_f32 v100, v152, v153
	v_cvt_pk_bf16_f32 v101, v154, v155
	v_cvt_pk_bf16_f32 v102, v156, v157
	v_cvt_pk_bf16_f32 v103, v158, v159
	v_add_u32_e32 v181, 0x1b00000, v177
	global_store_dwordx4 v181, v[96:99], s[78:79]
	global_store_dwordx4 v181, v[100:103], s[78:79] offset:1024
	v_add_u32_e32 v236, 0x1800, v237
	s_mov_b64 exec, 1
	global_store_dword v236, v184, s[78:79]
	s_mov_b64 exec, -1
	s_waitcnt vmcnt(0)
	v_lshlrev_b32_e32 v144, 16, v112
	v_and_b32_e32 v145, 0xffff0000, v112
	v_lshlrev_b32_e32 v146, 16, v113
	v_and_b32_e32 v147, 0xffff0000, v113
	v_lshlrev_b32_e32 v148, 16, v114
	v_and_b32_e32 v149, 0xffff0000, v114
	v_lshlrev_b32_e32 v150, 16, v115
	v_and_b32_e32 v151, 0xffff0000, v115
	v_lshlrev_b32_e32 v152, 16, v116
	v_and_b32_e32 v153, 0xffff0000, v116
	v_lshlrev_b32_e32 v154, 16, v117
	v_and_b32_e32 v155, 0xffff0000, v117
	v_lshlrev_b32_e32 v156, 16, v118
	v_and_b32_e32 v157, 0xffff0000, v118
	v_lshlrev_b32_e32 v158, 16, v119
	v_and_b32_e32 v159, 0xffff0000, v119
	v_lshlrev_b32_e32 v160, 16, v120
	v_and_b32_e32 v161, 0xffff0000, v120
	v_lshlrev_b32_e32 v162, 16, v121
	v_and_b32_e32 v163, 0xffff0000, v121
	v_lshlrev_b32_e32 v164, 16, v122
	v_and_b32_e32 v165, 0xffff0000, v122
	v_lshlrev_b32_e32 v166, 16, v123
	v_and_b32_e32 v167, 0xffff0000, v123
	v_lshlrev_b32_e32 v168, 16, v124
	v_and_b32_e32 v169, 0xffff0000, v124
	v_lshlrev_b32_e32 v170, 16, v125
	v_and_b32_e32 v171, 0xffff0000, v125
	v_lshlrev_b32_e32 v172, 16, v126
	v_and_b32_e32 v173, 0xffff0000, v126
	v_lshlrev_b32_e32 v174, 16, v127
	v_and_b32_e32 v175, 0xffff0000, v127
	v_pk_mul_f32 v[252:253], v[160:161], v[160:161]
	v_pk_mul_f32 v[254:255], v[162:163], v[162:163]
	v_pk_fma_f32 v[252:253], v[164:165], v[164:165], v[252:253]
	v_pk_fma_f32 v[254:255], v[166:167], v[166:167], v[254:255]
	v_pk_fma_f32 v[252:253], v[168:169], v[168:169], v[252:253]
	v_pk_fma_f32 v[254:255], v[170:171], v[170:171], v[254:255]
	v_pk_fma_f32 v[252:253], v[172:173], v[172:173], v[252:253]
	v_pk_fma_f32 v[254:255], v[174:175], v[174:175], v[254:255]
	v_pk_add_f32 v[252:253], v[252:253], v[254:255]
	s_nop 0
	v_add_f32_e32 v183, v252, v253
	s_nop 1
	v_add_f32_dpp v183, v183, v183 quad_perm:[1,0,3,2] row_mask:0xf bank_mask:0xf bound_ctrl:1
	s_nop 1
	v_add_f32_dpp v183, v183, v183 quad_perm:[2,3,0,1] row_mask:0xf bank_mask:0xf bound_ctrl:1
	s_nop 1
	v_add_f32_dpp v183, v183, v183 row_half_mirror row_mask:0xf bank_mask:0xf bound_ctrl:1
	s_nop 1
	v_add_f32_dpp v183, v183, v183 row_mirror row_mask:0xf bank_mask:0xf bound_ctrl:1
	s_nop 1
	v_readlane_b32 s98, v183, 0
	v_readlane_b32 s99, v183, 16
	v_readlane_b32 s100, v183, 32
	v_readlane_b32 s101, v183, 48
	s_nop 1
	v_mov_b32_e32 v183, s98
	v_add_f32_e32 v183, s99, v183
	v_add_f32_e32 v183, s100, v183
	v_add_f32_e32 v183, s101, v183
	v_fmamk_f32 v183, v183, 0x3a800000, v182
	v_cmp_gt_f32_e32 vcc, 0x800000, v183
	v_mul_f32_e32 v181, 0x4b800000, v183
	s_nop 1
	v_cndmask_b32_e32 v183, v183, v181, vcc
	v_rsq_f32_e32 v183, v183
	s_nop 0
	v_mul_f32_e32 v181, 0x45800000, v183
	v_cndmask_b32_e32 v184, v183, v181, vcc
	v_mov_b32_e32 v185, v184
	v_pk_mul_f32 v[160:161], v[160:161], v[184:185]
	v_pk_mul_f32 v[162:163], v[162:163], v[184:185]
	v_pk_mul_f32 v[164:165], v[164:165], v[184:185]
	v_pk_mul_f32 v[166:167], v[166:167], v[184:185]
	v_pk_mul_f32 v[168:169], v[168:169], v[184:185]
	v_pk_mul_f32 v[170:171], v[170:171], v[184:185]
	v_pk_mul_f32 v[172:173], v[172:173], v[184:185]
	v_pk_mul_f32 v[174:175], v[174:175], v[184:185]
	v_pk_fma_f32 v[144:145], v[160:161], v[128:129], v[144:145]
	v_pk_fma_f32 v[146:147], v[162:163], v[130:131], v[146:147]
	v_pk_fma_f32 v[148:149], v[164:165], v[132:133], v[148:149]
	v_pk_fma_f32 v[150:151], v[166:167], v[134:135], v[150:151]
	v_pk_fma_f32 v[152:153], v[168:169], v[136:137], v[152:153]
	v_pk_fma_f32 v[154:155], v[170:171], v[138:139], v[154:155]
	v_pk_fma_f32 v[156:157], v[172:173], v[140:141], v[156:157]
	v_pk_fma_f32 v[158:159], v[174:175], v[142:143], v[158:159]
	v_pk_mul_f32 v[252:253], v[144:145], v[144:145]
	v_pk_mul_f32 v[254:255], v[146:147], v[146:147]
	v_pk_fma_f32 v[252:253], v[148:149], v[148:149], v[252:253]
	v_pk_fma_f32 v[254:255], v[150:151], v[150:151], v[254:255]
	v_pk_fma_f32 v[252:253], v[152:153], v[152:153], v[252:253]
	v_pk_fma_f32 v[254:255], v[154:155], v[154:155], v[254:255]
	v_pk_fma_f32 v[252:253], v[156:157], v[156:157], v[252:253]
	v_pk_fma_f32 v[254:255], v[158:159], v[158:159], v[254:255]
	v_pk_add_f32 v[252:253], v[252:253], v[254:255]
	s_nop 0
	v_add_f32_e32 v183, v252, v253
	s_nop 1
	v_add_f32_dpp v183, v183, v183 quad_perm:[1,0,3,2] row_mask:0xf bank_mask:0xf bound_ctrl:1
	s_nop 1
	v_add_f32_dpp v183, v183, v183 quad_perm:[2,3,0,1] row_mask:0xf bank_mask:0xf bound_ctrl:1
	s_nop 1
	v_add_f32_dpp v183, v183, v183 row_half_mirror row_mask:0xf bank_mask:0xf bound_ctrl:1
	s_nop 1
	v_add_f32_dpp v183, v183, v183 row_mirror row_mask:0xf bank_mask:0xf bound_ctrl:1
	s_nop 1
	v_readlane_b32 s98, v183, 0
	v_readlane_b32 s99, v183, 16
	v_readlane_b32 s100, v183, 32
	v_readlane_b32 s101, v183, 48
	s_nop 1
	v_mov_b32_e32 v183, s98
	v_add_f32_e32 v183, s99, v183
	v_add_f32_e32 v183, s100, v183
	v_add_f32_e32 v183, s101, v183
	v_fmamk_f32 v183, v183, 0x3a800000, v182
	v_cmp_gt_f32_e32 vcc, 0x800000, v183
	v_mul_f32_e32 v181, 0x4b800000, v183
	s_nop 1
	v_cndmask_b32_e32 v183, v183, v181, vcc
	v_rsq_f32_e32 v183, v183
	s_nop 0
	v_mul_f32_e32 v181, 0x45800000, v183
	v_cndmask_b32_e32 v184, v183, v181, vcc
	v_mov_b32_e32 v185, v184
	v_cvt_pk_bf16_f32 v112, v144, v145
	v_cvt_pk_bf16_f32 v113, v146, v147
	v_cvt_pk_bf16_f32 v114, v148, v149
	v_cvt_pk_bf16_f32 v115, v150, v151
	v_cvt_pk_bf16_f32 v116, v152, v153
	v_cvt_pk_bf16_f32 v117, v154, v155
	v_cvt_pk_bf16_f32 v118, v156, v157
	v_cvt_pk_bf16_f32 v119, v158, v159
	v_add_u32_e32 v181, 0x1b80000, v177
	global_store_dwordx4 v181, v[112:115], s[78:79]
	global_store_dwordx4 v181, v[116:119], s[78:79] offset:1024
	v_add_u32_e32 v236, 0x1c00, v237
	s_mov_b64 exec, 1
	global_store_dword v236, v184, s[78:79]
	s_mov_b64 exec, -1
	v_readfirstlane_b32 s98, v179
	s_nop 3
	s_cmp_ge_u32 s98, 512
	s_cbranch_scc1 .Lmyxupd_done_2
	v_lshlrev_b32_e32 v177, 4, v176
	v_lshl_add_u32 v177, v179, 11, v177
	v_lshlrev_b32_e32 v237, 2, v179
	v_add_u32_e32 v237, 0x10000, v237
	v_add_u32_e32 v181, 0x3800000, v177
	global_load_dwordx4 v[0:3], v181, s[78:79]
	global_load_dwordx4 v[4:7], v181, s[78:79] offset:1024
	v_lshl_add_u32 v183, v179, 12, v180
	v_add_u32_e32 v183, 0xbf00000, v183
	v_add_u32_e32 v181, 0x0, v183
	global_load_dwordx4 v[8:11], v181, s[78:79]
	global_load_dwordx4 v[12:15], v181, s[78:79] offset:16
	global_load_dwordx4 v[16:19], v181, s[78:79] offset:2048
	global_load_dwordx4 v[20:23], v181, s[78:79] offset:2064
	v_add_u32_e32 v181, 0x200000, v183
	global_load_dwordx4 v[24:27], v181, s[78:79]
	global_load_dwordx4 v[28:31], v181, s[78:79] offset:16
	global_load_dwordx4 v[32:35], v181, s[78:79] offset:2048
	global_load_dwordx4 v[36:39], v181, s[78:79] offset:2064
	v_add_u32_e32 v181, 0x400000, v183
	global_load_dwordx4 v[40:43], v181, s[78:79]
	global_load_dwordx4 v[44:47], v181, s[78:79] offset:16
	global_load_dwordx4 v[48:51], v181, s[78:79] offset:2048
	global_load_dwordx4 v[52:55], v181, s[78:79] offset:2064
	v_add_u32_e32 v181, 0x600000, v183
	global_load_dwordx4 v[56:59], v181, s[78:79]
	global_load_dwordx4 v[60:63], v181, s[78:79] offset:16
	global_load_dwordx4 v[64:67], v181, s[78:79] offset:2048
	global_load_dwordx4 v[68:71], v181, s[78:79] offset:2064
	v_add_u32_e32 v181, 0x800000, v183
	global_load_dwordx4 v[72:75], v181, s[78:79]
	global_load_dwordx4 v[76:79], v181, s[78:79] offset:16
	global_load_dwordx4 v[80:83], v181, s[78:79] offset:2048
	global_load_dwordx4 v[84:87], v181, s[78:79] offset:2064
	v_add_u32_e32 v181, 0xa00000, v183
	global_load_dwordx4 v[88:91], v181, s[78:79]
	global_load_dwordx4 v[92:95], v181, s[78:79] offset:16
	global_load_dwordx4 v[96:99], v181, s[78:79] offset:2048
	global_load_dwordx4 v[100:103], v181, s[78:79] offset:2064
	s_waitcnt vmcnt(20)
	v_pk_add_f32 v[160:161], v[8:9], 0 op_sel_hi:[1,0]
	v_pk_add_f32 v[162:163], v[10:11], 0 op_sel_hi:[1,0]
	v_pk_add_f32 v[164:165], v[12:13], 0 op_sel_hi:[1,0]
	v_pk_add_f32 v[166:167], v[14:15], 0 op_sel_hi:[1,0]
	v_pk_add_f32 v[168:169], v[16:17], 0 op_sel_hi:[1,0]
	v_pk_add_f32 v[170:171], v[18:19], 0 op_sel_hi:[1,0]
	v_pk_add_f32 v[172:173], v[20:21], 0 op_sel_hi:[1,0]
	v_pk_add_f32 v[174:175], v[22:23], 0 op_sel_hi:[1,0]
	s_waitcnt vmcnt(16)
	v_pk_add_f32 v[160:161], v[160:161], v[24:25]
	v_pk_add_f32 v[162:163], v[162:163], v[26:27]
	v_pk_add_f32 v[164:165], v[164:165], v[28:29]
	v_pk_add_f32 v[166:167], v[166:167], v[30:31]
	v_pk_add_f32 v[168:169], v[168:169], v[32:33]
	v_pk_add_f32 v[170:171], v[170:171], v[34:35]
	v_pk_add_f32 v[172:173], v[172:173], v[36:37]
	v_pk_add_f32 v[174:175], v[174:175], v[38:39]
	s_waitcnt vmcnt(12)
	v_pk_add_f32 v[160:161], v[160:161], v[40:41]
	v_pk_add_f32 v[162:163], v[162:163], v[42:43]
	v_pk_add_f32 v[164:165], v[164:165], v[44:45]
	v_pk_add_f32 v[166:167], v[166:167], v[46:47]
	v_pk_add_f32 v[168:169], v[168:169], v[48:49]
	v_pk_add_f32 v[170:171], v[170:171], v[50:51]
	v_pk_add_f32 v[172:173], v[172:173], v[52:53]
	v_pk_add_f32 v[174:175], v[174:175], v[54:55]
	s_waitcnt vmcnt(8)
	v_pk_add_f32 v[160:161], v[160:161], v[56:57]
	v_pk_add_f32 v[162:163], v[162:163], v[58:59]
	v_pk_add_f32 v[164:165], v[164:165], v[60:61]
	v_pk_add_f32 v[166:167], v[166:167], v[62:63]
	v_pk_add_f32 v[168:169], v[168:169], v[64:65]
	v_pk_add_f32 v[170:171], v[170:171], v[66:67]
	v_pk_add_f32 v[172:173], v[172:173], v[68:69]
	v_pk_add_f32 v[174:175], v[174:175], v[70:71]
	s_waitcnt vmcnt(4)
	v_pk_add_f32 v[160:161], v[160:161], v[72:73]
	v_pk_add_f32 v[162:163], v[162:163], v[74:75]
	v_pk_add_f32 v[164:165], v[164:165], v[76:77]
	v_pk_add_f32 v[166:167], v[166:167], v[78:79]
	v_pk_add_f32 v[168:169], v[168:169], v[80:81]
	v_pk_add_f32 v[170:171], v[170:171], v[82:83]
	v_pk_add_f32 v[172:173], v[172:173], v[84:85]
	v_pk_add_f32 v[174:175], v[174:175], v[86:87]
	s_waitcnt vmcnt(0)
	v_pk_add_f32 v[160:161], v[160:161], v[88:89]
	v_pk_add_f32 v[162:163], v[162:163], v[90:91]
	v_pk_add_f32 v[164:165], v[164:165], v[92:93]
	v_pk_add_f32 v[166:167], v[166:167], v[94:95]
	v_pk_add_f32 v[168:169], v[168:169], v[96:97]
	v_pk_add_f32 v[170:171], v[170:171], v[98:99]
	v_pk_add_f32 v[172:173], v[172:173], v[100:101]
	v_pk_add_f32 v[174:175], v[174:175], v[102:103]
	v_lshlrev_b32_e32 v144, 16, v0
	v_and_b32_e32 v145, 0xffff0000, v0
	v_lshlrev_b32_e32 v146, 16, v1
	v_and_b32_e32 v147, 0xffff0000, v1
	v_lshlrev_b32_e32 v148, 16, v2
	v_and_b32_e32 v149, 0xffff0000, v2
	v_lshlrev_b32_e32 v150, 16, v3
	v_and_b32_e32 v151, 0xffff0000, v3
	v_lshlrev_b32_e32 v152, 16, v4
	v_and_b32_e32 v153, 0xffff0000, v4
	v_lshlrev_b32_e32 v154, 16, v5
	v_and_b32_e32 v155, 0xffff0000, v5
	v_lshlrev_b32_e32 v156, 16, v6
	v_and_b32_e32 v157, 0xffff0000, v6
	v_lshlrev_b32_e32 v158, 16, v7
	v_and_b32_e32 v159, 0xffff0000, v7
	v_add_u32_e32 v181, 0xc00000, v183
	global_load_dwordx4 v[8:11], v181, s[78:79]
	global_load_dwordx4 v[12:15], v181, s[78:79] offset:16
	global_load_dwordx4 v[16:19], v181, s[78:79] offset:2048
	global_load_dwordx4 v[20:23], v181, s[78:79] offset:2064
	v_add_u32_e32 v181, 0xe00000, v183
	global_load_dwordx4 v[24:27], v181, s[78:79]
	global_load_dwordx4 v[28:31], v181, s[78:79] offset:16
	global_load_dwordx4 v[32:35], v181, s[78:79] offset:2048
	global_load_dwordx4 v[36:39], v181, s[78:79] offset:2064
	s_waitcnt vmcnt(4)
	v_pk_add_f32 v[160:161], v[160:161], v[8:9]
	v_pk_add_f32 v[162:163], v[162:163], v[10:11]
	v_pk_add_f32 v[164:165], v[164:165], v[12:13]
	v_pk_add_f32 v[166:167], v[166:167], v[14:15]
	v_pk_add_f32 v[168:169], v[168:169], v[16:17]
	v_pk_add_f32 v[170:171], v[170:171], v[18:19]
	v_pk_add_f32 v[172:173], v[172:173], v[20:21]
	v_pk_add_f32 v[174:175], v[174:175], v[22:23]
	s_waitcnt vmcnt(0)
	v_pk_add_f32 v[160:161], v[160:161], v[24:25]
	v_pk_add_f32 v[162:163], v[162:163], v[26:27]
	v_pk_add_f32 v[164:165], v[164:165], v[28:29]
	v_pk_add_f32 v[166:167], v[166:167], v[30:31]
	v_pk_add_f32 v[168:169], v[168:169], v[32:33]
	v_pk_add_f32 v[170:171], v[170:171], v[34:35]
	v_pk_add_f32 v[172:173], v[172:173], v[36:37]
	v_pk_add_f32 v[174:175], v[174:175], v[38:39]
	v_pk_mul_f32 v[252:253], v[160:161], v[160:161]
	v_pk_mul_f32 v[254:255], v[162:163], v[162:163]
	v_pk_fma_f32 v[252:253], v[164:165], v[164:165], v[252:253]
	v_pk_fma_f32 v[254:255], v[166:167], v[166:167], v[254:255]
	v_pk_fma_f32 v[252:253], v[168:169], v[168:169], v[252:253]
	v_pk_fma_f32 v[254:255], v[170:171], v[170:171], v[254:255]
	v_pk_fma_f32 v[252:253], v[172:173], v[172:173], v[252:253]
	v_pk_fma_f32 v[254:255], v[174:175], v[174:175], v[254:255]
	v_pk_add_f32 v[252:253], v[252:253], v[254:255]
	s_nop 0
	v_add_f32_e32 v183, v252, v253
	s_nop 1
	v_add_f32_dpp v183, v183, v183 quad_perm:[1,0,3,2] row_mask:0xf bank_mask:0xf bound_ctrl:1
	s_nop 1
	v_add_f32_dpp v183, v183, v183 quad_perm:[2,3,0,1] row_mask:0xf bank_mask:0xf bound_ctrl:1
	s_nop 1
	v_add_f32_dpp v183, v183, v183 row_half_mirror row_mask:0xf bank_mask:0xf bound_ctrl:1
	s_nop 1
	v_add_f32_dpp v183, v183, v183 row_mirror row_mask:0xf bank_mask:0xf bound_ctrl:1
	s_nop 1
	v_readlane_b32 s98, v183, 0
	v_readlane_b32 s99, v183, 16
	v_readlane_b32 s100, v183, 32
	v_readlane_b32 s101, v183, 48
	s_nop 1
	v_mov_b32_e32 v183, s98
	v_add_f32_e32 v183, s99, v183
	v_add_f32_e32 v183, s100, v183
	v_add_f32_e32 v183, s101, v183
	v_fmamk_f32 v183, v183, 0x3a800000, v182
	v_cmp_gt_f32_e32 vcc, 0x800000, v183
	v_mul_f32_e32 v181, 0x4b800000, v183
	s_nop 1
	v_cndmask_b32_e32 v183, v183, v181, vcc
	v_rsq_f32_e32 v183, v183
	s_nop 0
	v_mul_f32_e32 v181, 0x45800000, v183
	v_cndmask_b32_e32 v184, v183, v181, vcc
	v_mov_b32_e32 v185, v184
	v_pk_mul_f32 v[160:161], v[160:161], v[184:185]
	v_pk_mul_f32 v[162:163], v[162:163], v[184:185]
	v_pk_mul_f32 v[164:165], v[164:165], v[184:185]
	v_pk_mul_f32 v[166:167], v[166:167], v[184:185]
	v_pk_mul_f32 v[168:169], v[168:169], v[184:185]
	v_pk_mul_f32 v[170:171], v[170:171], v[184:185]
	v_pk_mul_f32 v[172:173], v[172:173], v[184:185]
	v_pk_mul_f32 v[174:175], v[174:175], v[184:185]
	v_pk_fma_f32 v[144:145], v[160:161], v[128:129], v[144:145]
	v_pk_fma_f32 v[146:147], v[162:163], v[130:131], v[146:147]
	v_pk_fma_f32 v[148:149], v[164:165], v[132:133], v[148:149]
	v_pk_fma_f32 v[150:151], v[166:167], v[134:135], v[150:151]
	v_pk_fma_f32 v[152:153], v[168:169], v[136:137], v[152:153]
	v_pk_fma_f32 v[154:155], v[170:171], v[138:139], v[154:155]
	v_pk_fma_f32 v[156:157], v[172:173], v[140:141], v[156:157]
	v_pk_fma_f32 v[158:159], v[174:175], v[142:143], v[158:159]
	v_pk_mul_f32 v[252:253], v[144:145], v[144:145]
	v_pk_mul_f32 v[254:255], v[146:147], v[146:147]
	v_pk_fma_f32 v[252:253], v[148:149], v[148:149], v[252:253]
	v_pk_fma_f32 v[254:255], v[150:151], v[150:151], v[254:255]
	v_pk_fma_f32 v[252:253], v[152:153], v[152:153], v[252:253]
	v_pk_fma_f32 v[254:255], v[154:155], v[154:155], v[254:255]
	v_pk_fma_f32 v[252:253], v[156:157], v[156:157], v[252:253]
	v_pk_fma_f32 v[254:255], v[158:159], v[158:159], v[254:255]
	v_pk_add_f32 v[252:253], v[252:253], v[254:255]
	s_nop 0
	v_add_f32_e32 v183, v252, v253
	s_nop 1
	v_add_f32_dpp v183, v183, v183 quad_perm:[1,0,3,2] row_mask:0xf bank_mask:0xf bound_ctrl:1
	s_nop 1
	v_add_f32_dpp v183, v183, v183 quad_perm:[2,3,0,1] row_mask:0xf bank_mask:0xf bound_ctrl:1
	s_nop 1
	v_add_f32_dpp v183, v183, v183 row_half_mirror row_mask:0xf bank_mask:0xf bound_ctrl:1
	s_nop 1
	v_add_f32_dpp v183, v183, v183 row_mirror row_mask:0xf bank_mask:0xf bound_ctrl:1
	s_nop 1
	v_readlane_b32 s98, v183, 0
	v_readlane_b32 s99, v183, 16
	v_readlane_b32 s100, v183, 32
	v_readlane_b32 s101, v183, 48
	s_nop 1
	v_mov_b32_e32 v183, s98
	v_add_f32_e32 v183, s99, v183
	v_add_f32_e32 v183, s100, v183
	v_add_f32_e32 v183, s101, v183
	v_fmamk_f32 v183, v183, 0x3a800000, v182
	v_cmp_gt_f32_e32 vcc, 0x800000, v183
	v_mul_f32_e32 v181, 0x4b800000, v183
	s_nop 1
	v_cndmask_b32_e32 v183, v183, v181, vcc
	v_rsq_f32_e32 v183, v183
	s_nop 0
	v_mul_f32_e32 v181, 0x45800000, v183
	v_cndmask_b32_e32 v184, v183, v181, vcc
	v_mov_b32_e32 v185, v184
	v_cvt_pk_bf16_f32 v0, v144, v145
	v_cvt_pk_bf16_f32 v1, v146, v147
	v_cvt_pk_bf16_f32 v2, v148, v149
	v_cvt_pk_bf16_f32 v3, v150, v151
	v_cvt_pk_bf16_f32 v4, v152, v153
	v_cvt_pk_bf16_f32 v5, v154, v155
	v_cvt_pk_bf16_f32 v6, v156, v157
	v_cvt_pk_bf16_f32 v7, v158, v159
	v_add_u32_e32 v181, 0x3800000, v177
	global_store_dwordx4 v181, v[0:3], s[78:79]
	global_store_dwordx4 v181, v[4:7], s[78:79] offset:1024
	v_add_u32_e32 v236, 0x10000, v237
	s_mov_b64 exec, 1
	global_store_dword v236, v184, s[78:79]
	s_mov_b64 exec, -1

.LBB0_1430:
	v_readlane_b32 s0, v235, 52
	v_readlane_b32 s1, v235, 53
	s_and_b64 vcc, exec, s[0:1]
	s_waitcnt lgkmcnt(0)
	s_barrier
	v_mbcnt_lo_u32_b32 v0, -1, 0
	v_mbcnt_hi_u32_b32 v0, -1, v0
	s_cbranch_vccnz .LBB0_1450
	v_lshlrev_b32_e32 v2, 3, v0
	v_readlane_b32 s4, v235, 4
	v_ashrrev_i32_e32 v3, 31, v2
	v_readlane_b32 s6, v235, 6
	v_readlane_b32 s7, v235, 7
	v_lshlrev_b64 v[4:5], 1, v[2:3]
	v_lshlrev_b64 v[2:3], 2, v[2:3]
	v_readlane_b32 s5, v235, 5
	v_readlane_b32 s10, v235, 10
	v_readlane_b32 s11, v235, 11
	v_readlane_b32 s18, v235, 18
	v_readlane_b32 s19, v235, 19
	v_readlane_b32 s6, v235, 61
	v_lshl_add_u64 v[154:155], s[90:91], 0, v[2:3]
	v_readlane_b32 s8, v235, 8
	v_lshl_add_u64 v[2:3], s[18:19], 0, v[2:3]
	s_mov_b64 s[0:1], 0x1000
	v_readlane_b32 s4, v235, 0
	v_readlane_b32 s7, v235, 62
	s_mov_b32 s10, s6
	s_ashr_i32 s11, s6, 31
	v_readlane_b32 s9, v235, 9
	v_lshl_add_u64 v[158:159], v[2:3], 0, s[0:1]
	s_lshl_b32 s4, s4, 4
	s_add_i32 s0, s6, 0xffffc000
	s_lshl_b64 s[6:7], s[10:11], 2
	s_mov_b32 s8, s10
	v_readlane_b32 s12, v235, 12
	v_readlane_b32 s13, v235, 13
	v_readlane_b32 s14, v235, 14
	v_readlane_b32 s15, v235, 15
	v_readlane_b32 s16, v235, 16
	v_readlane_b32 s17, v235, 17
	v_readlane_b32 s5, v235, 1
	s_add_u32 s80, s6, 0x10000
	v_writelane_b32 v235, s8, 61
	s_addc_u32 s12, s7, 0
	s_ashr_i32 s5, s4, 31
	v_writelane_b32 v235, s9, 62
	s_lshl_b64 s[8:9], s[10:11], 11
	v_lshl_add_u64 v[152:153], s[86:87], 0, v[4:5]
	v_lshl_add_u64 v[156:157], s[54:55], 0, v[4:5]
	s_mov_b32 s1, 0
	v_cmp_eq_u32_e64 s[16:17], 0, v0
	s_lshl_b64 s[6:7], s[4:5], 2
	v_lshl_add_u64 v[160:161], s[8:9], 0, v[4:5]
	s_lshl_b64 s[8:9], s[4:5], 11
	s_mov_b64 s[20:21], 0x600000
	s_mov_b64 s[22:23], 0x600800
	s_mov_b64 s[24:25], 0x800000
	s_mov_b32 s5, 0x800000
	s_mov_b64 s[26:27], 0x800800
	s_mov_b64 s[28:29], 0xa00000
	s_mov_b64 s[36:37], 0xa00800
	s_mov_b64 s[38:39], 0xc00000
	s_mov_b64 s[40:41], 0xc00800
	s_mov_b64 s[42:43], 0xe00000
	s_mov_b64 s[44:45], 0xe00800
	s_mov_b64 s[46:47], 0x1000000
	s_mov_b32 s13, 0x1000000
	s_mov_b64 s[48:49], 0x1000800
	s_mov_b64 s[50:51], 0x1200000
	s_mov_b32 s14, 0x1200000
	s_mov_b64 s[10:11], 0x1200800
	s_mov_b64 s[82:83], 0x1400000
	s_mov_b32 s15, 0x1400000
	s_mov_b64 s[90:91], 0x1400800
	v_mov_b32_e32 v215, 0
	v_mov_b32_e32 v216, 0x358637bd
	v_mbcnt_lo_u32_b32 v176, -1, 0
	v_mbcnt_hi_u32_b32 v176, -1, v176
	v_readlane_b32 s98, v235, 49
	v_readlane_b32 s99, v235, 20
	v_readlane_b32 s100, v235, 18
	v_readlane_b32 s101, v235, 19
	s_nop 3
	s_lshr_b32 vcc_lo, s98, 3
	s_and_b32 vcc_hi, vcc_lo, 7
	s_lshr_b32 vcc_lo, vcc_lo, 3
	s_lshl_b32 vcc_lo, vcc_lo, 3
	s_add_i32 vcc_lo, vcc_lo, s99
	s_lshl_b32 s98, vcc_hi, 8
	s_add_i32 s98, s98, vcc_lo
	s_lshl_b32 s99, vcc_hi, 11
	s_add_i32 s99, s99, vcc_lo
	v_mov_b32_e32 v183, s99
	v_lshlrev_b32_e32 v177, 4, v176
	s_lshl_b32 s99, s99, 11
	v_add_u32_e32 v177, s99, v177
	v_add_u32_e32 v178, 0x1800000, v177
	v_add_u32_e32 v179, 0x9e00000, v177
	v_lshlrev_b32_e32 v180, 5, v176
	v_add_u32_e32 v181, 0x1000, v180
	global_load_dwordx4 v[128:131], v181, s[100:101]
	global_load_dwordx4 v[132:135], v181, s[100:101] offset:16
	global_load_dwordx4 v[136:139], v181, s[100:101] offset:2048
	global_load_dwordx4 v[140:143], v181, s[100:101] offset:2064
	v_mov_b32_e32 v182, 0x358637bd
	global_load_dwordx4 v[0:3], v178, s[78:79]
	global_load_dwordx4 v[4:7], v178, s[78:79] offset:1024
	global_load_dwordx4 v[8:11], v179, s[78:79]
	global_load_dwordx4 v[12:15], v179, s[78:79] offset:1024
	v_add_u32_e32 v178, 0x80000, v178
	v_add_u32_e32 v179, 0x80000, v179
	global_load_dwordx4 v[16:19], v178, s[78:79]
	global_load_dwordx4 v[20:23], v178, s[78:79] offset:1024
	global_load_dwordx4 v[24:27], v179, s[78:79]
	global_load_dwordx4 v[28:31], v179, s[78:79] offset:1024
	v_add_u32_e32 v178, 0x80000, v178
	v_add_u32_e32 v179, 0x80000, v179
	global_load_dwordx4 v[32:35], v178, s[78:79]
	global_load_dwordx4 v[36:39], v178, s[78:79] offset:1024
	global_load_dwordx4 v[40:43], v179, s[78:79]
	global_load_dwordx4 v[44:47], v179, s[78:79] offset:1024
	v_add_u32_e32 v178, 0x80000, v178
	v_add_u32_e32 v179, 0x80000, v179
	global_load_dwordx4 v[48:51], v178, s[78:79]
	global_load_dwordx4 v[52:55], v178, s[78:79] offset:1024
	global_load_dwordx4 v[56:59], v179, s[78:79]
	global_load_dwordx4 v[60:63], v179, s[78:79] offset:1024
	v_add_u32_e32 v178, 0x80000, v178
	v_add_u32_e32 v179, 0x80000, v179
	global_load_dwordx4 v[64:67], v178, s[78:79]
	global_load_dwordx4 v[68:71], v178, s[78:79] offset:1024
	global_load_dwordx4 v[72:75], v179, s[78:79]
	global_load_dwordx4 v[76:79], v179, s[78:79] offset:1024
	v_add_u32_e32 v178, 0x80000, v178
	v_add_u32_e32 v179, 0x80000, v179
	global_load_dwordx4 v[80:83], v178, s[78:79]
	global_load_dwordx4 v[84:87], v178, s[78:79] offset:1024
	global_load_dwordx4 v[88:91], v179, s[78:79]
	global_load_dwordx4 v[92:95], v179, s[78:79] offset:1024
	v_add_u32_e32 v178, 0x80000, v178
	v_add_u32_e32 v179, 0x80000, v179
	global_load_dwordx4 v[96:99], v178, s[78:79]
	global_load_dwordx4 v[100:103], v178, s[78:79] offset:1024
	global_load_dwordx4 v[104:107], v179, s[78:79]
	global_load_dwordx4 v[108:111], v179, s[78:79] offset:1024
	v_add_u32_e32 v178, 0x80000, v178
	v_add_u32_e32 v179, 0x80000, v179
	global_load_dwordx4 v[112:115], v178, s[78:79]
	global_load_dwordx4 v[116:119], v178, s[78:79] offset:1024
	global_load_dwordx4 v[120:123], v179, s[78:79]
	global_load_dwordx4 v[124:127], v179, s[78:79] offset:1024
	v_lshlrev_b32_e32 v237, 2, v183
	v_add_u32_e32 v237, 0x10000, v237
	v_mov_b32_e32 v179, s98
	s_waitcnt vmcnt(28)
	v_lshlrev_b32_e32 v144, 16, v0
	v_and_b32_e32 v145, 0xffff0000, v0
	v_lshlrev_b32_e32 v146, 16, v1
	v_and_b32_e32 v147, 0xffff0000, v1
	v_lshlrev_b32_e32 v148, 16, v2
	v_and_b32_e32 v149, 0xffff0000, v2
	v_lshlrev_b32_e32 v150, 16, v3
	v_and_b32_e32 v151, 0xffff0000, v3
	v_lshlrev_b32_e32 v152, 16, v4
	v_and_b32_e32 v153, 0xffff0000, v4
	v_lshlrev_b32_e32 v154, 16, v5
	v_and_b32_e32 v155, 0xffff0000, v5
	v_lshlrev_b32_e32 v156, 16, v6
	v_and_b32_e32 v157, 0xffff0000, v6
	v_lshlrev_b32_e32 v158, 16, v7
	v_and_b32_e32 v159, 0xffff0000, v7
	v_lshlrev_b32_e32 v160, 16, v8
	v_and_b32_e32 v161, 0xffff0000, v8
	v_lshlrev_b32_e32 v162, 16, v9
	v_and_b32_e32 v163, 0xffff0000, v9
	v_lshlrev_b32_e32 v164, 16, v10
	v_and_b32_e32 v165, 0xffff0000, v10
	v_lshlrev_b32_e32 v166, 16, v11
	v_and_b32_e32 v167, 0xffff0000, v11
	v_lshlrev_b32_e32 v168, 16, v12
	v_and_b32_e32 v169, 0xffff0000, v12
	v_lshlrev_b32_e32 v170, 16, v13
	v_and_b32_e32 v171, 0xffff0000, v13
	v_lshlrev_b32_e32 v172, 16, v14
	v_and_b32_e32 v173, 0xffff0000, v14
	v_lshlrev_b32_e32 v174, 16, v15
	v_and_b32_e32 v175, 0xffff0000, v15
	v_pk_mul_f32 v[252:253], v[160:161], v[160:161]
	v_pk_mul_f32 v[254:255], v[162:163], v[162:163]
	v_pk_fma_f32 v[252:253], v[164:165], v[164:165], v[252:253]
	v_pk_fma_f32 v[254:255], v[166:167], v[166:167], v[254:255]
	v_pk_fma_f32 v[252:253], v[168:169], v[168:169], v[252:253]
	v_pk_fma_f32 v[254:255], v[170:171], v[170:171], v[254:255]
	v_pk_fma_f32 v[252:253], v[172:173], v[172:173], v[252:253]
	v_pk_fma_f32 v[254:255], v[174:175], v[174:175], v[254:255]
	v_pk_add_f32 v[252:253], v[252:253], v[254:255]
	s_nop 0
	v_add_f32_e32 v183, v252, v253
	s_nop 1
	v_add_f32_dpp v183, v183, v183 quad_perm:[1,0,3,2] row_mask:0xf bank_mask:0xf bound_ctrl:1
	s_nop 1
	v_add_f32_dpp v183, v183, v183 quad_perm:[2,3,0,1] row_mask:0xf bank_mask:0xf bound_ctrl:1
	s_nop 1
	v_add_f32_dpp v183, v183, v183 row_half_mirror row_mask:0xf bank_mask:0xf bound_ctrl:1
	s_nop 1
	v_add_f32_dpp v183, v183, v183 row_mirror row_mask:0xf bank_mask:0xf bound_ctrl:1
	s_nop 1
	v_readlane_b32 s98, v183, 0
	v_readlane_b32 s99, v183, 16
	v_readlane_b32 s100, v183, 32
	v_readlane_b32 s101, v183, 48
	s_nop 1
	v_mov_b32_e32 v183, s98
	v_add_f32_e32 v183, s99, v183
	v_add_f32_e32 v183, s100, v183
	v_add_f32_e32 v183, s101, v183
	v_fmamk_f32 v183, v183, 0x3a800000, v182
	v_cmp_gt_f32_e32 vcc, 0x800000, v183
	v_mul_f32_e32 v181, 0x4b800000, v183
	s_nop 1
	v_cndmask_b32_e32 v183, v183, v181, vcc
	v_rsq_f32_e32 v183, v183
	s_nop 0
	v_mul_f32_e32 v181, 0x45800000, v183
	v_cndmask_b32_e32 v184, v183, v181, vcc
	v_mov_b32_e32 v185, v184
	v_pk_mul_f32 v[160:161], v[160:161], v[184:185]
	v_pk_mul_f32 v[162:163], v[162:163], v[184:185]
	v_pk_mul_f32 v[164:165], v[164:165], v[184:185]
	v_pk_mul_f32 v[166:167], v[166:167], v[184:185]
	v_pk_mul_f32 v[168:169], v[168:169], v[184:185]
	v_pk_mul_f32 v[170:171], v[170:171], v[184:185]
	v_pk_mul_f32 v[172:173], v[172:173], v[184:185]
	v_pk_mul_f32 v[174:175], v[174:175], v[184:185]
	v_pk_fma_f32 v[144:145], v[160:161], v[128:129], v[144:145]
	v_pk_fma_f32 v[146:147], v[162:163], v[130:131], v[146:147]
	v_pk_fma_f32 v[148:149], v[164:165], v[132:133], v[148:149]
	v_pk_fma_f32 v[150:151], v[166:167], v[134:135], v[150:151]
	v_pk_fma_f32 v[152:153], v[168:169], v[136:137], v[152:153]
	v_pk_fma_f32 v[154:155], v[170:171], v[138:139], v[154:155]
	v_pk_fma_f32 v[156:157], v[172:173], v[140:141], v[156:157]
	v_pk_fma_f32 v[158:159], v[174:175], v[142:143], v[158:159]
	v_pk_mul_f32 v[252:253], v[144:145], v[144:145]
	v_pk_mul_f32 v[254:255], v[146:147], v[146:147]
	v_pk_fma_f32 v[252:253], v[148:149], v[148:149], v[252:253]
	v_pk_fma_f32 v[254:255], v[150:151], v[150:151], v[254:255]
	v_pk_fma_f32 v[252:253], v[152:153], v[152:153], v[252:253]
	v_pk_fma_f32 v[254:255], v[154:155], v[154:155], v[254:255]
	v_pk_fma_f32 v[252:253], v[156:157], v[156:157], v[252:253]
	v_pk_fma_f32 v[254:255], v[158:159], v[158:159], v[254:255]
	v_pk_add_f32 v[252:253], v[252:253], v[254:255]
	s_nop 0
	v_add_f32_e32 v183, v252, v253
	s_nop 1
	v_add_f32_dpp v183, v183, v183 quad_perm:[1,0,3,2] row_mask:0xf bank_mask:0xf bound_ctrl:1
	s_nop 1
	v_add_f32_dpp v183, v183, v183 quad_perm:[2,3,0,1] row_mask:0xf bank_mask:0xf bound_ctrl:1
	s_nop 1
	v_add_f32_dpp v183, v183, v183 row_half_mirror row_mask:0xf bank_mask:0xf bound_ctrl:1
	s_nop 1
	v_add_f32_dpp v183, v183, v183 row_mirror row_mask:0xf bank_mask:0xf bound_ctrl:1
	s_nop 1
	v_readlane_b32 s98, v183, 0
	v_readlane_b32 s99, v183, 16
	v_readlane_b32 s100, v183, 32
	v_readlane_b32 s101, v183, 48
	s_nop 1
	v_mov_b32_e32 v183, s98
	v_add_f32_e32 v183, s99, v183
	v_add_f32_e32 v183, s100, v183
	v_add_f32_e32 v183, s101, v183
	v_fmamk_f32 v183, v183, 0x3a800000, v182
	v_cmp_gt_f32_e32 vcc, 0x800000, v183
	v_mul_f32_e32 v181, 0x4b800000, v183
	s_nop 1
	v_cndmask_b32_e32 v183, v183, v181, vcc
	v_rsq_f32_e32 v183, v183
	s_nop 0
	v_mul_f32_e32 v181, 0x45800000, v183
	v_cndmask_b32_e32 v184, v183, v181, vcc
	v_mov_b32_e32 v185, v184
	v_cvt_pk_bf16_f32 v0, v144, v145
	v_cvt_pk_bf16_f32 v1, v146, v147
	v_cvt_pk_bf16_f32 v2, v148, v149
	v_cvt_pk_bf16_f32 v3, v150, v151
	v_cvt_pk_bf16_f32 v4, v152, v153
	v_cvt_pk_bf16_f32 v5, v154, v155
	v_cvt_pk_bf16_f32 v6, v156, v157
	v_cvt_pk_bf16_f32 v7, v158, v159
	v_add_u32_e32 v181, 0x1800000, v177
	global_store_dwordx4 v181, v[0:3], s[78:79]
	global_store_dwordx4 v181, v[4:7], s[78:79] offset:1024
	v_add_u32_e32 v236, 0x0, v237
	s_mov_b64 exec, 1
	global_store_dword v236, v184, s[78:79]
	s_mov_b64 exec, -1
	s_waitcnt vmcnt(24)
	v_lshlrev_b32_e32 v144, 16, v16
	v_and_b32_e32 v145, 0xffff0000, v16
	v_lshlrev_b32_e32 v146, 16, v17
	v_and_b32_e32 v147, 0xffff0000, v17
	v_lshlrev_b32_e32 v148, 16, v18
	v_and_b32_e32 v149, 0xffff0000, v18
	v_lshlrev_b32_e32 v150, 16, v19
	v_and_b32_e32 v151, 0xffff0000, v19
	v_lshlrev_b32_e32 v152, 16, v20
	v_and_b32_e32 v153, 0xffff0000, v20
	v_lshlrev_b32_e32 v154, 16, v21
	v_and_b32_e32 v155, 0xffff0000, v21
	v_lshlrev_b32_e32 v156, 16, v22
	v_and_b32_e32 v157, 0xffff0000, v22
	v_lshlrev_b32_e32 v158, 16, v23
	v_and_b32_e32 v159, 0xffff0000, v23
	v_lshlrev_b32_e32 v160, 16, v24
	v_and_b32_e32 v161, 0xffff0000, v24
	v_lshlrev_b32_e32 v162, 16, v25
	v_and_b32_e32 v163, 0xffff0000, v25
	v_lshlrev_b32_e32 v164, 16, v26
	v_and_b32_e32 v165, 0xffff0000, v26
	v_lshlrev_b32_e32 v166, 16, v27
	v_and_b32_e32 v167, 0xffff0000, v27
	v_lshlrev_b32_e32 v168, 16, v28
	v_and_b32_e32 v169, 0xffff0000, v28
	v_lshlrev_b32_e32 v170, 16, v29
	v_and_b32_e32 v171, 0xffff0000, v29
	v_lshlrev_b32_e32 v172, 16, v30
	v_and_b32_e32 v173, 0xffff0000, v30
	v_lshlrev_b32_e32 v174, 16, v31
	v_and_b32_e32 v175, 0xffff0000, v31
	v_pk_mul_f32 v[252:253], v[160:161], v[160:161]
	v_pk_mul_f32 v[254:255], v[162:163], v[162:163]
	v_pk_fma_f32 v[252:253], v[164:165], v[164:165], v[252:253]
	v_pk_fma_f32 v[254:255], v[166:167], v[166:167], v[254:255]
	v_pk_fma_f32 v[252:253], v[168:169], v[168:169], v[252:253]
	v_pk_fma_f32 v[254:255], v[170:171], v[170:171], v[254:255]
	v_pk_fma_f32 v[252:253], v[172:173], v[172:173], v[252:253]
	v_pk_fma_f32 v[254:255], v[174:175], v[174:175], v[254:255]
	v_pk_add_f32 v[252:253], v[252:253], v[254:255]
	s_nop 0
	v_add_f32_e32 v183, v252, v253
	s_nop 1
	v_add_f32_dpp v183, v183, v183 quad_perm:[1,0,3,2] row_mask:0xf bank_mask:0xf bound_ctrl:1
	s_nop 1
	v_add_f32_dpp v183, v183, v183 quad_perm:[2,3,0,1] row_mask:0xf bank_mask:0xf bound_ctrl:1
	s_nop 1
	v_add_f32_dpp v183, v183, v183 row_half_mirror row_mask:0xf bank_mask:0xf bound_ctrl:1
	s_nop 1
	v_add_f32_dpp v183, v183, v183 row_mirror row_mask:0xf bank_mask:0xf bound_ctrl:1
	s_nop 1
	v_readlane_b32 s98, v183, 0
	v_readlane_b32 s99, v183, 16
	v_readlane_b32 s100, v183, 32
	v_readlane_b32 s101, v183, 48
	s_nop 1
	v_mov_b32_e32 v183, s98
	v_add_f32_e32 v183, s99, v183
	v_add_f32_e32 v183, s100, v183
	v_add_f32_e32 v183, s101, v183
	v_fmamk_f32 v183, v183, 0x3a800000, v182
	v_cmp_gt_f32_e32 vcc, 0x800000, v183
	v_mul_f32_e32 v181, 0x4b800000, v183
	s_nop 1
	v_cndmask_b32_e32 v183, v183, v181, vcc
	v_rsq_f32_e32 v183, v183
	s_nop 0
	v_mul_f32_e32 v181, 0x45800000, v183
	v_cndmask_b32_e32 v184, v183, v181, vcc
	v_mov_b32_e32 v185, v184
	v_pk_mul_f32 v[160:161], v[160:161], v[184:185]
	v_pk_mul_f32 v[162:163], v[162:163], v[184:185]
	v_pk_mul_f32 v[164:165], v[164:165], v[184:185]
	v_pk_mul_f32 v[166:167], v[166:167], v[184:185]
	v_pk_mul_f32 v[168:169], v[168:169], v[184:185]
	v_pk_mul_f32 v[170:171], v[170:171], v[184:185]
	v_pk_mul_f32 v[172:173], v[172:173], v[184:185]
	v_pk_mul_f32 v[174:175], v[174:175], v[184:185]
	v_pk_fma_f32 v[144:145], v[160:161], v[128:129], v[144:145]
	v_pk_fma_f32 v[146:147], v[162:163], v[130:131], v[146:147]
	v_pk_fma_f32 v[148:149], v[164:165], v[132:133], v[148:149]
	v_pk_fma_f32 v[150:151], v[166:167], v[134:135], v[150:151]
	v_pk_fma_f32 v[152:153], v[168:169], v[136:137], v[152:153]
	v_pk_fma_f32 v[154:155], v[170:171], v[138:139], v[154:155]
	v_pk_fma_f32 v[156:157], v[172:173], v[140:141], v[156:157]
	v_pk_fma_f32 v[158:159], v[174:175], v[142:143], v[158:159]
	v_pk_mul_f32 v[252:253], v[144:145], v[144:145]
	v_pk_mul_f32 v[254:255], v[146:147], v[146:147]
	v_pk_fma_f32 v[252:253], v[148:149], v[148:149], v[252:253]
	v_pk_fma_f32 v[254:255], v[150:151], v[150:151], v[254:255]
	v_pk_fma_f32 v[252:253], v[152:153], v[152:153], v[252:253]
	v_pk_fma_f32 v[254:255], v[154:155], v[154:155], v[254:255]
	v_pk_fma_f32 v[252:253], v[156:157], v[156:157], v[252:253]
	v_pk_fma_f32 v[254:255], v[158:159], v[158:159], v[254:255]
	v_pk_add_f32 v[252:253], v[252:253], v[254:255]
	s_nop 0
	v_add_f32_e32 v183, v252, v253
	s_nop 1
	v_add_f32_dpp v183, v183, v183 quad_perm:[1,0,3,2] row_mask:0xf bank_mask:0xf bound_ctrl:1
	s_nop 1
	v_add_f32_dpp v183, v183, v183 quad_perm:[2,3,0,1] row_mask:0xf bank_mask:0xf bound_ctrl:1
	s_nop 1
	v_add_f32_dpp v183, v183, v183 row_half_mirror row_mask:0xf bank_mask:0xf bound_ctrl:1
	s_nop 1
	v_add_f32_dpp v183, v183, v183 row_mirror row_mask:0xf bank_mask:0xf bound_ctrl:1
	s_nop 1
	v_readlane_b32 s98, v183, 0
	v_readlane_b32 s99, v183, 16
	v_readlane_b32 s100, v183, 32
	v_readlane_b32 s101, v183, 48
	s_nop 1
	v_mov_b32_e32 v183, s98
	v_add_f32_e32 v183, s99, v183
	v_add_f32_e32 v183, s100, v183
	v_add_f32_e32 v183, s101, v183
	v_fmamk_f32 v183, v183, 0x3a800000, v182
	v_cmp_gt_f32_e32 vcc, 0x800000, v183
	v_mul_f32_e32 v181, 0x4b800000, v183
	s_nop 1
	v_cndmask_b32_e32 v183, v183, v181, vcc
	v_rsq_f32_e32 v183, v183
	s_nop 0
	v_mul_f32_e32 v181, 0x45800000, v183
	v_cndmask_b32_e32 v184, v183, v181, vcc
	v_mov_b32_e32 v185, v184
	v_cvt_pk_bf16_f32 v16, v144, v145
	v_cvt_pk_bf16_f32 v17, v146, v147
	v_cvt_pk_bf16_f32 v18, v148, v149
	v_cvt_pk_bf16_f32 v19, v150, v151
	v_cvt_pk_bf16_f32 v20, v152, v153
	v_cvt_pk_bf16_f32 v21, v154, v155
	v_cvt_pk_bf16_f32 v22, v156, v157
	v_cvt_pk_bf16_f32 v23, v158, v159
	v_add_u32_e32 v181, 0x1880000, v177
	global_store_dwordx4 v181, v[16:19], s[78:79]
	global_store_dwordx4 v181, v[20:23], s[78:79] offset:1024
	v_add_u32_e32 v236, 0x400, v237
	s_mov_b64 exec, 1
	global_store_dword v236, v184, s[78:79]
	s_mov_b64 exec, -1
	s_waitcnt vmcnt(20)
	v_lshlrev_b32_e32 v144, 16, v32
	v_and_b32_e32 v145, 0xffff0000, v32
	v_lshlrev_b32_e32 v146, 16, v33
	v_and_b32_e32 v147, 0xffff0000, v33
	v_lshlrev_b32_e32 v148, 16, v34
	v_and_b32_e32 v149, 0xffff0000, v34
	v_lshlrev_b32_e32 v150, 16, v35
	v_and_b32_e32 v151, 0xffff0000, v35
	v_lshlrev_b32_e32 v152, 16, v36
	v_and_b32_e32 v153, 0xffff0000, v36
	v_lshlrev_b32_e32 v154, 16, v37
	v_and_b32_e32 v155, 0xffff0000, v37
	v_lshlrev_b32_e32 v156, 16, v38
	v_and_b32_e32 v157, 0xffff0000, v38
	v_lshlrev_b32_e32 v158, 16, v39
	v_and_b32_e32 v159, 0xffff0000, v39
	v_lshlrev_b32_e32 v160, 16, v40
	v_and_b32_e32 v161, 0xffff0000, v40
	v_lshlrev_b32_e32 v162, 16, v41
	v_and_b32_e32 v163, 0xffff0000, v41
	v_lshlrev_b32_e32 v164, 16, v42
	v_and_b32_e32 v165, 0xffff0000, v42
	v_lshlrev_b32_e32 v166, 16, v43
	v_and_b32_e32 v167, 0xffff0000, v43
	v_lshlrev_b32_e32 v168, 16, v44
	v_and_b32_e32 v169, 0xffff0000, v44
	v_lshlrev_b32_e32 v170, 16, v45
	v_and_b32_e32 v171, 0xffff0000, v45
	v_lshlrev_b32_e32 v172, 16, v46
	v_and_b32_e32 v173, 0xffff0000, v46
	v_lshlrev_b32_e32 v174, 16, v47
	v_and_b32_e32 v175, 0xffff0000, v47
	v_pk_mul_f32 v[252:253], v[160:161], v[160:161]
	v_pk_mul_f32 v[254:255], v[162:163], v[162:163]
	v_pk_fma_f32 v[252:253], v[164:165], v[164:165], v[252:253]
	v_pk_fma_f32 v[254:255], v[166:167], v[166:167], v[254:255]
	v_pk_fma_f32 v[252:253], v[168:169], v[168:169], v[252:253]
	v_pk_fma_f32 v[254:255], v[170:171], v[170:171], v[254:255]
	v_pk_fma_f32 v[252:253], v[172:173], v[172:173], v[252:253]
	v_pk_fma_f32 v[254:255], v[174:175], v[174:175], v[254:255]
	v_pk_add_f32 v[252:253], v[252:253], v[254:255]
	s_nop 0
	v_add_f32_e32 v183, v252, v253
	s_nop 1
	v_add_f32_dpp v183, v183, v183 quad_perm:[1,0,3,2] row_mask:0xf bank_mask:0xf bound_ctrl:1
	s_nop 1
	v_add_f32_dpp v183, v183, v183 quad_perm:[2,3,0,1] row_mask:0xf bank_mask:0xf bound_ctrl:1
	s_nop 1
	v_add_f32_dpp v183, v183, v183 row_half_mirror row_mask:0xf bank_mask:0xf bound_ctrl:1
	s_nop 1
	v_add_f32_dpp v183, v183, v183 row_mirror row_mask:0xf bank_mask:0xf bound_ctrl:1
	s_nop 1
	v_readlane_b32 s98, v183, 0
	v_readlane_b32 s99, v183, 16
	v_readlane_b32 s100, v183, 32
	v_readlane_b32 s101, v183, 48
	s_nop 1
	v_mov_b32_e32 v183, s98
	v_add_f32_e32 v183, s99, v183
	v_add_f32_e32 v183, s100, v183
	v_add_f32_e32 v183, s101, v183
	v_fmamk_f32 v183, v183, 0x3a800000, v182
	v_cmp_gt_f32_e32 vcc, 0x800000, v183
	v_mul_f32_e32 v181, 0x4b800000, v183
	s_nop 1
	v_cndmask_b32_e32 v183, v183, v181, vcc
	v_rsq_f32_e32 v183, v183
	s_nop 0
	v_mul_f32_e32 v181, 0x45800000, v183
	v_cndmask_b32_e32 v184, v183, v181, vcc
	v_mov_b32_e32 v185, v184
	v_pk_mul_f32 v[160:161], v[160:161], v[184:185]
	v_pk_mul_f32 v[162:163], v[162:163], v[184:185]
	v_pk_mul_f32 v[164:165], v[164:165], v[184:185]
	v_pk_mul_f32 v[166:167], v[166:167], v[184:185]
	v_pk_mul_f32 v[168:169], v[168:169], v[184:185]
	v_pk_mul_f32 v[170:171], v[170:171], v[184:185]
	v_pk_mul_f32 v[172:173], v[172:173], v[184:185]
	v_pk_mul_f32 v[174:175], v[174:175], v[184:185]
	v_pk_fma_f32 v[144:145], v[160:161], v[128:129], v[144:145]
	v_pk_fma_f32 v[146:147], v[162:163], v[130:131], v[146:147]
	v_pk_fma_f32 v[148:149], v[164:165], v[132:133], v[148:149]
	v_pk_fma_f32 v[150:151], v[166:167], v[134:135], v[150:151]
	v_pk_fma_f32 v[152:153], v[168:169], v[136:137], v[152:153]
	v_pk_fma_f32 v[154:155], v[170:171], v[138:139], v[154:155]
	v_pk_fma_f32 v[156:157], v[172:173], v[140:141], v[156:157]
	v_pk_fma_f32 v[158:159], v[174:175], v[142:143], v[158:159]
	v_pk_mul_f32 v[252:253], v[144:145], v[144:145]
	v_pk_mul_f32 v[254:255], v[146:147], v[146:147]
	v_pk_fma_f32 v[252:253], v[148:149], v[148:149], v[252:253]
	v_pk_fma_f32 v[254:255], v[150:151], v[150:151], v[254:255]
	v_pk_fma_f32 v[252:253], v[152:153], v[152:153], v[252:253]
	v_pk_fma_f32 v[254:255], v[154:155], v[154:155], v[254:255]
	v_pk_fma_f32 v[252:253], v[156:157], v[156:157], v[252:253]
	v_pk_fma_f32 v[254:255], v[158:159], v[158:159], v[254:255]
	v_pk_add_f32 v[252:253], v[252:253], v[254:255]
	s_nop 0
	v_add_f32_e32 v183, v252, v253
	s_nop 1
	v_add_f32_dpp v183, v183, v183 quad_perm:[1,0,3,2] row_mask:0xf bank_mask:0xf bound_ctrl:1
	s_nop 1
	v_add_f32_dpp v183, v183, v183 quad_perm:[2,3,0,1] row_mask:0xf bank_mask:0xf bound_ctrl:1
	s_nop 1
	v_add_f32_dpp v183, v183, v183 row_half_mirror row_mask:0xf bank_mask:0xf bound_ctrl:1
	s_nop 1
	v_add_f32_dpp v183, v183, v183 row_mirror row_mask:0xf bank_mask:0xf bound_ctrl:1
	s_nop 1
	v_readlane_b32 s98, v183, 0
	v_readlane_b32 s99, v183, 16
	v_readlane_b32 s100, v183, 32
	v_readlane_b32 s101, v183, 48
	s_nop 1
	v_mov_b32_e32 v183, s98
	v_add_f32_e32 v183, s99, v183
	v_add_f32_e32 v183, s100, v183
	v_add_f32_e32 v183, s101, v183
	v_fmamk_f32 v183, v183, 0x3a800000, v182
	v_cmp_gt_f32_e32 vcc, 0x800000, v183
	v_mul_f32_e32 v181, 0x4b800000, v183
	s_nop 1
	v_cndmask_b32_e32 v183, v183, v181, vcc
	v_rsq_f32_e32 v183, v183
	s_nop 0
	v_mul_f32_e32 v181, 0x45800000, v183
	v_cndmask_b32_e32 v184, v183, v181, vcc
	v_mov_b32_e32 v185, v184
	v_cvt_pk_bf16_f32 v32, v144, v145
	v_cvt_pk_bf16_f32 v33, v146, v147
	v_cvt_pk_bf16_f32 v34, v148, v149
	v_cvt_pk_bf16_f32 v35, v150, v151
	v_cvt_pk_bf16_f32 v36, v152, v153
	v_cvt_pk_bf16_f32 v37, v154, v155
	v_cvt_pk_bf16_f32 v38, v156, v157
	v_cvt_pk_bf16_f32 v39, v158, v159
	v_add_u32_e32 v181, 0x1900000, v177
	global_store_dwordx4 v181, v[32:35], s[78:79]
	global_store_dwordx4 v181, v[36:39], s[78:79] offset:1024
	v_add_u32_e32 v236, 0x800, v237
	s_mov_b64 exec, 1
	global_store_dword v236, v184, s[78:79]
	s_mov_b64 exec, -1
	s_waitcnt vmcnt(16)
	v_lshlrev_b32_e32 v144, 16, v48
	v_and_b32_e32 v145, 0xffff0000, v48
	v_lshlrev_b32_e32 v146, 16, v49
	v_and_b32_e32 v147, 0xffff0000, v49
	v_lshlrev_b32_e32 v148, 16, v50
	v_and_b32_e32 v149, 0xffff0000, v50
	v_lshlrev_b32_e32 v150, 16, v51
	v_and_b32_e32 v151, 0xffff0000, v51
	v_lshlrev_b32_e32 v152, 16, v52
	v_and_b32_e32 v153, 0xffff0000, v52
	v_lshlrev_b32_e32 v154, 16, v53
	v_and_b32_e32 v155, 0xffff0000, v53
	v_lshlrev_b32_e32 v156, 16, v54
	v_and_b32_e32 v157, 0xffff0000, v54
	v_lshlrev_b32_e32 v158, 16, v55
	v_and_b32_e32 v159, 0xffff0000, v55
	v_lshlrev_b32_e32 v160, 16, v56
	v_and_b32_e32 v161, 0xffff0000, v56
	v_lshlrev_b32_e32 v162, 16, v57
	v_and_b32_e32 v163, 0xffff0000, v57
	v_lshlrev_b32_e32 v164, 16, v58
	v_and_b32_e32 v165, 0xffff0000, v58
	v_lshlrev_b32_e32 v166, 16, v59
	v_and_b32_e32 v167, 0xffff0000, v59
	v_lshlrev_b32_e32 v168, 16, v60
	v_and_b32_e32 v169, 0xffff0000, v60
	v_lshlrev_b32_e32 v170, 16, v61
	v_and_b32_e32 v171, 0xffff0000, v61
	v_lshlrev_b32_e32 v172, 16, v62
	v_and_b32_e32 v173, 0xffff0000, v62
	v_lshlrev_b32_e32 v174, 16, v63
	v_and_b32_e32 v175, 0xffff0000, v63
	v_pk_mul_f32 v[252:253], v[160:161], v[160:161]
	v_pk_mul_f32 v[254:255], v[162:163], v[162:163]
	v_pk_fma_f32 v[252:253], v[164:165], v[164:165], v[252:253]
	v_pk_fma_f32 v[254:255], v[166:167], v[166:167], v[254:255]
	v_pk_fma_f32 v[252:253], v[168:169], v[168:169], v[252:253]
	v_pk_fma_f32 v[254:255], v[170:171], v[170:171], v[254:255]
	v_pk_fma_f32 v[252:253], v[172:173], v[172:173], v[252:253]
	v_pk_fma_f32 v[254:255], v[174:175], v[174:175], v[254:255]
	v_pk_add_f32 v[252:253], v[252:253], v[254:255]
	s_nop 0
	v_add_f32_e32 v183, v252, v253
	s_nop 1
	v_add_f32_dpp v183, v183, v183 quad_perm:[1,0,3,2] row_mask:0xf bank_mask:0xf bound_ctrl:1
	s_nop 1
	v_add_f32_dpp v183, v183, v183 quad_perm:[2,3,0,1] row_mask:0xf bank_mask:0xf bound_ctrl:1
	s_nop 1
	v_add_f32_dpp v183, v183, v183 row_half_mirror row_mask:0xf bank_mask:0xf bound_ctrl:1
	s_nop 1
	v_add_f32_dpp v183, v183, v183 row_mirror row_mask:0xf bank_mask:0xf bound_ctrl:1
	s_nop 1
	v_readlane_b32 s98, v183, 0
	v_readlane_b32 s99, v183, 16
	v_readlane_b32 s100, v183, 32
	v_readlane_b32 s101, v183, 48
	s_nop 1
	v_mov_b32_e32 v183, s98
	v_add_f32_e32 v183, s99, v183
	v_add_f32_e32 v183, s100, v183
	v_add_f32_e32 v183, s101, v183
	v_fmamk_f32 v183, v183, 0x3a800000, v182
	v_cmp_gt_f32_e32 vcc, 0x800000, v183
	v_mul_f32_e32 v181, 0x4b800000, v183
	s_nop 1
	v_cndmask_b32_e32 v183, v183, v181, vcc
	v_rsq_f32_e32 v183, v183
	s_nop 0
	v_mul_f32_e32 v181, 0x45800000, v183
	v_cndmask_b32_e32 v184, v183, v181, vcc
	v_mov_b32_e32 v185, v184
	v_pk_mul_f32 v[160:161], v[160:161], v[184:185]
	v_pk_mul_f32 v[162:163], v[162:163], v[184:185]
	v_pk_mul_f32 v[164:165], v[164:165], v[184:185]
	v_pk_mul_f32 v[166:167], v[166:167], v[184:185]
	v_pk_mul_f32 v[168:169], v[168:169], v[184:185]
	v_pk_mul_f32 v[170:171], v[170:171], v[184:185]
	v_pk_mul_f32 v[172:173], v[172:173], v[184:185]
	v_pk_mul_f32 v[174:175], v[174:175], v[184:185]
	v_pk_fma_f32 v[144:145], v[160:161], v[128:129], v[144:145]
	v_pk_fma_f32 v[146:147], v[162:163], v[130:131], v[146:147]
	v_pk_fma_f32 v[148:149], v[164:165], v[132:133], v[148:149]
	v_pk_fma_f32 v[150:151], v[166:167], v[134:135], v[150:151]
	v_pk_fma_f32 v[152:153], v[168:169], v[136:137], v[152:153]
	v_pk_fma_f32 v[154:155], v[170:171], v[138:139], v[154:155]
	v_pk_fma_f32 v[156:157], v[172:173], v[140:141], v[156:157]
	v_pk_fma_f32 v[158:159], v[174:175], v[142:143], v[158:159]
	v_pk_mul_f32 v[252:253], v[144:145], v[144:145]
	v_pk_mul_f32 v[254:255], v[146:147], v[146:147]
	v_pk_fma_f32 v[252:253], v[148:149], v[148:149], v[252:253]
	v_pk_fma_f32 v[254:255], v[150:151], v[150:151], v[254:255]
	v_pk_fma_f32 v[252:253], v[152:153], v[152:153], v[252:253]
	v_pk_fma_f32 v[254:255], v[154:155], v[154:155], v[254:255]
	v_pk_fma_f32 v[252:253], v[156:157], v[156:157], v[252:253]
	v_pk_fma_f32 v[254:255], v[158:159], v[158:159], v[254:255]
	v_pk_add_f32 v[252:253], v[252:253], v[254:255]
	s_nop 0
	v_add_f32_e32 v183, v252, v253
	s_nop 1
	v_add_f32_dpp v183, v183, v183 quad_perm:[1,0,3,2] row_mask:0xf bank_mask:0xf bound_ctrl:1
	s_nop 1
	v_add_f32_dpp v183, v183, v183 quad_perm:[2,3,0,1] row_mask:0xf bank_mask:0xf bound_ctrl:1
	s_nop 1
	v_add_f32_dpp v183, v183, v183 row_half_mirror row_mask:0xf bank_mask:0xf bound_ctrl:1
	s_nop 1
	v_add_f32_dpp v183, v183, v183 row_mirror row_mask:0xf bank_mask:0xf bound_ctrl:1
	s_nop 1
	v_readlane_b32 s98, v183, 0
	v_readlane_b32 s99, v183, 16
	v_readlane_b32 s100, v183, 32
	v_readlane_b32 s101, v183, 48
	s_nop 1
	v_mov_b32_e32 v183, s98
	v_add_f32_e32 v183, s99, v183
	v_add_f32_e32 v183, s100, v183
	v_add_f32_e32 v183, s101, v183
	v_fmamk_f32 v183, v183, 0x3a800000, v182
	v_cmp_gt_f32_e32 vcc, 0x800000, v183
	v_mul_f32_e32 v181, 0x4b800000, v183
	s_nop 1
	v_cndmask_b32_e32 v183, v183, v181, vcc
	v_rsq_f32_e32 v183, v183
	s_nop 0
	v_mul_f32_e32 v181, 0x45800000, v183
	v_cndmask_b32_e32 v184, v183, v181, vcc
	v_mov_b32_e32 v185, v184
	v_cvt_pk_bf16_f32 v48, v144, v145
	v_cvt_pk_bf16_f32 v49, v146, v147
	v_cvt_pk_bf16_f32 v50, v148, v149
	v_cvt_pk_bf16_f32 v51, v150, v151
	v_cvt_pk_bf16_f32 v52, v152, v153
	v_cvt_pk_bf16_f32 v53, v154, v155
	v_cvt_pk_bf16_f32 v54, v156, v157
	v_cvt_pk_bf16_f32 v55, v158, v159
	v_add_u32_e32 v181, 0x1980000, v177
	global_store_dwordx4 v181, v[48:51], s[78:79]
	global_store_dwordx4 v181, v[52:55], s[78:79] offset:1024
	v_add_u32_e32 v236, 0xc00, v237
	s_mov_b64 exec, 1
	global_store_dword v236, v184, s[78:79]
	s_mov_b64 exec, -1
	s_waitcnt vmcnt(12)
	v_lshlrev_b32_e32 v144, 16, v64
	v_and_b32_e32 v145, 0xffff0000, v64
	v_lshlrev_b32_e32 v146, 16, v65
	v_and_b32_e32 v147, 0xffff0000, v65
	v_lshlrev_b32_e32 v148, 16, v66
	v_and_b32_e32 v149, 0xffff0000, v66
	v_lshlrev_b32_e32 v150, 16, v67
	v_and_b32_e32 v151, 0xffff0000, v67
	v_lshlrev_b32_e32 v152, 16, v68
	v_and_b32_e32 v153, 0xffff0000, v68
	v_lshlrev_b32_e32 v154, 16, v69
	v_and_b32_e32 v155, 0xffff0000, v69
	v_lshlrev_b32_e32 v156, 16, v70
	v_and_b32_e32 v157, 0xffff0000, v70
	v_lshlrev_b32_e32 v158, 16, v71
	v_and_b32_e32 v159, 0xffff0000, v71
	v_lshlrev_b32_e32 v160, 16, v72
	v_and_b32_e32 v161, 0xffff0000, v72
	v_lshlrev_b32_e32 v162, 16, v73
	v_and_b32_e32 v163, 0xffff0000, v73
	v_lshlrev_b32_e32 v164, 16, v74
	v_and_b32_e32 v165, 0xffff0000, v74
	v_lshlrev_b32_e32 v166, 16, v75
	v_and_b32_e32 v167, 0xffff0000, v75
	v_lshlrev_b32_e32 v168, 16, v76
	v_and_b32_e32 v169, 0xffff0000, v76
	v_lshlrev_b32_e32 v170, 16, v77
	v_and_b32_e32 v171, 0xffff0000, v77
	v_lshlrev_b32_e32 v172, 16, v78
	v_and_b32_e32 v173, 0xffff0000, v78
	v_lshlrev_b32_e32 v174, 16, v79
	v_and_b32_e32 v175, 0xffff0000, v79
	v_pk_mul_f32 v[252:253], v[160:161], v[160:161]
	v_pk_mul_f32 v[254:255], v[162:163], v[162:163]
	v_pk_fma_f32 v[252:253], v[164:165], v[164:165], v[252:253]
	v_pk_fma_f32 v[254:255], v[166:167], v[166:167], v[254:255]
	v_pk_fma_f32 v[252:253], v[168:169], v[168:169], v[252:253]
	v_pk_fma_f32 v[254:255], v[170:171], v[170:171], v[254:255]
	v_pk_fma_f32 v[252:253], v[172:173], v[172:173], v[252:253]
	v_pk_fma_f32 v[254:255], v[174:175], v[174:175], v[254:255]
	v_pk_add_f32 v[252:253], v[252:253], v[254:255]
	s_nop 0
	v_add_f32_e32 v183, v252, v253
	s_nop 1
	v_add_f32_dpp v183, v183, v183 quad_perm:[1,0,3,2] row_mask:0xf bank_mask:0xf bound_ctrl:1
	s_nop 1
	v_add_f32_dpp v183, v183, v183 quad_perm:[2,3,0,1] row_mask:0xf bank_mask:0xf bound_ctrl:1
	s_nop 1
	v_add_f32_dpp v183, v183, v183 row_half_mirror row_mask:0xf bank_mask:0xf bound_ctrl:1
	s_nop 1
	v_add_f32_dpp v183, v183, v183 row_mirror row_mask:0xf bank_mask:0xf bound_ctrl:1
	s_nop 1
	v_readlane_b32 s98, v183, 0
	v_readlane_b32 s99, v183, 16
	v_readlane_b32 s100, v183, 32
	v_readlane_b32 s101, v183, 48
	s_nop 1
	v_mov_b32_e32 v183, s98
	v_add_f32_e32 v183, s99, v183
	v_add_f32_e32 v183, s100, v183
	v_add_f32_e32 v183, s101, v183
	v_fmamk_f32 v183, v183, 0x3a800000, v182
	v_cmp_gt_f32_e32 vcc, 0x800000, v183
	v_mul_f32_e32 v181, 0x4b800000, v183
	s_nop 1
	v_cndmask_b32_e32 v183, v183, v181, vcc
	v_rsq_f32_e32 v183, v183
	s_nop 0
	v_mul_f32_e32 v181, 0x45800000, v183
	v_cndmask_b32_e32 v184, v183, v181, vcc
	v_mov_b32_e32 v185, v184
	v_pk_mul_f32 v[160:161], v[160:161], v[184:185]
	v_pk_mul_f32 v[162:163], v[162:163], v[184:185]
	v_pk_mul_f32 v[164:165], v[164:165], v[184:185]
	v_pk_mul_f32 v[166:167], v[166:167], v[184:185]
	v_pk_mul_f32 v[168:169], v[168:169], v[184:185]
	v_pk_mul_f32 v[170:171], v[170:171], v[184:185]
	v_pk_mul_f32 v[172:173], v[172:173], v[184:185]
	v_pk_mul_f32 v[174:175], v[174:175], v[184:185]
	v_pk_fma_f32 v[144:145], v[160:161], v[128:129], v[144:145]
	v_pk_fma_f32 v[146:147], v[162:163], v[130:131], v[146:147]
	v_pk_fma_f32 v[148:149], v[164:165], v[132:133], v[148:149]
	v_pk_fma_f32 v[150:151], v[166:167], v[134:135], v[150:151]
	v_pk_fma_f32 v[152:153], v[168:169], v[136:137], v[152:153]
	v_pk_fma_f32 v[154:155], v[170:171], v[138:139], v[154:155]
	v_pk_fma_f32 v[156:157], v[172:173], v[140:141], v[156:157]
	v_pk_fma_f32 v[158:159], v[174:175], v[142:143], v[158:159]
	v_pk_mul_f32 v[252:253], v[144:145], v[144:145]
	v_pk_mul_f32 v[254:255], v[146:147], v[146:147]
	v_pk_fma_f32 v[252:253], v[148:149], v[148:149], v[252:253]
	v_pk_fma_f32 v[254:255], v[150:151], v[150:151], v[254:255]
	v_pk_fma_f32 v[252:253], v[152:153], v[152:153], v[252:253]
	v_pk_fma_f32 v[254:255], v[154:155], v[154:155], v[254:255]
	v_pk_fma_f32 v[252:253], v[156:157], v[156:157], v[252:253]
	v_pk_fma_f32 v[254:255], v[158:159], v[158:159], v[254:255]
	v_pk_add_f32 v[252:253], v[252:253], v[254:255]
	s_nop 0
	v_add_f32_e32 v183, v252, v253
	s_nop 1
	v_add_f32_dpp v183, v183, v183 quad_perm:[1,0,3,2] row_mask:0xf bank_mask:0xf bound_ctrl:1
	s_nop 1
	v_add_f32_dpp v183, v183, v183 quad_perm:[2,3,0,1] row_mask:0xf bank_mask:0xf bound_ctrl:1
	s_nop 1
	v_add_f32_dpp v183, v183, v183 row_half_mirror row_mask:0xf bank_mask:0xf bound_ctrl:1
	s_nop 1
	v_add_f32_dpp v183, v183, v183 row_mirror row_mask:0xf bank_mask:0xf bound_ctrl:1
	s_nop 1
	v_readlane_b32 s98, v183, 0
	v_readlane_b32 s99, v183, 16
	v_readlane_b32 s100, v183, 32
	v_readlane_b32 s101, v183, 48
	s_nop 1
	v_mov_b32_e32 v183, s98
	v_add_f32_e32 v183, s99, v183
	v_add_f32_e32 v183, s100, v183
	v_add_f32_e32 v183, s101, v183
	v_fmamk_f32 v183, v183, 0x3a800000, v182
	v_cmp_gt_f32_e32 vcc, 0x800000, v183
	v_mul_f32_e32 v181, 0x4b800000, v183
	s_nop 1
	v_cndmask_b32_e32 v183, v183, v181, vcc
	v_rsq_f32_e32 v183, v183
	s_nop 0
	v_mul_f32_e32 v181, 0x45800000, v183
	v_cndmask_b32_e32 v184, v183, v181, vcc
	v_mov_b32_e32 v185, v184
	v_cvt_pk_bf16_f32 v64, v144, v145
	v_cvt_pk_bf16_f32 v65, v146, v147
	v_cvt_pk_bf16_f32 v66, v148, v149
	v_cvt_pk_bf16_f32 v67, v150, v151
	v_cvt_pk_bf16_f32 v68, v152, v153
	v_cvt_pk_bf16_f32 v69, v154, v155
	v_cvt_pk_bf16_f32 v70, v156, v157
	v_cvt_pk_bf16_f32 v71, v158, v159
	v_add_u32_e32 v181, 0x1a00000, v177
	global_store_dwordx4 v181, v[64:67], s[78:79]
	global_store_dwordx4 v181, v[68:71], s[78:79] offset:1024
	v_add_u32_e32 v236, 0x1000, v237
	s_mov_b64 exec, 1
	global_store_dword v236, v184, s[78:79]
	s_mov_b64 exec, -1
	s_waitcnt vmcnt(8)
	v_lshlrev_b32_e32 v144, 16, v80
	v_and_b32_e32 v145, 0xffff0000, v80
	v_lshlrev_b32_e32 v146, 16, v81
	v_and_b32_e32 v147, 0xffff0000, v81
	v_lshlrev_b32_e32 v148, 16, v82
	v_and_b32_e32 v149, 0xffff0000, v82
	v_lshlrev_b32_e32 v150, 16, v83
	v_and_b32_e32 v151, 0xffff0000, v83
	v_lshlrev_b32_e32 v152, 16, v84
	v_and_b32_e32 v153, 0xffff0000, v84
	v_lshlrev_b32_e32 v154, 16, v85
	v_and_b32_e32 v155, 0xffff0000, v85
	v_lshlrev_b32_e32 v156, 16, v86
	v_and_b32_e32 v157, 0xffff0000, v86
	v_lshlrev_b32_e32 v158, 16, v87
	v_and_b32_e32 v159, 0xffff0000, v87
	v_lshlrev_b32_e32 v160, 16, v88
	v_and_b32_e32 v161, 0xffff0000, v88
	v_lshlrev_b32_e32 v162, 16, v89
	v_and_b32_e32 v163, 0xffff0000, v89
	v_lshlrev_b32_e32 v164, 16, v90
	v_and_b32_e32 v165, 0xffff0000, v90
	v_lshlrev_b32_e32 v166, 16, v91
	v_and_b32_e32 v167, 0xffff0000, v91
	v_lshlrev_b32_e32 v168, 16, v92
	v_and_b32_e32 v169, 0xffff0000, v92
	v_lshlrev_b32_e32 v170, 16, v93
	v_and_b32_e32 v171, 0xffff0000, v93
	v_lshlrev_b32_e32 v172, 16, v94
	v_and_b32_e32 v173, 0xffff0000, v94
	v_lshlrev_b32_e32 v174, 16, v95
	v_and_b32_e32 v175, 0xffff0000, v95
	v_pk_mul_f32 v[252:253], v[160:161], v[160:161]
	v_pk_mul_f32 v[254:255], v[162:163], v[162:163]
	v_pk_fma_f32 v[252:253], v[164:165], v[164:165], v[252:253]
	v_pk_fma_f32 v[254:255], v[166:167], v[166:167], v[254:255]
	v_pk_fma_f32 v[252:253], v[168:169], v[168:169], v[252:253]
	v_pk_fma_f32 v[254:255], v[170:171], v[170:171], v[254:255]
	v_pk_fma_f32 v[252:253], v[172:173], v[172:173], v[252:253]
	v_pk_fma_f32 v[254:255], v[174:175], v[174:175], v[254:255]
	v_pk_add_f32 v[252:253], v[252:253], v[254:255]
	s_nop 0
	v_add_f32_e32 v183, v252, v253
	s_nop 1
	v_add_f32_dpp v183, v183, v183 quad_perm:[1,0,3,2] row_mask:0xf bank_mask:0xf bound_ctrl:1
	s_nop 1
	v_add_f32_dpp v183, v183, v183 quad_perm:[2,3,0,1] row_mask:0xf bank_mask:0xf bound_ctrl:1
	s_nop 1
	v_add_f32_dpp v183, v183, v183 row_half_mirror row_mask:0xf bank_mask:0xf bound_ctrl:1
	s_nop 1
	v_add_f32_dpp v183, v183, v183 row_mirror row_mask:0xf bank_mask:0xf bound_ctrl:1
	s_nop 1
	v_readlane_b32 s98, v183, 0
	v_readlane_b32 s99, v183, 16
	v_readlane_b32 s100, v183, 32
	v_readlane_b32 s101, v183, 48
	s_nop 1
	v_mov_b32_e32 v183, s98
	v_add_f32_e32 v183, s99, v183
	v_add_f32_e32 v183, s100, v183
	v_add_f32_e32 v183, s101, v183
	v_fmamk_f32 v183, v183, 0x3a800000, v182
	v_cmp_gt_f32_e32 vcc, 0x800000, v183
	v_mul_f32_e32 v181, 0x4b800000, v183
	s_nop 1
	v_cndmask_b32_e32 v183, v183, v181, vcc
	v_rsq_f32_e32 v183, v183
	s_nop 0
	v_mul_f32_e32 v181, 0x45800000, v183
	v_cndmask_b32_e32 v184, v183, v181, vcc
	v_mov_b32_e32 v185, v184
	v_pk_mul_f32 v[160:161], v[160:161], v[184:185]
	v_pk_mul_f32 v[162:163], v[162:163], v[184:185]
	v_pk_mul_f32 v[164:165], v[164:165], v[184:185]
	v_pk_mul_f32 v[166:167], v[166:167], v[184:185]
	v_pk_mul_f32 v[168:169], v[168:169], v[184:185]
	v_pk_mul_f32 v[170:171], v[170:171], v[184:185]
	v_pk_mul_f32 v[172:173], v[172:173], v[184:185]
	v_pk_mul_f32 v[174:175], v[174:175], v[184:185]
	v_pk_fma_f32 v[144:145], v[160:161], v[128:129], v[144:145]
	v_pk_fma_f32 v[146:147], v[162:163], v[130:131], v[146:147]
	v_pk_fma_f32 v[148:149], v[164:165], v[132:133], v[148:149]
	v_pk_fma_f32 v[150:151], v[166:167], v[134:135], v[150:151]
	v_pk_fma_f32 v[152:153], v[168:169], v[136:137], v[152:153]
	v_pk_fma_f32 v[154:155], v[170:171], v[138:139], v[154:155]
	v_pk_fma_f32 v[156:157], v[172:173], v[140:141], v[156:157]
	v_pk_fma_f32 v[158:159], v[174:175], v[142:143], v[158:159]
	v_pk_mul_f32 v[252:253], v[144:145], v[144:145]
	v_pk_mul_f32 v[254:255], v[146:147], v[146:147]
	v_pk_fma_f32 v[252:253], v[148:149], v[148:149], v[252:253]
	v_pk_fma_f32 v[254:255], v[150:151], v[150:151], v[254:255]
	v_pk_fma_f32 v[252:253], v[152:153], v[152:153], v[252:253]
	v_pk_fma_f32 v[254:255], v[154:155], v[154:155], v[254:255]
	v_pk_fma_f32 v[252:253], v[156:157], v[156:157], v[252:253]
	v_pk_fma_f32 v[254:255], v[158:159], v[158:159], v[254:255]
	v_pk_add_f32 v[252:253], v[252:253], v[254:255]
	s_nop 0
	v_add_f32_e32 v183, v252, v253
	s_nop 1
	v_add_f32_dpp v183, v183, v183 quad_perm:[1,0,3,2] row_mask:0xf bank_mask:0xf bound_ctrl:1
	s_nop 1
	v_add_f32_dpp v183, v183, v183 quad_perm:[2,3,0,1] row_mask:0xf bank_mask:0xf bound_ctrl:1
	s_nop 1
	v_add_f32_dpp v183, v183, v183 row_half_mirror row_mask:0xf bank_mask:0xf bound_ctrl:1
	s_nop 1
	v_add_f32_dpp v183, v183, v183 row_mirror row_mask:0xf bank_mask:0xf bound_ctrl:1
	s_nop 1
	v_readlane_b32 s98, v183, 0
	v_readlane_b32 s99, v183, 16
	v_readlane_b32 s100, v183, 32
	v_readlane_b32 s101, v183, 48
	s_nop 1
	v_mov_b32_e32 v183, s98
	v_add_f32_e32 v183, s99, v183
	v_add_f32_e32 v183, s100, v183
	v_add_f32_e32 v183, s101, v183
	v_fmamk_f32 v183, v183, 0x3a800000, v182
	v_cmp_gt_f32_e32 vcc, 0x800000, v183
	v_mul_f32_e32 v181, 0x4b800000, v183
	s_nop 1
	v_cndmask_b32_e32 v183, v183, v181, vcc
	v_rsq_f32_e32 v183, v183
	s_nop 0
	v_mul_f32_e32 v181, 0x45800000, v183
	v_cndmask_b32_e32 v184, v183, v181, vcc
	v_mov_b32_e32 v185, v184
	v_cvt_pk_bf16_f32 v80, v144, v145
	v_cvt_pk_bf16_f32 v81, v146, v147
	v_cvt_pk_bf16_f32 v82, v148, v149
	v_cvt_pk_bf16_f32 v83, v150, v151
	v_cvt_pk_bf16_f32 v84, v152, v153
	v_cvt_pk_bf16_f32 v85, v154, v155
	v_cvt_pk_bf16_f32 v86, v156, v157
	v_cvt_pk_bf16_f32 v87, v158, v159
	v_add_u32_e32 v181, 0x1a80000, v177
	global_store_dwordx4 v181, v[80:83], s[78:79]
	global_store_dwordx4 v181, v[84:87], s[78:79] offset:1024
	v_add_u32_e32 v236, 0x1400, v237
	s_mov_b64 exec, 1
	global_store_dword v236, v184, s[78:79]
	s_mov_b64 exec, -1
	s_waitcnt vmcnt(4)
	v_lshlrev_b32_e32 v144, 16, v96
	v_and_b32_e32 v145, 0xffff0000, v96
	v_lshlrev_b32_e32 v146, 16, v97
	v_and_b32_e32 v147, 0xffff0000, v97
	v_lshlrev_b32_e32 v148, 16, v98
	v_and_b32_e32 v149, 0xffff0000, v98
	v_lshlrev_b32_e32 v150, 16, v99
	v_and_b32_e32 v151, 0xffff0000, v99
	v_lshlrev_b32_e32 v152, 16, v100
	v_and_b32_e32 v153, 0xffff0000, v100
	v_lshlrev_b32_e32 v154, 16, v101
	v_and_b32_e32 v155, 0xffff0000, v101
	v_lshlrev_b32_e32 v156, 16, v102
	v_and_b32_e32 v157, 0xffff0000, v102
	v_lshlrev_b32_e32 v158, 16, v103
	v_and_b32_e32 v159, 0xffff0000, v103
	v_lshlrev_b32_e32 v160, 16, v104
	v_and_b32_e32 v161, 0xffff0000, v104
	v_lshlrev_b32_e32 v162, 16, v105
	v_and_b32_e32 v163, 0xffff0000, v105
	v_lshlrev_b32_e32 v164, 16, v106
	v_and_b32_e32 v165, 0xffff0000, v106
	v_lshlrev_b32_e32 v166, 16, v107
	v_and_b32_e32 v167, 0xffff0000, v107
	v_lshlrev_b32_e32 v168, 16, v108
	v_and_b32_e32 v169, 0xffff0000, v108
	v_lshlrev_b32_e32 v170, 16, v109
	v_and_b32_e32 v171, 0xffff0000, v109
	v_lshlrev_b32_e32 v172, 16, v110
	v_and_b32_e32 v173, 0xffff0000, v110
	v_lshlrev_b32_e32 v174, 16, v111
	v_and_b32_e32 v175, 0xffff0000, v111
	v_pk_mul_f32 v[252:253], v[160:161], v[160:161]
	v_pk_mul_f32 v[254:255], v[162:163], v[162:163]
	v_pk_fma_f32 v[252:253], v[164:165], v[164:165], v[252:253]
	v_pk_fma_f32 v[254:255], v[166:167], v[166:167], v[254:255]
	v_pk_fma_f32 v[252:253], v[168:169], v[168:169], v[252:253]
	v_pk_fma_f32 v[254:255], v[170:171], v[170:171], v[254:255]
	v_pk_fma_f32 v[252:253], v[172:173], v[172:173], v[252:253]
	v_pk_fma_f32 v[254:255], v[174:175], v[174:175], v[254:255]
	v_pk_add_f32 v[252:253], v[252:253], v[254:255]
	s_nop 0
	v_add_f32_e32 v183, v252, v253
	s_nop 1
	v_add_f32_dpp v183, v183, v183 quad_perm:[1,0,3,2] row_mask:0xf bank_mask:0xf bound_ctrl:1
	s_nop 1
	v_add_f32_dpp v183, v183, v183 quad_perm:[2,3,0,1] row_mask:0xf bank_mask:0xf bound_ctrl:1
	s_nop 1
	v_add_f32_dpp v183, v183, v183 row_half_mirror row_mask:0xf bank_mask:0xf bound_ctrl:1
	s_nop 1
	v_add_f32_dpp v183, v183, v183 row_mirror row_mask:0xf bank_mask:0xf bound_ctrl:1
	s_nop 1
	v_readlane_b32 s98, v183, 0
	v_readlane_b32 s99, v183, 16
	v_readlane_b32 s100, v183, 32
	v_readlane_b32 s101, v183, 48
	s_nop 1
	v_mov_b32_e32 v183, s98
	v_add_f32_e32 v183, s99, v183
	v_add_f32_e32 v183, s100, v183
	v_add_f32_e32 v183, s101, v183
	v_fmamk_f32 v183, v183, 0x3a800000, v182
	v_cmp_gt_f32_e32 vcc, 0x800000, v183
	v_mul_f32_e32 v181, 0x4b800000, v183
	s_nop 1
	v_cndmask_b32_e32 v183, v183, v181, vcc
	v_rsq_f32_e32 v183, v183
	s_nop 0
	v_mul_f32_e32 v181, 0x45800000, v183
	v_cndmask_b32_e32 v184, v183, v181, vcc
	v_mov_b32_e32 v185, v184
	v_pk_mul_f32 v[160:161], v[160:161], v[184:185]
	v_pk_mul_f32 v[162:163], v[162:163], v[184:185]
	v_pk_mul_f32 v[164:165], v[164:165], v[184:185]
	v_pk_mul_f32 v[166:167], v[166:167], v[184:185]
	v_pk_mul_f32 v[168:169], v[168:169], v[184:185]
	v_pk_mul_f32 v[170:171], v[170:171], v[184:185]
	v_pk_mul_f32 v[172:173], v[172:173], v[184:185]
	v_pk_mul_f32 v[174:175], v[174:175], v[184:185]
	v_pk_fma_f32 v[144:145], v[160:161], v[128:129], v[144:145]
	v_pk_fma_f32 v[146:147], v[162:163], v[130:131], v[146:147]
	v_pk_fma_f32 v[148:149], v[164:165], v[132:133], v[148:149]
	v_pk_fma_f32 v[150:151], v[166:167], v[134:135], v[150:151]
	v_pk_fma_f32 v[152:153], v[168:169], v[136:137], v[152:153]
	v_pk_fma_f32 v[154:155], v[170:171], v[138:139], v[154:155]
	v_pk_fma_f32 v[156:157], v[172:173], v[140:141], v[156:157]
	v_pk_fma_f32 v[158:159], v[174:175], v[142:143], v[158:159]
	v_pk_mul_f32 v[252:253], v[144:145], v[144:145]
	v_pk_mul_f32 v[254:255], v[146:147], v[146:147]
	v_pk_fma_f32 v[252:253], v[148:149], v[148:149], v[252:253]
	v_pk_fma_f32 v[254:255], v[150:151], v[150:151], v[254:255]
	v_pk_fma_f32 v[252:253], v[152:153], v[152:153], v[252:253]
	v_pk_fma_f32 v[254:255], v[154:155], v[154:155], v[254:255]
	v_pk_fma_f32 v[252:253], v[156:157], v[156:157], v[252:253]
	v_pk_fma_f32 v[254:255], v[158:159], v[158:159], v[254:255]
	v_pk_add_f32 v[252:253], v[252:253], v[254:255]
	s_nop 0
	v_add_f32_e32 v183, v252, v253
	s_nop 1
	v_add_f32_dpp v183, v183, v183 quad_perm:[1,0,3,2] row_mask:0xf bank_mask:0xf bound_ctrl:1
	s_nop 1
	v_add_f32_dpp v183, v183, v183 quad_perm:[2,3,0,1] row_mask:0xf bank_mask:0xf bound_ctrl:1
	s_nop 1
	v_add_f32_dpp v183, v183, v183 row_half_mirror row_mask:0xf bank_mask:0xf bound_ctrl:1
	s_nop 1
	v_add_f32_dpp v183, v183, v183 row_mirror row_mask:0xf bank_mask:0xf bound_ctrl:1
	s_nop 1
	v_readlane_b32 s98, v183, 0
	v_readlane_b32 s99, v183, 16
	v_readlane_b32 s100, v183, 32
	v_readlane_b32 s101, v183, 48
	s_nop 1
	v_mov_b32_e32 v183, s98
	v_add_f32_e32 v183, s99, v183
	v_add_f32_e32 v183, s100, v183
	v_add_f32_e32 v183, s101, v183
	v_fmamk_f32 v183, v183, 0x3a800000, v182
	v_cmp_gt_f32_e32 vcc, 0x800000, v183
	v_mul_f32_e32 v181, 0x4b800000, v183
	s_nop 1
	v_cndmask_b32_e32 v183, v183, v181, vcc
	v_rsq_f32_e32 v183, v183
	s_nop 0
	v_mul_f32_e32 v181, 0x45800000, v183
	v_cndmask_b32_e32 v184, v183, v181, vcc
	v_mov_b32_e32 v185, v184
	v_cvt_pk_bf16_f32 v96, v144, v145
	v_cvt_pk_bf16_f32 v97, v146, v147
	v_cvt_pk_bf16_f32 v98, v148, v149
	v_cvt_pk_bf16_f32 v99, v150, v151
	v_cvt_pk_bf16_f32 v100, v152, v153
	v_cvt_pk_bf16_f32 v101, v154, v155
	v_cvt_pk_bf16_f32 v102, v156, v157
	v_cvt_pk_bf16_f32 v103, v158, v159
	v_add_u32_e32 v181, 0x1b00000, v177
	global_store_dwordx4 v181, v[96:99], s[78:79]
	global_store_dwordx4 v181, v[100:103], s[78:79] offset:1024
	v_add_u32_e32 v236, 0x1800, v237
	s_mov_b64 exec, 1
	global_store_dword v236, v184, s[78:79]
	s_mov_b64 exec, -1
	s_waitcnt vmcnt(0)
	v_lshlrev_b32_e32 v144, 16, v112
	v_and_b32_e32 v145, 0xffff0000, v112
	v_lshlrev_b32_e32 v146, 16, v113
	v_and_b32_e32 v147, 0xffff0000, v113
	v_lshlrev_b32_e32 v148, 16, v114
	v_and_b32_e32 v149, 0xffff0000, v114
	v_lshlrev_b32_e32 v150, 16, v115
	v_and_b32_e32 v151, 0xffff0000, v115
	v_lshlrev_b32_e32 v152, 16, v116
	v_and_b32_e32 v153, 0xffff0000, v116
	v_lshlrev_b32_e32 v154, 16, v117
	v_and_b32_e32 v155, 0xffff0000, v117
	v_lshlrev_b32_e32 v156, 16, v118
	v_and_b32_e32 v157, 0xffff0000, v118
	v_lshlrev_b32_e32 v158, 16, v119
	v_and_b32_e32 v159, 0xffff0000, v119
	v_lshlrev_b32_e32 v160, 16, v120
	v_and_b32_e32 v161, 0xffff0000, v120
	v_lshlrev_b32_e32 v162, 16, v121
	v_and_b32_e32 v163, 0xffff0000, v121
	v_lshlrev_b32_e32 v164, 16, v122
	v_and_b32_e32 v165, 0xffff0000, v122
	v_lshlrev_b32_e32 v166, 16, v123
	v_and_b32_e32 v167, 0xffff0000, v123
	v_lshlrev_b32_e32 v168, 16, v124
	v_and_b32_e32 v169, 0xffff0000, v124
	v_lshlrev_b32_e32 v170, 16, v125
	v_and_b32_e32 v171, 0xffff0000, v125
	v_lshlrev_b32_e32 v172, 16, v126
	v_and_b32_e32 v173, 0xffff0000, v126
	v_lshlrev_b32_e32 v174, 16, v127
	v_and_b32_e32 v175, 0xffff0000, v127
	v_pk_mul_f32 v[252:253], v[160:161], v[160:161]
	v_pk_mul_f32 v[254:255], v[162:163], v[162:163]
	v_pk_fma_f32 v[252:253], v[164:165], v[164:165], v[252:253]
	v_pk_fma_f32 v[254:255], v[166:167], v[166:167], v[254:255]
	v_pk_fma_f32 v[252:253], v[168:169], v[168:169], v[252:253]
	v_pk_fma_f32 v[254:255], v[170:171], v[170:171], v[254:255]
	v_pk_fma_f32 v[252:253], v[172:173], v[172:173], v[252:253]
	v_pk_fma_f32 v[254:255], v[174:175], v[174:175], v[254:255]
	v_pk_add_f32 v[252:253], v[252:253], v[254:255]
	s_nop 0
	v_add_f32_e32 v183, v252, v253
	s_nop 1
	v_add_f32_dpp v183, v183, v183 quad_perm:[1,0,3,2] row_mask:0xf bank_mask:0xf bound_ctrl:1
	s_nop 1
	v_add_f32_dpp v183, v183, v183 quad_perm:[2,3,0,1] row_mask:0xf bank_mask:0xf bound_ctrl:1
	s_nop 1
	v_add_f32_dpp v183, v183, v183 row_half_mirror row_mask:0xf bank_mask:0xf bound_ctrl:1
	s_nop 1
	v_add_f32_dpp v183, v183, v183 row_mirror row_mask:0xf bank_mask:0xf bound_ctrl:1
	s_nop 1
	v_readlane_b32 s98, v183, 0
	v_readlane_b32 s99, v183, 16
	v_readlane_b32 s100, v183, 32
	v_readlane_b32 s101, v183, 48
	s_nop 1
	v_mov_b32_e32 v183, s98
	v_add_f32_e32 v183, s99, v183
	v_add_f32_e32 v183, s100, v183
	v_add_f32_e32 v183, s101, v183
	v_fmamk_f32 v183, v183, 0x3a800000, v182
	v_cmp_gt_f32_e32 vcc, 0x800000, v183
	v_mul_f32_e32 v181, 0x4b800000, v183
	s_nop 1
	v_cndmask_b32_e32 v183, v183, v181, vcc
	v_rsq_f32_e32 v183, v183
	s_nop 0
	v_mul_f32_e32 v181, 0x45800000, v183
	v_cndmask_b32_e32 v184, v183, v181, vcc
	v_mov_b32_e32 v185, v184
	v_pk_mul_f32 v[160:161], v[160:161], v[184:185]
	v_pk_mul_f32 v[162:163], v[162:163], v[184:185]
	v_pk_mul_f32 v[164:165], v[164:165], v[184:185]
	v_pk_mul_f32 v[166:167], v[166:167], v[184:185]
	v_pk_mul_f32 v[168:169], v[168:169], v[184:185]
	v_pk_mul_f32 v[170:171], v[170:171], v[184:185]
	v_pk_mul_f32 v[172:173], v[172:173], v[184:185]
	v_pk_mul_f32 v[174:175], v[174:175], v[184:185]
	v_pk_fma_f32 v[144:145], v[160:161], v[128:129], v[144:145]
	v_pk_fma_f32 v[146:147], v[162:163], v[130:131], v[146:147]
	v_pk_fma_f32 v[148:149], v[164:165], v[132:133], v[148:149]
	v_pk_fma_f32 v[150:151], v[166:167], v[134:135], v[150:151]
	v_pk_fma_f32 v[152:153], v[168:169], v[136:137], v[152:153]
	v_pk_fma_f32 v[154:155], v[170:171], v[138:139], v[154:155]
	v_pk_fma_f32 v[156:157], v[172:173], v[140:141], v[156:157]
	v_pk_fma_f32 v[158:159], v[174:175], v[142:143], v[158:159]
	v_pk_mul_f32 v[252:253], v[144:145], v[144:145]
	v_pk_mul_f32 v[254:255], v[146:147], v[146:147]
	v_pk_fma_f32 v[252:253], v[148:149], v[148:149], v[252:253]
	v_pk_fma_f32 v[254:255], v[150:151], v[150:151], v[254:255]
	v_pk_fma_f32 v[252:253], v[152:153], v[152:153], v[252:253]
	v_pk_fma_f32 v[254:255], v[154:155], v[154:155], v[254:255]
	v_pk_fma_f32 v[252:253], v[156:157], v[156:157], v[252:253]
	v_pk_fma_f32 v[254:255], v[158:159], v[158:159], v[254:255]
	v_pk_add_f32 v[252:253], v[252:253], v[254:255]
	s_nop 0
	v_add_f32_e32 v183, v252, v253
	s_nop 1
	v_add_f32_dpp v183, v183, v183 quad_perm:[1,0,3,2] row_mask:0xf bank_mask:0xf bound_ctrl:1
	s_nop 1
	v_add_f32_dpp v183, v183, v183 quad_perm:[2,3,0,1] row_mask:0xf bank_mask:0xf bound_ctrl:1
	s_nop 1
	v_add_f32_dpp v183, v183, v183 row_half_mirror row_mask:0xf bank_mask:0xf bound_ctrl:1
	s_nop 1
	v_add_f32_dpp v183, v183, v183 row_mirror row_mask:0xf bank_mask:0xf bound_ctrl:1
	s_nop 1
	v_readlane_b32 s98, v183, 0
	v_readlane_b32 s99, v183, 16
	v_readlane_b32 s100, v183, 32
	v_readlane_b32 s101, v183, 48
	s_nop 1
	v_mov_b32_e32 v183, s98
	v_add_f32_e32 v183, s99, v183
	v_add_f32_e32 v183, s100, v183
	v_add_f32_e32 v183, s101, v183
	v_fmamk_f32 v183, v183, 0x3a800000, v182
	v_cmp_gt_f32_e32 vcc, 0x800000, v183
	v_mul_f32_e32 v181, 0x4b800000, v183
	s_nop 1
	v_cndmask_b32_e32 v183, v183, v181, vcc
	v_rsq_f32_e32 v183, v183
	s_nop 0
	v_mul_f32_e32 v181, 0x45800000, v183
	v_cndmask_b32_e32 v184, v183, v181, vcc
	v_mov_b32_e32 v185, v184
	v_cvt_pk_bf16_f32 v112, v144, v145
	v_cvt_pk_bf16_f32 v113, v146, v147
	v_cvt_pk_bf16_f32 v114, v148, v149
	v_cvt_pk_bf16_f32 v115, v150, v151
	v_cvt_pk_bf16_f32 v116, v152, v153
	v_cvt_pk_bf16_f32 v117, v154, v155
	v_cvt_pk_bf16_f32 v118, v156, v157
	v_cvt_pk_bf16_f32 v119, v158, v159
	v_add_u32_e32 v181, 0x1b80000, v177
	global_store_dwordx4 v181, v[112:115], s[78:79]
	global_store_dwordx4 v181, v[116:119], s[78:79] offset:1024
	v_add_u32_e32 v236, 0x1c00, v237
	s_mov_b64 exec, 1
	global_store_dword v236, v184, s[78:79]
	s_mov_b64 exec, -1
	v_readfirstlane_b32 s98, v179
	s_nop 3
	s_cmp_ge_u32 s98, 512
	s_cbranch_scc1 .Lmyxupd_done_3
	v_lshlrev_b32_e32 v177, 4, v176
	v_lshl_add_u32 v177, v179, 11, v177
	v_lshlrev_b32_e32 v237, 2, v179
	v_add_u32_e32 v237, 0x10000, v237
	v_add_u32_e32 v181, 0x3800000, v177
	global_load_dwordx4 v[0:3], v181, s[78:79]
	global_load_dwordx4 v[4:7], v181, s[78:79] offset:1024
	v_lshl_add_u32 v183, v179, 12, v180
	v_add_u32_e32 v183, 0xbf00000, v183
	v_add_u32_e32 v181, 0x0, v183
	global_load_dwordx4 v[8:11], v181, s[78:79]
	global_load_dwordx4 v[12:15], v181, s[78:79] offset:16
	global_load_dwordx4 v[16:19], v181, s[78:79] offset:2048
	global_load_dwordx4 v[20:23], v181, s[78:79] offset:2064
	v_add_u32_e32 v181, 0x200000, v183
	global_load_dwordx4 v[24:27], v181, s[78:79]
	global_load_dwordx4 v[28:31], v181, s[78:79] offset:16
	global_load_dwordx4 v[32:35], v181, s[78:79] offset:2048
	global_load_dwordx4 v[36:39], v181, s[78:79] offset:2064
	v_add_u32_e32 v181, 0x400000, v183
	global_load_dwordx4 v[40:43], v181, s[78:79]
	global_load_dwordx4 v[44:47], v181, s[78:79] offset:16
	global_load_dwordx4 v[48:51], v181, s[78:79] offset:2048
	global_load_dwordx4 v[52:55], v181, s[78:79] offset:2064
	v_add_u32_e32 v181, 0x600000, v183
	global_load_dwordx4 v[56:59], v181, s[78:79]
	global_load_dwordx4 v[60:63], v181, s[78:79] offset:16
	global_load_dwordx4 v[64:67], v181, s[78:79] offset:2048
	global_load_dwordx4 v[68:71], v181, s[78:79] offset:2064
	v_add_u32_e32 v181, 0x800000, v183
	global_load_dwordx4 v[72:75], v181, s[78:79]
	global_load_dwordx4 v[76:79], v181, s[78:79] offset:16
	global_load_dwordx4 v[80:83], v181, s[78:79] offset:2048
	global_load_dwordx4 v[84:87], v181, s[78:79] offset:2064
	v_add_u32_e32 v181, 0xa00000, v183
	global_load_dwordx4 v[88:91], v181, s[78:79]
	global_load_dwordx4 v[92:95], v181, s[78:79] offset:16
	global_load_dwordx4 v[96:99], v181, s[78:79] offset:2048
	global_load_dwordx4 v[100:103], v181, s[78:79] offset:2064
	s_waitcnt vmcnt(20)
	v_pk_add_f32 v[160:161], v[8:9], 0 op_sel_hi:[1,0]
	v_pk_add_f32 v[162:163], v[10:11], 0 op_sel_hi:[1,0]
	v_pk_add_f32 v[164:165], v[12:13], 0 op_sel_hi:[1,0]
	v_pk_add_f32 v[166:167], v[14:15], 0 op_sel_hi:[1,0]
	v_pk_add_f32 v[168:169], v[16:17], 0 op_sel_hi:[1,0]
	v_pk_add_f32 v[170:171], v[18:19], 0 op_sel_hi:[1,0]
	v_pk_add_f32 v[172:173], v[20:21], 0 op_sel_hi:[1,0]
	v_pk_add_f32 v[174:175], v[22:23], 0 op_sel_hi:[1,0]
	s_waitcnt vmcnt(16)
	v_pk_add_f32 v[160:161], v[160:161], v[24:25]
	v_pk_add_f32 v[162:163], v[162:163], v[26:27]
	v_pk_add_f32 v[164:165], v[164:165], v[28:29]
	v_pk_add_f32 v[166:167], v[166:167], v[30:31]
	v_pk_add_f32 v[168:169], v[168:169], v[32:33]
	v_pk_add_f32 v[170:171], v[170:171], v[34:35]
	v_pk_add_f32 v[172:173], v[172:173], v[36:37]
	v_pk_add_f32 v[174:175], v[174:175], v[38:39]
	s_waitcnt vmcnt(12)
	v_pk_add_f32 v[160:161], v[160:161], v[40:41]
	v_pk_add_f32 v[162:163], v[162:163], v[42:43]
	v_pk_add_f32 v[164:165], v[164:165], v[44:45]
	v_pk_add_f32 v[166:167], v[166:167], v[46:47]
	v_pk_add_f32 v[168:169], v[168:169], v[48:49]
	v_pk_add_f32 v[170:171], v[170:171], v[50:51]
	v_pk_add_f32 v[172:173], v[172:173], v[52:53]
	v_pk_add_f32 v[174:175], v[174:175], v[54:55]
	s_waitcnt vmcnt(8)
	v_pk_add_f32 v[160:161], v[160:161], v[56:57]
	v_pk_add_f32 v[162:163], v[162:163], v[58:59]
	v_pk_add_f32 v[164:165], v[164:165], v[60:61]
	v_pk_add_f32 v[166:167], v[166:167], v[62:63]
	v_pk_add_f32 v[168:169], v[168:169], v[64:65]
	v_pk_add_f32 v[170:171], v[170:171], v[66:67]
	v_pk_add_f32 v[172:173], v[172:173], v[68:69]
	v_pk_add_f32 v[174:175], v[174:175], v[70:71]
	s_waitcnt vmcnt(4)
	v_pk_add_f32 v[160:161], v[160:161], v[72:73]
	v_pk_add_f32 v[162:163], v[162:163], v[74:75]
	v_pk_add_f32 v[164:165], v[164:165], v[76:77]
	v_pk_add_f32 v[166:167], v[166:167], v[78:79]
	v_pk_add_f32 v[168:169], v[168:169], v[80:81]
	v_pk_add_f32 v[170:171], v[170:171], v[82:83]
	v_pk_add_f32 v[172:173], v[172:173], v[84:85]
	v_pk_add_f32 v[174:175], v[174:175], v[86:87]
	s_waitcnt vmcnt(0)
	v_pk_add_f32 v[160:161], v[160:161], v[88:89]
	v_pk_add_f32 v[162:163], v[162:163], v[90:91]
	v_pk_add_f32 v[164:165], v[164:165], v[92:93]
	v_pk_add_f32 v[166:167], v[166:167], v[94:95]
	v_pk_add_f32 v[168:169], v[168:169], v[96:97]
	v_pk_add_f32 v[170:171], v[170:171], v[98:99]
	v_pk_add_f32 v[172:173], v[172:173], v[100:101]
	v_pk_add_f32 v[174:175], v[174:175], v[102:103]
	v_lshlrev_b32_e32 v144, 16, v0
	v_and_b32_e32 v145, 0xffff0000, v0
	v_lshlrev_b32_e32 v146, 16, v1
	v_and_b32_e32 v147, 0xffff0000, v1
	v_lshlrev_b32_e32 v148, 16, v2
	v_and_b32_e32 v149, 0xffff0000, v2
	v_lshlrev_b32_e32 v150, 16, v3
	v_and_b32_e32 v151, 0xffff0000, v3
	v_lshlrev_b32_e32 v152, 16, v4
	v_and_b32_e32 v153, 0xffff0000, v4
	v_lshlrev_b32_e32 v154, 16, v5
	v_and_b32_e32 v155, 0xffff0000, v5
	v_lshlrev_b32_e32 v156, 16, v6
	v_and_b32_e32 v157, 0xffff0000, v6
	v_lshlrev_b32_e32 v158, 16, v7
	v_and_b32_e32 v159, 0xffff0000, v7
	v_add_u32_e32 v181, 0xc00000, v183
	global_load_dwordx4 v[8:11], v181, s[78:79]
	global_load_dwordx4 v[12:15], v181, s[78:79] offset:16
	global_load_dwordx4 v[16:19], v181, s[78:79] offset:2048
	global_load_dwordx4 v[20:23], v181, s[78:79] offset:2064
	v_add_u32_e32 v181, 0xe00000, v183
	global_load_dwordx4 v[24:27], v181, s[78:79]
	global_load_dwordx4 v[28:31], v181, s[78:79] offset:16
	global_load_dwordx4 v[32:35], v181, s[78:79] offset:2048
	global_load_dwordx4 v[36:39], v181, s[78:79] offset:2064
	v_add_u32_e32 v181, 0x1000000, v183
	global_load_dwordx4 v[40:43], v181, s[78:79]
	global_load_dwordx4 v[44:47], v181, s[78:79] offset:16
	global_load_dwordx4 v[48:51], v181, s[78:79] offset:2048
	global_load_dwordx4 v[52:55], v181, s[78:79] offset:2064
	v_add_u32_e32 v181, 0x1200000, v183
	global_load_dwordx4 v[56:59], v181, s[78:79]
	global_load_dwordx4 v[60:63], v181, s[78:79] offset:16
	global_load_dwordx4 v[64:67], v181, s[78:79] offset:2048
	global_load_dwordx4 v[68:71], v181, s[78:79] offset:2064
	v_add_u32_e32 v181, 0x1400000, v183
	global_load_dwordx4 v[72:75], v181, s[78:79]
	global_load_dwordx4 v[76:79], v181, s[78:79] offset:16
	global_load_dwordx4 v[80:83], v181, s[78:79] offset:2048
	global_load_dwordx4 v[84:87], v181, s[78:79] offset:2064
	s_waitcnt vmcnt(16)
	v_pk_add_f32 v[160:161], v[160:161], v[8:9]
	v_pk_add_f32 v[162:163], v[162:163], v[10:11]
	v_pk_add_f32 v[164:165], v[164:165], v[12:13]
	v_pk_add_f32 v[166:167], v[166:167], v[14:15]
	v_pk_add_f32 v[168:169], v[168:169], v[16:17]
	v_pk_add_f32 v[170:171], v[170:171], v[18:19]
	v_pk_add_f32 v[172:173], v[172:173], v[20:21]
	v_pk_add_f32 v[174:175], v[174:175], v[22:23]
	s_waitcnt vmcnt(12)
	v_pk_add_f32 v[160:161], v[160:161], v[24:25]
	v_pk_add_f32 v[162:163], v[162:163], v[26:27]
	v_pk_add_f32 v[164:165], v[164:165], v[28:29]
	v_pk_add_f32 v[166:167], v[166:167], v[30:31]
	v_pk_add_f32 v[168:169], v[168:169], v[32:33]
	v_pk_add_f32 v[170:171], v[170:171], v[34:35]
	v_pk_add_f32 v[172:173], v[172:173], v[36:37]
	v_pk_add_f32 v[174:175], v[174:175], v[38:39]
	s_waitcnt vmcnt(8)
	v_pk_add_f32 v[160:161], v[160:161], v[40:41]
	v_pk_add_f32 v[162:163], v[162:163], v[42:43]
	v_pk_add_f32 v[164:165], v[164:165], v[44:45]
	v_pk_add_f32 v[166:167], v[166:167], v[46:47]
	v_pk_add_f32 v[168:169], v[168:169], v[48:49]
	v_pk_add_f32 v[170:171], v[170:171], v[50:51]
	v_pk_add_f32 v[172:173], v[172:173], v[52:53]
	v_pk_add_f32 v[174:175], v[174:175], v[54:55]
	s_waitcnt vmcnt(4)
	v_pk_add_f32 v[160:161], v[160:161], v[56:57]
	v_pk_add_f32 v[162:163], v[162:163], v[58:59]
	v_pk_add_f32 v[164:165], v[164:165], v[60:61]
	v_pk_add_f32 v[166:167], v[166:167], v[62:63]
	v_pk_add_f32 v[168:169], v[168:169], v[64:65]
	v_pk_add_f32 v[170:171], v[170:171], v[66:67]
	v_pk_add_f32 v[172:173], v[172:173], v[68:69]
	v_pk_add_f32 v[174:175], v[174:175], v[70:71]
	s_waitcnt vmcnt(0)
	v_pk_add_f32 v[160:161], v[160:161], v[72:73]
	v_pk_add_f32 v[162:163], v[162:163], v[74:75]
	v_pk_add_f32 v[164:165], v[164:165], v[76:77]
	v_pk_add_f32 v[166:167], v[166:167], v[78:79]
	v_pk_add_f32 v[168:169], v[168:169], v[80:81]
	v_pk_add_f32 v[170:171], v[170:171], v[82:83]
	v_pk_add_f32 v[172:173], v[172:173], v[84:85]
	v_pk_add_f32 v[174:175], v[174:175], v[86:87]
	v_pk_mul_f32 v[252:253], v[160:161], v[160:161]
	v_pk_mul_f32 v[254:255], v[162:163], v[162:163]
	v_pk_fma_f32 v[252:253], v[164:165], v[164:165], v[252:253]
	v_pk_fma_f32 v[254:255], v[166:167], v[166:167], v[254:255]
	v_pk_fma_f32 v[252:253], v[168:169], v[168:169], v[252:253]
	v_pk_fma_f32 v[254:255], v[170:171], v[170:171], v[254:255]
	v_pk_fma_f32 v[252:253], v[172:173], v[172:173], v[252:253]
	v_pk_fma_f32 v[254:255], v[174:175], v[174:175], v[254:255]
	v_pk_add_f32 v[252:253], v[252:253], v[254:255]
	s_nop 0
	v_add_f32_e32 v183, v252, v253
	s_nop 1
	v_add_f32_dpp v183, v183, v183 quad_perm:[1,0,3,2] row_mask:0xf bank_mask:0xf bound_ctrl:1
	s_nop 1
	v_add_f32_dpp v183, v183, v183 quad_perm:[2,3,0,1] row_mask:0xf bank_mask:0xf bound_ctrl:1
	s_nop 1
	v_add_f32_dpp v183, v183, v183 row_half_mirror row_mask:0xf bank_mask:0xf bound_ctrl:1
	s_nop 1
	v_add_f32_dpp v183, v183, v183 row_mirror row_mask:0xf bank_mask:0xf bound_ctrl:1
	s_nop 1
	v_readlane_b32 s98, v183, 0
	v_readlane_b32 s99, v183, 16
	v_readlane_b32 s100, v183, 32
	v_readlane_b32 s101, v183, 48
	s_nop 1
	v_mov_b32_e32 v183, s98
	v_add_f32_e32 v183, s99, v183
	v_add_f32_e32 v183, s100, v183
	v_add_f32_e32 v183, s101, v183
	v_fmamk_f32 v183, v183, 0x3a800000, v182
	v_cmp_gt_f32_e32 vcc, 0x800000, v183
	v_mul_f32_e32 v181, 0x4b800000, v183
	s_nop 1
	v_cndmask_b32_e32 v183, v183, v181, vcc
	v_rsq_f32_e32 v183, v183
	s_nop 0
	v_mul_f32_e32 v181, 0x45800000, v183
	v_cndmask_b32_e32 v184, v183, v181, vcc
	v_mov_b32_e32 v185, v184
	v_pk_mul_f32 v[160:161], v[160:161], v[184:185]
	v_pk_mul_f32 v[162:163], v[162:163], v[184:185]
	v_pk_mul_f32 v[164:165], v[164:165], v[184:185]
	v_pk_mul_f32 v[166:167], v[166:167], v[184:185]
	v_pk_mul_f32 v[168:169], v[168:169], v[184:185]
	v_pk_mul_f32 v[170:171], v[170:171], v[184:185]
	v_pk_mul_f32 v[172:173], v[172:173], v[184:185]
	v_pk_mul_f32 v[174:175], v[174:175], v[184:185]
	v_pk_fma_f32 v[144:145], v[160:161], v[128:129], v[144:145]
	v_pk_fma_f32 v[146:147], v[162:163], v[130:131], v[146:147]
	v_pk_fma_f32 v[148:149], v[164:165], v[132:133], v[148:149]
	v_pk_fma_f32 v[150:151], v[166:167], v[134:135], v[150:151]
	v_pk_fma_f32 v[152:153], v[168:169], v[136:137], v[152:153]
	v_pk_fma_f32 v[154:155], v[170:171], v[138:139], v[154:155]
	v_pk_fma_f32 v[156:157], v[172:173], v[140:141], v[156:157]
	v_pk_fma_f32 v[158:159], v[174:175], v[142:143], v[158:159]
	v_pk_mul_f32 v[252:253], v[144:145], v[144:145]
	v_pk_mul_f32 v[254:255], v[146:147], v[146:147]
	v_pk_fma_f32 v[252:253], v[148:149], v[148:149], v[252:253]
	v_pk_fma_f32 v[254:255], v[150:151], v[150:151], v[254:255]
	v_pk_fma_f32 v[252:253], v[152:153], v[152:153], v[252:253]
	v_pk_fma_f32 v[254:255], v[154:155], v[154:155], v[254:255]
	v_pk_fma_f32 v[252:253], v[156:157], v[156:157], v[252:253]
	v_pk_fma_f32 v[254:255], v[158:159], v[158:159], v[254:255]
	v_pk_add_f32 v[252:253], v[252:253], v[254:255]
	s_nop 0
	v_add_f32_e32 v183, v252, v253
	s_nop 1
	v_add_f32_dpp v183, v183, v183 quad_perm:[1,0,3,2] row_mask:0xf bank_mask:0xf bound_ctrl:1
	s_nop 1
	v_add_f32_dpp v183, v183, v183 quad_perm:[2,3,0,1] row_mask:0xf bank_mask:0xf bound_ctrl:1
	s_nop 1
	v_add_f32_dpp v183, v183, v183 row_half_mirror row_mask:0xf bank_mask:0xf bound_ctrl:1
	s_nop 1
	v_add_f32_dpp v183, v183, v183 row_mirror row_mask:0xf bank_mask:0xf bound_ctrl:1
	s_nop 1
	v_readlane_b32 s98, v183, 0
	v_readlane_b32 s99, v183, 16
	v_readlane_b32 s100, v183, 32
	v_readlane_b32 s101, v183, 48
	s_nop 1
	v_mov_b32_e32 v183, s98
	v_add_f32_e32 v183, s99, v183
	v_add_f32_e32 v183, s100, v183
	v_add_f32_e32 v183, s101, v183
	v_fmamk_f32 v183, v183, 0x3a800000, v182
	v_cmp_gt_f32_e32 vcc, 0x800000, v183
	v_mul_f32_e32 v181, 0x4b800000, v183
	s_nop 1
	v_cndmask_b32_e32 v183, v183, v181, vcc
	v_rsq_f32_e32 v183, v183
	s_nop 0
	v_mul_f32_e32 v181, 0x45800000, v183
	v_cndmask_b32_e32 v184, v183, v181, vcc
	v_mov_b32_e32 v185, v184
	v_cvt_pk_bf16_f32 v0, v144, v145
	v_cvt_pk_bf16_f32 v1, v146, v147
	v_cvt_pk_bf16_f32 v2, v148, v149
	v_cvt_pk_bf16_f32 v3, v150, v151
	v_cvt_pk_bf16_f32 v4, v152, v153
	v_cvt_pk_bf16_f32 v5, v154, v155
	v_cvt_pk_bf16_f32 v6, v156, v157
	v_cvt_pk_bf16_f32 v7, v158, v159
	v_add_u32_e32 v181, 0x3800000, v177
	global_store_dwordx4 v181, v[0:3], s[78:79]
	global_store_dwordx4 v181, v[4:7], s[78:79] offset:1024
	v_add_u32_e32 v236, 0x10000, v237
	s_mov_b64 exec, 1
	global_store_dword v236, v184, s[78:79]
	s_mov_b64 exec, -1

.LBB0_1863:
	v_readlane_b32 s0, v235, 52
	v_readlane_b32 s1, v235, 53
	s_and_b64 vcc, exec, s[0:1]
	s_waitcnt lgkmcnt(0)
	s_barrier
	v_mbcnt_lo_u32_b32 v0, -1, 0
	v_mbcnt_hi_u32_b32 v0, -1, v0
	s_cbranch_vccnz .LBB0_1883
	v_lshlrev_b32_e32 v2, 3, v0
	v_ashrrev_i32_e32 v3, 31, v2
	v_readlane_b32 s4, v235, 4
	v_lshlrev_b64 v[4:5], 1, v[2:3]
	v_lshlrev_b64 v[2:3], 2, v[2:3]
	v_readlane_b32 s14, v235, 14
	v_readlane_b32 s15, v235, 15
	v_lshl_add_u64 v[62:63], s[90:91], 0, v[2:3]
	v_readlane_b32 s5, v235, 5
	v_readlane_b32 s6, v235, 6
	v_readlane_b32 s7, v235, 7
	v_readlane_b32 s8, v235, 8
	v_readlane_b32 s9, v235, 9
	v_readlane_b32 s10, v235, 10
	v_readlane_b32 s11, v235, 11
	v_readlane_b32 s12, v235, 12
	v_readlane_b32 s13, v235, 13
	v_readlane_b32 s16, v235, 16
	v_readlane_b32 s17, v235, 17
	v_readlane_b32 s18, v235, 18
	v_readlane_b32 s19, v235, 19
	v_lshl_add_u64 v[2:3], s[14:15], 0, v[2:3]
	s_mov_b64 s[0:1], 0x2000
	v_lshl_add_u64 v[60:61], s[86:87], 0, v[4:5]
	v_lshl_add_u64 v[64:65], s[54:55], 0, v[4:5]
	v_lshl_add_u64 v[66:67], v[2:3], 0, s[0:1]
	s_mov_b32 s1, 0
	v_cmp_eq_u32_e64 s[16:17], 0, v0
	s_mov_b64 s[4:5], 0x200000
	s_mov_b64 s[6:7], 0x200800
	s_mov_b64 s[8:9], 0x400000
	s_mov_b64 s[10:11], 0x400800
	s_mov_b64 s[12:13], 0x600000
	s_mov_b64 s[14:15], 0x600800
	s_mov_b64 s[18:19], 0x800000
	s_mov_b32 s48, 0x800000
	s_mov_b64 s[20:21], 0x800800
	s_mov_b64 s[22:23], 0xa00000
	s_mov_b64 s[24:25], 0xa00800
	s_mov_b64 s[26:27], 0xc00000
	s_mov_b64 s[28:29], 0xc00800
	s_mov_b64 s[36:37], 0xe00000
	s_mov_b64 s[38:39], 0xe00800
	v_mov_b32_e32 v104, 0
	v_mov_b32_e32 v105, 0x358637bd
	v_readlane_b32 s42, v235, 61
	v_readlane_b32 s43, v235, 62
	v_mbcnt_lo_u32_b32 v176, -1, 0
	v_mbcnt_hi_u32_b32 v176, -1, v176
	v_readlane_b32 s98, v235, 49
	v_readlane_b32 s99, v235, 20
	v_readlane_b32 s100, v235, 14
	v_readlane_b32 s101, v235, 15
	s_nop 3
	s_lshr_b32 vcc_lo, s98, 3
	s_and_b32 vcc_hi, vcc_lo, 7
	s_lshr_b32 vcc_lo, vcc_lo, 3
	s_lshl_b32 vcc_lo, vcc_lo, 3
	s_add_i32 vcc_lo, vcc_lo, s99
	s_lshl_b32 s98, vcc_hi, 8
	s_add_i32 s98, s98, vcc_lo
	s_lshl_b32 s99, vcc_hi, 11
	s_add_i32 s99, s99, vcc_lo
	v_mov_b32_e32 v183, s99
	v_lshlrev_b32_e32 v177, 4, v176
	s_lshl_b32 s99, s99, 11
	v_add_u32_e32 v177, s99, v177
	v_add_u32_e32 v178, 0x1800000, v177
	v_add_u32_e32 v179, 0x9e00000, v177
	v_lshlrev_b32_e32 v180, 5, v176
	v_add_u32_e32 v181, 0x2000, v180
	global_load_dwordx4 v[128:131], v181, s[100:101]
	global_load_dwordx4 v[132:135], v181, s[100:101] offset:16
	global_load_dwordx4 v[136:139], v181, s[100:101] offset:2048
	global_load_dwordx4 v[140:143], v181, s[100:101] offset:2064
	v_mov_b32_e32 v182, 0x358637bd
	global_load_dwordx4 v[0:3], v178, s[78:79]
	global_load_dwordx4 v[4:7], v178, s[78:79] offset:1024
	global_load_dwordx4 v[8:11], v179, s[78:79]
	global_load_dwordx4 v[12:15], v179, s[78:79] offset:1024
	v_add_u32_e32 v178, 0x80000, v178
	v_add_u32_e32 v179, 0x80000, v179
	global_load_dwordx4 v[16:19], v178, s[78:79]
	global_load_dwordx4 v[20:23], v178, s[78:79] offset:1024
	global_load_dwordx4 v[24:27], v179, s[78:79]
	global_load_dwordx4 v[28:31], v179, s[78:79] offset:1024
	v_add_u32_e32 v178, 0x80000, v178
	v_add_u32_e32 v179, 0x80000, v179
	global_load_dwordx4 v[32:35], v178, s[78:79]
	global_load_dwordx4 v[36:39], v178, s[78:79] offset:1024
	global_load_dwordx4 v[40:43], v179, s[78:79]
	global_load_dwordx4 v[44:47], v179, s[78:79] offset:1024
	v_add_u32_e32 v178, 0x80000, v178
	v_add_u32_e32 v179, 0x80000, v179
	global_load_dwordx4 v[48:51], v178, s[78:79]
	global_load_dwordx4 v[52:55], v178, s[78:79] offset:1024
	global_load_dwordx4 v[56:59], v179, s[78:79]
	global_load_dwordx4 v[60:63], v179, s[78:79] offset:1024
	v_add_u32_e32 v178, 0x80000, v178
	v_add_u32_e32 v179, 0x80000, v179
	global_load_dwordx4 v[64:67], v178, s[78:79]
	global_load_dwordx4 v[68:71], v178, s[78:79] offset:1024
	global_load_dwordx4 v[72:75], v179, s[78:79]
	global_load_dwordx4 v[76:79], v179, s[78:79] offset:1024
	v_add_u32_e32 v178, 0x80000, v178
	v_add_u32_e32 v179, 0x80000, v179
	global_load_dwordx4 v[80:83], v178, s[78:79]
	global_load_dwordx4 v[84:87], v178, s[78:79] offset:1024
	global_load_dwordx4 v[88:91], v179, s[78:79]
	global_load_dwordx4 v[92:95], v179, s[78:79] offset:1024
	v_add_u32_e32 v178, 0x80000, v178
	v_add_u32_e32 v179, 0x80000, v179
	global_load_dwordx4 v[96:99], v178, s[78:79]
	global_load_dwordx4 v[100:103], v178, s[78:79] offset:1024
	global_load_dwordx4 v[104:107], v179, s[78:79]
	global_load_dwordx4 v[108:111], v179, s[78:79] offset:1024
	v_add_u32_e32 v178, 0x80000, v178
	v_add_u32_e32 v179, 0x80000, v179
	global_load_dwordx4 v[112:115], v178, s[78:79]
	global_load_dwordx4 v[116:119], v178, s[78:79] offset:1024
	global_load_dwordx4 v[120:123], v179, s[78:79]
	global_load_dwordx4 v[124:127], v179, s[78:79] offset:1024
	v_lshlrev_b32_e32 v237, 2, v183
	v_add_u32_e32 v237, 0x10000, v237
	v_mov_b32_e32 v179, s98
	s_waitcnt vmcnt(28)
	v_lshlrev_b32_e32 v144, 16, v0
	v_and_b32_e32 v145, 0xffff0000, v0
	v_lshlrev_b32_e32 v146, 16, v1
	v_and_b32_e32 v147, 0xffff0000, v1
	v_lshlrev_b32_e32 v148, 16, v2
	v_and_b32_e32 v149, 0xffff0000, v2
	v_lshlrev_b32_e32 v150, 16, v3
	v_and_b32_e32 v151, 0xffff0000, v3
	v_lshlrev_b32_e32 v152, 16, v4
	v_and_b32_e32 v153, 0xffff0000, v4
	v_lshlrev_b32_e32 v154, 16, v5
	v_and_b32_e32 v155, 0xffff0000, v5
	v_lshlrev_b32_e32 v156, 16, v6
	v_and_b32_e32 v157, 0xffff0000, v6
	v_lshlrev_b32_e32 v158, 16, v7
	v_and_b32_e32 v159, 0xffff0000, v7
	v_lshlrev_b32_e32 v160, 16, v8
	v_and_b32_e32 v161, 0xffff0000, v8
	v_lshlrev_b32_e32 v162, 16, v9
	v_and_b32_e32 v163, 0xffff0000, v9
	v_lshlrev_b32_e32 v164, 16, v10
	v_and_b32_e32 v165, 0xffff0000, v10
	v_lshlrev_b32_e32 v166, 16, v11
	v_and_b32_e32 v167, 0xffff0000, v11
	v_lshlrev_b32_e32 v168, 16, v12
	v_and_b32_e32 v169, 0xffff0000, v12
	v_lshlrev_b32_e32 v170, 16, v13
	v_and_b32_e32 v171, 0xffff0000, v13
	v_lshlrev_b32_e32 v172, 16, v14
	v_and_b32_e32 v173, 0xffff0000, v14
	v_lshlrev_b32_e32 v174, 16, v15
	v_and_b32_e32 v175, 0xffff0000, v15
	v_pk_mul_f32 v[252:253], v[160:161], v[160:161]
	v_pk_mul_f32 v[254:255], v[162:163], v[162:163]
	v_pk_fma_f32 v[252:253], v[164:165], v[164:165], v[252:253]
	v_pk_fma_f32 v[254:255], v[166:167], v[166:167], v[254:255]
	v_pk_fma_f32 v[252:253], v[168:169], v[168:169], v[252:253]
	v_pk_fma_f32 v[254:255], v[170:171], v[170:171], v[254:255]
	v_pk_fma_f32 v[252:253], v[172:173], v[172:173], v[252:253]
	v_pk_fma_f32 v[254:255], v[174:175], v[174:175], v[254:255]
	v_pk_add_f32 v[252:253], v[252:253], v[254:255]
	s_nop 0
	v_add_f32_e32 v183, v252, v253
	s_nop 1
	v_add_f32_dpp v183, v183, v183 quad_perm:[1,0,3,2] row_mask:0xf bank_mask:0xf bound_ctrl:1
	s_nop 1
	v_add_f32_dpp v183, v183, v183 quad_perm:[2,3,0,1] row_mask:0xf bank_mask:0xf bound_ctrl:1
	s_nop 1
	v_add_f32_dpp v183, v183, v183 row_half_mirror row_mask:0xf bank_mask:0xf bound_ctrl:1
	s_nop 1
	v_add_f32_dpp v183, v183, v183 row_mirror row_mask:0xf bank_mask:0xf bound_ctrl:1
	s_nop 1
	v_readlane_b32 s98, v183, 0
	v_readlane_b32 s99, v183, 16
	v_readlane_b32 s100, v183, 32
	v_readlane_b32 s101, v183, 48
	s_nop 1
	v_mov_b32_e32 v183, s98
	v_add_f32_e32 v183, s99, v183
	v_add_f32_e32 v183, s100, v183
	v_add_f32_e32 v183, s101, v183
	v_fmamk_f32 v183, v183, 0x3a800000, v182
	v_cmp_gt_f32_e32 vcc, 0x800000, v183
	v_mul_f32_e32 v181, 0x4b800000, v183
	s_nop 1
	v_cndmask_b32_e32 v183, v183, v181, vcc
	v_rsq_f32_e32 v183, v183
	s_nop 0
	v_mul_f32_e32 v181, 0x45800000, v183
	v_cndmask_b32_e32 v184, v183, v181, vcc
	v_mov_b32_e32 v185, v184
	v_pk_mul_f32 v[160:161], v[160:161], v[184:185]
	v_pk_mul_f32 v[162:163], v[162:163], v[184:185]
	v_pk_mul_f32 v[164:165], v[164:165], v[184:185]
	v_pk_mul_f32 v[166:167], v[166:167], v[184:185]
	v_pk_mul_f32 v[168:169], v[168:169], v[184:185]
	v_pk_mul_f32 v[170:171], v[170:171], v[184:185]
	v_pk_mul_f32 v[172:173], v[172:173], v[184:185]
	v_pk_mul_f32 v[174:175], v[174:175], v[184:185]
	v_pk_fma_f32 v[144:145], v[160:161], v[128:129], v[144:145]
	v_pk_fma_f32 v[146:147], v[162:163], v[130:131], v[146:147]
	v_pk_fma_f32 v[148:149], v[164:165], v[132:133], v[148:149]
	v_pk_fma_f32 v[150:151], v[166:167], v[134:135], v[150:151]
	v_pk_fma_f32 v[152:153], v[168:169], v[136:137], v[152:153]
	v_pk_fma_f32 v[154:155], v[170:171], v[138:139], v[154:155]
	v_pk_fma_f32 v[156:157], v[172:173], v[140:141], v[156:157]
	v_pk_fma_f32 v[158:159], v[174:175], v[142:143], v[158:159]
	v_pk_mul_f32 v[252:253], v[144:145], v[144:145]
	v_pk_mul_f32 v[254:255], v[146:147], v[146:147]
	v_pk_fma_f32 v[252:253], v[148:149], v[148:149], v[252:253]
	v_pk_fma_f32 v[254:255], v[150:151], v[150:151], v[254:255]
	v_pk_fma_f32 v[252:253], v[152:153], v[152:153], v[252:253]
	v_pk_fma_f32 v[254:255], v[154:155], v[154:155], v[254:255]
	v_pk_fma_f32 v[252:253], v[156:157], v[156:157], v[252:253]
	v_pk_fma_f32 v[254:255], v[158:159], v[158:159], v[254:255]
	v_pk_add_f32 v[252:253], v[252:253], v[254:255]
	s_nop 0
	v_add_f32_e32 v183, v252, v253
	s_nop 1
	v_add_f32_dpp v183, v183, v183 quad_perm:[1,0,3,2] row_mask:0xf bank_mask:0xf bound_ctrl:1
	s_nop 1
	v_add_f32_dpp v183, v183, v183 quad_perm:[2,3,0,1] row_mask:0xf bank_mask:0xf bound_ctrl:1
	s_nop 1
	v_add_f32_dpp v183, v183, v183 row_half_mirror row_mask:0xf bank_mask:0xf bound_ctrl:1
	s_nop 1
	v_add_f32_dpp v183, v183, v183 row_mirror row_mask:0xf bank_mask:0xf bound_ctrl:1
	s_nop 1
	v_readlane_b32 s98, v183, 0
	v_readlane_b32 s99, v183, 16
	v_readlane_b32 s100, v183, 32
	v_readlane_b32 s101, v183, 48
	s_nop 1
	v_mov_b32_e32 v183, s98
	v_add_f32_e32 v183, s99, v183
	v_add_f32_e32 v183, s100, v183
	v_add_f32_e32 v183, s101, v183
	v_fmamk_f32 v183, v183, 0x3a800000, v182
	v_cmp_gt_f32_e32 vcc, 0x800000, v183
	v_mul_f32_e32 v181, 0x4b800000, v183
	s_nop 1
	v_cndmask_b32_e32 v183, v183, v181, vcc
	v_rsq_f32_e32 v183, v183
	s_nop 0
	v_mul_f32_e32 v181, 0x45800000, v183
	v_cndmask_b32_e32 v184, v183, v181, vcc
	v_mov_b32_e32 v185, v184
	v_cvt_pk_bf16_f32 v0, v144, v145
	v_cvt_pk_bf16_f32 v1, v146, v147
	v_cvt_pk_bf16_f32 v2, v148, v149
	v_cvt_pk_bf16_f32 v3, v150, v151
	v_cvt_pk_bf16_f32 v4, v152, v153
	v_cvt_pk_bf16_f32 v5, v154, v155
	v_cvt_pk_bf16_f32 v6, v156, v157
	v_cvt_pk_bf16_f32 v7, v158, v159
	v_add_u32_e32 v181, 0x1800000, v177
	global_store_dwordx4 v181, v[0:3], s[78:79]
	global_store_dwordx4 v181, v[4:7], s[78:79] offset:1024
	v_add_u32_e32 v236, 0x0, v237
	s_mov_b64 exec, 1
	global_store_dword v236, v184, s[78:79]
	s_mov_b64 exec, -1
	s_waitcnt vmcnt(24)
	v_lshlrev_b32_e32 v144, 16, v16
	v_and_b32_e32 v145, 0xffff0000, v16
	v_lshlrev_b32_e32 v146, 16, v17
	v_and_b32_e32 v147, 0xffff0000, v17
	v_lshlrev_b32_e32 v148, 16, v18
	v_and_b32_e32 v149, 0xffff0000, v18
	v_lshlrev_b32_e32 v150, 16, v19
	v_and_b32_e32 v151, 0xffff0000, v19
	v_lshlrev_b32_e32 v152, 16, v20
	v_and_b32_e32 v153, 0xffff0000, v20
	v_lshlrev_b32_e32 v154, 16, v21
	v_and_b32_e32 v155, 0xffff0000, v21
	v_lshlrev_b32_e32 v156, 16, v22
	v_and_b32_e32 v157, 0xffff0000, v22
	v_lshlrev_b32_e32 v158, 16, v23
	v_and_b32_e32 v159, 0xffff0000, v23
	v_lshlrev_b32_e32 v160, 16, v24
	v_and_b32_e32 v161, 0xffff0000, v24
	v_lshlrev_b32_e32 v162, 16, v25
	v_and_b32_e32 v163, 0xffff0000, v25
	v_lshlrev_b32_e32 v164, 16, v26
	v_and_b32_e32 v165, 0xffff0000, v26
	v_lshlrev_b32_e32 v166, 16, v27
	v_and_b32_e32 v167, 0xffff0000, v27
	v_lshlrev_b32_e32 v168, 16, v28
	v_and_b32_e32 v169, 0xffff0000, v28
	v_lshlrev_b32_e32 v170, 16, v29
	v_and_b32_e32 v171, 0xffff0000, v29
	v_lshlrev_b32_e32 v172, 16, v30
	v_and_b32_e32 v173, 0xffff0000, v30
	v_lshlrev_b32_e32 v174, 16, v31
	v_and_b32_e32 v175, 0xffff0000, v31
	v_pk_mul_f32 v[252:253], v[160:161], v[160:161]
	v_pk_mul_f32 v[254:255], v[162:163], v[162:163]
	v_pk_fma_f32 v[252:253], v[164:165], v[164:165], v[252:253]
	v_pk_fma_f32 v[254:255], v[166:167], v[166:167], v[254:255]
	v_pk_fma_f32 v[252:253], v[168:169], v[168:169], v[252:253]
	v_pk_fma_f32 v[254:255], v[170:171], v[170:171], v[254:255]
	v_pk_fma_f32 v[252:253], v[172:173], v[172:173], v[252:253]
	v_pk_fma_f32 v[254:255], v[174:175], v[174:175], v[254:255]
	v_pk_add_f32 v[252:253], v[252:253], v[254:255]
	s_nop 0
	v_add_f32_e32 v183, v252, v253
	s_nop 1
	v_add_f32_dpp v183, v183, v183 quad_perm:[1,0,3,2] row_mask:0xf bank_mask:0xf bound_ctrl:1
	s_nop 1
	v_add_f32_dpp v183, v183, v183 quad_perm:[2,3,0,1] row_mask:0xf bank_mask:0xf bound_ctrl:1
	s_nop 1
	v_add_f32_dpp v183, v183, v183 row_half_mirror row_mask:0xf bank_mask:0xf bound_ctrl:1
	s_nop 1
	v_add_f32_dpp v183, v183, v183 row_mirror row_mask:0xf bank_mask:0xf bound_ctrl:1
	s_nop 1
	v_readlane_b32 s98, v183, 0
	v_readlane_b32 s99, v183, 16
	v_readlane_b32 s100, v183, 32
	v_readlane_b32 s101, v183, 48
	s_nop 1
	v_mov_b32_e32 v183, s98
	v_add_f32_e32 v183, s99, v183
	v_add_f32_e32 v183, s100, v183
	v_add_f32_e32 v183, s101, v183
	v_fmamk_f32 v183, v183, 0x3a800000, v182
	v_cmp_gt_f32_e32 vcc, 0x800000, v183
	v_mul_f32_e32 v181, 0x4b800000, v183
	s_nop 1
	v_cndmask_b32_e32 v183, v183, v181, vcc
	v_rsq_f32_e32 v183, v183
	s_nop 0
	v_mul_f32_e32 v181, 0x45800000, v183
	v_cndmask_b32_e32 v184, v183, v181, vcc
	v_mov_b32_e32 v185, v184
	v_pk_mul_f32 v[160:161], v[160:161], v[184:185]
	v_pk_mul_f32 v[162:163], v[162:163], v[184:185]
	v_pk_mul_f32 v[164:165], v[164:165], v[184:185]
	v_pk_mul_f32 v[166:167], v[166:167], v[184:185]
	v_pk_mul_f32 v[168:169], v[168:169], v[184:185]
	v_pk_mul_f32 v[170:171], v[170:171], v[184:185]
	v_pk_mul_f32 v[172:173], v[172:173], v[184:185]
	v_pk_mul_f32 v[174:175], v[174:175], v[184:185]
	v_pk_fma_f32 v[144:145], v[160:161], v[128:129], v[144:145]
	v_pk_fma_f32 v[146:147], v[162:163], v[130:131], v[146:147]
	v_pk_fma_f32 v[148:149], v[164:165], v[132:133], v[148:149]
	v_pk_fma_f32 v[150:151], v[166:167], v[134:135], v[150:151]
	v_pk_fma_f32 v[152:153], v[168:169], v[136:137], v[152:153]
	v_pk_fma_f32 v[154:155], v[170:171], v[138:139], v[154:155]
	v_pk_fma_f32 v[156:157], v[172:173], v[140:141], v[156:157]
	v_pk_fma_f32 v[158:159], v[174:175], v[142:143], v[158:159]
	v_pk_mul_f32 v[252:253], v[144:145], v[144:145]
	v_pk_mul_f32 v[254:255], v[146:147], v[146:147]
	v_pk_fma_f32 v[252:253], v[148:149], v[148:149], v[252:253]
	v_pk_fma_f32 v[254:255], v[150:151], v[150:151], v[254:255]
	v_pk_fma_f32 v[252:253], v[152:153], v[152:153], v[252:253]
	v_pk_fma_f32 v[254:255], v[154:155], v[154:155], v[254:255]
	v_pk_fma_f32 v[252:253], v[156:157], v[156:157], v[252:253]
	v_pk_fma_f32 v[254:255], v[158:159], v[158:159], v[254:255]
	v_pk_add_f32 v[252:253], v[252:253], v[254:255]
	s_nop 0
	v_add_f32_e32 v183, v252, v253
	s_nop 1
	v_add_f32_dpp v183, v183, v183 quad_perm:[1,0,3,2] row_mask:0xf bank_mask:0xf bound_ctrl:1
	s_nop 1
	v_add_f32_dpp v183, v183, v183 quad_perm:[2,3,0,1] row_mask:0xf bank_mask:0xf bound_ctrl:1
	s_nop 1
	v_add_f32_dpp v183, v183, v183 row_half_mirror row_mask:0xf bank_mask:0xf bound_ctrl:1
	s_nop 1
	v_add_f32_dpp v183, v183, v183 row_mirror row_mask:0xf bank_mask:0xf bound_ctrl:1
	s_nop 1
	v_readlane_b32 s98, v183, 0
	v_readlane_b32 s99, v183, 16
	v_readlane_b32 s100, v183, 32
	v_readlane_b32 s101, v183, 48
	s_nop 1
	v_mov_b32_e32 v183, s98
	v_add_f32_e32 v183, s99, v183
	v_add_f32_e32 v183, s100, v183
	v_add_f32_e32 v183, s101, v183
	v_fmamk_f32 v183, v183, 0x3a800000, v182
	v_cmp_gt_f32_e32 vcc, 0x800000, v183
	v_mul_f32_e32 v181, 0x4b800000, v183
	s_nop 1
	v_cndmask_b32_e32 v183, v183, v181, vcc
	v_rsq_f32_e32 v183, v183
	s_nop 0
	v_mul_f32_e32 v181, 0x45800000, v183
	v_cndmask_b32_e32 v184, v183, v181, vcc
	v_mov_b32_e32 v185, v184
	v_cvt_pk_bf16_f32 v16, v144, v145
	v_cvt_pk_bf16_f32 v17, v146, v147
	v_cvt_pk_bf16_f32 v18, v148, v149
	v_cvt_pk_bf16_f32 v19, v150, v151
	v_cvt_pk_bf16_f32 v20, v152, v153
	v_cvt_pk_bf16_f32 v21, v154, v155
	v_cvt_pk_bf16_f32 v22, v156, v157
	v_cvt_pk_bf16_f32 v23, v158, v159
	v_add_u32_e32 v181, 0x1880000, v177
	global_store_dwordx4 v181, v[16:19], s[78:79]
	global_store_dwordx4 v181, v[20:23], s[78:79] offset:1024
	v_add_u32_e32 v236, 0x400, v237
	s_mov_b64 exec, 1
	global_store_dword v236, v184, s[78:79]
	s_mov_b64 exec, -1
	s_waitcnt vmcnt(20)
	v_lshlrev_b32_e32 v144, 16, v32
	v_and_b32_e32 v145, 0xffff0000, v32
	v_lshlrev_b32_e32 v146, 16, v33
	v_and_b32_e32 v147, 0xffff0000, v33
	v_lshlrev_b32_e32 v148, 16, v34
	v_and_b32_e32 v149, 0xffff0000, v34
	v_lshlrev_b32_e32 v150, 16, v35
	v_and_b32_e32 v151, 0xffff0000, v35
	v_lshlrev_b32_e32 v152, 16, v36
	v_and_b32_e32 v153, 0xffff0000, v36
	v_lshlrev_b32_e32 v154, 16, v37
	v_and_b32_e32 v155, 0xffff0000, v37
	v_lshlrev_b32_e32 v156, 16, v38
	v_and_b32_e32 v157, 0xffff0000, v38
	v_lshlrev_b32_e32 v158, 16, v39
	v_and_b32_e32 v159, 0xffff0000, v39
	v_lshlrev_b32_e32 v160, 16, v40
	v_and_b32_e32 v161, 0xffff0000, v40
	v_lshlrev_b32_e32 v162, 16, v41
	v_and_b32_e32 v163, 0xffff0000, v41
	v_lshlrev_b32_e32 v164, 16, v42
	v_and_b32_e32 v165, 0xffff0000, v42
	v_lshlrev_b32_e32 v166, 16, v43
	v_and_b32_e32 v167, 0xffff0000, v43
	v_lshlrev_b32_e32 v168, 16, v44
	v_and_b32_e32 v169, 0xffff0000, v44
	v_lshlrev_b32_e32 v170, 16, v45
	v_and_b32_e32 v171, 0xffff0000, v45
	v_lshlrev_b32_e32 v172, 16, v46
	v_and_b32_e32 v173, 0xffff0000, v46
	v_lshlrev_b32_e32 v174, 16, v47
	v_and_b32_e32 v175, 0xffff0000, v47
	v_pk_mul_f32 v[252:253], v[160:161], v[160:161]
	v_pk_mul_f32 v[254:255], v[162:163], v[162:163]
	v_pk_fma_f32 v[252:253], v[164:165], v[164:165], v[252:253]
	v_pk_fma_f32 v[254:255], v[166:167], v[166:167], v[254:255]
	v_pk_fma_f32 v[252:253], v[168:169], v[168:169], v[252:253]
	v_pk_fma_f32 v[254:255], v[170:171], v[170:171], v[254:255]
	v_pk_fma_f32 v[252:253], v[172:173], v[172:173], v[252:253]
	v_pk_fma_f32 v[254:255], v[174:175], v[174:175], v[254:255]
	v_pk_add_f32 v[252:253], v[252:253], v[254:255]
	s_nop 0
	v_add_f32_e32 v183, v252, v253
	s_nop 1
	v_add_f32_dpp v183, v183, v183 quad_perm:[1,0,3,2] row_mask:0xf bank_mask:0xf bound_ctrl:1
	s_nop 1
	v_add_f32_dpp v183, v183, v183 quad_perm:[2,3,0,1] row_mask:0xf bank_mask:0xf bound_ctrl:1
	s_nop 1
	v_add_f32_dpp v183, v183, v183 row_half_mirror row_mask:0xf bank_mask:0xf bound_ctrl:1
	s_nop 1
	v_add_f32_dpp v183, v183, v183 row_mirror row_mask:0xf bank_mask:0xf bound_ctrl:1
	s_nop 1
	v_readlane_b32 s98, v183, 0
	v_readlane_b32 s99, v183, 16
	v_readlane_b32 s100, v183, 32
	v_readlane_b32 s101, v183, 48
	s_nop 1
	v_mov_b32_e32 v183, s98
	v_add_f32_e32 v183, s99, v183
	v_add_f32_e32 v183, s100, v183
	v_add_f32_e32 v183, s101, v183
	v_fmamk_f32 v183, v183, 0x3a800000, v182
	v_cmp_gt_f32_e32 vcc, 0x800000, v183
	v_mul_f32_e32 v181, 0x4b800000, v183
	s_nop 1
	v_cndmask_b32_e32 v183, v183, v181, vcc
	v_rsq_f32_e32 v183, v183
	s_nop 0
	v_mul_f32_e32 v181, 0x45800000, v183
	v_cndmask_b32_e32 v184, v183, v181, vcc
	v_mov_b32_e32 v185, v184
	v_pk_mul_f32 v[160:161], v[160:161], v[184:185]
	v_pk_mul_f32 v[162:163], v[162:163], v[184:185]
	v_pk_mul_f32 v[164:165], v[164:165], v[184:185]
	v_pk_mul_f32 v[166:167], v[166:167], v[184:185]
	v_pk_mul_f32 v[168:169], v[168:169], v[184:185]
	v_pk_mul_f32 v[170:171], v[170:171], v[184:185]
	v_pk_mul_f32 v[172:173], v[172:173], v[184:185]
	v_pk_mul_f32 v[174:175], v[174:175], v[184:185]
	v_pk_fma_f32 v[144:145], v[160:161], v[128:129], v[144:145]
	v_pk_fma_f32 v[146:147], v[162:163], v[130:131], v[146:147]
	v_pk_fma_f32 v[148:149], v[164:165], v[132:133], v[148:149]
	v_pk_fma_f32 v[150:151], v[166:167], v[134:135], v[150:151]
	v_pk_fma_f32 v[152:153], v[168:169], v[136:137], v[152:153]
	v_pk_fma_f32 v[154:155], v[170:171], v[138:139], v[154:155]
	v_pk_fma_f32 v[156:157], v[172:173], v[140:141], v[156:157]
	v_pk_fma_f32 v[158:159], v[174:175], v[142:143], v[158:159]
	v_pk_mul_f32 v[252:253], v[144:145], v[144:145]
	v_pk_mul_f32 v[254:255], v[146:147], v[146:147]
	v_pk_fma_f32 v[252:253], v[148:149], v[148:149], v[252:253]
	v_pk_fma_f32 v[254:255], v[150:151], v[150:151], v[254:255]
	v_pk_fma_f32 v[252:253], v[152:153], v[152:153], v[252:253]
	v_pk_fma_f32 v[254:255], v[154:155], v[154:155], v[254:255]
	v_pk_fma_f32 v[252:253], v[156:157], v[156:157], v[252:253]
	v_pk_fma_f32 v[254:255], v[158:159], v[158:159], v[254:255]
	v_pk_add_f32 v[252:253], v[252:253], v[254:255]
	s_nop 0
	v_add_f32_e32 v183, v252, v253
	s_nop 1
	v_add_f32_dpp v183, v183, v183 quad_perm:[1,0,3,2] row_mask:0xf bank_mask:0xf bound_ctrl:1
	s_nop 1
	v_add_f32_dpp v183, v183, v183 quad_perm:[2,3,0,1] row_mask:0xf bank_mask:0xf bound_ctrl:1
	s_nop 1
	v_add_f32_dpp v183, v183, v183 row_half_mirror row_mask:0xf bank_mask:0xf bound_ctrl:1
	s_nop 1
	v_add_f32_dpp v183, v183, v183 row_mirror row_mask:0xf bank_mask:0xf bound_ctrl:1
	s_nop 1
	v_readlane_b32 s98, v183, 0
	v_readlane_b32 s99, v183, 16
	v_readlane_b32 s100, v183, 32
	v_readlane_b32 s101, v183, 48
	s_nop 1
	v_mov_b32_e32 v183, s98
	v_add_f32_e32 v183, s99, v183
	v_add_f32_e32 v183, s100, v183
	v_add_f32_e32 v183, s101, v183
	v_fmamk_f32 v183, v183, 0x3a800000, v182
	v_cmp_gt_f32_e32 vcc, 0x800000, v183
	v_mul_f32_e32 v181, 0x4b800000, v183
	s_nop 1
	v_cndmask_b32_e32 v183, v183, v181, vcc
	v_rsq_f32_e32 v183, v183
	s_nop 0
	v_mul_f32_e32 v181, 0x45800000, v183
	v_cndmask_b32_e32 v184, v183, v181, vcc
	v_mov_b32_e32 v185, v184
	v_cvt_pk_bf16_f32 v32, v144, v145
	v_cvt_pk_bf16_f32 v33, v146, v147
	v_cvt_pk_bf16_f32 v34, v148, v149
	v_cvt_pk_bf16_f32 v35, v150, v151
	v_cvt_pk_bf16_f32 v36, v152, v153
	v_cvt_pk_bf16_f32 v37, v154, v155
	v_cvt_pk_bf16_f32 v38, v156, v157
	v_cvt_pk_bf16_f32 v39, v158, v159
	v_add_u32_e32 v181, 0x1900000, v177
	global_store_dwordx4 v181, v[32:35], s[78:79]
	global_store_dwordx4 v181, v[36:39], s[78:79] offset:1024
	v_add_u32_e32 v236, 0x800, v237
	s_mov_b64 exec, 1
	global_store_dword v236, v184, s[78:79]
	s_mov_b64 exec, -1
	s_waitcnt vmcnt(16)
	v_lshlrev_b32_e32 v144, 16, v48
	v_and_b32_e32 v145, 0xffff0000, v48
	v_lshlrev_b32_e32 v146, 16, v49
	v_and_b32_e32 v147, 0xffff0000, v49
	v_lshlrev_b32_e32 v148, 16, v50
	v_and_b32_e32 v149, 0xffff0000, v50
	v_lshlrev_b32_e32 v150, 16, v51
	v_and_b32_e32 v151, 0xffff0000, v51
	v_lshlrev_b32_e32 v152, 16, v52
	v_and_b32_e32 v153, 0xffff0000, v52
	v_lshlrev_b32_e32 v154, 16, v53
	v_and_b32_e32 v155, 0xffff0000, v53
	v_lshlrev_b32_e32 v156, 16, v54
	v_and_b32_e32 v157, 0xffff0000, v54
	v_lshlrev_b32_e32 v158, 16, v55
	v_and_b32_e32 v159, 0xffff0000, v55
	v_lshlrev_b32_e32 v160, 16, v56
	v_and_b32_e32 v161, 0xffff0000, v56
	v_lshlrev_b32_e32 v162, 16, v57
	v_and_b32_e32 v163, 0xffff0000, v57
	v_lshlrev_b32_e32 v164, 16, v58
	v_and_b32_e32 v165, 0xffff0000, v58
	v_lshlrev_b32_e32 v166, 16, v59
	v_and_b32_e32 v167, 0xffff0000, v59
	v_lshlrev_b32_e32 v168, 16, v60
	v_and_b32_e32 v169, 0xffff0000, v60
	v_lshlrev_b32_e32 v170, 16, v61
	v_and_b32_e32 v171, 0xffff0000, v61
	v_lshlrev_b32_e32 v172, 16, v62
	v_and_b32_e32 v173, 0xffff0000, v62
	v_lshlrev_b32_e32 v174, 16, v63
	v_and_b32_e32 v175, 0xffff0000, v63
	v_pk_mul_f32 v[252:253], v[160:161], v[160:161]
	v_pk_mul_f32 v[254:255], v[162:163], v[162:163]
	v_pk_fma_f32 v[252:253], v[164:165], v[164:165], v[252:253]
	v_pk_fma_f32 v[254:255], v[166:167], v[166:167], v[254:255]
	v_pk_fma_f32 v[252:253], v[168:169], v[168:169], v[252:253]
	v_pk_fma_f32 v[254:255], v[170:171], v[170:171], v[254:255]
	v_pk_fma_f32 v[252:253], v[172:173], v[172:173], v[252:253]
	v_pk_fma_f32 v[254:255], v[174:175], v[174:175], v[254:255]
	v_pk_add_f32 v[252:253], v[252:253], v[254:255]
	s_nop 0
	v_add_f32_e32 v183, v252, v253
	s_nop 1
	v_add_f32_dpp v183, v183, v183 quad_perm:[1,0,3,2] row_mask:0xf bank_mask:0xf bound_ctrl:1
	s_nop 1
	v_add_f32_dpp v183, v183, v183 quad_perm:[2,3,0,1] row_mask:0xf bank_mask:0xf bound_ctrl:1
	s_nop 1
	v_add_f32_dpp v183, v183, v183 row_half_mirror row_mask:0xf bank_mask:0xf bound_ctrl:1
	s_nop 1
	v_add_f32_dpp v183, v183, v183 row_mirror row_mask:0xf bank_mask:0xf bound_ctrl:1
	s_nop 1
	v_readlane_b32 s98, v183, 0
	v_readlane_b32 s99, v183, 16
	v_readlane_b32 s100, v183, 32
	v_readlane_b32 s101, v183, 48
	s_nop 1
	v_mov_b32_e32 v183, s98
	v_add_f32_e32 v183, s99, v183
	v_add_f32_e32 v183, s100, v183
	v_add_f32_e32 v183, s101, v183
	v_fmamk_f32 v183, v183, 0x3a800000, v182
	v_cmp_gt_f32_e32 vcc, 0x800000, v183
	v_mul_f32_e32 v181, 0x4b800000, v183
	s_nop 1
	v_cndmask_b32_e32 v183, v183, v181, vcc
	v_rsq_f32_e32 v183, v183
	s_nop 0
	v_mul_f32_e32 v181, 0x45800000, v183
	v_cndmask_b32_e32 v184, v183, v181, vcc
	v_mov_b32_e32 v185, v184
	v_pk_mul_f32 v[160:161], v[160:161], v[184:185]
	v_pk_mul_f32 v[162:163], v[162:163], v[184:185]
	v_pk_mul_f32 v[164:165], v[164:165], v[184:185]
	v_pk_mul_f32 v[166:167], v[166:167], v[184:185]
	v_pk_mul_f32 v[168:169], v[168:169], v[184:185]
	v_pk_mul_f32 v[170:171], v[170:171], v[184:185]
	v_pk_mul_f32 v[172:173], v[172:173], v[184:185]
	v_pk_mul_f32 v[174:175], v[174:175], v[184:185]
	v_pk_fma_f32 v[144:145], v[160:161], v[128:129], v[144:145]
	v_pk_fma_f32 v[146:147], v[162:163], v[130:131], v[146:147]
	v_pk_fma_f32 v[148:149], v[164:165], v[132:133], v[148:149]
	v_pk_fma_f32 v[150:151], v[166:167], v[134:135], v[150:151]
	v_pk_fma_f32 v[152:153], v[168:169], v[136:137], v[152:153]
	v_pk_fma_f32 v[154:155], v[170:171], v[138:139], v[154:155]
	v_pk_fma_f32 v[156:157], v[172:173], v[140:141], v[156:157]
	v_pk_fma_f32 v[158:159], v[174:175], v[142:143], v[158:159]
	v_pk_mul_f32 v[252:253], v[144:145], v[144:145]
	v_pk_mul_f32 v[254:255], v[146:147], v[146:147]
	v_pk_fma_f32 v[252:253], v[148:149], v[148:149], v[252:253]
	v_pk_fma_f32 v[254:255], v[150:151], v[150:151], v[254:255]
	v_pk_fma_f32 v[252:253], v[152:153], v[152:153], v[252:253]
	v_pk_fma_f32 v[254:255], v[154:155], v[154:155], v[254:255]
	v_pk_fma_f32 v[252:253], v[156:157], v[156:157], v[252:253]
	v_pk_fma_f32 v[254:255], v[158:159], v[158:159], v[254:255]
	v_pk_add_f32 v[252:253], v[252:253], v[254:255]
	s_nop 0
	v_add_f32_e32 v183, v252, v253
	s_nop 1
	v_add_f32_dpp v183, v183, v183 quad_perm:[1,0,3,2] row_mask:0xf bank_mask:0xf bound_ctrl:1
	s_nop 1
	v_add_f32_dpp v183, v183, v183 quad_perm:[2,3,0,1] row_mask:0xf bank_mask:0xf bound_ctrl:1
	s_nop 1
	v_add_f32_dpp v183, v183, v183 row_half_mirror row_mask:0xf bank_mask:0xf bound_ctrl:1
	s_nop 1
	v_add_f32_dpp v183, v183, v183 row_mirror row_mask:0xf bank_mask:0xf bound_ctrl:1
	s_nop 1
	v_readlane_b32 s98, v183, 0
	v_readlane_b32 s99, v183, 16
	v_readlane_b32 s100, v183, 32
	v_readlane_b32 s101, v183, 48
	s_nop 1
	v_mov_b32_e32 v183, s98
	v_add_f32_e32 v183, s99, v183
	v_add_f32_e32 v183, s100, v183
	v_add_f32_e32 v183, s101, v183
	v_fmamk_f32 v183, v183, 0x3a800000, v182
	v_cmp_gt_f32_e32 vcc, 0x800000, v183
	v_mul_f32_e32 v181, 0x4b800000, v183
	s_nop 1
	v_cndmask_b32_e32 v183, v183, v181, vcc
	v_rsq_f32_e32 v183, v183
	s_nop 0
	v_mul_f32_e32 v181, 0x45800000, v183
	v_cndmask_b32_e32 v184, v183, v181, vcc
	v_mov_b32_e32 v185, v184
	v_cvt_pk_bf16_f32 v48, v144, v145
	v_cvt_pk_bf16_f32 v49, v146, v147
	v_cvt_pk_bf16_f32 v50, v148, v149
	v_cvt_pk_bf16_f32 v51, v150, v151
	v_cvt_pk_bf16_f32 v52, v152, v153
	v_cvt_pk_bf16_f32 v53, v154, v155
	v_cvt_pk_bf16_f32 v54, v156, v157
	v_cvt_pk_bf16_f32 v55, v158, v159
	v_add_u32_e32 v181, 0x1980000, v177
	global_store_dwordx4 v181, v[48:51], s[78:79]
	global_store_dwordx4 v181, v[52:55], s[78:79] offset:1024
	v_add_u32_e32 v236, 0xc00, v237
	s_mov_b64 exec, 1
	global_store_dword v236, v184, s[78:79]
	s_mov_b64 exec, -1
	s_waitcnt vmcnt(12)
	v_lshlrev_b32_e32 v144, 16, v64
	v_and_b32_e32 v145, 0xffff0000, v64
	v_lshlrev_b32_e32 v146, 16, v65
	v_and_b32_e32 v147, 0xffff0000, v65
	v_lshlrev_b32_e32 v148, 16, v66
	v_and_b32_e32 v149, 0xffff0000, v66
	v_lshlrev_b32_e32 v150, 16, v67
	v_and_b32_e32 v151, 0xffff0000, v67
	v_lshlrev_b32_e32 v152, 16, v68
	v_and_b32_e32 v153, 0xffff0000, v68
	v_lshlrev_b32_e32 v154, 16, v69
	v_and_b32_e32 v155, 0xffff0000, v69
	v_lshlrev_b32_e32 v156, 16, v70
	v_and_b32_e32 v157, 0xffff0000, v70
	v_lshlrev_b32_e32 v158, 16, v71
	v_and_b32_e32 v159, 0xffff0000, v71
	v_lshlrev_b32_e32 v160, 16, v72
	v_and_b32_e32 v161, 0xffff0000, v72
	v_lshlrev_b32_e32 v162, 16, v73
	v_and_b32_e32 v163, 0xffff0000, v73
	v_lshlrev_b32_e32 v164, 16, v74
	v_and_b32_e32 v165, 0xffff0000, v74
	v_lshlrev_b32_e32 v166, 16, v75
	v_and_b32_e32 v167, 0xffff0000, v75
	v_lshlrev_b32_e32 v168, 16, v76
	v_and_b32_e32 v169, 0xffff0000, v76
	v_lshlrev_b32_e32 v170, 16, v77
	v_and_b32_e32 v171, 0xffff0000, v77
	v_lshlrev_b32_e32 v172, 16, v78
	v_and_b32_e32 v173, 0xffff0000, v78
	v_lshlrev_b32_e32 v174, 16, v79
	v_and_b32_e32 v175, 0xffff0000, v79
	v_pk_mul_f32 v[252:253], v[160:161], v[160:161]
	v_pk_mul_f32 v[254:255], v[162:163], v[162:163]
	v_pk_fma_f32 v[252:253], v[164:165], v[164:165], v[252:253]
	v_pk_fma_f32 v[254:255], v[166:167], v[166:167], v[254:255]
	v_pk_fma_f32 v[252:253], v[168:169], v[168:169], v[252:253]
	v_pk_fma_f32 v[254:255], v[170:171], v[170:171], v[254:255]
	v_pk_fma_f32 v[252:253], v[172:173], v[172:173], v[252:253]
	v_pk_fma_f32 v[254:255], v[174:175], v[174:175], v[254:255]
	v_pk_add_f32 v[252:253], v[252:253], v[254:255]
	s_nop 0
	v_add_f32_e32 v183, v252, v253
	s_nop 1
	v_add_f32_dpp v183, v183, v183 quad_perm:[1,0,3,2] row_mask:0xf bank_mask:0xf bound_ctrl:1
	s_nop 1
	v_add_f32_dpp v183, v183, v183 quad_perm:[2,3,0,1] row_mask:0xf bank_mask:0xf bound_ctrl:1
	s_nop 1
	v_add_f32_dpp v183, v183, v183 row_half_mirror row_mask:0xf bank_mask:0xf bound_ctrl:1
	s_nop 1
	v_add_f32_dpp v183, v183, v183 row_mirror row_mask:0xf bank_mask:0xf bound_ctrl:1
	s_nop 1
	v_readlane_b32 s98, v183, 0
	v_readlane_b32 s99, v183, 16
	v_readlane_b32 s100, v183, 32
	v_readlane_b32 s101, v183, 48
	s_nop 1
	v_mov_b32_e32 v183, s98
	v_add_f32_e32 v183, s99, v183
	v_add_f32_e32 v183, s100, v183
	v_add_f32_e32 v183, s101, v183
	v_fmamk_f32 v183, v183, 0x3a800000, v182
	v_cmp_gt_f32_e32 vcc, 0x800000, v183
	v_mul_f32_e32 v181, 0x4b800000, v183
	s_nop 1
	v_cndmask_b32_e32 v183, v183, v181, vcc
	v_rsq_f32_e32 v183, v183
	s_nop 0
	v_mul_f32_e32 v181, 0x45800000, v183
	v_cndmask_b32_e32 v184, v183, v181, vcc
	v_mov_b32_e32 v185, v184
	v_pk_mul_f32 v[160:161], v[160:161], v[184:185]
	v_pk_mul_f32 v[162:163], v[162:163], v[184:185]
	v_pk_mul_f32 v[164:165], v[164:165], v[184:185]
	v_pk_mul_f32 v[166:167], v[166:167], v[184:185]
	v_pk_mul_f32 v[168:169], v[168:169], v[184:185]
	v_pk_mul_f32 v[170:171], v[170:171], v[184:185]
	v_pk_mul_f32 v[172:173], v[172:173], v[184:185]
	v_pk_mul_f32 v[174:175], v[174:175], v[184:185]
	v_pk_fma_f32 v[144:145], v[160:161], v[128:129], v[144:145]
	v_pk_fma_f32 v[146:147], v[162:163], v[130:131], v[146:147]
	v_pk_fma_f32 v[148:149], v[164:165], v[132:133], v[148:149]
	v_pk_fma_f32 v[150:151], v[166:167], v[134:135], v[150:151]
	v_pk_fma_f32 v[152:153], v[168:169], v[136:137], v[152:153]
	v_pk_fma_f32 v[154:155], v[170:171], v[138:139], v[154:155]
	v_pk_fma_f32 v[156:157], v[172:173], v[140:141], v[156:157]
	v_pk_fma_f32 v[158:159], v[174:175], v[142:143], v[158:159]
	v_pk_mul_f32 v[252:253], v[144:145], v[144:145]
	v_pk_mul_f32 v[254:255], v[146:147], v[146:147]
	v_pk_fma_f32 v[252:253], v[148:149], v[148:149], v[252:253]
	v_pk_fma_f32 v[254:255], v[150:151], v[150:151], v[254:255]
	v_pk_fma_f32 v[252:253], v[152:153], v[152:153], v[252:253]
	v_pk_fma_f32 v[254:255], v[154:155], v[154:155], v[254:255]
	v_pk_fma_f32 v[252:253], v[156:157], v[156:157], v[252:253]
	v_pk_fma_f32 v[254:255], v[158:159], v[158:159], v[254:255]
	v_pk_add_f32 v[252:253], v[252:253], v[254:255]
	s_nop 0
	v_add_f32_e32 v183, v252, v253
	s_nop 1
	v_add_f32_dpp v183, v183, v183 quad_perm:[1,0,3,2] row_mask:0xf bank_mask:0xf bound_ctrl:1
	s_nop 1
	v_add_f32_dpp v183, v183, v183 quad_perm:[2,3,0,1] row_mask:0xf bank_mask:0xf bound_ctrl:1
	s_nop 1
	v_add_f32_dpp v183, v183, v183 row_half_mirror row_mask:0xf bank_mask:0xf bound_ctrl:1
	s_nop 1
	v_add_f32_dpp v183, v183, v183 row_mirror row_mask:0xf bank_mask:0xf bound_ctrl:1
	s_nop 1
	v_readlane_b32 s98, v183, 0
	v_readlane_b32 s99, v183, 16
	v_readlane_b32 s100, v183, 32
	v_readlane_b32 s101, v183, 48
	s_nop 1
	v_mov_b32_e32 v183, s98
	v_add_f32_e32 v183, s99, v183
	v_add_f32_e32 v183, s100, v183
	v_add_f32_e32 v183, s101, v183
	v_fmamk_f32 v183, v183, 0x3a800000, v182
	v_cmp_gt_f32_e32 vcc, 0x800000, v183
	v_mul_f32_e32 v181, 0x4b800000, v183
	s_nop 1
	v_cndmask_b32_e32 v183, v183, v181, vcc
	v_rsq_f32_e32 v183, v183
	s_nop 0
	v_mul_f32_e32 v181, 0x45800000, v183
	v_cndmask_b32_e32 v184, v183, v181, vcc
	v_mov_b32_e32 v185, v184
	v_cvt_pk_bf16_f32 v64, v144, v145
	v_cvt_pk_bf16_f32 v65, v146, v147
	v_cvt_pk_bf16_f32 v66, v148, v149
	v_cvt_pk_bf16_f32 v67, v150, v151
	v_cvt_pk_bf16_f32 v68, v152, v153
	v_cvt_pk_bf16_f32 v69, v154, v155
	v_cvt_pk_bf16_f32 v70, v156, v157
	v_cvt_pk_bf16_f32 v71, v158, v159
	v_add_u32_e32 v181, 0x1a00000, v177
	global_store_dwordx4 v181, v[64:67], s[78:79]
	global_store_dwordx4 v181, v[68:71], s[78:79] offset:1024
	v_add_u32_e32 v236, 0x1000, v237
	s_mov_b64 exec, 1
	global_store_dword v236, v184, s[78:79]
	s_mov_b64 exec, -1
	s_waitcnt vmcnt(8)
	v_lshlrev_b32_e32 v144, 16, v80
	v_and_b32_e32 v145, 0xffff0000, v80
	v_lshlrev_b32_e32 v146, 16, v81
	v_and_b32_e32 v147, 0xffff0000, v81
	v_lshlrev_b32_e32 v148, 16, v82
	v_and_b32_e32 v149, 0xffff0000, v82
	v_lshlrev_b32_e32 v150, 16, v83
	v_and_b32_e32 v151, 0xffff0000, v83
	v_lshlrev_b32_e32 v152, 16, v84
	v_and_b32_e32 v153, 0xffff0000, v84
	v_lshlrev_b32_e32 v154, 16, v85
	v_and_b32_e32 v155, 0xffff0000, v85
	v_lshlrev_b32_e32 v156, 16, v86
	v_and_b32_e32 v157, 0xffff0000, v86
	v_lshlrev_b32_e32 v158, 16, v87
	v_and_b32_e32 v159, 0xffff0000, v87
	v_lshlrev_b32_e32 v160, 16, v88
	v_and_b32_e32 v161, 0xffff0000, v88
	v_lshlrev_b32_e32 v162, 16, v89
	v_and_b32_e32 v163, 0xffff0000, v89
	v_lshlrev_b32_e32 v164, 16, v90
	v_and_b32_e32 v165, 0xffff0000, v90
	v_lshlrev_b32_e32 v166, 16, v91
	v_and_b32_e32 v167, 0xffff0000, v91
	v_lshlrev_b32_e32 v168, 16, v92
	v_and_b32_e32 v169, 0xffff0000, v92
	v_lshlrev_b32_e32 v170, 16, v93
	v_and_b32_e32 v171, 0xffff0000, v93
	v_lshlrev_b32_e32 v172, 16, v94
	v_and_b32_e32 v173, 0xffff0000, v94
	v_lshlrev_b32_e32 v174, 16, v95
	v_and_b32_e32 v175, 0xffff0000, v95
	v_pk_mul_f32 v[252:253], v[160:161], v[160:161]
	v_pk_mul_f32 v[254:255], v[162:163], v[162:163]
	v_pk_fma_f32 v[252:253], v[164:165], v[164:165], v[252:253]
	v_pk_fma_f32 v[254:255], v[166:167], v[166:167], v[254:255]
	v_pk_fma_f32 v[252:253], v[168:169], v[168:169], v[252:253]
	v_pk_fma_f32 v[254:255], v[170:171], v[170:171], v[254:255]
	v_pk_fma_f32 v[252:253], v[172:173], v[172:173], v[252:253]
	v_pk_fma_f32 v[254:255], v[174:175], v[174:175], v[254:255]
	v_pk_add_f32 v[252:253], v[252:253], v[254:255]
	s_nop 0
	v_add_f32_e32 v183, v252, v253
	s_nop 1
	v_add_f32_dpp v183, v183, v183 quad_perm:[1,0,3,2] row_mask:0xf bank_mask:0xf bound_ctrl:1
	s_nop 1
	v_add_f32_dpp v183, v183, v183 quad_perm:[2,3,0,1] row_mask:0xf bank_mask:0xf bound_ctrl:1
	s_nop 1
	v_add_f32_dpp v183, v183, v183 row_half_mirror row_mask:0xf bank_mask:0xf bound_ctrl:1
	s_nop 1
	v_add_f32_dpp v183, v183, v183 row_mirror row_mask:0xf bank_mask:0xf bound_ctrl:1
	s_nop 1
	v_readlane_b32 s98, v183, 0
	v_readlane_b32 s99, v183, 16
	v_readlane_b32 s100, v183, 32
	v_readlane_b32 s101, v183, 48
	s_nop 1
	v_mov_b32_e32 v183, s98
	v_add_f32_e32 v183, s99, v183
	v_add_f32_e32 v183, s100, v183
	v_add_f32_e32 v183, s101, v183
	v_fmamk_f32 v183, v183, 0x3a800000, v182
	v_cmp_gt_f32_e32 vcc, 0x800000, v183
	v_mul_f32_e32 v181, 0x4b800000, v183
	s_nop 1
	v_cndmask_b32_e32 v183, v183, v181, vcc
	v_rsq_f32_e32 v183, v183
	s_nop 0
	v_mul_f32_e32 v181, 0x45800000, v183
	v_cndmask_b32_e32 v184, v183, v181, vcc
	v_mov_b32_e32 v185, v184
	v_pk_mul_f32 v[160:161], v[160:161], v[184:185]
	v_pk_mul_f32 v[162:163], v[162:163], v[184:185]
	v_pk_mul_f32 v[164:165], v[164:165], v[184:185]
	v_pk_mul_f32 v[166:167], v[166:167], v[184:185]
	v_pk_mul_f32 v[168:169], v[168:169], v[184:185]
	v_pk_mul_f32 v[170:171], v[170:171], v[184:185]
	v_pk_mul_f32 v[172:173], v[172:173], v[184:185]
	v_pk_mul_f32 v[174:175], v[174:175], v[184:185]
	v_pk_fma_f32 v[144:145], v[160:161], v[128:129], v[144:145]
	v_pk_fma_f32 v[146:147], v[162:163], v[130:131], v[146:147]
	v_pk_fma_f32 v[148:149], v[164:165], v[132:133], v[148:149]
	v_pk_fma_f32 v[150:151], v[166:167], v[134:135], v[150:151]
	v_pk_fma_f32 v[152:153], v[168:169], v[136:137], v[152:153]
	v_pk_fma_f32 v[154:155], v[170:171], v[138:139], v[154:155]
	v_pk_fma_f32 v[156:157], v[172:173], v[140:141], v[156:157]
	v_pk_fma_f32 v[158:159], v[174:175], v[142:143], v[158:159]
	v_pk_mul_f32 v[252:253], v[144:145], v[144:145]
	v_pk_mul_f32 v[254:255], v[146:147], v[146:147]
	v_pk_fma_f32 v[252:253], v[148:149], v[148:149], v[252:253]
	v_pk_fma_f32 v[254:255], v[150:151], v[150:151], v[254:255]
	v_pk_fma_f32 v[252:253], v[152:153], v[152:153], v[252:253]
	v_pk_fma_f32 v[254:255], v[154:155], v[154:155], v[254:255]
	v_pk_fma_f32 v[252:253], v[156:157], v[156:157], v[252:253]
	v_pk_fma_f32 v[254:255], v[158:159], v[158:159], v[254:255]
	v_pk_add_f32 v[252:253], v[252:253], v[254:255]
	s_nop 0
	v_add_f32_e32 v183, v252, v253
	s_nop 1
	v_add_f32_dpp v183, v183, v183 quad_perm:[1,0,3,2] row_mask:0xf bank_mask:0xf bound_ctrl:1
	s_nop 1
	v_add_f32_dpp v183, v183, v183 quad_perm:[2,3,0,1] row_mask:0xf bank_mask:0xf bound_ctrl:1
	s_nop 1
	v_add_f32_dpp v183, v183, v183 row_half_mirror row_mask:0xf bank_mask:0xf bound_ctrl:1
	s_nop 1
	v_add_f32_dpp v183, v183, v183 row_mirror row_mask:0xf bank_mask:0xf bound_ctrl:1
	s_nop 1
	v_readlane_b32 s98, v183, 0
	v_readlane_b32 s99, v183, 16
	v_readlane_b32 s100, v183, 32
	v_readlane_b32 s101, v183, 48
	s_nop 1
	v_mov_b32_e32 v183, s98
	v_add_f32_e32 v183, s99, v183
	v_add_f32_e32 v183, s100, v183
	v_add_f32_e32 v183, s101, v183
	v_fmamk_f32 v183, v183, 0x3a800000, v182
	v_cmp_gt_f32_e32 vcc, 0x800000, v183
	v_mul_f32_e32 v181, 0x4b800000, v183
	s_nop 1
	v_cndmask_b32_e32 v183, v183, v181, vcc
	v_rsq_f32_e32 v183, v183
	s_nop 0
	v_mul_f32_e32 v181, 0x45800000, v183
	v_cndmask_b32_e32 v184, v183, v181, vcc
	v_mov_b32_e32 v185, v184
	v_cvt_pk_bf16_f32 v80, v144, v145
	v_cvt_pk_bf16_f32 v81, v146, v147
	v_cvt_pk_bf16_f32 v82, v148, v149
	v_cvt_pk_bf16_f32 v83, v150, v151
	v_cvt_pk_bf16_f32 v84, v152, v153
	v_cvt_pk_bf16_f32 v85, v154, v155
	v_cvt_pk_bf16_f32 v86, v156, v157
	v_cvt_pk_bf16_f32 v87, v158, v159
	v_add_u32_e32 v181, 0x1a80000, v177
	global_store_dwordx4 v181, v[80:83], s[78:79]
	global_store_dwordx4 v181, v[84:87], s[78:79] offset:1024
	v_add_u32_e32 v236, 0x1400, v237
	s_mov_b64 exec, 1
	global_store_dword v236, v184, s[78:79]
	s_mov_b64 exec, -1
	s_waitcnt vmcnt(4)
	v_lshlrev_b32_e32 v144, 16, v96
	v_and_b32_e32 v145, 0xffff0000, v96
	v_lshlrev_b32_e32 v146, 16, v97
	v_and_b32_e32 v147, 0xffff0000, v97
	v_lshlrev_b32_e32 v148, 16, v98
	v_and_b32_e32 v149, 0xffff0000, v98
	v_lshlrev_b32_e32 v150, 16, v99
	v_and_b32_e32 v151, 0xffff0000, v99
	v_lshlrev_b32_e32 v152, 16, v100
	v_and_b32_e32 v153, 0xffff0000, v100
	v_lshlrev_b32_e32 v154, 16, v101
	v_and_b32_e32 v155, 0xffff0000, v101
	v_lshlrev_b32_e32 v156, 16, v102
	v_and_b32_e32 v157, 0xffff0000, v102
	v_lshlrev_b32_e32 v158, 16, v103
	v_and_b32_e32 v159, 0xffff0000, v103
	v_lshlrev_b32_e32 v160, 16, v104
	v_and_b32_e32 v161, 0xffff0000, v104
	v_lshlrev_b32_e32 v162, 16, v105
	v_and_b32_e32 v163, 0xffff0000, v105
	v_lshlrev_b32_e32 v164, 16, v106
	v_and_b32_e32 v165, 0xffff0000, v106
	v_lshlrev_b32_e32 v166, 16, v107
	v_and_b32_e32 v167, 0xffff0000, v107
	v_lshlrev_b32_e32 v168, 16, v108
	v_and_b32_e32 v169, 0xffff0000, v108
	v_lshlrev_b32_e32 v170, 16, v109
	v_and_b32_e32 v171, 0xffff0000, v109
	v_lshlrev_b32_e32 v172, 16, v110
	v_and_b32_e32 v173, 0xffff0000, v110
	v_lshlrev_b32_e32 v174, 16, v111
	v_and_b32_e32 v175, 0xffff0000, v111
	v_pk_mul_f32 v[252:253], v[160:161], v[160:161]
	v_pk_mul_f32 v[254:255], v[162:163], v[162:163]
	v_pk_fma_f32 v[252:253], v[164:165], v[164:165], v[252:253]
	v_pk_fma_f32 v[254:255], v[166:167], v[166:167], v[254:255]
	v_pk_fma_f32 v[252:253], v[168:169], v[168:169], v[252:253]
	v_pk_fma_f32 v[254:255], v[170:171], v[170:171], v[254:255]
	v_pk_fma_f32 v[252:253], v[172:173], v[172:173], v[252:253]
	v_pk_fma_f32 v[254:255], v[174:175], v[174:175], v[254:255]
	v_pk_add_f32 v[252:253], v[252:253], v[254:255]
	s_nop 0
	v_add_f32_e32 v183, v252, v253
	s_nop 1
	v_add_f32_dpp v183, v183, v183 quad_perm:[1,0,3,2] row_mask:0xf bank_mask:0xf bound_ctrl:1
	s_nop 1
	v_add_f32_dpp v183, v183, v183 quad_perm:[2,3,0,1] row_mask:0xf bank_mask:0xf bound_ctrl:1
	s_nop 1
	v_add_f32_dpp v183, v183, v183 row_half_mirror row_mask:0xf bank_mask:0xf bound_ctrl:1
	s_nop 1
	v_add_f32_dpp v183, v183, v183 row_mirror row_mask:0xf bank_mask:0xf bound_ctrl:1
	s_nop 1
	v_readlane_b32 s98, v183, 0
	v_readlane_b32 s99, v183, 16
	v_readlane_b32 s100, v183, 32
	v_readlane_b32 s101, v183, 48
	s_nop 1
	v_mov_b32_e32 v183, s98
	v_add_f32_e32 v183, s99, v183
	v_add_f32_e32 v183, s100, v183
	v_add_f32_e32 v183, s101, v183
	v_fmamk_f32 v183, v183, 0x3a800000, v182
	v_cmp_gt_f32_e32 vcc, 0x800000, v183
	v_mul_f32_e32 v181, 0x4b800000, v183
	s_nop 1
	v_cndmask_b32_e32 v183, v183, v181, vcc
	v_rsq_f32_e32 v183, v183
	s_nop 0
	v_mul_f32_e32 v181, 0x45800000, v183
	v_cndmask_b32_e32 v184, v183, v181, vcc
	v_mov_b32_e32 v185, v184
	v_pk_mul_f32 v[160:161], v[160:161], v[184:185]
	v_pk_mul_f32 v[162:163], v[162:163], v[184:185]
	v_pk_mul_f32 v[164:165], v[164:165], v[184:185]
	v_pk_mul_f32 v[166:167], v[166:167], v[184:185]
	v_pk_mul_f32 v[168:169], v[168:169], v[184:185]
	v_pk_mul_f32 v[170:171], v[170:171], v[184:185]
	v_pk_mul_f32 v[172:173], v[172:173], v[184:185]
	v_pk_mul_f32 v[174:175], v[174:175], v[184:185]
	v_pk_fma_f32 v[144:145], v[160:161], v[128:129], v[144:145]
	v_pk_fma_f32 v[146:147], v[162:163], v[130:131], v[146:147]
	v_pk_fma_f32 v[148:149], v[164:165], v[132:133], v[148:149]
	v_pk_fma_f32 v[150:151], v[166:167], v[134:135], v[150:151]
	v_pk_fma_f32 v[152:153], v[168:169], v[136:137], v[152:153]
	v_pk_fma_f32 v[154:155], v[170:171], v[138:139], v[154:155]
	v_pk_fma_f32 v[156:157], v[172:173], v[140:141], v[156:157]
	v_pk_fma_f32 v[158:159], v[174:175], v[142:143], v[158:159]
	v_pk_mul_f32 v[252:253], v[144:145], v[144:145]
	v_pk_mul_f32 v[254:255], v[146:147], v[146:147]
	v_pk_fma_f32 v[252:253], v[148:149], v[148:149], v[252:253]
	v_pk_fma_f32 v[254:255], v[150:151], v[150:151], v[254:255]
	v_pk_fma_f32 v[252:253], v[152:153], v[152:153], v[252:253]
	v_pk_fma_f32 v[254:255], v[154:155], v[154:155], v[254:255]
	v_pk_fma_f32 v[252:253], v[156:157], v[156:157], v[252:253]
	v_pk_fma_f32 v[254:255], v[158:159], v[158:159], v[254:255]
	v_pk_add_f32 v[252:253], v[252:253], v[254:255]
	s_nop 0
	v_add_f32_e32 v183, v252, v253
	s_nop 1
	v_add_f32_dpp v183, v183, v183 quad_perm:[1,0,3,2] row_mask:0xf bank_mask:0xf bound_ctrl:1
	s_nop 1
	v_add_f32_dpp v183, v183, v183 quad_perm:[2,3,0,1] row_mask:0xf bank_mask:0xf bound_ctrl:1
	s_nop 1
	v_add_f32_dpp v183, v183, v183 row_half_mirror row_mask:0xf bank_mask:0xf bound_ctrl:1
	s_nop 1
	v_add_f32_dpp v183, v183, v183 row_mirror row_mask:0xf bank_mask:0xf bound_ctrl:1
	s_nop 1
	v_readlane_b32 s98, v183, 0
	v_readlane_b32 s99, v183, 16
	v_readlane_b32 s100, v183, 32
	v_readlane_b32 s101, v183, 48
	s_nop 1
	v_mov_b32_e32 v183, s98
	v_add_f32_e32 v183, s99, v183
	v_add_f32_e32 v183, s100, v183
	v_add_f32_e32 v183, s101, v183
	v_fmamk_f32 v183, v183, 0x3a800000, v182
	v_cmp_gt_f32_e32 vcc, 0x800000, v183
	v_mul_f32_e32 v181, 0x4b800000, v183
	s_nop 1
	v_cndmask_b32_e32 v183, v183, v181, vcc
	v_rsq_f32_e32 v183, v183
	s_nop 0
	v_mul_f32_e32 v181, 0x45800000, v183
	v_cndmask_b32_e32 v184, v183, v181, vcc
	v_mov_b32_e32 v185, v184
	v_cvt_pk_bf16_f32 v96, v144, v145
	v_cvt_pk_bf16_f32 v97, v146, v147
	v_cvt_pk_bf16_f32 v98, v148, v149
	v_cvt_pk_bf16_f32 v99, v150, v151
	v_cvt_pk_bf16_f32 v100, v152, v153
	v_cvt_pk_bf16_f32 v101, v154, v155
	v_cvt_pk_bf16_f32 v102, v156, v157
	v_cvt_pk_bf16_f32 v103, v158, v159
	v_add_u32_e32 v181, 0x1b00000, v177
	global_store_dwordx4 v181, v[96:99], s[78:79]
	global_store_dwordx4 v181, v[100:103], s[78:79] offset:1024
	v_add_u32_e32 v236, 0x1800, v237
	s_mov_b64 exec, 1
	global_store_dword v236, v184, s[78:79]
	s_mov_b64 exec, -1
	s_waitcnt vmcnt(0)
	v_lshlrev_b32_e32 v144, 16, v112
	v_and_b32_e32 v145, 0xffff0000, v112
	v_lshlrev_b32_e32 v146, 16, v113
	v_and_b32_e32 v147, 0xffff0000, v113
	v_lshlrev_b32_e32 v148, 16, v114
	v_and_b32_e32 v149, 0xffff0000, v114
	v_lshlrev_b32_e32 v150, 16, v115
	v_and_b32_e32 v151, 0xffff0000, v115
	v_lshlrev_b32_e32 v152, 16, v116
	v_and_b32_e32 v153, 0xffff0000, v116
	v_lshlrev_b32_e32 v154, 16, v117
	v_and_b32_e32 v155, 0xffff0000, v117
	v_lshlrev_b32_e32 v156, 16, v118
	v_and_b32_e32 v157, 0xffff0000, v118
	v_lshlrev_b32_e32 v158, 16, v119
	v_and_b32_e32 v159, 0xffff0000, v119
	v_lshlrev_b32_e32 v160, 16, v120
	v_and_b32_e32 v161, 0xffff0000, v120
	v_lshlrev_b32_e32 v162, 16, v121
	v_and_b32_e32 v163, 0xffff0000, v121
	v_lshlrev_b32_e32 v164, 16, v122
	v_and_b32_e32 v165, 0xffff0000, v122
	v_lshlrev_b32_e32 v166, 16, v123
	v_and_b32_e32 v167, 0xffff0000, v123
	v_lshlrev_b32_e32 v168, 16, v124
	v_and_b32_e32 v169, 0xffff0000, v124
	v_lshlrev_b32_e32 v170, 16, v125
	v_and_b32_e32 v171, 0xffff0000, v125
	v_lshlrev_b32_e32 v172, 16, v126
	v_and_b32_e32 v173, 0xffff0000, v126
	v_lshlrev_b32_e32 v174, 16, v127
	v_and_b32_e32 v175, 0xffff0000, v127
	v_pk_mul_f32 v[252:253], v[160:161], v[160:161]
	v_pk_mul_f32 v[254:255], v[162:163], v[162:163]
	v_pk_fma_f32 v[252:253], v[164:165], v[164:165], v[252:253]
	v_pk_fma_f32 v[254:255], v[166:167], v[166:167], v[254:255]
	v_pk_fma_f32 v[252:253], v[168:169], v[168:169], v[252:253]
	v_pk_fma_f32 v[254:255], v[170:171], v[170:171], v[254:255]
	v_pk_fma_f32 v[252:253], v[172:173], v[172:173], v[252:253]
	v_pk_fma_f32 v[254:255], v[174:175], v[174:175], v[254:255]
	v_pk_add_f32 v[252:253], v[252:253], v[254:255]
	s_nop 0
	v_add_f32_e32 v183, v252, v253
	s_nop 1
	v_add_f32_dpp v183, v183, v183 quad_perm:[1,0,3,2] row_mask:0xf bank_mask:0xf bound_ctrl:1
	s_nop 1
	v_add_f32_dpp v183, v183, v183 quad_perm:[2,3,0,1] row_mask:0xf bank_mask:0xf bound_ctrl:1
	s_nop 1
	v_add_f32_dpp v183, v183, v183 row_half_mirror row_mask:0xf bank_mask:0xf bound_ctrl:1
	s_nop 1
	v_add_f32_dpp v183, v183, v183 row_mirror row_mask:0xf bank_mask:0xf bound_ctrl:1
	s_nop 1
	v_readlane_b32 s98, v183, 0
	v_readlane_b32 s99, v183, 16
	v_readlane_b32 s100, v183, 32
	v_readlane_b32 s101, v183, 48
	s_nop 1
	v_mov_b32_e32 v183, s98
	v_add_f32_e32 v183, s99, v183
	v_add_f32_e32 v183, s100, v183
	v_add_f32_e32 v183, s101, v183
	v_fmamk_f32 v183, v183, 0x3a800000, v182
	v_cmp_gt_f32_e32 vcc, 0x800000, v183
	v_mul_f32_e32 v181, 0x4b800000, v183
	s_nop 1
	v_cndmask_b32_e32 v183, v183, v181, vcc
	v_rsq_f32_e32 v183, v183
	s_nop 0
	v_mul_f32_e32 v181, 0x45800000, v183
	v_cndmask_b32_e32 v184, v183, v181, vcc
	v_mov_b32_e32 v185, v184
	v_pk_mul_f32 v[160:161], v[160:161], v[184:185]
	v_pk_mul_f32 v[162:163], v[162:163], v[184:185]
	v_pk_mul_f32 v[164:165], v[164:165], v[184:185]
	v_pk_mul_f32 v[166:167], v[166:167], v[184:185]
	v_pk_mul_f32 v[168:169], v[168:169], v[184:185]
	v_pk_mul_f32 v[170:171], v[170:171], v[184:185]
	v_pk_mul_f32 v[172:173], v[172:173], v[184:185]
	v_pk_mul_f32 v[174:175], v[174:175], v[184:185]
	v_pk_fma_f32 v[144:145], v[160:161], v[128:129], v[144:145]
	v_pk_fma_f32 v[146:147], v[162:163], v[130:131], v[146:147]
	v_pk_fma_f32 v[148:149], v[164:165], v[132:133], v[148:149]
	v_pk_fma_f32 v[150:151], v[166:167], v[134:135], v[150:151]
	v_pk_fma_f32 v[152:153], v[168:169], v[136:137], v[152:153]
	v_pk_fma_f32 v[154:155], v[170:171], v[138:139], v[154:155]
	v_pk_fma_f32 v[156:157], v[172:173], v[140:141], v[156:157]
	v_pk_fma_f32 v[158:159], v[174:175], v[142:143], v[158:159]
	v_pk_mul_f32 v[252:253], v[144:145], v[144:145]
	v_pk_mul_f32 v[254:255], v[146:147], v[146:147]
	v_pk_fma_f32 v[252:253], v[148:149], v[148:149], v[252:253]
	v_pk_fma_f32 v[254:255], v[150:151], v[150:151], v[254:255]
	v_pk_fma_f32 v[252:253], v[152:153], v[152:153], v[252:253]
	v_pk_fma_f32 v[254:255], v[154:155], v[154:155], v[254:255]
	v_pk_fma_f32 v[252:253], v[156:157], v[156:157], v[252:253]
	v_pk_fma_f32 v[254:255], v[158:159], v[158:159], v[254:255]
	v_pk_add_f32 v[252:253], v[252:253], v[254:255]
	s_nop 0
	v_add_f32_e32 v183, v252, v253
	s_nop 1
	v_add_f32_dpp v183, v183, v183 quad_perm:[1,0,3,2] row_mask:0xf bank_mask:0xf bound_ctrl:1
	s_nop 1
	v_add_f32_dpp v183, v183, v183 quad_perm:[2,3,0,1] row_mask:0xf bank_mask:0xf bound_ctrl:1
	s_nop 1
	v_add_f32_dpp v183, v183, v183 row_half_mirror row_mask:0xf bank_mask:0xf bound_ctrl:1
	s_nop 1
	v_add_f32_dpp v183, v183, v183 row_mirror row_mask:0xf bank_mask:0xf bound_ctrl:1
	s_nop 1
	v_readlane_b32 s98, v183, 0
	v_readlane_b32 s99, v183, 16
	v_readlane_b32 s100, v183, 32
	v_readlane_b32 s101, v183, 48
	s_nop 1
	v_mov_b32_e32 v183, s98
	v_add_f32_e32 v183, s99, v183
	v_add_f32_e32 v183, s100, v183
	v_add_f32_e32 v183, s101, v183
	v_fmamk_f32 v183, v183, 0x3a800000, v182
	v_cmp_gt_f32_e32 vcc, 0x800000, v183
	v_mul_f32_e32 v181, 0x4b800000, v183
	s_nop 1
	v_cndmask_b32_e32 v183, v183, v181, vcc
	v_rsq_f32_e32 v183, v183
	s_nop 0
	v_mul_f32_e32 v181, 0x45800000, v183
	v_cndmask_b32_e32 v184, v183, v181, vcc
	v_mov_b32_e32 v185, v184
	v_cvt_pk_bf16_f32 v112, v144, v145
	v_cvt_pk_bf16_f32 v113, v146, v147
	v_cvt_pk_bf16_f32 v114, v148, v149
	v_cvt_pk_bf16_f32 v115, v150, v151
	v_cvt_pk_bf16_f32 v116, v152, v153
	v_cvt_pk_bf16_f32 v117, v154, v155
	v_cvt_pk_bf16_f32 v118, v156, v157
	v_cvt_pk_bf16_f32 v119, v158, v159
	v_add_u32_e32 v181, 0x1b80000, v177
	global_store_dwordx4 v181, v[112:115], s[78:79]
	global_store_dwordx4 v181, v[116:119], s[78:79] offset:1024
	v_add_u32_e32 v236, 0x1c00, v237
	s_mov_b64 exec, 1
	global_store_dword v236, v184, s[78:79]
	s_mov_b64 exec, -1
	v_readfirstlane_b32 s98, v179
	s_nop 3
	s_cmp_ge_u32 s98, 512
	s_cbranch_scc1 .Lmyxupd_done_4
	v_lshlrev_b32_e32 v177, 4, v176
	v_lshl_add_u32 v177, v179, 11, v177
	v_lshlrev_b32_e32 v237, 2, v179
	v_add_u32_e32 v237, 0x10000, v237
	v_add_u32_e32 v181, 0x3800000, v177
	global_load_dwordx4 v[0:3], v181, s[78:79]
	global_load_dwordx4 v[4:7], v181, s[78:79] offset:1024
	v_lshl_add_u32 v183, v179, 12, v180
	v_add_u32_e32 v183, 0xbf00000, v183
	v_add_u32_e32 v181, 0x0, v183
	global_load_dwordx4 v[8:11], v181, s[78:79]
	global_load_dwordx4 v[12:15], v181, s[78:79] offset:16
	global_load_dwordx4 v[16:19], v181, s[78:79] offset:2048
	global_load_dwordx4 v[20:23], v181, s[78:79] offset:2064
	v_add_u32_e32 v181, 0x200000, v183
	global_load_dwordx4 v[24:27], v181, s[78:79]
	global_load_dwordx4 v[28:31], v181, s[78:79] offset:16
	global_load_dwordx4 v[32:35], v181, s[78:79] offset:2048
	global_load_dwordx4 v[36:39], v181, s[78:79] offset:2064
	v_add_u32_e32 v181, 0x400000, v183
	global_load_dwordx4 v[40:43], v181, s[78:79]
	global_load_dwordx4 v[44:47], v181, s[78:79] offset:16
	global_load_dwordx4 v[48:51], v181, s[78:79] offset:2048
	global_load_dwordx4 v[52:55], v181, s[78:79] offset:2064
	v_add_u32_e32 v181, 0x600000, v183
	global_load_dwordx4 v[56:59], v181, s[78:79]
	global_load_dwordx4 v[60:63], v181, s[78:79] offset:16
	global_load_dwordx4 v[64:67], v181, s[78:79] offset:2048
	global_load_dwordx4 v[68:71], v181, s[78:79] offset:2064
	v_add_u32_e32 v181, 0x800000, v183
	global_load_dwordx4 v[72:75], v181, s[78:79]
	global_load_dwordx4 v[76:79], v181, s[78:79] offset:16
	global_load_dwordx4 v[80:83], v181, s[78:79] offset:2048
	global_load_dwordx4 v[84:87], v181, s[78:79] offset:2064
	v_add_u32_e32 v181, 0xa00000, v183
	global_load_dwordx4 v[88:91], v181, s[78:79]
	global_load_dwordx4 v[92:95], v181, s[78:79] offset:16
	global_load_dwordx4 v[96:99], v181, s[78:79] offset:2048
	global_load_dwordx4 v[100:103], v181, s[78:79] offset:2064
	s_waitcnt vmcnt(20)
	v_pk_add_f32 v[160:161], v[8:9], 0 op_sel_hi:[1,0]
	v_pk_add_f32 v[162:163], v[10:11], 0 op_sel_hi:[1,0]
	v_pk_add_f32 v[164:165], v[12:13], 0 op_sel_hi:[1,0]
	v_pk_add_f32 v[166:167], v[14:15], 0 op_sel_hi:[1,0]
	v_pk_add_f32 v[168:169], v[16:17], 0 op_sel_hi:[1,0]
	v_pk_add_f32 v[170:171], v[18:19], 0 op_sel_hi:[1,0]
	v_pk_add_f32 v[172:173], v[20:21], 0 op_sel_hi:[1,0]
	v_pk_add_f32 v[174:175], v[22:23], 0 op_sel_hi:[1,0]
	s_waitcnt vmcnt(16)
	v_pk_add_f32 v[160:161], v[160:161], v[24:25]
	v_pk_add_f32 v[162:163], v[162:163], v[26:27]
	v_pk_add_f32 v[164:165], v[164:165], v[28:29]
	v_pk_add_f32 v[166:167], v[166:167], v[30:31]
	v_pk_add_f32 v[168:169], v[168:169], v[32:33]
	v_pk_add_f32 v[170:171], v[170:171], v[34:35]
	v_pk_add_f32 v[172:173], v[172:173], v[36:37]
	v_pk_add_f32 v[174:175], v[174:175], v[38:39]
	s_waitcnt vmcnt(12)
	v_pk_add_f32 v[160:161], v[160:161], v[40:41]
	v_pk_add_f32 v[162:163], v[162:163], v[42:43]
	v_pk_add_f32 v[164:165], v[164:165], v[44:45]
	v_pk_add_f32 v[166:167], v[166:167], v[46:47]
	v_pk_add_f32 v[168:169], v[168:169], v[48:49]
	v_pk_add_f32 v[170:171], v[170:171], v[50:51]
	v_pk_add_f32 v[172:173], v[172:173], v[52:53]
	v_pk_add_f32 v[174:175], v[174:175], v[54:55]
	s_waitcnt vmcnt(8)
	v_pk_add_f32 v[160:161], v[160:161], v[56:57]
	v_pk_add_f32 v[162:163], v[162:163], v[58:59]
	v_pk_add_f32 v[164:165], v[164:165], v[60:61]
	v_pk_add_f32 v[166:167], v[166:167], v[62:63]
	v_pk_add_f32 v[168:169], v[168:169], v[64:65]
	v_pk_add_f32 v[170:171], v[170:171], v[66:67]
	v_pk_add_f32 v[172:173], v[172:173], v[68:69]
	v_pk_add_f32 v[174:175], v[174:175], v[70:71]
	s_waitcnt vmcnt(4)
	v_pk_add_f32 v[160:161], v[160:161], v[72:73]
	v_pk_add_f32 v[162:163], v[162:163], v[74:75]
	v_pk_add_f32 v[164:165], v[164:165], v[76:77]
	v_pk_add_f32 v[166:167], v[166:167], v[78:79]
	v_pk_add_f32 v[168:169], v[168:169], v[80:81]
	v_pk_add_f32 v[170:171], v[170:171], v[82:83]
	v_pk_add_f32 v[172:173], v[172:173], v[84:85]
	v_pk_add_f32 v[174:175], v[174:175], v[86:87]
	s_waitcnt vmcnt(0)
	v_pk_add_f32 v[160:161], v[160:161], v[88:89]
	v_pk_add_f32 v[162:163], v[162:163], v[90:91]
	v_pk_add_f32 v[164:165], v[164:165], v[92:93]
	v_pk_add_f32 v[166:167], v[166:167], v[94:95]
	v_pk_add_f32 v[168:169], v[168:169], v[96:97]
	v_pk_add_f32 v[170:171], v[170:171], v[98:99]
	v_pk_add_f32 v[172:173], v[172:173], v[100:101]
	v_pk_add_f32 v[174:175], v[174:175], v[102:103]
	v_lshlrev_b32_e32 v144, 16, v0
	v_and_b32_e32 v145, 0xffff0000, v0
	v_lshlrev_b32_e32 v146, 16, v1
	v_and_b32_e32 v147, 0xffff0000, v1
	v_lshlrev_b32_e32 v148, 16, v2
	v_and_b32_e32 v149, 0xffff0000, v2
	v_lshlrev_b32_e32 v150, 16, v3
	v_and_b32_e32 v151, 0xffff0000, v3
	v_lshlrev_b32_e32 v152, 16, v4
	v_and_b32_e32 v153, 0xffff0000, v4
	v_lshlrev_b32_e32 v154, 16, v5
	v_and_b32_e32 v155, 0xffff0000, v5
	v_lshlrev_b32_e32 v156, 16, v6
	v_and_b32_e32 v157, 0xffff0000, v6
	v_lshlrev_b32_e32 v158, 16, v7
	v_and_b32_e32 v159, 0xffff0000, v7
	v_add_u32_e32 v181, 0xc00000, v183
	global_load_dwordx4 v[8:11], v181, s[78:79]
	global_load_dwordx4 v[12:15], v181, s[78:79] offset:16
	global_load_dwordx4 v[16:19], v181, s[78:79] offset:2048
	global_load_dwordx4 v[20:23], v181, s[78:79] offset:2064
	v_add_u32_e32 v181, 0xe00000, v183
	global_load_dwordx4 v[24:27], v181, s[78:79]
	global_load_dwordx4 v[28:31], v181, s[78:79] offset:16
	global_load_dwordx4 v[32:35], v181, s[78:79] offset:2048
	global_load_dwordx4 v[36:39], v181, s[78:79] offset:2064
	s_waitcnt vmcnt(4)
	v_pk_add_f32 v[160:161], v[160:161], v[8:9]
	v_pk_add_f32 v[162:163], v[162:163], v[10:11]
	v_pk_add_f32 v[164:165], v[164:165], v[12:13]
	v_pk_add_f32 v[166:167], v[166:167], v[14:15]
	v_pk_add_f32 v[168:169], v[168:169], v[16:17]
	v_pk_add_f32 v[170:171], v[170:171], v[18:19]
	v_pk_add_f32 v[172:173], v[172:173], v[20:21]
	v_pk_add_f32 v[174:175], v[174:175], v[22:23]
	s_waitcnt vmcnt(0)
	v_pk_add_f32 v[160:161], v[160:161], v[24:25]
	v_pk_add_f32 v[162:163], v[162:163], v[26:27]
	v_pk_add_f32 v[164:165], v[164:165], v[28:29]
	v_pk_add_f32 v[166:167], v[166:167], v[30:31]
	v_pk_add_f32 v[168:169], v[168:169], v[32:33]
	v_pk_add_f32 v[170:171], v[170:171], v[34:35]
	v_pk_add_f32 v[172:173], v[172:173], v[36:37]
	v_pk_add_f32 v[174:175], v[174:175], v[38:39]
	v_pk_mul_f32 v[252:253], v[160:161], v[160:161]
	v_pk_mul_f32 v[254:255], v[162:163], v[162:163]
	v_pk_fma_f32 v[252:253], v[164:165], v[164:165], v[252:253]
	v_pk_fma_f32 v[254:255], v[166:167], v[166:167], v[254:255]
	v_pk_fma_f32 v[252:253], v[168:169], v[168:169], v[252:253]
	v_pk_fma_f32 v[254:255], v[170:171], v[170:171], v[254:255]
	v_pk_fma_f32 v[252:253], v[172:173], v[172:173], v[252:253]
	v_pk_fma_f32 v[254:255], v[174:175], v[174:175], v[254:255]
	v_pk_add_f32 v[252:253], v[252:253], v[254:255]
	s_nop 0
	v_add_f32_e32 v183, v252, v253
	s_nop 1
	v_add_f32_dpp v183, v183, v183 quad_perm:[1,0,3,2] row_mask:0xf bank_mask:0xf bound_ctrl:1
	s_nop 1
	v_add_f32_dpp v183, v183, v183 quad_perm:[2,3,0,1] row_mask:0xf bank_mask:0xf bound_ctrl:1
	s_nop 1
	v_add_f32_dpp v183, v183, v183 row_half_mirror row_mask:0xf bank_mask:0xf bound_ctrl:1
	s_nop 1
	v_add_f32_dpp v183, v183, v183 row_mirror row_mask:0xf bank_mask:0xf bound_ctrl:1
	s_nop 1
	v_readlane_b32 s98, v183, 0
	v_readlane_b32 s99, v183, 16
	v_readlane_b32 s100, v183, 32
	v_readlane_b32 s101, v183, 48
	s_nop 1
	v_mov_b32_e32 v183, s98
	v_add_f32_e32 v183, s99, v183
	v_add_f32_e32 v183, s100, v183
	v_add_f32_e32 v183, s101, v183
	v_fmamk_f32 v183, v183, 0x3a800000, v182
	v_cmp_gt_f32_e32 vcc, 0x800000, v183
	v_mul_f32_e32 v181, 0x4b800000, v183
	s_nop 1
	v_cndmask_b32_e32 v183, v183, v181, vcc
	v_rsq_f32_e32 v183, v183
	s_nop 0
	v_mul_f32_e32 v181, 0x45800000, v183
	v_cndmask_b32_e32 v184, v183, v181, vcc
	v_mov_b32_e32 v185, v184
	v_pk_mul_f32 v[160:161], v[160:161], v[184:185]
	v_pk_mul_f32 v[162:163], v[162:163], v[184:185]
	v_pk_mul_f32 v[164:165], v[164:165], v[184:185]
	v_pk_mul_f32 v[166:167], v[166:167], v[184:185]
	v_pk_mul_f32 v[168:169], v[168:169], v[184:185]
	v_pk_mul_f32 v[170:171], v[170:171], v[184:185]
	v_pk_mul_f32 v[172:173], v[172:173], v[184:185]
	v_pk_mul_f32 v[174:175], v[174:175], v[184:185]
	v_pk_fma_f32 v[144:145], v[160:161], v[128:129], v[144:145]
	v_pk_fma_f32 v[146:147], v[162:163], v[130:131], v[146:147]
	v_pk_fma_f32 v[148:149], v[164:165], v[132:133], v[148:149]
	v_pk_fma_f32 v[150:151], v[166:167], v[134:135], v[150:151]
	v_pk_fma_f32 v[152:153], v[168:169], v[136:137], v[152:153]
	v_pk_fma_f32 v[154:155], v[170:171], v[138:139], v[154:155]
	v_pk_fma_f32 v[156:157], v[172:173], v[140:141], v[156:157]
	v_pk_fma_f32 v[158:159], v[174:175], v[142:143], v[158:159]
	v_pk_mul_f32 v[252:253], v[144:145], v[144:145]
	v_pk_mul_f32 v[254:255], v[146:147], v[146:147]
	v_pk_fma_f32 v[252:253], v[148:149], v[148:149], v[252:253]
	v_pk_fma_f32 v[254:255], v[150:151], v[150:151], v[254:255]
	v_pk_fma_f32 v[252:253], v[152:153], v[152:153], v[252:253]
	v_pk_fma_f32 v[254:255], v[154:155], v[154:155], v[254:255]
	v_pk_fma_f32 v[252:253], v[156:157], v[156:157], v[252:253]
	v_pk_fma_f32 v[254:255], v[158:159], v[158:159], v[254:255]
	v_pk_add_f32 v[252:253], v[252:253], v[254:255]
	s_nop 0
	v_add_f32_e32 v183, v252, v253
	s_nop 1
	v_add_f32_dpp v183, v183, v183 quad_perm:[1,0,3,2] row_mask:0xf bank_mask:0xf bound_ctrl:1
	s_nop 1
	v_add_f32_dpp v183, v183, v183 quad_perm:[2,3,0,1] row_mask:0xf bank_mask:0xf bound_ctrl:1
	s_nop 1
	v_add_f32_dpp v183, v183, v183 row_half_mirror row_mask:0xf bank_mask:0xf bound_ctrl:1
	s_nop 1
	v_add_f32_dpp v183, v183, v183 row_mirror row_mask:0xf bank_mask:0xf bound_ctrl:1
	s_nop 1
	v_readlane_b32 s98, v183, 0
	v_readlane_b32 s99, v183, 16
	v_readlane_b32 s100, v183, 32
	v_readlane_b32 s101, v183, 48
	s_nop 1
	v_mov_b32_e32 v183, s98
	v_add_f32_e32 v183, s99, v183
	v_add_f32_e32 v183, s100, v183
	v_add_f32_e32 v183, s101, v183
	v_fmamk_f32 v183, v183, 0x3a800000, v182
	v_cmp_gt_f32_e32 vcc, 0x800000, v183
	v_mul_f32_e32 v181, 0x4b800000, v183
	s_nop 1
	v_cndmask_b32_e32 v183, v183, v181, vcc
	v_rsq_f32_e32 v183, v183
	s_nop 0
	v_mul_f32_e32 v181, 0x45800000, v183
	v_cndmask_b32_e32 v184, v183, v181, vcc
	v_mov_b32_e32 v185, v184
	v_cvt_pk_bf16_f32 v0, v144, v145
	v_cvt_pk_bf16_f32 v1, v146, v147
	v_cvt_pk_bf16_f32 v2, v148, v149
	v_cvt_pk_bf16_f32 v3, v150, v151
	v_cvt_pk_bf16_f32 v4, v152, v153
	v_cvt_pk_bf16_f32 v5, v154, v155
	v_cvt_pk_bf16_f32 v6, v156, v157
	v_cvt_pk_bf16_f32 v7, v158, v159
	v_add_u32_e32 v181, 0x3800000, v177
	global_store_dwordx4 v181, v[0:3], s[78:79]
	global_store_dwordx4 v181, v[4:7], s[78:79] offset:1024
	v_add_u32_e32 v236, 0x10000, v237
	s_mov_b64 exec, 1
	global_store_dword v236, v184, s[78:79]
	s_mov_b64 exec, -1

.LBB0_2139:
	v_readlane_b32 s0, v235, 52
	v_readlane_b32 s1, v235, 53
	s_and_b64 vcc, exec, s[0:1]
	s_waitcnt lgkmcnt(0)
	s_barrier
	v_mbcnt_lo_u32_b32 v0, -1, 0
	v_mbcnt_hi_u32_b32 v0, -1, v0
	s_cbranch_vccnz .LBB0_2159
	v_lshlrev_b32_e32 v2, 3, v0
	v_readlane_b32 s4, v235, 4
	v_ashrrev_i32_e32 v3, 31, v2
	v_readlane_b32 s6, v235, 6
	v_readlane_b32 s7, v235, 7
	v_lshlrev_b64 v[4:5], 1, v[2:3]
	v_lshlrev_b64 v[2:3], 2, v[2:3]
	v_readlane_b32 s5, v235, 5
	v_readlane_b32 s10, v235, 10
	v_readlane_b32 s11, v235, 11
	v_readlane_b32 s18, v235, 18
	v_readlane_b32 s19, v235, 19
	v_readlane_b32 s6, v235, 61
	v_lshl_add_u64 v[154:155], s[90:91], 0, v[2:3]
	v_readlane_b32 s8, v235, 8
	v_lshl_add_u64 v[2:3], s[18:19], 0, v[2:3]
	s_mov_b64 s[0:1], 0x2000
	v_readlane_b32 s4, v235, 0
	v_readlane_b32 s7, v235, 62
	s_mov_b32 s10, s6
	s_ashr_i32 s11, s6, 31
	v_readlane_b32 s9, v235, 9
	v_lshl_add_u64 v[158:159], v[2:3], 0, s[0:1]
	s_lshl_b32 s4, s4, 4
	s_add_i32 s0, s6, 0xffffc000
	s_lshl_b64 s[6:7], s[10:11], 2
	s_mov_b32 s8, s10
	v_readlane_b32 s12, v235, 12
	v_readlane_b32 s13, v235, 13
	v_readlane_b32 s14, v235, 14
	v_readlane_b32 s15, v235, 15
	v_readlane_b32 s16, v235, 16
	v_readlane_b32 s17, v235, 17
	v_readlane_b32 s5, v235, 1
	s_add_u32 s80, s6, 0x10000
	v_writelane_b32 v235, s8, 61
	s_addc_u32 s12, s7, 0
	s_ashr_i32 s5, s4, 31
	v_writelane_b32 v235, s9, 62
	s_lshl_b64 s[8:9], s[10:11], 11
	v_lshl_add_u64 v[152:153], s[86:87], 0, v[4:5]
	v_lshl_add_u64 v[156:157], s[54:55], 0, v[4:5]
	s_mov_b32 s1, 0
	v_cmp_eq_u32_e64 s[16:17], 0, v0
	s_lshl_b64 s[6:7], s[4:5], 2
	v_lshl_add_u64 v[160:161], s[8:9], 0, v[4:5]
	s_lshl_b64 s[8:9], s[4:5], 11
	s_mov_b64 s[20:21], 0x600000
	s_mov_b64 s[22:23], 0x600800
	s_mov_b64 s[24:25], 0x800000
	s_mov_b32 s5, 0x800000
	s_mov_b64 s[26:27], 0x800800
	s_mov_b64 s[28:29], 0xa00000
	s_mov_b64 s[36:37], 0xa00800
	s_mov_b64 s[38:39], 0xc00000
	s_mov_b64 s[40:41], 0xc00800
	s_mov_b64 s[42:43], 0xe00000
	s_mov_b64 s[44:45], 0xe00800
	s_mov_b64 s[46:47], 0x1000000
	s_mov_b32 s13, 0x1000000
	s_mov_b64 s[48:49], 0x1000800
	s_mov_b64 s[50:51], 0x1200000
	s_mov_b32 s14, 0x1200000
	s_mov_b64 s[10:11], 0x1200800
	s_mov_b64 s[82:83], 0x1400000
	s_mov_b32 s15, 0x1400000
	s_mov_b64 s[90:91], 0x1400800
	v_mov_b32_e32 v215, 0
	v_mov_b32_e32 v216, 0x358637bd
	v_mbcnt_lo_u32_b32 v176, -1, 0
	v_mbcnt_hi_u32_b32 v176, -1, v176
	v_readlane_b32 s98, v235, 49
	v_readlane_b32 s99, v235, 20
	v_readlane_b32 s100, v235, 18
	v_readlane_b32 s101, v235, 19
	s_nop 3
	s_lshr_b32 vcc_lo, s98, 3
	s_and_b32 vcc_hi, vcc_lo, 7
	s_lshr_b32 vcc_lo, vcc_lo, 3
	s_lshl_b32 vcc_lo, vcc_lo, 3
	s_add_i32 vcc_lo, vcc_lo, s99
	s_lshl_b32 s98, vcc_hi, 8
	s_add_i32 s98, s98, vcc_lo
	s_lshl_b32 s99, vcc_hi, 11
	s_add_i32 s99, s99, vcc_lo
	v_mov_b32_e32 v183, s99
	v_lshlrev_b32_e32 v177, 4, v176
	s_lshl_b32 s99, s99, 11
	v_add_u32_e32 v177, s99, v177
	v_add_u32_e32 v178, 0x1800000, v177
	v_add_u32_e32 v179, 0x9e00000, v177
	v_lshlrev_b32_e32 v180, 5, v176
	v_add_u32_e32 v181, 0x2000, v180
	global_load_dwordx4 v[128:131], v181, s[100:101]
	global_load_dwordx4 v[132:135], v181, s[100:101] offset:16
	global_load_dwordx4 v[136:139], v181, s[100:101] offset:2048
	global_load_dwordx4 v[140:143], v181, s[100:101] offset:2064
	v_mov_b32_e32 v182, 0x358637bd
	global_load_dwordx4 v[0:3], v178, s[78:79]
	global_load_dwordx4 v[4:7], v178, s[78:79] offset:1024
	global_load_dwordx4 v[8:11], v179, s[78:79]
	global_load_dwordx4 v[12:15], v179, s[78:79] offset:1024
	v_add_u32_e32 v178, 0x80000, v178
	v_add_u32_e32 v179, 0x80000, v179
	global_load_dwordx4 v[16:19], v178, s[78:79]
	global_load_dwordx4 v[20:23], v178, s[78:79] offset:1024
	global_load_dwordx4 v[24:27], v179, s[78:79]
	global_load_dwordx4 v[28:31], v179, s[78:79] offset:1024
	v_add_u32_e32 v178, 0x80000, v178
	v_add_u32_e32 v179, 0x80000, v179
	global_load_dwordx4 v[32:35], v178, s[78:79]
	global_load_dwordx4 v[36:39], v178, s[78:79] offset:1024
	global_load_dwordx4 v[40:43], v179, s[78:79]
	global_load_dwordx4 v[44:47], v179, s[78:79] offset:1024
	v_add_u32_e32 v178, 0x80000, v178
	v_add_u32_e32 v179, 0x80000, v179
	global_load_dwordx4 v[48:51], v178, s[78:79]
	global_load_dwordx4 v[52:55], v178, s[78:79] offset:1024
	global_load_dwordx4 v[56:59], v179, s[78:79]
	global_load_dwordx4 v[60:63], v179, s[78:79] offset:1024
	v_add_u32_e32 v178, 0x80000, v178
	v_add_u32_e32 v179, 0x80000, v179
	global_load_dwordx4 v[64:67], v178, s[78:79]
	global_load_dwordx4 v[68:71], v178, s[78:79] offset:1024
	global_load_dwordx4 v[72:75], v179, s[78:79]
	global_load_dwordx4 v[76:79], v179, s[78:79] offset:1024
	v_add_u32_e32 v178, 0x80000, v178
	v_add_u32_e32 v179, 0x80000, v179
	global_load_dwordx4 v[80:83], v178, s[78:79]
	global_load_dwordx4 v[84:87], v178, s[78:79] offset:1024
	global_load_dwordx4 v[88:91], v179, s[78:79]
	global_load_dwordx4 v[92:95], v179, s[78:79] offset:1024
	v_add_u32_e32 v178, 0x80000, v178
	v_add_u32_e32 v179, 0x80000, v179
	global_load_dwordx4 v[96:99], v178, s[78:79]
	global_load_dwordx4 v[100:103], v178, s[78:79] offset:1024
	global_load_dwordx4 v[104:107], v179, s[78:79]
	global_load_dwordx4 v[108:111], v179, s[78:79] offset:1024
	v_add_u32_e32 v178, 0x80000, v178
	v_add_u32_e32 v179, 0x80000, v179
	global_load_dwordx4 v[112:115], v178, s[78:79]
	global_load_dwordx4 v[116:119], v178, s[78:79] offset:1024
	global_load_dwordx4 v[120:123], v179, s[78:79]
	global_load_dwordx4 v[124:127], v179, s[78:79] offset:1024
	v_lshlrev_b32_e32 v237, 2, v183
	v_add_u32_e32 v237, 0x10000, v237
	v_mov_b32_e32 v179, s98
	s_waitcnt vmcnt(28)
	v_lshlrev_b32_e32 v144, 16, v0
	v_and_b32_e32 v145, 0xffff0000, v0
	v_lshlrev_b32_e32 v146, 16, v1
	v_and_b32_e32 v147, 0xffff0000, v1
	v_lshlrev_b32_e32 v148, 16, v2
	v_and_b32_e32 v149, 0xffff0000, v2
	v_lshlrev_b32_e32 v150, 16, v3
	v_and_b32_e32 v151, 0xffff0000, v3
	v_lshlrev_b32_e32 v152, 16, v4
	v_and_b32_e32 v153, 0xffff0000, v4
	v_lshlrev_b32_e32 v154, 16, v5
	v_and_b32_e32 v155, 0xffff0000, v5
	v_lshlrev_b32_e32 v156, 16, v6
	v_and_b32_e32 v157, 0xffff0000, v6
	v_lshlrev_b32_e32 v158, 16, v7
	v_and_b32_e32 v159, 0xffff0000, v7
	v_lshlrev_b32_e32 v160, 16, v8
	v_and_b32_e32 v161, 0xffff0000, v8
	v_lshlrev_b32_e32 v162, 16, v9
	v_and_b32_e32 v163, 0xffff0000, v9
	v_lshlrev_b32_e32 v164, 16, v10
	v_and_b32_e32 v165, 0xffff0000, v10
	v_lshlrev_b32_e32 v166, 16, v11
	v_and_b32_e32 v167, 0xffff0000, v11
	v_lshlrev_b32_e32 v168, 16, v12
	v_and_b32_e32 v169, 0xffff0000, v12
	v_lshlrev_b32_e32 v170, 16, v13
	v_and_b32_e32 v171, 0xffff0000, v13
	v_lshlrev_b32_e32 v172, 16, v14
	v_and_b32_e32 v173, 0xffff0000, v14
	v_lshlrev_b32_e32 v174, 16, v15
	v_and_b32_e32 v175, 0xffff0000, v15
	v_pk_mul_f32 v[252:253], v[160:161], v[160:161]
	v_pk_mul_f32 v[254:255], v[162:163], v[162:163]
	v_pk_fma_f32 v[252:253], v[164:165], v[164:165], v[252:253]
	v_pk_fma_f32 v[254:255], v[166:167], v[166:167], v[254:255]
	v_pk_fma_f32 v[252:253], v[168:169], v[168:169], v[252:253]
	v_pk_fma_f32 v[254:255], v[170:171], v[170:171], v[254:255]
	v_pk_fma_f32 v[252:253], v[172:173], v[172:173], v[252:253]
	v_pk_fma_f32 v[254:255], v[174:175], v[174:175], v[254:255]
	v_pk_add_f32 v[252:253], v[252:253], v[254:255]
	s_nop 0
	v_add_f32_e32 v183, v252, v253
	s_nop 1
	v_add_f32_dpp v183, v183, v183 quad_perm:[1,0,3,2] row_mask:0xf bank_mask:0xf bound_ctrl:1
	s_nop 1
	v_add_f32_dpp v183, v183, v183 quad_perm:[2,3,0,1] row_mask:0xf bank_mask:0xf bound_ctrl:1
	s_nop 1
	v_add_f32_dpp v183, v183, v183 row_half_mirror row_mask:0xf bank_mask:0xf bound_ctrl:1
	s_nop 1
	v_add_f32_dpp v183, v183, v183 row_mirror row_mask:0xf bank_mask:0xf bound_ctrl:1
	s_nop 1
	v_readlane_b32 s98, v183, 0
	v_readlane_b32 s99, v183, 16
	v_readlane_b32 s100, v183, 32
	v_readlane_b32 s101, v183, 48
	s_nop 1
	v_mov_b32_e32 v183, s98
	v_add_f32_e32 v183, s99, v183
	v_add_f32_e32 v183, s100, v183
	v_add_f32_e32 v183, s101, v183
	v_fmamk_f32 v183, v183, 0x3a800000, v182
	v_cmp_gt_f32_e32 vcc, 0x800000, v183
	v_mul_f32_e32 v181, 0x4b800000, v183
	s_nop 1
	v_cndmask_b32_e32 v183, v183, v181, vcc
	v_rsq_f32_e32 v183, v183
	s_nop 0
	v_mul_f32_e32 v181, 0x45800000, v183
	v_cndmask_b32_e32 v184, v183, v181, vcc
	v_mov_b32_e32 v185, v184
	v_pk_mul_f32 v[160:161], v[160:161], v[184:185]
	v_pk_mul_f32 v[162:163], v[162:163], v[184:185]
	v_pk_mul_f32 v[164:165], v[164:165], v[184:185]
	v_pk_mul_f32 v[166:167], v[166:167], v[184:185]
	v_pk_mul_f32 v[168:169], v[168:169], v[184:185]
	v_pk_mul_f32 v[170:171], v[170:171], v[184:185]
	v_pk_mul_f32 v[172:173], v[172:173], v[184:185]
	v_pk_mul_f32 v[174:175], v[174:175], v[184:185]
	v_pk_fma_f32 v[144:145], v[160:161], v[128:129], v[144:145]
	v_pk_fma_f32 v[146:147], v[162:163], v[130:131], v[146:147]
	v_pk_fma_f32 v[148:149], v[164:165], v[132:133], v[148:149]
	v_pk_fma_f32 v[150:151], v[166:167], v[134:135], v[150:151]
	v_pk_fma_f32 v[152:153], v[168:169], v[136:137], v[152:153]
	v_pk_fma_f32 v[154:155], v[170:171], v[138:139], v[154:155]
	v_pk_fma_f32 v[156:157], v[172:173], v[140:141], v[156:157]
	v_pk_fma_f32 v[158:159], v[174:175], v[142:143], v[158:159]
	v_pk_mul_f32 v[252:253], v[144:145], v[144:145]
	v_pk_mul_f32 v[254:255], v[146:147], v[146:147]
	v_pk_fma_f32 v[252:253], v[148:149], v[148:149], v[252:253]
	v_pk_fma_f32 v[254:255], v[150:151], v[150:151], v[254:255]
	v_pk_fma_f32 v[252:253], v[152:153], v[152:153], v[252:253]
	v_pk_fma_f32 v[254:255], v[154:155], v[154:155], v[254:255]
	v_pk_fma_f32 v[252:253], v[156:157], v[156:157], v[252:253]
	v_pk_fma_f32 v[254:255], v[158:159], v[158:159], v[254:255]
	v_pk_add_f32 v[252:253], v[252:253], v[254:255]
	s_nop 0
	v_add_f32_e32 v183, v252, v253
	s_nop 1
	v_add_f32_dpp v183, v183, v183 quad_perm:[1,0,3,2] row_mask:0xf bank_mask:0xf bound_ctrl:1
	s_nop 1
	v_add_f32_dpp v183, v183, v183 quad_perm:[2,3,0,1] row_mask:0xf bank_mask:0xf bound_ctrl:1
	s_nop 1
	v_add_f32_dpp v183, v183, v183 row_half_mirror row_mask:0xf bank_mask:0xf bound_ctrl:1
	s_nop 1
	v_add_f32_dpp v183, v183, v183 row_mirror row_mask:0xf bank_mask:0xf bound_ctrl:1
	s_nop 1
	v_readlane_b32 s98, v183, 0
	v_readlane_b32 s99, v183, 16
	v_readlane_b32 s100, v183, 32
	v_readlane_b32 s101, v183, 48
	s_nop 1
	v_mov_b32_e32 v183, s98
	v_add_f32_e32 v183, s99, v183
	v_add_f32_e32 v183, s100, v183
	v_add_f32_e32 v183, s101, v183
	v_fmamk_f32 v183, v183, 0x3a800000, v182
	v_cmp_gt_f32_e32 vcc, 0x800000, v183
	v_mul_f32_e32 v181, 0x4b800000, v183
	s_nop 1
	v_cndmask_b32_e32 v183, v183, v181, vcc
	v_rsq_f32_e32 v183, v183
	s_nop 0
	v_mul_f32_e32 v181, 0x45800000, v183
	v_cndmask_b32_e32 v184, v183, v181, vcc
	v_mov_b32_e32 v185, v184
	v_cvt_pk_bf16_f32 v0, v144, v145
	v_cvt_pk_bf16_f32 v1, v146, v147
	v_cvt_pk_bf16_f32 v2, v148, v149
	v_cvt_pk_bf16_f32 v3, v150, v151
	v_cvt_pk_bf16_f32 v4, v152, v153
	v_cvt_pk_bf16_f32 v5, v154, v155
	v_cvt_pk_bf16_f32 v6, v156, v157
	v_cvt_pk_bf16_f32 v7, v158, v159
	v_add_u32_e32 v181, 0x1800000, v177
	global_store_dwordx4 v181, v[0:3], s[78:79]
	global_store_dwordx4 v181, v[4:7], s[78:79] offset:1024
	v_add_u32_e32 v236, 0x0, v237
	s_mov_b64 exec, 1
	global_store_dword v236, v184, s[78:79]
	s_mov_b64 exec, -1
	s_waitcnt vmcnt(24)
	v_lshlrev_b32_e32 v144, 16, v16
	v_and_b32_e32 v145, 0xffff0000, v16
	v_lshlrev_b32_e32 v146, 16, v17
	v_and_b32_e32 v147, 0xffff0000, v17
	v_lshlrev_b32_e32 v148, 16, v18
	v_and_b32_e32 v149, 0xffff0000, v18
	v_lshlrev_b32_e32 v150, 16, v19
	v_and_b32_e32 v151, 0xffff0000, v19
	v_lshlrev_b32_e32 v152, 16, v20
	v_and_b32_e32 v153, 0xffff0000, v20
	v_lshlrev_b32_e32 v154, 16, v21
	v_and_b32_e32 v155, 0xffff0000, v21
	v_lshlrev_b32_e32 v156, 16, v22
	v_and_b32_e32 v157, 0xffff0000, v22
	v_lshlrev_b32_e32 v158, 16, v23
	v_and_b32_e32 v159, 0xffff0000, v23
	v_lshlrev_b32_e32 v160, 16, v24
	v_and_b32_e32 v161, 0xffff0000, v24
	v_lshlrev_b32_e32 v162, 16, v25
	v_and_b32_e32 v163, 0xffff0000, v25
	v_lshlrev_b32_e32 v164, 16, v26
	v_and_b32_e32 v165, 0xffff0000, v26
	v_lshlrev_b32_e32 v166, 16, v27
	v_and_b32_e32 v167, 0xffff0000, v27
	v_lshlrev_b32_e32 v168, 16, v28
	v_and_b32_e32 v169, 0xffff0000, v28
	v_lshlrev_b32_e32 v170, 16, v29
	v_and_b32_e32 v171, 0xffff0000, v29
	v_lshlrev_b32_e32 v172, 16, v30
	v_and_b32_e32 v173, 0xffff0000, v30
	v_lshlrev_b32_e32 v174, 16, v31
	v_and_b32_e32 v175, 0xffff0000, v31
	v_pk_mul_f32 v[252:253], v[160:161], v[160:161]
	v_pk_mul_f32 v[254:255], v[162:163], v[162:163]
	v_pk_fma_f32 v[252:253], v[164:165], v[164:165], v[252:253]
	v_pk_fma_f32 v[254:255], v[166:167], v[166:167], v[254:255]
	v_pk_fma_f32 v[252:253], v[168:169], v[168:169], v[252:253]
	v_pk_fma_f32 v[254:255], v[170:171], v[170:171], v[254:255]
	v_pk_fma_f32 v[252:253], v[172:173], v[172:173], v[252:253]
	v_pk_fma_f32 v[254:255], v[174:175], v[174:175], v[254:255]
	v_pk_add_f32 v[252:253], v[252:253], v[254:255]
	s_nop 0
	v_add_f32_e32 v183, v252, v253
	s_nop 1
	v_add_f32_dpp v183, v183, v183 quad_perm:[1,0,3,2] row_mask:0xf bank_mask:0xf bound_ctrl:1
	s_nop 1
	v_add_f32_dpp v183, v183, v183 quad_perm:[2,3,0,1] row_mask:0xf bank_mask:0xf bound_ctrl:1
	s_nop 1
	v_add_f32_dpp v183, v183, v183 row_half_mirror row_mask:0xf bank_mask:0xf bound_ctrl:1
	s_nop 1
	v_add_f32_dpp v183, v183, v183 row_mirror row_mask:0xf bank_mask:0xf bound_ctrl:1
	s_nop 1
	v_readlane_b32 s98, v183, 0
	v_readlane_b32 s99, v183, 16
	v_readlane_b32 s100, v183, 32
	v_readlane_b32 s101, v183, 48
	s_nop 1
	v_mov_b32_e32 v183, s98
	v_add_f32_e32 v183, s99, v183
	v_add_f32_e32 v183, s100, v183
	v_add_f32_e32 v183, s101, v183
	v_fmamk_f32 v183, v183, 0x3a800000, v182
	v_cmp_gt_f32_e32 vcc, 0x800000, v183
	v_mul_f32_e32 v181, 0x4b800000, v183
	s_nop 1
	v_cndmask_b32_e32 v183, v183, v181, vcc
	v_rsq_f32_e32 v183, v183
	s_nop 0
	v_mul_f32_e32 v181, 0x45800000, v183
	v_cndmask_b32_e32 v184, v183, v181, vcc
	v_mov_b32_e32 v185, v184
	v_pk_mul_f32 v[160:161], v[160:161], v[184:185]
	v_pk_mul_f32 v[162:163], v[162:163], v[184:185]
	v_pk_mul_f32 v[164:165], v[164:165], v[184:185]
	v_pk_mul_f32 v[166:167], v[166:167], v[184:185]
	v_pk_mul_f32 v[168:169], v[168:169], v[184:185]
	v_pk_mul_f32 v[170:171], v[170:171], v[184:185]
	v_pk_mul_f32 v[172:173], v[172:173], v[184:185]
	v_pk_mul_f32 v[174:175], v[174:175], v[184:185]
	v_pk_fma_f32 v[144:145], v[160:161], v[128:129], v[144:145]
	v_pk_fma_f32 v[146:147], v[162:163], v[130:131], v[146:147]
	v_pk_fma_f32 v[148:149], v[164:165], v[132:133], v[148:149]
	v_pk_fma_f32 v[150:151], v[166:167], v[134:135], v[150:151]
	v_pk_fma_f32 v[152:153], v[168:169], v[136:137], v[152:153]
	v_pk_fma_f32 v[154:155], v[170:171], v[138:139], v[154:155]
	v_pk_fma_f32 v[156:157], v[172:173], v[140:141], v[156:157]
	v_pk_fma_f32 v[158:159], v[174:175], v[142:143], v[158:159]
	v_pk_mul_f32 v[252:253], v[144:145], v[144:145]
	v_pk_mul_f32 v[254:255], v[146:147], v[146:147]
	v_pk_fma_f32 v[252:253], v[148:149], v[148:149], v[252:253]
	v_pk_fma_f32 v[254:255], v[150:151], v[150:151], v[254:255]
	v_pk_fma_f32 v[252:253], v[152:153], v[152:153], v[252:253]
	v_pk_fma_f32 v[254:255], v[154:155], v[154:155], v[254:255]
	v_pk_fma_f32 v[252:253], v[156:157], v[156:157], v[252:253]
	v_pk_fma_f32 v[254:255], v[158:159], v[158:159], v[254:255]
	v_pk_add_f32 v[252:253], v[252:253], v[254:255]
	s_nop 0
	v_add_f32_e32 v183, v252, v253
	s_nop 1
	v_add_f32_dpp v183, v183, v183 quad_perm:[1,0,3,2] row_mask:0xf bank_mask:0xf bound_ctrl:1
	s_nop 1
	v_add_f32_dpp v183, v183, v183 quad_perm:[2,3,0,1] row_mask:0xf bank_mask:0xf bound_ctrl:1
	s_nop 1
	v_add_f32_dpp v183, v183, v183 row_half_mirror row_mask:0xf bank_mask:0xf bound_ctrl:1
	s_nop 1
	v_add_f32_dpp v183, v183, v183 row_mirror row_mask:0xf bank_mask:0xf bound_ctrl:1
	s_nop 1
	v_readlane_b32 s98, v183, 0
	v_readlane_b32 s99, v183, 16
	v_readlane_b32 s100, v183, 32
	v_readlane_b32 s101, v183, 48
	s_nop 1
	v_mov_b32_e32 v183, s98
	v_add_f32_e32 v183, s99, v183
	v_add_f32_e32 v183, s100, v183
	v_add_f32_e32 v183, s101, v183
	v_fmamk_f32 v183, v183, 0x3a800000, v182
	v_cmp_gt_f32_e32 vcc, 0x800000, v183
	v_mul_f32_e32 v181, 0x4b800000, v183
	s_nop 1
	v_cndmask_b32_e32 v183, v183, v181, vcc
	v_rsq_f32_e32 v183, v183
	s_nop 0
	v_mul_f32_e32 v181, 0x45800000, v183
	v_cndmask_b32_e32 v184, v183, v181, vcc
	v_mov_b32_e32 v185, v184
	v_cvt_pk_bf16_f32 v16, v144, v145
	v_cvt_pk_bf16_f32 v17, v146, v147
	v_cvt_pk_bf16_f32 v18, v148, v149
	v_cvt_pk_bf16_f32 v19, v150, v151
	v_cvt_pk_bf16_f32 v20, v152, v153
	v_cvt_pk_bf16_f32 v21, v154, v155
	v_cvt_pk_bf16_f32 v22, v156, v157
	v_cvt_pk_bf16_f32 v23, v158, v159
	v_add_u32_e32 v181, 0x1880000, v177
	global_store_dwordx4 v181, v[16:19], s[78:79]
	global_store_dwordx4 v181, v[20:23], s[78:79] offset:1024
	v_add_u32_e32 v236, 0x400, v237
	s_mov_b64 exec, 1
	global_store_dword v236, v184, s[78:79]
	s_mov_b64 exec, -1
	s_waitcnt vmcnt(20)
	v_lshlrev_b32_e32 v144, 16, v32
	v_and_b32_e32 v145, 0xffff0000, v32
	v_lshlrev_b32_e32 v146, 16, v33
	v_and_b32_e32 v147, 0xffff0000, v33
	v_lshlrev_b32_e32 v148, 16, v34
	v_and_b32_e32 v149, 0xffff0000, v34
	v_lshlrev_b32_e32 v150, 16, v35
	v_and_b32_e32 v151, 0xffff0000, v35
	v_lshlrev_b32_e32 v152, 16, v36
	v_and_b32_e32 v153, 0xffff0000, v36
	v_lshlrev_b32_e32 v154, 16, v37
	v_and_b32_e32 v155, 0xffff0000, v37
	v_lshlrev_b32_e32 v156, 16, v38
	v_and_b32_e32 v157, 0xffff0000, v38
	v_lshlrev_b32_e32 v158, 16, v39
	v_and_b32_e32 v159, 0xffff0000, v39
	v_lshlrev_b32_e32 v160, 16, v40
	v_and_b32_e32 v161, 0xffff0000, v40
	v_lshlrev_b32_e32 v162, 16, v41
	v_and_b32_e32 v163, 0xffff0000, v41
	v_lshlrev_b32_e32 v164, 16, v42
	v_and_b32_e32 v165, 0xffff0000, v42
	v_lshlrev_b32_e32 v166, 16, v43
	v_and_b32_e32 v167, 0xffff0000, v43
	v_lshlrev_b32_e32 v168, 16, v44
	v_and_b32_e32 v169, 0xffff0000, v44
	v_lshlrev_b32_e32 v170, 16, v45
	v_and_b32_e32 v171, 0xffff0000, v45
	v_lshlrev_b32_e32 v172, 16, v46
	v_and_b32_e32 v173, 0xffff0000, v46
	v_lshlrev_b32_e32 v174, 16, v47
	v_and_b32_e32 v175, 0xffff0000, v47
	v_pk_mul_f32 v[252:253], v[160:161], v[160:161]
	v_pk_mul_f32 v[254:255], v[162:163], v[162:163]
	v_pk_fma_f32 v[252:253], v[164:165], v[164:165], v[252:253]
	v_pk_fma_f32 v[254:255], v[166:167], v[166:167], v[254:255]
	v_pk_fma_f32 v[252:253], v[168:169], v[168:169], v[252:253]
	v_pk_fma_f32 v[254:255], v[170:171], v[170:171], v[254:255]
	v_pk_fma_f32 v[252:253], v[172:173], v[172:173], v[252:253]
	v_pk_fma_f32 v[254:255], v[174:175], v[174:175], v[254:255]
	v_pk_add_f32 v[252:253], v[252:253], v[254:255]
	s_nop 0
	v_add_f32_e32 v183, v252, v253
	s_nop 1
	v_add_f32_dpp v183, v183, v183 quad_perm:[1,0,3,2] row_mask:0xf bank_mask:0xf bound_ctrl:1
	s_nop 1
	v_add_f32_dpp v183, v183, v183 quad_perm:[2,3,0,1] row_mask:0xf bank_mask:0xf bound_ctrl:1
	s_nop 1
	v_add_f32_dpp v183, v183, v183 row_half_mirror row_mask:0xf bank_mask:0xf bound_ctrl:1
	s_nop 1
	v_add_f32_dpp v183, v183, v183 row_mirror row_mask:0xf bank_mask:0xf bound_ctrl:1
	s_nop 1
	v_readlane_b32 s98, v183, 0
	v_readlane_b32 s99, v183, 16
	v_readlane_b32 s100, v183, 32
	v_readlane_b32 s101, v183, 48
	s_nop 1
	v_mov_b32_e32 v183, s98
	v_add_f32_e32 v183, s99, v183
	v_add_f32_e32 v183, s100, v183
	v_add_f32_e32 v183, s101, v183
	v_fmamk_f32 v183, v183, 0x3a800000, v182
	v_cmp_gt_f32_e32 vcc, 0x800000, v183
	v_mul_f32_e32 v181, 0x4b800000, v183
	s_nop 1
	v_cndmask_b32_e32 v183, v183, v181, vcc
	v_rsq_f32_e32 v183, v183
	s_nop 0
	v_mul_f32_e32 v181, 0x45800000, v183
	v_cndmask_b32_e32 v184, v183, v181, vcc
	v_mov_b32_e32 v185, v184
	v_pk_mul_f32 v[160:161], v[160:161], v[184:185]
	v_pk_mul_f32 v[162:163], v[162:163], v[184:185]
	v_pk_mul_f32 v[164:165], v[164:165], v[184:185]
	v_pk_mul_f32 v[166:167], v[166:167], v[184:185]
	v_pk_mul_f32 v[168:169], v[168:169], v[184:185]
	v_pk_mul_f32 v[170:171], v[170:171], v[184:185]
	v_pk_mul_f32 v[172:173], v[172:173], v[184:185]
	v_pk_mul_f32 v[174:175], v[174:175], v[184:185]
	v_pk_fma_f32 v[144:145], v[160:161], v[128:129], v[144:145]
	v_pk_fma_f32 v[146:147], v[162:163], v[130:131], v[146:147]
	v_pk_fma_f32 v[148:149], v[164:165], v[132:133], v[148:149]
	v_pk_fma_f32 v[150:151], v[166:167], v[134:135], v[150:151]
	v_pk_fma_f32 v[152:153], v[168:169], v[136:137], v[152:153]
	v_pk_fma_f32 v[154:155], v[170:171], v[138:139], v[154:155]
	v_pk_fma_f32 v[156:157], v[172:173], v[140:141], v[156:157]
	v_pk_fma_f32 v[158:159], v[174:175], v[142:143], v[158:159]
	v_pk_mul_f32 v[252:253], v[144:145], v[144:145]
	v_pk_mul_f32 v[254:255], v[146:147], v[146:147]
	v_pk_fma_f32 v[252:253], v[148:149], v[148:149], v[252:253]
	v_pk_fma_f32 v[254:255], v[150:151], v[150:151], v[254:255]
	v_pk_fma_f32 v[252:253], v[152:153], v[152:153], v[252:253]
	v_pk_fma_f32 v[254:255], v[154:155], v[154:155], v[254:255]
	v_pk_fma_f32 v[252:253], v[156:157], v[156:157], v[252:253]
	v_pk_fma_f32 v[254:255], v[158:159], v[158:159], v[254:255]
	v_pk_add_f32 v[252:253], v[252:253], v[254:255]
	s_nop 0
	v_add_f32_e32 v183, v252, v253
	s_nop 1
	v_add_f32_dpp v183, v183, v183 quad_perm:[1,0,3,2] row_mask:0xf bank_mask:0xf bound_ctrl:1
	s_nop 1
	v_add_f32_dpp v183, v183, v183 quad_perm:[2,3,0,1] row_mask:0xf bank_mask:0xf bound_ctrl:1
	s_nop 1
	v_add_f32_dpp v183, v183, v183 row_half_mirror row_mask:0xf bank_mask:0xf bound_ctrl:1
	s_nop 1
	v_add_f32_dpp v183, v183, v183 row_mirror row_mask:0xf bank_mask:0xf bound_ctrl:1
	s_nop 1
	v_readlane_b32 s98, v183, 0
	v_readlane_b32 s99, v183, 16
	v_readlane_b32 s100, v183, 32
	v_readlane_b32 s101, v183, 48
	s_nop 1
	v_mov_b32_e32 v183, s98
	v_add_f32_e32 v183, s99, v183
	v_add_f32_e32 v183, s100, v183
	v_add_f32_e32 v183, s101, v183
	v_fmamk_f32 v183, v183, 0x3a800000, v182
	v_cmp_gt_f32_e32 vcc, 0x800000, v183
	v_mul_f32_e32 v181, 0x4b800000, v183
	s_nop 1
	v_cndmask_b32_e32 v183, v183, v181, vcc
	v_rsq_f32_e32 v183, v183
	s_nop 0
	v_mul_f32_e32 v181, 0x45800000, v183
	v_cndmask_b32_e32 v184, v183, v181, vcc
	v_mov_b32_e32 v185, v184
	v_cvt_pk_bf16_f32 v32, v144, v145
	v_cvt_pk_bf16_f32 v33, v146, v147
	v_cvt_pk_bf16_f32 v34, v148, v149
	v_cvt_pk_bf16_f32 v35, v150, v151
	v_cvt_pk_bf16_f32 v36, v152, v153
	v_cvt_pk_bf16_f32 v37, v154, v155
	v_cvt_pk_bf16_f32 v38, v156, v157
	v_cvt_pk_bf16_f32 v39, v158, v159
	v_add_u32_e32 v181, 0x1900000, v177
	global_store_dwordx4 v181, v[32:35], s[78:79]
	global_store_dwordx4 v181, v[36:39], s[78:79] offset:1024
	v_add_u32_e32 v236, 0x800, v237
	s_mov_b64 exec, 1
	global_store_dword v236, v184, s[78:79]
	s_mov_b64 exec, -1
	s_waitcnt vmcnt(16)
	v_lshlrev_b32_e32 v144, 16, v48
	v_and_b32_e32 v145, 0xffff0000, v48
	v_lshlrev_b32_e32 v146, 16, v49
	v_and_b32_e32 v147, 0xffff0000, v49
	v_lshlrev_b32_e32 v148, 16, v50
	v_and_b32_e32 v149, 0xffff0000, v50
	v_lshlrev_b32_e32 v150, 16, v51
	v_and_b32_e32 v151, 0xffff0000, v51
	v_lshlrev_b32_e32 v152, 16, v52
	v_and_b32_e32 v153, 0xffff0000, v52
	v_lshlrev_b32_e32 v154, 16, v53
	v_and_b32_e32 v155, 0xffff0000, v53
	v_lshlrev_b32_e32 v156, 16, v54
	v_and_b32_e32 v157, 0xffff0000, v54
	v_lshlrev_b32_e32 v158, 16, v55
	v_and_b32_e32 v159, 0xffff0000, v55
	v_lshlrev_b32_e32 v160, 16, v56
	v_and_b32_e32 v161, 0xffff0000, v56
	v_lshlrev_b32_e32 v162, 16, v57
	v_and_b32_e32 v163, 0xffff0000, v57
	v_lshlrev_b32_e32 v164, 16, v58
	v_and_b32_e32 v165, 0xffff0000, v58
	v_lshlrev_b32_e32 v166, 16, v59
	v_and_b32_e32 v167, 0xffff0000, v59
	v_lshlrev_b32_e32 v168, 16, v60
	v_and_b32_e32 v169, 0xffff0000, v60
	v_lshlrev_b32_e32 v170, 16, v61
	v_and_b32_e32 v171, 0xffff0000, v61
	v_lshlrev_b32_e32 v172, 16, v62
	v_and_b32_e32 v173, 0xffff0000, v62
	v_lshlrev_b32_e32 v174, 16, v63
	v_and_b32_e32 v175, 0xffff0000, v63
	v_pk_mul_f32 v[252:253], v[160:161], v[160:161]
	v_pk_mul_f32 v[254:255], v[162:163], v[162:163]
	v_pk_fma_f32 v[252:253], v[164:165], v[164:165], v[252:253]
	v_pk_fma_f32 v[254:255], v[166:167], v[166:167], v[254:255]
	v_pk_fma_f32 v[252:253], v[168:169], v[168:169], v[252:253]
	v_pk_fma_f32 v[254:255], v[170:171], v[170:171], v[254:255]
	v_pk_fma_f32 v[252:253], v[172:173], v[172:173], v[252:253]
	v_pk_fma_f32 v[254:255], v[174:175], v[174:175], v[254:255]
	v_pk_add_f32 v[252:253], v[252:253], v[254:255]
	s_nop 0
	v_add_f32_e32 v183, v252, v253
	s_nop 1
	v_add_f32_dpp v183, v183, v183 quad_perm:[1,0,3,2] row_mask:0xf bank_mask:0xf bound_ctrl:1
	s_nop 1
	v_add_f32_dpp v183, v183, v183 quad_perm:[2,3,0,1] row_mask:0xf bank_mask:0xf bound_ctrl:1
	s_nop 1
	v_add_f32_dpp v183, v183, v183 row_half_mirror row_mask:0xf bank_mask:0xf bound_ctrl:1
	s_nop 1
	v_add_f32_dpp v183, v183, v183 row_mirror row_mask:0xf bank_mask:0xf bound_ctrl:1
	s_nop 1
	v_readlane_b32 s98, v183, 0
	v_readlane_b32 s99, v183, 16
	v_readlane_b32 s100, v183, 32
	v_readlane_b32 s101, v183, 48
	s_nop 1
	v_mov_b32_e32 v183, s98
	v_add_f32_e32 v183, s99, v183
	v_add_f32_e32 v183, s100, v183
	v_add_f32_e32 v183, s101, v183
	v_fmamk_f32 v183, v183, 0x3a800000, v182
	v_cmp_gt_f32_e32 vcc, 0x800000, v183
	v_mul_f32_e32 v181, 0x4b800000, v183
	s_nop 1
	v_cndmask_b32_e32 v183, v183, v181, vcc
	v_rsq_f32_e32 v183, v183
	s_nop 0
	v_mul_f32_e32 v181, 0x45800000, v183
	v_cndmask_b32_e32 v184, v183, v181, vcc
	v_mov_b32_e32 v185, v184
	v_pk_mul_f32 v[160:161], v[160:161], v[184:185]
	v_pk_mul_f32 v[162:163], v[162:163], v[184:185]
	v_pk_mul_f32 v[164:165], v[164:165], v[184:185]
	v_pk_mul_f32 v[166:167], v[166:167], v[184:185]
	v_pk_mul_f32 v[168:169], v[168:169], v[184:185]
	v_pk_mul_f32 v[170:171], v[170:171], v[184:185]
	v_pk_mul_f32 v[172:173], v[172:173], v[184:185]
	v_pk_mul_f32 v[174:175], v[174:175], v[184:185]
	v_pk_fma_f32 v[144:145], v[160:161], v[128:129], v[144:145]
	v_pk_fma_f32 v[146:147], v[162:163], v[130:131], v[146:147]
	v_pk_fma_f32 v[148:149], v[164:165], v[132:133], v[148:149]
	v_pk_fma_f32 v[150:151], v[166:167], v[134:135], v[150:151]
	v_pk_fma_f32 v[152:153], v[168:169], v[136:137], v[152:153]
	v_pk_fma_f32 v[154:155], v[170:171], v[138:139], v[154:155]
	v_pk_fma_f32 v[156:157], v[172:173], v[140:141], v[156:157]
	v_pk_fma_f32 v[158:159], v[174:175], v[142:143], v[158:159]
	v_pk_mul_f32 v[252:253], v[144:145], v[144:145]
	v_pk_mul_f32 v[254:255], v[146:147], v[146:147]
	v_pk_fma_f32 v[252:253], v[148:149], v[148:149], v[252:253]
	v_pk_fma_f32 v[254:255], v[150:151], v[150:151], v[254:255]
	v_pk_fma_f32 v[252:253], v[152:153], v[152:153], v[252:253]
	v_pk_fma_f32 v[254:255], v[154:155], v[154:155], v[254:255]
	v_pk_fma_f32 v[252:253], v[156:157], v[156:157], v[252:253]
	v_pk_fma_f32 v[254:255], v[158:159], v[158:159], v[254:255]
	v_pk_add_f32 v[252:253], v[252:253], v[254:255]
	s_nop 0
	v_add_f32_e32 v183, v252, v253
	s_nop 1
	v_add_f32_dpp v183, v183, v183 quad_perm:[1,0,3,2] row_mask:0xf bank_mask:0xf bound_ctrl:1
	s_nop 1
	v_add_f32_dpp v183, v183, v183 quad_perm:[2,3,0,1] row_mask:0xf bank_mask:0xf bound_ctrl:1
	s_nop 1
	v_add_f32_dpp v183, v183, v183 row_half_mirror row_mask:0xf bank_mask:0xf bound_ctrl:1
	s_nop 1
	v_add_f32_dpp v183, v183, v183 row_mirror row_mask:0xf bank_mask:0xf bound_ctrl:1
	s_nop 1
	v_readlane_b32 s98, v183, 0
	v_readlane_b32 s99, v183, 16
	v_readlane_b32 s100, v183, 32
	v_readlane_b32 s101, v183, 48
	s_nop 1
	v_mov_b32_e32 v183, s98
	v_add_f32_e32 v183, s99, v183
	v_add_f32_e32 v183, s100, v183
	v_add_f32_e32 v183, s101, v183
	v_fmamk_f32 v183, v183, 0x3a800000, v182
	v_cmp_gt_f32_e32 vcc, 0x800000, v183
	v_mul_f32_e32 v181, 0x4b800000, v183
	s_nop 1
	v_cndmask_b32_e32 v183, v183, v181, vcc
	v_rsq_f32_e32 v183, v183
	s_nop 0
	v_mul_f32_e32 v181, 0x45800000, v183
	v_cndmask_b32_e32 v184, v183, v181, vcc
	v_mov_b32_e32 v185, v184
	v_cvt_pk_bf16_f32 v48, v144, v145
	v_cvt_pk_bf16_f32 v49, v146, v147
	v_cvt_pk_bf16_f32 v50, v148, v149
	v_cvt_pk_bf16_f32 v51, v150, v151
	v_cvt_pk_bf16_f32 v52, v152, v153
	v_cvt_pk_bf16_f32 v53, v154, v155
	v_cvt_pk_bf16_f32 v54, v156, v157
	v_cvt_pk_bf16_f32 v55, v158, v159
	v_add_u32_e32 v181, 0x1980000, v177
	global_store_dwordx4 v181, v[48:51], s[78:79]
	global_store_dwordx4 v181, v[52:55], s[78:79] offset:1024
	v_add_u32_e32 v236, 0xc00, v237
	s_mov_b64 exec, 1
	global_store_dword v236, v184, s[78:79]
	s_mov_b64 exec, -1
	s_waitcnt vmcnt(12)
	v_lshlrev_b32_e32 v144, 16, v64
	v_and_b32_e32 v145, 0xffff0000, v64
	v_lshlrev_b32_e32 v146, 16, v65
	v_and_b32_e32 v147, 0xffff0000, v65
	v_lshlrev_b32_e32 v148, 16, v66
	v_and_b32_e32 v149, 0xffff0000, v66
	v_lshlrev_b32_e32 v150, 16, v67
	v_and_b32_e32 v151, 0xffff0000, v67
	v_lshlrev_b32_e32 v152, 16, v68
	v_and_b32_e32 v153, 0xffff0000, v68
	v_lshlrev_b32_e32 v154, 16, v69
	v_and_b32_e32 v155, 0xffff0000, v69
	v_lshlrev_b32_e32 v156, 16, v70
	v_and_b32_e32 v157, 0xffff0000, v70
	v_lshlrev_b32_e32 v158, 16, v71
	v_and_b32_e32 v159, 0xffff0000, v71
	v_lshlrev_b32_e32 v160, 16, v72
	v_and_b32_e32 v161, 0xffff0000, v72
	v_lshlrev_b32_e32 v162, 16, v73
	v_and_b32_e32 v163, 0xffff0000, v73
	v_lshlrev_b32_e32 v164, 16, v74
	v_and_b32_e32 v165, 0xffff0000, v74
	v_lshlrev_b32_e32 v166, 16, v75
	v_and_b32_e32 v167, 0xffff0000, v75
	v_lshlrev_b32_e32 v168, 16, v76
	v_and_b32_e32 v169, 0xffff0000, v76
	v_lshlrev_b32_e32 v170, 16, v77
	v_and_b32_e32 v171, 0xffff0000, v77
	v_lshlrev_b32_e32 v172, 16, v78
	v_and_b32_e32 v173, 0xffff0000, v78
	v_lshlrev_b32_e32 v174, 16, v79
	v_and_b32_e32 v175, 0xffff0000, v79
	v_pk_mul_f32 v[252:253], v[160:161], v[160:161]
	v_pk_mul_f32 v[254:255], v[162:163], v[162:163]
	v_pk_fma_f32 v[252:253], v[164:165], v[164:165], v[252:253]
	v_pk_fma_f32 v[254:255], v[166:167], v[166:167], v[254:255]
	v_pk_fma_f32 v[252:253], v[168:169], v[168:169], v[252:253]
	v_pk_fma_f32 v[254:255], v[170:171], v[170:171], v[254:255]
	v_pk_fma_f32 v[252:253], v[172:173], v[172:173], v[252:253]
	v_pk_fma_f32 v[254:255], v[174:175], v[174:175], v[254:255]
	v_pk_add_f32 v[252:253], v[252:253], v[254:255]
	s_nop 0
	v_add_f32_e32 v183, v252, v253
	s_nop 1
	v_add_f32_dpp v183, v183, v183 quad_perm:[1,0,3,2] row_mask:0xf bank_mask:0xf bound_ctrl:1
	s_nop 1
	v_add_f32_dpp v183, v183, v183 quad_perm:[2,3,0,1] row_mask:0xf bank_mask:0xf bound_ctrl:1
	s_nop 1
	v_add_f32_dpp v183, v183, v183 row_half_mirror row_mask:0xf bank_mask:0xf bound_ctrl:1
	s_nop 1
	v_add_f32_dpp v183, v183, v183 row_mirror row_mask:0xf bank_mask:0xf bound_ctrl:1
	s_nop 1
	v_readlane_b32 s98, v183, 0
	v_readlane_b32 s99, v183, 16
	v_readlane_b32 s100, v183, 32
	v_readlane_b32 s101, v183, 48
	s_nop 1
	v_mov_b32_e32 v183, s98
	v_add_f32_e32 v183, s99, v183
	v_add_f32_e32 v183, s100, v183
	v_add_f32_e32 v183, s101, v183
	v_fmamk_f32 v183, v183, 0x3a800000, v182
	v_cmp_gt_f32_e32 vcc, 0x800000, v183
	v_mul_f32_e32 v181, 0x4b800000, v183
	s_nop 1
	v_cndmask_b32_e32 v183, v183, v181, vcc
	v_rsq_f32_e32 v183, v183
	s_nop 0
	v_mul_f32_e32 v181, 0x45800000, v183
	v_cndmask_b32_e32 v184, v183, v181, vcc
	v_mov_b32_e32 v185, v184
	v_pk_mul_f32 v[160:161], v[160:161], v[184:185]
	v_pk_mul_f32 v[162:163], v[162:163], v[184:185]
	v_pk_mul_f32 v[164:165], v[164:165], v[184:185]
	v_pk_mul_f32 v[166:167], v[166:167], v[184:185]
	v_pk_mul_f32 v[168:169], v[168:169], v[184:185]
	v_pk_mul_f32 v[170:171], v[170:171], v[184:185]
	v_pk_mul_f32 v[172:173], v[172:173], v[184:185]
	v_pk_mul_f32 v[174:175], v[174:175], v[184:185]
	v_pk_fma_f32 v[144:145], v[160:161], v[128:129], v[144:145]
	v_pk_fma_f32 v[146:147], v[162:163], v[130:131], v[146:147]
	v_pk_fma_f32 v[148:149], v[164:165], v[132:133], v[148:149]
	v_pk_fma_f32 v[150:151], v[166:167], v[134:135], v[150:151]
	v_pk_fma_f32 v[152:153], v[168:169], v[136:137], v[152:153]
	v_pk_fma_f32 v[154:155], v[170:171], v[138:139], v[154:155]
	v_pk_fma_f32 v[156:157], v[172:173], v[140:141], v[156:157]
	v_pk_fma_f32 v[158:159], v[174:175], v[142:143], v[158:159]
	v_pk_mul_f32 v[252:253], v[144:145], v[144:145]
	v_pk_mul_f32 v[254:255], v[146:147], v[146:147]
	v_pk_fma_f32 v[252:253], v[148:149], v[148:149], v[252:253]
	v_pk_fma_f32 v[254:255], v[150:151], v[150:151], v[254:255]
	v_pk_fma_f32 v[252:253], v[152:153], v[152:153], v[252:253]
	v_pk_fma_f32 v[254:255], v[154:155], v[154:155], v[254:255]
	v_pk_fma_f32 v[252:253], v[156:157], v[156:157], v[252:253]
	v_pk_fma_f32 v[254:255], v[158:159], v[158:159], v[254:255]
	v_pk_add_f32 v[252:253], v[252:253], v[254:255]
	s_nop 0
	v_add_f32_e32 v183, v252, v253
	s_nop 1
	v_add_f32_dpp v183, v183, v183 quad_perm:[1,0,3,2] row_mask:0xf bank_mask:0xf bound_ctrl:1
	s_nop 1
	v_add_f32_dpp v183, v183, v183 quad_perm:[2,3,0,1] row_mask:0xf bank_mask:0xf bound_ctrl:1
	s_nop 1
	v_add_f32_dpp v183, v183, v183 row_half_mirror row_mask:0xf bank_mask:0xf bound_ctrl:1
	s_nop 1
	v_add_f32_dpp v183, v183, v183 row_mirror row_mask:0xf bank_mask:0xf bound_ctrl:1
	s_nop 1
	v_readlane_b32 s98, v183, 0
	v_readlane_b32 s99, v183, 16
	v_readlane_b32 s100, v183, 32
	v_readlane_b32 s101, v183, 48
	s_nop 1
	v_mov_b32_e32 v183, s98
	v_add_f32_e32 v183, s99, v183
	v_add_f32_e32 v183, s100, v183
	v_add_f32_e32 v183, s101, v183
	v_fmamk_f32 v183, v183, 0x3a800000, v182
	v_cmp_gt_f32_e32 vcc, 0x800000, v183
	v_mul_f32_e32 v181, 0x4b800000, v183
	s_nop 1
	v_cndmask_b32_e32 v183, v183, v181, vcc
	v_rsq_f32_e32 v183, v183
	s_nop 0
	v_mul_f32_e32 v181, 0x45800000, v183
	v_cndmask_b32_e32 v184, v183, v181, vcc
	v_mov_b32_e32 v185, v184
	v_cvt_pk_bf16_f32 v64, v144, v145
	v_cvt_pk_bf16_f32 v65, v146, v147
	v_cvt_pk_bf16_f32 v66, v148, v149
	v_cvt_pk_bf16_f32 v67, v150, v151
	v_cvt_pk_bf16_f32 v68, v152, v153
	v_cvt_pk_bf16_f32 v69, v154, v155
	v_cvt_pk_bf16_f32 v70, v156, v157
	v_cvt_pk_bf16_f32 v71, v158, v159
	v_add_u32_e32 v181, 0x1a00000, v177
	global_store_dwordx4 v181, v[64:67], s[78:79]
	global_store_dwordx4 v181, v[68:71], s[78:79] offset:1024
	v_add_u32_e32 v236, 0x1000, v237
	s_mov_b64 exec, 1
	global_store_dword v236, v184, s[78:79]
	s_mov_b64 exec, -1
	s_waitcnt vmcnt(8)
	v_lshlrev_b32_e32 v144, 16, v80
	v_and_b32_e32 v145, 0xffff0000, v80
	v_lshlrev_b32_e32 v146, 16, v81
	v_and_b32_e32 v147, 0xffff0000, v81
	v_lshlrev_b32_e32 v148, 16, v82
	v_and_b32_e32 v149, 0xffff0000, v82
	v_lshlrev_b32_e32 v150, 16, v83
	v_and_b32_e32 v151, 0xffff0000, v83
	v_lshlrev_b32_e32 v152, 16, v84
	v_and_b32_e32 v153, 0xffff0000, v84
	v_lshlrev_b32_e32 v154, 16, v85
	v_and_b32_e32 v155, 0xffff0000, v85
	v_lshlrev_b32_e32 v156, 16, v86
	v_and_b32_e32 v157, 0xffff0000, v86
	v_lshlrev_b32_e32 v158, 16, v87
	v_and_b32_e32 v159, 0xffff0000, v87
	v_lshlrev_b32_e32 v160, 16, v88
	v_and_b32_e32 v161, 0xffff0000, v88
	v_lshlrev_b32_e32 v162, 16, v89
	v_and_b32_e32 v163, 0xffff0000, v89
	v_lshlrev_b32_e32 v164, 16, v90
	v_and_b32_e32 v165, 0xffff0000, v90
	v_lshlrev_b32_e32 v166, 16, v91
	v_and_b32_e32 v167, 0xffff0000, v91
	v_lshlrev_b32_e32 v168, 16, v92
	v_and_b32_e32 v169, 0xffff0000, v92
	v_lshlrev_b32_e32 v170, 16, v93
	v_and_b32_e32 v171, 0xffff0000, v93
	v_lshlrev_b32_e32 v172, 16, v94
	v_and_b32_e32 v173, 0xffff0000, v94
	v_lshlrev_b32_e32 v174, 16, v95
	v_and_b32_e32 v175, 0xffff0000, v95
	v_pk_mul_f32 v[252:253], v[160:161], v[160:161]
	v_pk_mul_f32 v[254:255], v[162:163], v[162:163]
	v_pk_fma_f32 v[252:253], v[164:165], v[164:165], v[252:253]
	v_pk_fma_f32 v[254:255], v[166:167], v[166:167], v[254:255]
	v_pk_fma_f32 v[252:253], v[168:169], v[168:169], v[252:253]
	v_pk_fma_f32 v[254:255], v[170:171], v[170:171], v[254:255]
	v_pk_fma_f32 v[252:253], v[172:173], v[172:173], v[252:253]
	v_pk_fma_f32 v[254:255], v[174:175], v[174:175], v[254:255]
	v_pk_add_f32 v[252:253], v[252:253], v[254:255]
	s_nop 0
	v_add_f32_e32 v183, v252, v253
	s_nop 1
	v_add_f32_dpp v183, v183, v183 quad_perm:[1,0,3,2] row_mask:0xf bank_mask:0xf bound_ctrl:1
	s_nop 1
	v_add_f32_dpp v183, v183, v183 quad_perm:[2,3,0,1] row_mask:0xf bank_mask:0xf bound_ctrl:1
	s_nop 1
	v_add_f32_dpp v183, v183, v183 row_half_mirror row_mask:0xf bank_mask:0xf bound_ctrl:1
	s_nop 1
	v_add_f32_dpp v183, v183, v183 row_mirror row_mask:0xf bank_mask:0xf bound_ctrl:1
	s_nop 1
	v_readlane_b32 s98, v183, 0
	v_readlane_b32 s99, v183, 16
	v_readlane_b32 s100, v183, 32
	v_readlane_b32 s101, v183, 48
	s_nop 1
	v_mov_b32_e32 v183, s98
	v_add_f32_e32 v183, s99, v183
	v_add_f32_e32 v183, s100, v183
	v_add_f32_e32 v183, s101, v183
	v_fmamk_f32 v183, v183, 0x3a800000, v182
	v_cmp_gt_f32_e32 vcc, 0x800000, v183
	v_mul_f32_e32 v181, 0x4b800000, v183
	s_nop 1
	v_cndmask_b32_e32 v183, v183, v181, vcc
	v_rsq_f32_e32 v183, v183
	s_nop 0
	v_mul_f32_e32 v181, 0x45800000, v183
	v_cndmask_b32_e32 v184, v183, v181, vcc
	v_mov_b32_e32 v185, v184
	v_pk_mul_f32 v[160:161], v[160:161], v[184:185]
	v_pk_mul_f32 v[162:163], v[162:163], v[184:185]
	v_pk_mul_f32 v[164:165], v[164:165], v[184:185]
	v_pk_mul_f32 v[166:167], v[166:167], v[184:185]
	v_pk_mul_f32 v[168:169], v[168:169], v[184:185]
	v_pk_mul_f32 v[170:171], v[170:171], v[184:185]
	v_pk_mul_f32 v[172:173], v[172:173], v[184:185]
	v_pk_mul_f32 v[174:175], v[174:175], v[184:185]
	v_pk_fma_f32 v[144:145], v[160:161], v[128:129], v[144:145]
	v_pk_fma_f32 v[146:147], v[162:163], v[130:131], v[146:147]
	v_pk_fma_f32 v[148:149], v[164:165], v[132:133], v[148:149]
	v_pk_fma_f32 v[150:151], v[166:167], v[134:135], v[150:151]
	v_pk_fma_f32 v[152:153], v[168:169], v[136:137], v[152:153]
	v_pk_fma_f32 v[154:155], v[170:171], v[138:139], v[154:155]
	v_pk_fma_f32 v[156:157], v[172:173], v[140:141], v[156:157]
	v_pk_fma_f32 v[158:159], v[174:175], v[142:143], v[158:159]
	v_pk_mul_f32 v[252:253], v[144:145], v[144:145]
	v_pk_mul_f32 v[254:255], v[146:147], v[146:147]
	v_pk_fma_f32 v[252:253], v[148:149], v[148:149], v[252:253]
	v_pk_fma_f32 v[254:255], v[150:151], v[150:151], v[254:255]
	v_pk_fma_f32 v[252:253], v[152:153], v[152:153], v[252:253]
	v_pk_fma_f32 v[254:255], v[154:155], v[154:155], v[254:255]
	v_pk_fma_f32 v[252:253], v[156:157], v[156:157], v[252:253]
	v_pk_fma_f32 v[254:255], v[158:159], v[158:159], v[254:255]
	v_pk_add_f32 v[252:253], v[252:253], v[254:255]
	s_nop 0
	v_add_f32_e32 v183, v252, v253
	s_nop 1
	v_add_f32_dpp v183, v183, v183 quad_perm:[1,0,3,2] row_mask:0xf bank_mask:0xf bound_ctrl:1
	s_nop 1
	v_add_f32_dpp v183, v183, v183 quad_perm:[2,3,0,1] row_mask:0xf bank_mask:0xf bound_ctrl:1
	s_nop 1
	v_add_f32_dpp v183, v183, v183 row_half_mirror row_mask:0xf bank_mask:0xf bound_ctrl:1
	s_nop 1
	v_add_f32_dpp v183, v183, v183 row_mirror row_mask:0xf bank_mask:0xf bound_ctrl:1
	s_nop 1
	v_readlane_b32 s98, v183, 0
	v_readlane_b32 s99, v183, 16
	v_readlane_b32 s100, v183, 32
	v_readlane_b32 s101, v183, 48
	s_nop 1
	v_mov_b32_e32 v183, s98
	v_add_f32_e32 v183, s99, v183
	v_add_f32_e32 v183, s100, v183
	v_add_f32_e32 v183, s101, v183
	v_fmamk_f32 v183, v183, 0x3a800000, v182
	v_cmp_gt_f32_e32 vcc, 0x800000, v183
	v_mul_f32_e32 v181, 0x4b800000, v183
	s_nop 1
	v_cndmask_b32_e32 v183, v183, v181, vcc
	v_rsq_f32_e32 v183, v183
	s_nop 0
	v_mul_f32_e32 v181, 0x45800000, v183
	v_cndmask_b32_e32 v184, v183, v181, vcc
	v_mov_b32_e32 v185, v184
	v_cvt_pk_bf16_f32 v80, v144, v145
	v_cvt_pk_bf16_f32 v81, v146, v147
	v_cvt_pk_bf16_f32 v82, v148, v149
	v_cvt_pk_bf16_f32 v83, v150, v151
	v_cvt_pk_bf16_f32 v84, v152, v153
	v_cvt_pk_bf16_f32 v85, v154, v155
	v_cvt_pk_bf16_f32 v86, v156, v157
	v_cvt_pk_bf16_f32 v87, v158, v159
	v_add_u32_e32 v181, 0x1a80000, v177
	global_store_dwordx4 v181, v[80:83], s[78:79]
	global_store_dwordx4 v181, v[84:87], s[78:79] offset:1024
	v_add_u32_e32 v236, 0x1400, v237
	s_mov_b64 exec, 1
	global_store_dword v236, v184, s[78:79]
	s_mov_b64 exec, -1
	s_waitcnt vmcnt(4)
	v_lshlrev_b32_e32 v144, 16, v96
	v_and_b32_e32 v145, 0xffff0000, v96
	v_lshlrev_b32_e32 v146, 16, v97
	v_and_b32_e32 v147, 0xffff0000, v97
	v_lshlrev_b32_e32 v148, 16, v98
	v_and_b32_e32 v149, 0xffff0000, v98
	v_lshlrev_b32_e32 v150, 16, v99
	v_and_b32_e32 v151, 0xffff0000, v99
	v_lshlrev_b32_e32 v152, 16, v100
	v_and_b32_e32 v153, 0xffff0000, v100
	v_lshlrev_b32_e32 v154, 16, v101
	v_and_b32_e32 v155, 0xffff0000, v101
	v_lshlrev_b32_e32 v156, 16, v102
	v_and_b32_e32 v157, 0xffff0000, v102
	v_lshlrev_b32_e32 v158, 16, v103
	v_and_b32_e32 v159, 0xffff0000, v103
	v_lshlrev_b32_e32 v160, 16, v104
	v_and_b32_e32 v161, 0xffff0000, v104
	v_lshlrev_b32_e32 v162, 16, v105
	v_and_b32_e32 v163, 0xffff0000, v105
	v_lshlrev_b32_e32 v164, 16, v106
	v_and_b32_e32 v165, 0xffff0000, v106
	v_lshlrev_b32_e32 v166, 16, v107
	v_and_b32_e32 v167, 0xffff0000, v107
	v_lshlrev_b32_e32 v168, 16, v108
	v_and_b32_e32 v169, 0xffff0000, v108
	v_lshlrev_b32_e32 v170, 16, v109
	v_and_b32_e32 v171, 0xffff0000, v109
	v_lshlrev_b32_e32 v172, 16, v110
	v_and_b32_e32 v173, 0xffff0000, v110
	v_lshlrev_b32_e32 v174, 16, v111
	v_and_b32_e32 v175, 0xffff0000, v111
	v_pk_mul_f32 v[252:253], v[160:161], v[160:161]
	v_pk_mul_f32 v[254:255], v[162:163], v[162:163]
	v_pk_fma_f32 v[252:253], v[164:165], v[164:165], v[252:253]
	v_pk_fma_f32 v[254:255], v[166:167], v[166:167], v[254:255]
	v_pk_fma_f32 v[252:253], v[168:169], v[168:169], v[252:253]
	v_pk_fma_f32 v[254:255], v[170:171], v[170:171], v[254:255]
	v_pk_fma_f32 v[252:253], v[172:173], v[172:173], v[252:253]
	v_pk_fma_f32 v[254:255], v[174:175], v[174:175], v[254:255]
	v_pk_add_f32 v[252:253], v[252:253], v[254:255]
	s_nop 0
	v_add_f32_e32 v183, v252, v253
	s_nop 1
	v_add_f32_dpp v183, v183, v183 quad_perm:[1,0,3,2] row_mask:0xf bank_mask:0xf bound_ctrl:1
	s_nop 1
	v_add_f32_dpp v183, v183, v183 quad_perm:[2,3,0,1] row_mask:0xf bank_mask:0xf bound_ctrl:1
	s_nop 1
	v_add_f32_dpp v183, v183, v183 row_half_mirror row_mask:0xf bank_mask:0xf bound_ctrl:1
	s_nop 1
	v_add_f32_dpp v183, v183, v183 row_mirror row_mask:0xf bank_mask:0xf bound_ctrl:1
	s_nop 1
	v_readlane_b32 s98, v183, 0
	v_readlane_b32 s99, v183, 16
	v_readlane_b32 s100, v183, 32
	v_readlane_b32 s101, v183, 48
	s_nop 1
	v_mov_b32_e32 v183, s98
	v_add_f32_e32 v183, s99, v183
	v_add_f32_e32 v183, s100, v183
	v_add_f32_e32 v183, s101, v183
	v_fmamk_f32 v183, v183, 0x3a800000, v182
	v_cmp_gt_f32_e32 vcc, 0x800000, v183
	v_mul_f32_e32 v181, 0x4b800000, v183
	s_nop 1
	v_cndmask_b32_e32 v183, v183, v181, vcc
	v_rsq_f32_e32 v183, v183
	s_nop 0
	v_mul_f32_e32 v181, 0x45800000, v183
	v_cndmask_b32_e32 v184, v183, v181, vcc
	v_mov_b32_e32 v185, v184
	v_pk_mul_f32 v[160:161], v[160:161], v[184:185]
	v_pk_mul_f32 v[162:163], v[162:163], v[184:185]
	v_pk_mul_f32 v[164:165], v[164:165], v[184:185]
	v_pk_mul_f32 v[166:167], v[166:167], v[184:185]
	v_pk_mul_f32 v[168:169], v[168:169], v[184:185]
	v_pk_mul_f32 v[170:171], v[170:171], v[184:185]
	v_pk_mul_f32 v[172:173], v[172:173], v[184:185]
	v_pk_mul_f32 v[174:175], v[174:175], v[184:185]
	v_pk_fma_f32 v[144:145], v[160:161], v[128:129], v[144:145]
	v_pk_fma_f32 v[146:147], v[162:163], v[130:131], v[146:147]
	v_pk_fma_f32 v[148:149], v[164:165], v[132:133], v[148:149]
	v_pk_fma_f32 v[150:151], v[166:167], v[134:135], v[150:151]
	v_pk_fma_f32 v[152:153], v[168:169], v[136:137], v[152:153]
	v_pk_fma_f32 v[154:155], v[170:171], v[138:139], v[154:155]
	v_pk_fma_f32 v[156:157], v[172:173], v[140:141], v[156:157]
	v_pk_fma_f32 v[158:159], v[174:175], v[142:143], v[158:159]
	v_pk_mul_f32 v[252:253], v[144:145], v[144:145]
	v_pk_mul_f32 v[254:255], v[146:147], v[146:147]
	v_pk_fma_f32 v[252:253], v[148:149], v[148:149], v[252:253]
	v_pk_fma_f32 v[254:255], v[150:151], v[150:151], v[254:255]
	v_pk_fma_f32 v[252:253], v[152:153], v[152:153], v[252:253]
	v_pk_fma_f32 v[254:255], v[154:155], v[154:155], v[254:255]
	v_pk_fma_f32 v[252:253], v[156:157], v[156:157], v[252:253]
	v_pk_fma_f32 v[254:255], v[158:159], v[158:159], v[254:255]
	v_pk_add_f32 v[252:253], v[252:253], v[254:255]
	s_nop 0
	v_add_f32_e32 v183, v252, v253
	s_nop 1
	v_add_f32_dpp v183, v183, v183 quad_perm:[1,0,3,2] row_mask:0xf bank_mask:0xf bound_ctrl:1
	s_nop 1
	v_add_f32_dpp v183, v183, v183 quad_perm:[2,3,0,1] row_mask:0xf bank_mask:0xf bound_ctrl:1
	s_nop 1
	v_add_f32_dpp v183, v183, v183 row_half_mirror row_mask:0xf bank_mask:0xf bound_ctrl:1
	s_nop 1
	v_add_f32_dpp v183, v183, v183 row_mirror row_mask:0xf bank_mask:0xf bound_ctrl:1
	s_nop 1
	v_readlane_b32 s98, v183, 0
	v_readlane_b32 s99, v183, 16
	v_readlane_b32 s100, v183, 32
	v_readlane_b32 s101, v183, 48
	s_nop 1
	v_mov_b32_e32 v183, s98
	v_add_f32_e32 v183, s99, v183
	v_add_f32_e32 v183, s100, v183
	v_add_f32_e32 v183, s101, v183
	v_fmamk_f32 v183, v183, 0x3a800000, v182
	v_cmp_gt_f32_e32 vcc, 0x800000, v183
	v_mul_f32_e32 v181, 0x4b800000, v183
	s_nop 1
	v_cndmask_b32_e32 v183, v183, v181, vcc
	v_rsq_f32_e32 v183, v183
	s_nop 0
	v_mul_f32_e32 v181, 0x45800000, v183
	v_cndmask_b32_e32 v184, v183, v181, vcc
	v_mov_b32_e32 v185, v184
	v_cvt_pk_bf16_f32 v96, v144, v145
	v_cvt_pk_bf16_f32 v97, v146, v147
	v_cvt_pk_bf16_f32 v98, v148, v149
	v_cvt_pk_bf16_f32 v99, v150, v151
	v_cvt_pk_bf16_f32 v100, v152, v153
	v_cvt_pk_bf16_f32 v101, v154, v155
	v_cvt_pk_bf16_f32 v102, v156, v157
	v_cvt_pk_bf16_f32 v103, v158, v159
	v_add_u32_e32 v181, 0x1b00000, v177
	global_store_dwordx4 v181, v[96:99], s[78:79]
	global_store_dwordx4 v181, v[100:103], s[78:79] offset:1024
	v_add_u32_e32 v236, 0x1800, v237
	s_mov_b64 exec, 1
	global_store_dword v236, v184, s[78:79]
	s_mov_b64 exec, -1
	s_waitcnt vmcnt(0)
	v_lshlrev_b32_e32 v144, 16, v112
	v_and_b32_e32 v145, 0xffff0000, v112
	v_lshlrev_b32_e32 v146, 16, v113
	v_and_b32_e32 v147, 0xffff0000, v113
	v_lshlrev_b32_e32 v148, 16, v114
	v_and_b32_e32 v149, 0xffff0000, v114
	v_lshlrev_b32_e32 v150, 16, v115
	v_and_b32_e32 v151, 0xffff0000, v115
	v_lshlrev_b32_e32 v152, 16, v116
	v_and_b32_e32 v153, 0xffff0000, v116
	v_lshlrev_b32_e32 v154, 16, v117
	v_and_b32_e32 v155, 0xffff0000, v117
	v_lshlrev_b32_e32 v156, 16, v118
	v_and_b32_e32 v157, 0xffff0000, v118
	v_lshlrev_b32_e32 v158, 16, v119
	v_and_b32_e32 v159, 0xffff0000, v119
	v_lshlrev_b32_e32 v160, 16, v120
	v_and_b32_e32 v161, 0xffff0000, v120
	v_lshlrev_b32_e32 v162, 16, v121
	v_and_b32_e32 v163, 0xffff0000, v121
	v_lshlrev_b32_e32 v164, 16, v122
	v_and_b32_e32 v165, 0xffff0000, v122
	v_lshlrev_b32_e32 v166, 16, v123
	v_and_b32_e32 v167, 0xffff0000, v123
	v_lshlrev_b32_e32 v168, 16, v124
	v_and_b32_e32 v169, 0xffff0000, v124
	v_lshlrev_b32_e32 v170, 16, v125
	v_and_b32_e32 v171, 0xffff0000, v125
	v_lshlrev_b32_e32 v172, 16, v126
	v_and_b32_e32 v173, 0xffff0000, v126
	v_lshlrev_b32_e32 v174, 16, v127
	v_and_b32_e32 v175, 0xffff0000, v127
	v_pk_mul_f32 v[252:253], v[160:161], v[160:161]
	v_pk_mul_f32 v[254:255], v[162:163], v[162:163]
	v_pk_fma_f32 v[252:253], v[164:165], v[164:165], v[252:253]
	v_pk_fma_f32 v[254:255], v[166:167], v[166:167], v[254:255]
	v_pk_fma_f32 v[252:253], v[168:169], v[168:169], v[252:253]
	v_pk_fma_f32 v[254:255], v[170:171], v[170:171], v[254:255]
	v_pk_fma_f32 v[252:253], v[172:173], v[172:173], v[252:253]
	v_pk_fma_f32 v[254:255], v[174:175], v[174:175], v[254:255]
	v_pk_add_f32 v[252:253], v[252:253], v[254:255]
	s_nop 0
	v_add_f32_e32 v183, v252, v253
	s_nop 1
	v_add_f32_dpp v183, v183, v183 quad_perm:[1,0,3,2] row_mask:0xf bank_mask:0xf bound_ctrl:1
	s_nop 1
	v_add_f32_dpp v183, v183, v183 quad_perm:[2,3,0,1] row_mask:0xf bank_mask:0xf bound_ctrl:1
	s_nop 1
	v_add_f32_dpp v183, v183, v183 row_half_mirror row_mask:0xf bank_mask:0xf bound_ctrl:1
	s_nop 1
	v_add_f32_dpp v183, v183, v183 row_mirror row_mask:0xf bank_mask:0xf bound_ctrl:1
	s_nop 1
	v_readlane_b32 s98, v183, 0
	v_readlane_b32 s99, v183, 16
	v_readlane_b32 s100, v183, 32
	v_readlane_b32 s101, v183, 48
	s_nop 1
	v_mov_b32_e32 v183, s98
	v_add_f32_e32 v183, s99, v183
	v_add_f32_e32 v183, s100, v183
	v_add_f32_e32 v183, s101, v183
	v_fmamk_f32 v183, v183, 0x3a800000, v182
	v_cmp_gt_f32_e32 vcc, 0x800000, v183
	v_mul_f32_e32 v181, 0x4b800000, v183
	s_nop 1
	v_cndmask_b32_e32 v183, v183, v181, vcc
	v_rsq_f32_e32 v183, v183
	s_nop 0
	v_mul_f32_e32 v181, 0x45800000, v183
	v_cndmask_b32_e32 v184, v183, v181, vcc
	v_mov_b32_e32 v185, v184
	v_pk_mul_f32 v[160:161], v[160:161], v[184:185]
	v_pk_mul_f32 v[162:163], v[162:163], v[184:185]
	v_pk_mul_f32 v[164:165], v[164:165], v[184:185]
	v_pk_mul_f32 v[166:167], v[166:167], v[184:185]
	v_pk_mul_f32 v[168:169], v[168:169], v[184:185]
	v_pk_mul_f32 v[170:171], v[170:171], v[184:185]
	v_pk_mul_f32 v[172:173], v[172:173], v[184:185]
	v_pk_mul_f32 v[174:175], v[174:175], v[184:185]
	v_pk_fma_f32 v[144:145], v[160:161], v[128:129], v[144:145]
	v_pk_fma_f32 v[146:147], v[162:163], v[130:131], v[146:147]
	v_pk_fma_f32 v[148:149], v[164:165], v[132:133], v[148:149]
	v_pk_fma_f32 v[150:151], v[166:167], v[134:135], v[150:151]
	v_pk_fma_f32 v[152:153], v[168:169], v[136:137], v[152:153]
	v_pk_fma_f32 v[154:155], v[170:171], v[138:139], v[154:155]
	v_pk_fma_f32 v[156:157], v[172:173], v[140:141], v[156:157]
	v_pk_fma_f32 v[158:159], v[174:175], v[142:143], v[158:159]
	v_pk_mul_f32 v[252:253], v[144:145], v[144:145]
	v_pk_mul_f32 v[254:255], v[146:147], v[146:147]
	v_pk_fma_f32 v[252:253], v[148:149], v[148:149], v[252:253]
	v_pk_fma_f32 v[254:255], v[150:151], v[150:151], v[254:255]
	v_pk_fma_f32 v[252:253], v[152:153], v[152:153], v[252:253]
	v_pk_fma_f32 v[254:255], v[154:155], v[154:155], v[254:255]
	v_pk_fma_f32 v[252:253], v[156:157], v[156:157], v[252:253]
	v_pk_fma_f32 v[254:255], v[158:159], v[158:159], v[254:255]
	v_pk_add_f32 v[252:253], v[252:253], v[254:255]
	s_nop 0
	v_add_f32_e32 v183, v252, v253
	s_nop 1
	v_add_f32_dpp v183, v183, v183 quad_perm:[1,0,3,2] row_mask:0xf bank_mask:0xf bound_ctrl:1
	s_nop 1
	v_add_f32_dpp v183, v183, v183 quad_perm:[2,3,0,1] row_mask:0xf bank_mask:0xf bound_ctrl:1
	s_nop 1
	v_add_f32_dpp v183, v183, v183 row_half_mirror row_mask:0xf bank_mask:0xf bound_ctrl:1
	s_nop 1
	v_add_f32_dpp v183, v183, v183 row_mirror row_mask:0xf bank_mask:0xf bound_ctrl:1
	s_nop 1
	v_readlane_b32 s98, v183, 0
	v_readlane_b32 s99, v183, 16
	v_readlane_b32 s100, v183, 32
	v_readlane_b32 s101, v183, 48
	s_nop 1
	v_mov_b32_e32 v183, s98
	v_add_f32_e32 v183, s99, v183
	v_add_f32_e32 v183, s100, v183
	v_add_f32_e32 v183, s101, v183
	v_fmamk_f32 v183, v183, 0x3a800000, v182
	v_cmp_gt_f32_e32 vcc, 0x800000, v183
	v_mul_f32_e32 v181, 0x4b800000, v183
	s_nop 1
	v_cndmask_b32_e32 v183, v183, v181, vcc
	v_rsq_f32_e32 v183, v183
	s_nop 0
	v_mul_f32_e32 v181, 0x45800000, v183
	v_cndmask_b32_e32 v184, v183, v181, vcc
	v_mov_b32_e32 v185, v184
	v_cvt_pk_bf16_f32 v112, v144, v145
	v_cvt_pk_bf16_f32 v113, v146, v147
	v_cvt_pk_bf16_f32 v114, v148, v149
	v_cvt_pk_bf16_f32 v115, v150, v151
	v_cvt_pk_bf16_f32 v116, v152, v153
	v_cvt_pk_bf16_f32 v117, v154, v155
	v_cvt_pk_bf16_f32 v118, v156, v157
	v_cvt_pk_bf16_f32 v119, v158, v159
	v_add_u32_e32 v181, 0x1b80000, v177
	global_store_dwordx4 v181, v[112:115], s[78:79]
	global_store_dwordx4 v181, v[116:119], s[78:79] offset:1024
	v_add_u32_e32 v236, 0x1c00, v237
	s_mov_b64 exec, 1
	global_store_dword v236, v184, s[78:79]
	s_mov_b64 exec, -1
	v_readfirstlane_b32 s98, v179
	s_nop 3
	s_cmp_ge_u32 s98, 512
	s_cbranch_scc1 .Lmyxupd_done_5
	v_lshlrev_b32_e32 v177, 4, v176
	v_lshl_add_u32 v177, v179, 11, v177
	v_lshlrev_b32_e32 v237, 2, v179
	v_add_u32_e32 v237, 0x10000, v237
	v_add_u32_e32 v181, 0x3800000, v177
	global_load_dwordx4 v[0:3], v181, s[78:79]
	global_load_dwordx4 v[4:7], v181, s[78:79] offset:1024
	v_lshl_add_u32 v183, v179, 12, v180
	v_add_u32_e32 v183, 0xbf00000, v183
	v_add_u32_e32 v181, 0x0, v183
	global_load_dwordx4 v[8:11], v181, s[78:79]
	global_load_dwordx4 v[12:15], v181, s[78:79] offset:16
	global_load_dwordx4 v[16:19], v181, s[78:79] offset:2048
	global_load_dwordx4 v[20:23], v181, s[78:79] offset:2064
	v_add_u32_e32 v181, 0x200000, v183
	global_load_dwordx4 v[24:27], v181, s[78:79]
	global_load_dwordx4 v[28:31], v181, s[78:79] offset:16
	global_load_dwordx4 v[32:35], v181, s[78:79] offset:2048
	global_load_dwordx4 v[36:39], v181, s[78:79] offset:2064
	v_add_u32_e32 v181, 0x400000, v183
	global_load_dwordx4 v[40:43], v181, s[78:79]
	global_load_dwordx4 v[44:47], v181, s[78:79] offset:16
	global_load_dwordx4 v[48:51], v181, s[78:79] offset:2048
	global_load_dwordx4 v[52:55], v181, s[78:79] offset:2064
	v_add_u32_e32 v181, 0x600000, v183
	global_load_dwordx4 v[56:59], v181, s[78:79]
	global_load_dwordx4 v[60:63], v181, s[78:79] offset:16
	global_load_dwordx4 v[64:67], v181, s[78:79] offset:2048
	global_load_dwordx4 v[68:71], v181, s[78:79] offset:2064
	v_add_u32_e32 v181, 0x800000, v183
	global_load_dwordx4 v[72:75], v181, s[78:79]
	global_load_dwordx4 v[76:79], v181, s[78:79] offset:16
	global_load_dwordx4 v[80:83], v181, s[78:79] offset:2048
	global_load_dwordx4 v[84:87], v181, s[78:79] offset:2064
	v_add_u32_e32 v181, 0xa00000, v183
	global_load_dwordx4 v[88:91], v181, s[78:79]
	global_load_dwordx4 v[92:95], v181, s[78:79] offset:16
	global_load_dwordx4 v[96:99], v181, s[78:79] offset:2048
	global_load_dwordx4 v[100:103], v181, s[78:79] offset:2064
	s_waitcnt vmcnt(20)
	v_pk_add_f32 v[160:161], v[8:9], 0 op_sel_hi:[1,0]
	v_pk_add_f32 v[162:163], v[10:11], 0 op_sel_hi:[1,0]
	v_pk_add_f32 v[164:165], v[12:13], 0 op_sel_hi:[1,0]
	v_pk_add_f32 v[166:167], v[14:15], 0 op_sel_hi:[1,0]
	v_pk_add_f32 v[168:169], v[16:17], 0 op_sel_hi:[1,0]
	v_pk_add_f32 v[170:171], v[18:19], 0 op_sel_hi:[1,0]
	v_pk_add_f32 v[172:173], v[20:21], 0 op_sel_hi:[1,0]
	v_pk_add_f32 v[174:175], v[22:23], 0 op_sel_hi:[1,0]
	s_waitcnt vmcnt(16)
	v_pk_add_f32 v[160:161], v[160:161], v[24:25]
	v_pk_add_f32 v[162:163], v[162:163], v[26:27]
	v_pk_add_f32 v[164:165], v[164:165], v[28:29]
	v_pk_add_f32 v[166:167], v[166:167], v[30:31]
	v_pk_add_f32 v[168:169], v[168:169], v[32:33]
	v_pk_add_f32 v[170:171], v[170:171], v[34:35]
	v_pk_add_f32 v[172:173], v[172:173], v[36:37]
	v_pk_add_f32 v[174:175], v[174:175], v[38:39]
	s_waitcnt vmcnt(12)
	v_pk_add_f32 v[160:161], v[160:161], v[40:41]
	v_pk_add_f32 v[162:163], v[162:163], v[42:43]
	v_pk_add_f32 v[164:165], v[164:165], v[44:45]
	v_pk_add_f32 v[166:167], v[166:167], v[46:47]
	v_pk_add_f32 v[168:169], v[168:169], v[48:49]
	v_pk_add_f32 v[170:171], v[170:171], v[50:51]
	v_pk_add_f32 v[172:173], v[172:173], v[52:53]
	v_pk_add_f32 v[174:175], v[174:175], v[54:55]
	s_waitcnt vmcnt(8)
	v_pk_add_f32 v[160:161], v[160:161], v[56:57]
	v_pk_add_f32 v[162:163], v[162:163], v[58:59]
	v_pk_add_f32 v[164:165], v[164:165], v[60:61]
	v_pk_add_f32 v[166:167], v[166:167], v[62:63]
	v_pk_add_f32 v[168:169], v[168:169], v[64:65]
	v_pk_add_f32 v[170:171], v[170:171], v[66:67]
	v_pk_add_f32 v[172:173], v[172:173], v[68:69]
	v_pk_add_f32 v[174:175], v[174:175], v[70:71]
	s_waitcnt vmcnt(4)
	v_pk_add_f32 v[160:161], v[160:161], v[72:73]
	v_pk_add_f32 v[162:163], v[162:163], v[74:75]
	v_pk_add_f32 v[164:165], v[164:165], v[76:77]
	v_pk_add_f32 v[166:167], v[166:167], v[78:79]
	v_pk_add_f32 v[168:169], v[168:169], v[80:81]
	v_pk_add_f32 v[170:171], v[170:171], v[82:83]
	v_pk_add_f32 v[172:173], v[172:173], v[84:85]
	v_pk_add_f32 v[174:175], v[174:175], v[86:87]
	s_waitcnt vmcnt(0)
	v_pk_add_f32 v[160:161], v[160:161], v[88:89]
	v_pk_add_f32 v[162:163], v[162:163], v[90:91]
	v_pk_add_f32 v[164:165], v[164:165], v[92:93]
	v_pk_add_f32 v[166:167], v[166:167], v[94:95]
	v_pk_add_f32 v[168:169], v[168:169], v[96:97]
	v_pk_add_f32 v[170:171], v[170:171], v[98:99]
	v_pk_add_f32 v[172:173], v[172:173], v[100:101]
	v_pk_add_f32 v[174:175], v[174:175], v[102:103]
	v_lshlrev_b32_e32 v144, 16, v0
	v_and_b32_e32 v145, 0xffff0000, v0
	v_lshlrev_b32_e32 v146, 16, v1
	v_and_b32_e32 v147, 0xffff0000, v1
	v_lshlrev_b32_e32 v148, 16, v2
	v_and_b32_e32 v149, 0xffff0000, v2
	v_lshlrev_b32_e32 v150, 16, v3
	v_and_b32_e32 v151, 0xffff0000, v3
	v_lshlrev_b32_e32 v152, 16, v4
	v_and_b32_e32 v153, 0xffff0000, v4
	v_lshlrev_b32_e32 v154, 16, v5
	v_and_b32_e32 v155, 0xffff0000, v5
	v_lshlrev_b32_e32 v156, 16, v6
	v_and_b32_e32 v157, 0xffff0000, v6
	v_lshlrev_b32_e32 v158, 16, v7
	v_and_b32_e32 v159, 0xffff0000, v7
	v_add_u32_e32 v181, 0xc00000, v183
	global_load_dwordx4 v[8:11], v181, s[78:79]
	global_load_dwordx4 v[12:15], v181, s[78:79] offset:16
	global_load_dwordx4 v[16:19], v181, s[78:79] offset:2048
	global_load_dwordx4 v[20:23], v181, s[78:79] offset:2064
	v_add_u32_e32 v181, 0xe00000, v183
	global_load_dwordx4 v[24:27], v181, s[78:79]
	global_load_dwordx4 v[28:31], v181, s[78:79] offset:16
	global_load_dwordx4 v[32:35], v181, s[78:79] offset:2048
	global_load_dwordx4 v[36:39], v181, s[78:79] offset:2064
	v_add_u32_e32 v181, 0x1000000, v183
	global_load_dwordx4 v[40:43], v181, s[78:79]
	global_load_dwordx4 v[44:47], v181, s[78:79] offset:16
	global_load_dwordx4 v[48:51], v181, s[78:79] offset:2048
	global_load_dwordx4 v[52:55], v181, s[78:79] offset:2064
	v_add_u32_e32 v181, 0x1200000, v183
	global_load_dwordx4 v[56:59], v181, s[78:79]
	global_load_dwordx4 v[60:63], v181, s[78:79] offset:16
	global_load_dwordx4 v[64:67], v181, s[78:79] offset:2048
	global_load_dwordx4 v[68:71], v181, s[78:79] offset:2064
	v_add_u32_e32 v181, 0x1400000, v183
	global_load_dwordx4 v[72:75], v181, s[78:79]
	global_load_dwordx4 v[76:79], v181, s[78:79] offset:16
	global_load_dwordx4 v[80:83], v181, s[78:79] offset:2048
	global_load_dwordx4 v[84:87], v181, s[78:79] offset:2064
	s_waitcnt vmcnt(16)
	v_pk_add_f32 v[160:161], v[160:161], v[8:9]
	v_pk_add_f32 v[162:163], v[162:163], v[10:11]
	v_pk_add_f32 v[164:165], v[164:165], v[12:13]
	v_pk_add_f32 v[166:167], v[166:167], v[14:15]
	v_pk_add_f32 v[168:169], v[168:169], v[16:17]
	v_pk_add_f32 v[170:171], v[170:171], v[18:19]
	v_pk_add_f32 v[172:173], v[172:173], v[20:21]
	v_pk_add_f32 v[174:175], v[174:175], v[22:23]
	s_waitcnt vmcnt(12)
	v_pk_add_f32 v[160:161], v[160:161], v[24:25]
	v_pk_add_f32 v[162:163], v[162:163], v[26:27]
	v_pk_add_f32 v[164:165], v[164:165], v[28:29]
	v_pk_add_f32 v[166:167], v[166:167], v[30:31]
	v_pk_add_f32 v[168:169], v[168:169], v[32:33]
	v_pk_add_f32 v[170:171], v[170:171], v[34:35]
	v_pk_add_f32 v[172:173], v[172:173], v[36:37]
	v_pk_add_f32 v[174:175], v[174:175], v[38:39]
	s_waitcnt vmcnt(8)
	v_pk_add_f32 v[160:161], v[160:161], v[40:41]
	v_pk_add_f32 v[162:163], v[162:163], v[42:43]
	v_pk_add_f32 v[164:165], v[164:165], v[44:45]
	v_pk_add_f32 v[166:167], v[166:167], v[46:47]
	v_pk_add_f32 v[168:169], v[168:169], v[48:49]
	v_pk_add_f32 v[170:171], v[170:171], v[50:51]
	v_pk_add_f32 v[172:173], v[172:173], v[52:53]
	v_pk_add_f32 v[174:175], v[174:175], v[54:55]
	s_waitcnt vmcnt(4)
	v_pk_add_f32 v[160:161], v[160:161], v[56:57]
	v_pk_add_f32 v[162:163], v[162:163], v[58:59]
	v_pk_add_f32 v[164:165], v[164:165], v[60:61]
	v_pk_add_f32 v[166:167], v[166:167], v[62:63]
	v_pk_add_f32 v[168:169], v[168:169], v[64:65]
	v_pk_add_f32 v[170:171], v[170:171], v[66:67]
	v_pk_add_f32 v[172:173], v[172:173], v[68:69]
	v_pk_add_f32 v[174:175], v[174:175], v[70:71]
	s_waitcnt vmcnt(0)
	v_pk_add_f32 v[160:161], v[160:161], v[72:73]
	v_pk_add_f32 v[162:163], v[162:163], v[74:75]
	v_pk_add_f32 v[164:165], v[164:165], v[76:77]
	v_pk_add_f32 v[166:167], v[166:167], v[78:79]
	v_pk_add_f32 v[168:169], v[168:169], v[80:81]
	v_pk_add_f32 v[170:171], v[170:171], v[82:83]
	v_pk_add_f32 v[172:173], v[172:173], v[84:85]
	v_pk_add_f32 v[174:175], v[174:175], v[86:87]
	v_pk_mul_f32 v[252:253], v[160:161], v[160:161]
	v_pk_mul_f32 v[254:255], v[162:163], v[162:163]
	v_pk_fma_f32 v[252:253], v[164:165], v[164:165], v[252:253]
	v_pk_fma_f32 v[254:255], v[166:167], v[166:167], v[254:255]
	v_pk_fma_f32 v[252:253], v[168:169], v[168:169], v[252:253]
	v_pk_fma_f32 v[254:255], v[170:171], v[170:171], v[254:255]
	v_pk_fma_f32 v[252:253], v[172:173], v[172:173], v[252:253]
	v_pk_fma_f32 v[254:255], v[174:175], v[174:175], v[254:255]
	v_pk_add_f32 v[252:253], v[252:253], v[254:255]
	s_nop 0
	v_add_f32_e32 v183, v252, v253
	s_nop 1
	v_add_f32_dpp v183, v183, v183 quad_perm:[1,0,3,2] row_mask:0xf bank_mask:0xf bound_ctrl:1
	s_nop 1
	v_add_f32_dpp v183, v183, v183 quad_perm:[2,3,0,1] row_mask:0xf bank_mask:0xf bound_ctrl:1
	s_nop 1
	v_add_f32_dpp v183, v183, v183 row_half_mirror row_mask:0xf bank_mask:0xf bound_ctrl:1
	s_nop 1
	v_add_f32_dpp v183, v183, v183 row_mirror row_mask:0xf bank_mask:0xf bound_ctrl:1
	s_nop 1
	v_readlane_b32 s98, v183, 0
	v_readlane_b32 s99, v183, 16
	v_readlane_b32 s100, v183, 32
	v_readlane_b32 s101, v183, 48
	s_nop 1
	v_mov_b32_e32 v183, s98
	v_add_f32_e32 v183, s99, v183
	v_add_f32_e32 v183, s100, v183
	v_add_f32_e32 v183, s101, v183
	v_fmamk_f32 v183, v183, 0x3a800000, v182
	v_cmp_gt_f32_e32 vcc, 0x800000, v183
	v_mul_f32_e32 v181, 0x4b800000, v183
	s_nop 1
	v_cndmask_b32_e32 v183, v183, v181, vcc
	v_rsq_f32_e32 v183, v183
	s_nop 0
	v_mul_f32_e32 v181, 0x45800000, v183
	v_cndmask_b32_e32 v184, v183, v181, vcc
	v_mov_b32_e32 v185, v184
	v_pk_mul_f32 v[160:161], v[160:161], v[184:185]
	v_pk_mul_f32 v[162:163], v[162:163], v[184:185]
	v_pk_mul_f32 v[164:165], v[164:165], v[184:185]
	v_pk_mul_f32 v[166:167], v[166:167], v[184:185]
	v_pk_mul_f32 v[168:169], v[168:169], v[184:185]
	v_pk_mul_f32 v[170:171], v[170:171], v[184:185]
	v_pk_mul_f32 v[172:173], v[172:173], v[184:185]
	v_pk_mul_f32 v[174:175], v[174:175], v[184:185]
	v_pk_fma_f32 v[144:145], v[160:161], v[128:129], v[144:145]
	v_pk_fma_f32 v[146:147], v[162:163], v[130:131], v[146:147]
	v_pk_fma_f32 v[148:149], v[164:165], v[132:133], v[148:149]
	v_pk_fma_f32 v[150:151], v[166:167], v[134:135], v[150:151]
	v_pk_fma_f32 v[152:153], v[168:169], v[136:137], v[152:153]
	v_pk_fma_f32 v[154:155], v[170:171], v[138:139], v[154:155]
	v_pk_fma_f32 v[156:157], v[172:173], v[140:141], v[156:157]
	v_pk_fma_f32 v[158:159], v[174:175], v[142:143], v[158:159]
	v_pk_mul_f32 v[252:253], v[144:145], v[144:145]
	v_pk_mul_f32 v[254:255], v[146:147], v[146:147]
	v_pk_fma_f32 v[252:253], v[148:149], v[148:149], v[252:253]
	v_pk_fma_f32 v[254:255], v[150:151], v[150:151], v[254:255]
	v_pk_fma_f32 v[252:253], v[152:153], v[152:153], v[252:253]
	v_pk_fma_f32 v[254:255], v[154:155], v[154:155], v[254:255]
	v_pk_fma_f32 v[252:253], v[156:157], v[156:157], v[252:253]
	v_pk_fma_f32 v[254:255], v[158:159], v[158:159], v[254:255]
	v_pk_add_f32 v[252:253], v[252:253], v[254:255]
	s_nop 0
	v_add_f32_e32 v183, v252, v253
	s_nop 1
	v_add_f32_dpp v183, v183, v183 quad_perm:[1,0,3,2] row_mask:0xf bank_mask:0xf bound_ctrl:1
	s_nop 1
	v_add_f32_dpp v183, v183, v183 quad_perm:[2,3,0,1] row_mask:0xf bank_mask:0xf bound_ctrl:1
	s_nop 1
	v_add_f32_dpp v183, v183, v183 row_half_mirror row_mask:0xf bank_mask:0xf bound_ctrl:1
	s_nop 1
	v_add_f32_dpp v183, v183, v183 row_mirror row_mask:0xf bank_mask:0xf bound_ctrl:1
	s_nop 1
	v_readlane_b32 s98, v183, 0
	v_readlane_b32 s99, v183, 16
	v_readlane_b32 s100, v183, 32
	v_readlane_b32 s101, v183, 48
	s_nop 1
	v_mov_b32_e32 v183, s98
	v_add_f32_e32 v183, s99, v183
	v_add_f32_e32 v183, s100, v183
	v_add_f32_e32 v183, s101, v183
	v_fmamk_f32 v183, v183, 0x3a800000, v182
	v_cmp_gt_f32_e32 vcc, 0x800000, v183
	v_mul_f32_e32 v181, 0x4b800000, v183
	s_nop 1
	v_cndmask_b32_e32 v183, v183, v181, vcc
	v_rsq_f32_e32 v183, v183
	s_nop 0
	v_mul_f32_e32 v181, 0x45800000, v183
	v_cndmask_b32_e32 v184, v183, v181, vcc
	v_mov_b32_e32 v185, v184
	v_cvt_pk_bf16_f32 v0, v144, v145
	v_cvt_pk_bf16_f32 v1, v146, v147
	v_cvt_pk_bf16_f32 v2, v148, v149
	v_cvt_pk_bf16_f32 v3, v150, v151
	v_cvt_pk_bf16_f32 v4, v152, v153
	v_cvt_pk_bf16_f32 v5, v154, v155
	v_cvt_pk_bf16_f32 v6, v156, v157
	v_cvt_pk_bf16_f32 v7, v158, v159
	v_add_u32_e32 v181, 0x3800000, v177
	global_store_dwordx4 v181, v[0:3], s[78:79]
	global_store_dwordx4 v181, v[4:7], s[78:79] offset:1024
	v_add_u32_e32 v236, 0x10000, v237
	s_mov_b64 exec, 1
	global_store_dword v236, v184, s[78:79]
	s_mov_b64 exec, -1

.LBB0_2573:
	v_readlane_b32 s0, v235, 52
	v_readlane_b32 s1, v235, 53
	s_and_b64 vcc, exec, s[0:1]
	s_waitcnt lgkmcnt(0)
	s_barrier
	v_mbcnt_lo_u32_b32 v0, -1, 0
	v_mbcnt_hi_u32_b32 v0, -1, v0
	s_cbranch_vccnz .LBB0_2593
	v_lshlrev_b32_e32 v2, 3, v0
	v_ashrrev_i32_e32 v3, 31, v2
	v_readlane_b32 s4, v235, 4
	v_lshlrev_b64 v[4:5], 1, v[2:3]
	v_lshlrev_b64 v[2:3], 2, v[2:3]
	v_readlane_b32 s14, v235, 14
	v_readlane_b32 s15, v235, 15
	v_lshl_add_u64 v[62:63], s[90:91], 0, v[2:3]
	v_readlane_b32 s5, v235, 5
	v_readlane_b32 s6, v235, 6
	v_readlane_b32 s7, v235, 7
	v_readlane_b32 s8, v235, 8
	v_readlane_b32 s9, v235, 9
	v_readlane_b32 s10, v235, 10
	v_readlane_b32 s11, v235, 11
	v_readlane_b32 s12, v235, 12
	v_readlane_b32 s13, v235, 13
	v_readlane_b32 s16, v235, 16
	v_readlane_b32 s17, v235, 17
	v_readlane_b32 s18, v235, 18
	v_readlane_b32 s19, v235, 19
	v_lshl_add_u64 v[2:3], s[14:15], 0, v[2:3]
	s_mov_b64 s[0:1], 0x3000
	v_lshl_add_u64 v[60:61], s[86:87], 0, v[4:5]
	v_lshl_add_u64 v[64:65], s[54:55], 0, v[4:5]
	v_lshl_add_u64 v[66:67], v[2:3], 0, s[0:1]
	s_mov_b32 s1, 0
	v_cmp_eq_u32_e64 s[4:5], 0, v0
	s_mov_b64 s[6:7], 0x200000
	s_mov_b64 s[8:9], 0x200800
	s_mov_b64 s[10:11], 0x400000
	s_mov_b64 s[12:13], 0x400800
	s_mov_b64 s[14:15], 0x600000
	s_mov_b64 s[16:17], 0x600800
	s_mov_b64 s[18:19], 0x800000
	s_mov_b32 s48, 0x800000
	s_mov_b64 s[20:21], 0x800800
	s_mov_b64 s[22:23], 0xa00000
	s_mov_b64 s[24:25], 0xa00800
	s_mov_b64 s[26:27], 0xc00000
	s_mov_b64 s[28:29], 0xc00800
	s_mov_b64 s[30:31], 0xe00000
	s_mov_b64 s[36:37], 0xe00800
	v_mov_b32_e32 v104, 0
	v_mov_b32_e32 v105, 0x358637bd
	v_readlane_b32 s38, v235, 61
	v_readlane_b32 s39, v235, 62
	v_mbcnt_lo_u32_b32 v176, -1, 0
	v_mbcnt_hi_u32_b32 v176, -1, v176
	v_readlane_b32 s98, v235, 49
	v_readlane_b32 s99, v235, 20
	v_readlane_b32 s100, v235, 14
	v_readlane_b32 s101, v235, 15
	s_nop 3
	s_lshr_b32 vcc_lo, s98, 3
	s_and_b32 vcc_hi, vcc_lo, 7
	s_lshr_b32 vcc_lo, vcc_lo, 3
	s_lshl_b32 vcc_lo, vcc_lo, 3
	s_add_i32 vcc_lo, vcc_lo, s99
	s_lshl_b32 s98, vcc_hi, 8
	s_add_i32 s98, s98, vcc_lo
	s_lshl_b32 s99, vcc_hi, 11
	s_add_i32 s99, s99, vcc_lo
	v_mov_b32_e32 v183, s99
	v_lshlrev_b32_e32 v177, 4, v176
	s_lshl_b32 s99, s99, 11
	v_add_u32_e32 v177, s99, v177
	v_add_u32_e32 v178, 0x1800000, v177
	v_add_u32_e32 v179, 0x9e00000, v177
	v_lshlrev_b32_e32 v180, 5, v176
	v_add_u32_e32 v181, 0x3000, v180
	global_load_dwordx4 v[128:131], v181, s[100:101]
	global_load_dwordx4 v[132:135], v181, s[100:101] offset:16
	global_load_dwordx4 v[136:139], v181, s[100:101] offset:2048
	global_load_dwordx4 v[140:143], v181, s[100:101] offset:2064
	v_mov_b32_e32 v182, 0x358637bd
	global_load_dwordx4 v[0:3], v178, s[78:79]
	global_load_dwordx4 v[4:7], v178, s[78:79] offset:1024
	global_load_dwordx4 v[8:11], v179, s[78:79]
	global_load_dwordx4 v[12:15], v179, s[78:79] offset:1024
	v_add_u32_e32 v178, 0x80000, v178
	v_add_u32_e32 v179, 0x80000, v179
	global_load_dwordx4 v[16:19], v178, s[78:79]
	global_load_dwordx4 v[20:23], v178, s[78:79] offset:1024
	global_load_dwordx4 v[24:27], v179, s[78:79]
	global_load_dwordx4 v[28:31], v179, s[78:79] offset:1024
	v_add_u32_e32 v178, 0x80000, v178
	v_add_u32_e32 v179, 0x80000, v179
	global_load_dwordx4 v[32:35], v178, s[78:79]
	global_load_dwordx4 v[36:39], v178, s[78:79] offset:1024
	global_load_dwordx4 v[40:43], v179, s[78:79]
	global_load_dwordx4 v[44:47], v179, s[78:79] offset:1024
	v_add_u32_e32 v178, 0x80000, v178
	v_add_u32_e32 v179, 0x80000, v179
	global_load_dwordx4 v[48:51], v178, s[78:79]
	global_load_dwordx4 v[52:55], v178, s[78:79] offset:1024
	global_load_dwordx4 v[56:59], v179, s[78:79]
	global_load_dwordx4 v[60:63], v179, s[78:79] offset:1024
	v_add_u32_e32 v178, 0x80000, v178
	v_add_u32_e32 v179, 0x80000, v179
	global_load_dwordx4 v[64:67], v178, s[78:79]
	global_load_dwordx4 v[68:71], v178, s[78:79] offset:1024
	global_load_dwordx4 v[72:75], v179, s[78:79]
	global_load_dwordx4 v[76:79], v179, s[78:79] offset:1024
	v_add_u32_e32 v178, 0x80000, v178
	v_add_u32_e32 v179, 0x80000, v179
	global_load_dwordx4 v[80:83], v178, s[78:79]
	global_load_dwordx4 v[84:87], v178, s[78:79] offset:1024
	global_load_dwordx4 v[88:91], v179, s[78:79]
	global_load_dwordx4 v[92:95], v179, s[78:79] offset:1024
	v_add_u32_e32 v178, 0x80000, v178
	v_add_u32_e32 v179, 0x80000, v179
	global_load_dwordx4 v[96:99], v178, s[78:79]
	global_load_dwordx4 v[100:103], v178, s[78:79] offset:1024
	global_load_dwordx4 v[104:107], v179, s[78:79]
	global_load_dwordx4 v[108:111], v179, s[78:79] offset:1024
	v_add_u32_e32 v178, 0x80000, v178
	v_add_u32_e32 v179, 0x80000, v179
	global_load_dwordx4 v[112:115], v178, s[78:79]
	global_load_dwordx4 v[116:119], v178, s[78:79] offset:1024
	global_load_dwordx4 v[120:123], v179, s[78:79]
	global_load_dwordx4 v[124:127], v179, s[78:79] offset:1024
	v_lshlrev_b32_e32 v237, 2, v183
	v_add_u32_e32 v237, 0x10000, v237
	v_mov_b32_e32 v179, s98
	s_waitcnt vmcnt(28)
	v_lshlrev_b32_e32 v144, 16, v0
	v_and_b32_e32 v145, 0xffff0000, v0
	v_lshlrev_b32_e32 v146, 16, v1
	v_and_b32_e32 v147, 0xffff0000, v1
	v_lshlrev_b32_e32 v148, 16, v2
	v_and_b32_e32 v149, 0xffff0000, v2
	v_lshlrev_b32_e32 v150, 16, v3
	v_and_b32_e32 v151, 0xffff0000, v3
	v_lshlrev_b32_e32 v152, 16, v4
	v_and_b32_e32 v153, 0xffff0000, v4
	v_lshlrev_b32_e32 v154, 16, v5
	v_and_b32_e32 v155, 0xffff0000, v5
	v_lshlrev_b32_e32 v156, 16, v6
	v_and_b32_e32 v157, 0xffff0000, v6
	v_lshlrev_b32_e32 v158, 16, v7
	v_and_b32_e32 v159, 0xffff0000, v7
	v_lshlrev_b32_e32 v160, 16, v8
	v_and_b32_e32 v161, 0xffff0000, v8
	v_lshlrev_b32_e32 v162, 16, v9
	v_and_b32_e32 v163, 0xffff0000, v9
	v_lshlrev_b32_e32 v164, 16, v10
	v_and_b32_e32 v165, 0xffff0000, v10
	v_lshlrev_b32_e32 v166, 16, v11
	v_and_b32_e32 v167, 0xffff0000, v11
	v_lshlrev_b32_e32 v168, 16, v12
	v_and_b32_e32 v169, 0xffff0000, v12
	v_lshlrev_b32_e32 v170, 16, v13
	v_and_b32_e32 v171, 0xffff0000, v13
	v_lshlrev_b32_e32 v172, 16, v14
	v_and_b32_e32 v173, 0xffff0000, v14
	v_lshlrev_b32_e32 v174, 16, v15
	v_and_b32_e32 v175, 0xffff0000, v15
	v_pk_mul_f32 v[252:253], v[160:161], v[160:161]
	v_pk_mul_f32 v[254:255], v[162:163], v[162:163]
	v_pk_fma_f32 v[252:253], v[164:165], v[164:165], v[252:253]
	v_pk_fma_f32 v[254:255], v[166:167], v[166:167], v[254:255]
	v_pk_fma_f32 v[252:253], v[168:169], v[168:169], v[252:253]
	v_pk_fma_f32 v[254:255], v[170:171], v[170:171], v[254:255]
	v_pk_fma_f32 v[252:253], v[172:173], v[172:173], v[252:253]
	v_pk_fma_f32 v[254:255], v[174:175], v[174:175], v[254:255]
	v_pk_add_f32 v[252:253], v[252:253], v[254:255]
	s_nop 0
	v_add_f32_e32 v183, v252, v253
	s_nop 1
	v_add_f32_dpp v183, v183, v183 quad_perm:[1,0,3,2] row_mask:0xf bank_mask:0xf bound_ctrl:1
	s_nop 1
	v_add_f32_dpp v183, v183, v183 quad_perm:[2,3,0,1] row_mask:0xf bank_mask:0xf bound_ctrl:1
	s_nop 1
	v_add_f32_dpp v183, v183, v183 row_half_mirror row_mask:0xf bank_mask:0xf bound_ctrl:1
	s_nop 1
	v_add_f32_dpp v183, v183, v183 row_mirror row_mask:0xf bank_mask:0xf bound_ctrl:1
	s_nop 1
	v_readlane_b32 s98, v183, 0
	v_readlane_b32 s99, v183, 16
	v_readlane_b32 s100, v183, 32
	v_readlane_b32 s101, v183, 48
	s_nop 1
	v_mov_b32_e32 v183, s98
	v_add_f32_e32 v183, s99, v183
	v_add_f32_e32 v183, s100, v183
	v_add_f32_e32 v183, s101, v183
	v_fmamk_f32 v183, v183, 0x3a800000, v182
	v_cmp_gt_f32_e32 vcc, 0x800000, v183
	v_mul_f32_e32 v181, 0x4b800000, v183
	s_nop 1
	v_cndmask_b32_e32 v183, v183, v181, vcc
	v_rsq_f32_e32 v183, v183
	s_nop 0
	v_mul_f32_e32 v181, 0x45800000, v183
	v_cndmask_b32_e32 v184, v183, v181, vcc
	v_mov_b32_e32 v185, v184
	v_pk_mul_f32 v[160:161], v[160:161], v[184:185]
	v_pk_mul_f32 v[162:163], v[162:163], v[184:185]
	v_pk_mul_f32 v[164:165], v[164:165], v[184:185]
	v_pk_mul_f32 v[166:167], v[166:167], v[184:185]
	v_pk_mul_f32 v[168:169], v[168:169], v[184:185]
	v_pk_mul_f32 v[170:171], v[170:171], v[184:185]
	v_pk_mul_f32 v[172:173], v[172:173], v[184:185]
	v_pk_mul_f32 v[174:175], v[174:175], v[184:185]
	v_pk_fma_f32 v[144:145], v[160:161], v[128:129], v[144:145]
	v_pk_fma_f32 v[146:147], v[162:163], v[130:131], v[146:147]
	v_pk_fma_f32 v[148:149], v[164:165], v[132:133], v[148:149]
	v_pk_fma_f32 v[150:151], v[166:167], v[134:135], v[150:151]
	v_pk_fma_f32 v[152:153], v[168:169], v[136:137], v[152:153]
	v_pk_fma_f32 v[154:155], v[170:171], v[138:139], v[154:155]
	v_pk_fma_f32 v[156:157], v[172:173], v[140:141], v[156:157]
	v_pk_fma_f32 v[158:159], v[174:175], v[142:143], v[158:159]
	v_pk_mul_f32 v[252:253], v[144:145], v[144:145]
	v_pk_mul_f32 v[254:255], v[146:147], v[146:147]
	v_pk_fma_f32 v[252:253], v[148:149], v[148:149], v[252:253]
	v_pk_fma_f32 v[254:255], v[150:151], v[150:151], v[254:255]
	v_pk_fma_f32 v[252:253], v[152:153], v[152:153], v[252:253]
	v_pk_fma_f32 v[254:255], v[154:155], v[154:155], v[254:255]
	v_pk_fma_f32 v[252:253], v[156:157], v[156:157], v[252:253]
	v_pk_fma_f32 v[254:255], v[158:159], v[158:159], v[254:255]
	v_pk_add_f32 v[252:253], v[252:253], v[254:255]
	s_nop 0
	v_add_f32_e32 v183, v252, v253
	s_nop 1
	v_add_f32_dpp v183, v183, v183 quad_perm:[1,0,3,2] row_mask:0xf bank_mask:0xf bound_ctrl:1
	s_nop 1
	v_add_f32_dpp v183, v183, v183 quad_perm:[2,3,0,1] row_mask:0xf bank_mask:0xf bound_ctrl:1
	s_nop 1
	v_add_f32_dpp v183, v183, v183 row_half_mirror row_mask:0xf bank_mask:0xf bound_ctrl:1
	s_nop 1
	v_add_f32_dpp v183, v183, v183 row_mirror row_mask:0xf bank_mask:0xf bound_ctrl:1
	s_nop 1
	v_readlane_b32 s98, v183, 0
	v_readlane_b32 s99, v183, 16
	v_readlane_b32 s100, v183, 32
	v_readlane_b32 s101, v183, 48
	s_nop 1
	v_mov_b32_e32 v183, s98
	v_add_f32_e32 v183, s99, v183
	v_add_f32_e32 v183, s100, v183
	v_add_f32_e32 v183, s101, v183
	v_fmamk_f32 v183, v183, 0x3a800000, v182
	v_cmp_gt_f32_e32 vcc, 0x800000, v183
	v_mul_f32_e32 v181, 0x4b800000, v183
	s_nop 1
	v_cndmask_b32_e32 v183, v183, v181, vcc
	v_rsq_f32_e32 v183, v183
	s_nop 0
	v_mul_f32_e32 v181, 0x45800000, v183
	v_cndmask_b32_e32 v184, v183, v181, vcc
	v_mov_b32_e32 v185, v184
	v_cvt_pk_bf16_f32 v0, v144, v145
	v_cvt_pk_bf16_f32 v1, v146, v147
	v_cvt_pk_bf16_f32 v2, v148, v149
	v_cvt_pk_bf16_f32 v3, v150, v151
	v_cvt_pk_bf16_f32 v4, v152, v153
	v_cvt_pk_bf16_f32 v5, v154, v155
	v_cvt_pk_bf16_f32 v6, v156, v157
	v_cvt_pk_bf16_f32 v7, v158, v159
	v_add_u32_e32 v181, 0x1800000, v177
	global_store_dwordx4 v181, v[0:3], s[78:79]
	global_store_dwordx4 v181, v[4:7], s[78:79] offset:1024
	v_add_u32_e32 v236, 0x0, v237
	s_mov_b64 exec, 1
	global_store_dword v236, v184, s[78:79]
	s_mov_b64 exec, -1
	s_waitcnt vmcnt(24)
	v_lshlrev_b32_e32 v144, 16, v16
	v_and_b32_e32 v145, 0xffff0000, v16
	v_lshlrev_b32_e32 v146, 16, v17
	v_and_b32_e32 v147, 0xffff0000, v17
	v_lshlrev_b32_e32 v148, 16, v18
	v_and_b32_e32 v149, 0xffff0000, v18
	v_lshlrev_b32_e32 v150, 16, v19
	v_and_b32_e32 v151, 0xffff0000, v19
	v_lshlrev_b32_e32 v152, 16, v20
	v_and_b32_e32 v153, 0xffff0000, v20
	v_lshlrev_b32_e32 v154, 16, v21
	v_and_b32_e32 v155, 0xffff0000, v21
	v_lshlrev_b32_e32 v156, 16, v22
	v_and_b32_e32 v157, 0xffff0000, v22
	v_lshlrev_b32_e32 v158, 16, v23
	v_and_b32_e32 v159, 0xffff0000, v23
	v_lshlrev_b32_e32 v160, 16, v24
	v_and_b32_e32 v161, 0xffff0000, v24
	v_lshlrev_b32_e32 v162, 16, v25
	v_and_b32_e32 v163, 0xffff0000, v25
	v_lshlrev_b32_e32 v164, 16, v26
	v_and_b32_e32 v165, 0xffff0000, v26
	v_lshlrev_b32_e32 v166, 16, v27
	v_and_b32_e32 v167, 0xffff0000, v27
	v_lshlrev_b32_e32 v168, 16, v28
	v_and_b32_e32 v169, 0xffff0000, v28
	v_lshlrev_b32_e32 v170, 16, v29
	v_and_b32_e32 v171, 0xffff0000, v29
	v_lshlrev_b32_e32 v172, 16, v30
	v_and_b32_e32 v173, 0xffff0000, v30
	v_lshlrev_b32_e32 v174, 16, v31
	v_and_b32_e32 v175, 0xffff0000, v31
	v_pk_mul_f32 v[252:253], v[160:161], v[160:161]
	v_pk_mul_f32 v[254:255], v[162:163], v[162:163]
	v_pk_fma_f32 v[252:253], v[164:165], v[164:165], v[252:253]
	v_pk_fma_f32 v[254:255], v[166:167], v[166:167], v[254:255]
	v_pk_fma_f32 v[252:253], v[168:169], v[168:169], v[252:253]
	v_pk_fma_f32 v[254:255], v[170:171], v[170:171], v[254:255]
	v_pk_fma_f32 v[252:253], v[172:173], v[172:173], v[252:253]
	v_pk_fma_f32 v[254:255], v[174:175], v[174:175], v[254:255]
	v_pk_add_f32 v[252:253], v[252:253], v[254:255]
	s_nop 0
	v_add_f32_e32 v183, v252, v253
	s_nop 1
	v_add_f32_dpp v183, v183, v183 quad_perm:[1,0,3,2] row_mask:0xf bank_mask:0xf bound_ctrl:1
	s_nop 1
	v_add_f32_dpp v183, v183, v183 quad_perm:[2,3,0,1] row_mask:0xf bank_mask:0xf bound_ctrl:1
	s_nop 1
	v_add_f32_dpp v183, v183, v183 row_half_mirror row_mask:0xf bank_mask:0xf bound_ctrl:1
	s_nop 1
	v_add_f32_dpp v183, v183, v183 row_mirror row_mask:0xf bank_mask:0xf bound_ctrl:1
	s_nop 1
	v_readlane_b32 s98, v183, 0
	v_readlane_b32 s99, v183, 16
	v_readlane_b32 s100, v183, 32
	v_readlane_b32 s101, v183, 48
	s_nop 1
	v_mov_b32_e32 v183, s98
	v_add_f32_e32 v183, s99, v183
	v_add_f32_e32 v183, s100, v183
	v_add_f32_e32 v183, s101, v183
	v_fmamk_f32 v183, v183, 0x3a800000, v182
	v_cmp_gt_f32_e32 vcc, 0x800000, v183
	v_mul_f32_e32 v181, 0x4b800000, v183
	s_nop 1
	v_cndmask_b32_e32 v183, v183, v181, vcc
	v_rsq_f32_e32 v183, v183
	s_nop 0
	v_mul_f32_e32 v181, 0x45800000, v183
	v_cndmask_b32_e32 v184, v183, v181, vcc
	v_mov_b32_e32 v185, v184
	v_pk_mul_f32 v[160:161], v[160:161], v[184:185]
	v_pk_mul_f32 v[162:163], v[162:163], v[184:185]
	v_pk_mul_f32 v[164:165], v[164:165], v[184:185]
	v_pk_mul_f32 v[166:167], v[166:167], v[184:185]
	v_pk_mul_f32 v[168:169], v[168:169], v[184:185]
	v_pk_mul_f32 v[170:171], v[170:171], v[184:185]
	v_pk_mul_f32 v[172:173], v[172:173], v[184:185]
	v_pk_mul_f32 v[174:175], v[174:175], v[184:185]
	v_pk_fma_f32 v[144:145], v[160:161], v[128:129], v[144:145]
	v_pk_fma_f32 v[146:147], v[162:163], v[130:131], v[146:147]
	v_pk_fma_f32 v[148:149], v[164:165], v[132:133], v[148:149]
	v_pk_fma_f32 v[150:151], v[166:167], v[134:135], v[150:151]
	v_pk_fma_f32 v[152:153], v[168:169], v[136:137], v[152:153]
	v_pk_fma_f32 v[154:155], v[170:171], v[138:139], v[154:155]
	v_pk_fma_f32 v[156:157], v[172:173], v[140:141], v[156:157]
	v_pk_fma_f32 v[158:159], v[174:175], v[142:143], v[158:159]
	v_pk_mul_f32 v[252:253], v[144:145], v[144:145]
	v_pk_mul_f32 v[254:255], v[146:147], v[146:147]
	v_pk_fma_f32 v[252:253], v[148:149], v[148:149], v[252:253]
	v_pk_fma_f32 v[254:255], v[150:151], v[150:151], v[254:255]
	v_pk_fma_f32 v[252:253], v[152:153], v[152:153], v[252:253]
	v_pk_fma_f32 v[254:255], v[154:155], v[154:155], v[254:255]
	v_pk_fma_f32 v[252:253], v[156:157], v[156:157], v[252:253]
	v_pk_fma_f32 v[254:255], v[158:159], v[158:159], v[254:255]
	v_pk_add_f32 v[252:253], v[252:253], v[254:255]
	s_nop 0
	v_add_f32_e32 v183, v252, v253
	s_nop 1
	v_add_f32_dpp v183, v183, v183 quad_perm:[1,0,3,2] row_mask:0xf bank_mask:0xf bound_ctrl:1
	s_nop 1
	v_add_f32_dpp v183, v183, v183 quad_perm:[2,3,0,1] row_mask:0xf bank_mask:0xf bound_ctrl:1
	s_nop 1
	v_add_f32_dpp v183, v183, v183 row_half_mirror row_mask:0xf bank_mask:0xf bound_ctrl:1
	s_nop 1
	v_add_f32_dpp v183, v183, v183 row_mirror row_mask:0xf bank_mask:0xf bound_ctrl:1
	s_nop 1
	v_readlane_b32 s98, v183, 0
	v_readlane_b32 s99, v183, 16
	v_readlane_b32 s100, v183, 32
	v_readlane_b32 s101, v183, 48
	s_nop 1
	v_mov_b32_e32 v183, s98
	v_add_f32_e32 v183, s99, v183
	v_add_f32_e32 v183, s100, v183
	v_add_f32_e32 v183, s101, v183
	v_fmamk_f32 v183, v183, 0x3a800000, v182
	v_cmp_gt_f32_e32 vcc, 0x800000, v183
	v_mul_f32_e32 v181, 0x4b800000, v183
	s_nop 1
	v_cndmask_b32_e32 v183, v183, v181, vcc
	v_rsq_f32_e32 v183, v183
	s_nop 0
	v_mul_f32_e32 v181, 0x45800000, v183
	v_cndmask_b32_e32 v184, v183, v181, vcc
	v_mov_b32_e32 v185, v184
	v_cvt_pk_bf16_f32 v16, v144, v145
	v_cvt_pk_bf16_f32 v17, v146, v147
	v_cvt_pk_bf16_f32 v18, v148, v149
	v_cvt_pk_bf16_f32 v19, v150, v151
	v_cvt_pk_bf16_f32 v20, v152, v153
	v_cvt_pk_bf16_f32 v21, v154, v155
	v_cvt_pk_bf16_f32 v22, v156, v157
	v_cvt_pk_bf16_f32 v23, v158, v159
	v_add_u32_e32 v181, 0x1880000, v177
	global_store_dwordx4 v181, v[16:19], s[78:79]
	global_store_dwordx4 v181, v[20:23], s[78:79] offset:1024
	v_add_u32_e32 v236, 0x400, v237
	s_mov_b64 exec, 1
	global_store_dword v236, v184, s[78:79]
	s_mov_b64 exec, -1
	s_waitcnt vmcnt(20)
	v_lshlrev_b32_e32 v144, 16, v32
	v_and_b32_e32 v145, 0xffff0000, v32
	v_lshlrev_b32_e32 v146, 16, v33
	v_and_b32_e32 v147, 0xffff0000, v33
	v_lshlrev_b32_e32 v148, 16, v34
	v_and_b32_e32 v149, 0xffff0000, v34
	v_lshlrev_b32_e32 v150, 16, v35
	v_and_b32_e32 v151, 0xffff0000, v35
	v_lshlrev_b32_e32 v152, 16, v36
	v_and_b32_e32 v153, 0xffff0000, v36
	v_lshlrev_b32_e32 v154, 16, v37
	v_and_b32_e32 v155, 0xffff0000, v37
	v_lshlrev_b32_e32 v156, 16, v38
	v_and_b32_e32 v157, 0xffff0000, v38
	v_lshlrev_b32_e32 v158, 16, v39
	v_and_b32_e32 v159, 0xffff0000, v39
	v_lshlrev_b32_e32 v160, 16, v40
	v_and_b32_e32 v161, 0xffff0000, v40
	v_lshlrev_b32_e32 v162, 16, v41
	v_and_b32_e32 v163, 0xffff0000, v41
	v_lshlrev_b32_e32 v164, 16, v42
	v_and_b32_e32 v165, 0xffff0000, v42
	v_lshlrev_b32_e32 v166, 16, v43
	v_and_b32_e32 v167, 0xffff0000, v43
	v_lshlrev_b32_e32 v168, 16, v44
	v_and_b32_e32 v169, 0xffff0000, v44
	v_lshlrev_b32_e32 v170, 16, v45
	v_and_b32_e32 v171, 0xffff0000, v45
	v_lshlrev_b32_e32 v172, 16, v46
	v_and_b32_e32 v173, 0xffff0000, v46
	v_lshlrev_b32_e32 v174, 16, v47
	v_and_b32_e32 v175, 0xffff0000, v47
	v_pk_mul_f32 v[252:253], v[160:161], v[160:161]
	v_pk_mul_f32 v[254:255], v[162:163], v[162:163]
	v_pk_fma_f32 v[252:253], v[164:165], v[164:165], v[252:253]
	v_pk_fma_f32 v[254:255], v[166:167], v[166:167], v[254:255]
	v_pk_fma_f32 v[252:253], v[168:169], v[168:169], v[252:253]
	v_pk_fma_f32 v[254:255], v[170:171], v[170:171], v[254:255]
	v_pk_fma_f32 v[252:253], v[172:173], v[172:173], v[252:253]
	v_pk_fma_f32 v[254:255], v[174:175], v[174:175], v[254:255]
	v_pk_add_f32 v[252:253], v[252:253], v[254:255]
	s_nop 0
	v_add_f32_e32 v183, v252, v253
	s_nop 1
	v_add_f32_dpp v183, v183, v183 quad_perm:[1,0,3,2] row_mask:0xf bank_mask:0xf bound_ctrl:1
	s_nop 1
	v_add_f32_dpp v183, v183, v183 quad_perm:[2,3,0,1] row_mask:0xf bank_mask:0xf bound_ctrl:1
	s_nop 1
	v_add_f32_dpp v183, v183, v183 row_half_mirror row_mask:0xf bank_mask:0xf bound_ctrl:1
	s_nop 1
	v_add_f32_dpp v183, v183, v183 row_mirror row_mask:0xf bank_mask:0xf bound_ctrl:1
	s_nop 1
	v_readlane_b32 s98, v183, 0
	v_readlane_b32 s99, v183, 16
	v_readlane_b32 s100, v183, 32
	v_readlane_b32 s101, v183, 48
	s_nop 1
	v_mov_b32_e32 v183, s98
	v_add_f32_e32 v183, s99, v183
	v_add_f32_e32 v183, s100, v183
	v_add_f32_e32 v183, s101, v183
	v_fmamk_f32 v183, v183, 0x3a800000, v182
	v_cmp_gt_f32_e32 vcc, 0x800000, v183
	v_mul_f32_e32 v181, 0x4b800000, v183
	s_nop 1
	v_cndmask_b32_e32 v183, v183, v181, vcc
	v_rsq_f32_e32 v183, v183
	s_nop 0
	v_mul_f32_e32 v181, 0x45800000, v183
	v_cndmask_b32_e32 v184, v183, v181, vcc
	v_mov_b32_e32 v185, v184
	v_pk_mul_f32 v[160:161], v[160:161], v[184:185]
	v_pk_mul_f32 v[162:163], v[162:163], v[184:185]
	v_pk_mul_f32 v[164:165], v[164:165], v[184:185]
	v_pk_mul_f32 v[166:167], v[166:167], v[184:185]
	v_pk_mul_f32 v[168:169], v[168:169], v[184:185]
	v_pk_mul_f32 v[170:171], v[170:171], v[184:185]
	v_pk_mul_f32 v[172:173], v[172:173], v[184:185]
	v_pk_mul_f32 v[174:175], v[174:175], v[184:185]
	v_pk_fma_f32 v[144:145], v[160:161], v[128:129], v[144:145]
	v_pk_fma_f32 v[146:147], v[162:163], v[130:131], v[146:147]
	v_pk_fma_f32 v[148:149], v[164:165], v[132:133], v[148:149]
	v_pk_fma_f32 v[150:151], v[166:167], v[134:135], v[150:151]
	v_pk_fma_f32 v[152:153], v[168:169], v[136:137], v[152:153]
	v_pk_fma_f32 v[154:155], v[170:171], v[138:139], v[154:155]
	v_pk_fma_f32 v[156:157], v[172:173], v[140:141], v[156:157]
	v_pk_fma_f32 v[158:159], v[174:175], v[142:143], v[158:159]
	v_pk_mul_f32 v[252:253], v[144:145], v[144:145]
	v_pk_mul_f32 v[254:255], v[146:147], v[146:147]
	v_pk_fma_f32 v[252:253], v[148:149], v[148:149], v[252:253]
	v_pk_fma_f32 v[254:255], v[150:151], v[150:151], v[254:255]
	v_pk_fma_f32 v[252:253], v[152:153], v[152:153], v[252:253]
	v_pk_fma_f32 v[254:255], v[154:155], v[154:155], v[254:255]
	v_pk_fma_f32 v[252:253], v[156:157], v[156:157], v[252:253]
	v_pk_fma_f32 v[254:255], v[158:159], v[158:159], v[254:255]
	v_pk_add_f32 v[252:253], v[252:253], v[254:255]
	s_nop 0
	v_add_f32_e32 v183, v252, v253
	s_nop 1
	v_add_f32_dpp v183, v183, v183 quad_perm:[1,0,3,2] row_mask:0xf bank_mask:0xf bound_ctrl:1
	s_nop 1
	v_add_f32_dpp v183, v183, v183 quad_perm:[2,3,0,1] row_mask:0xf bank_mask:0xf bound_ctrl:1
	s_nop 1
	v_add_f32_dpp v183, v183, v183 row_half_mirror row_mask:0xf bank_mask:0xf bound_ctrl:1
	s_nop 1
	v_add_f32_dpp v183, v183, v183 row_mirror row_mask:0xf bank_mask:0xf bound_ctrl:1
	s_nop 1
	v_readlane_b32 s98, v183, 0
	v_readlane_b32 s99, v183, 16
	v_readlane_b32 s100, v183, 32
	v_readlane_b32 s101, v183, 48
	s_nop 1
	v_mov_b32_e32 v183, s98
	v_add_f32_e32 v183, s99, v183
	v_add_f32_e32 v183, s100, v183
	v_add_f32_e32 v183, s101, v183
	v_fmamk_f32 v183, v183, 0x3a800000, v182
	v_cmp_gt_f32_e32 vcc, 0x800000, v183
	v_mul_f32_e32 v181, 0x4b800000, v183
	s_nop 1
	v_cndmask_b32_e32 v183, v183, v181, vcc
	v_rsq_f32_e32 v183, v183
	s_nop 0
	v_mul_f32_e32 v181, 0x45800000, v183
	v_cndmask_b32_e32 v184, v183, v181, vcc
	v_mov_b32_e32 v185, v184
	v_cvt_pk_bf16_f32 v32, v144, v145
	v_cvt_pk_bf16_f32 v33, v146, v147
	v_cvt_pk_bf16_f32 v34, v148, v149
	v_cvt_pk_bf16_f32 v35, v150, v151
	v_cvt_pk_bf16_f32 v36, v152, v153
	v_cvt_pk_bf16_f32 v37, v154, v155
	v_cvt_pk_bf16_f32 v38, v156, v157
	v_cvt_pk_bf16_f32 v39, v158, v159
	v_add_u32_e32 v181, 0x1900000, v177
	global_store_dwordx4 v181, v[32:35], s[78:79]
	global_store_dwordx4 v181, v[36:39], s[78:79] offset:1024
	v_add_u32_e32 v236, 0x800, v237
	s_mov_b64 exec, 1
	global_store_dword v236, v184, s[78:79]
	s_mov_b64 exec, -1
	s_waitcnt vmcnt(16)
	v_lshlrev_b32_e32 v144, 16, v48
	v_and_b32_e32 v145, 0xffff0000, v48
	v_lshlrev_b32_e32 v146, 16, v49
	v_and_b32_e32 v147, 0xffff0000, v49
	v_lshlrev_b32_e32 v148, 16, v50
	v_and_b32_e32 v149, 0xffff0000, v50
	v_lshlrev_b32_e32 v150, 16, v51
	v_and_b32_e32 v151, 0xffff0000, v51
	v_lshlrev_b32_e32 v152, 16, v52
	v_and_b32_e32 v153, 0xffff0000, v52
	v_lshlrev_b32_e32 v154, 16, v53
	v_and_b32_e32 v155, 0xffff0000, v53
	v_lshlrev_b32_e32 v156, 16, v54
	v_and_b32_e32 v157, 0xffff0000, v54
	v_lshlrev_b32_e32 v158, 16, v55
	v_and_b32_e32 v159, 0xffff0000, v55
	v_lshlrev_b32_e32 v160, 16, v56
	v_and_b32_e32 v161, 0xffff0000, v56
	v_lshlrev_b32_e32 v162, 16, v57
	v_and_b32_e32 v163, 0xffff0000, v57
	v_lshlrev_b32_e32 v164, 16, v58
	v_and_b32_e32 v165, 0xffff0000, v58
	v_lshlrev_b32_e32 v166, 16, v59
	v_and_b32_e32 v167, 0xffff0000, v59
	v_lshlrev_b32_e32 v168, 16, v60
	v_and_b32_e32 v169, 0xffff0000, v60
	v_lshlrev_b32_e32 v170, 16, v61
	v_and_b32_e32 v171, 0xffff0000, v61
	v_lshlrev_b32_e32 v172, 16, v62
	v_and_b32_e32 v173, 0xffff0000, v62
	v_lshlrev_b32_e32 v174, 16, v63
	v_and_b32_e32 v175, 0xffff0000, v63
	v_pk_mul_f32 v[252:253], v[160:161], v[160:161]
	v_pk_mul_f32 v[254:255], v[162:163], v[162:163]
	v_pk_fma_f32 v[252:253], v[164:165], v[164:165], v[252:253]
	v_pk_fma_f32 v[254:255], v[166:167], v[166:167], v[254:255]
	v_pk_fma_f32 v[252:253], v[168:169], v[168:169], v[252:253]
	v_pk_fma_f32 v[254:255], v[170:171], v[170:171], v[254:255]
	v_pk_fma_f32 v[252:253], v[172:173], v[172:173], v[252:253]
	v_pk_fma_f32 v[254:255], v[174:175], v[174:175], v[254:255]
	v_pk_add_f32 v[252:253], v[252:253], v[254:255]
	s_nop 0
	v_add_f32_e32 v183, v252, v253
	s_nop 1
	v_add_f32_dpp v183, v183, v183 quad_perm:[1,0,3,2] row_mask:0xf bank_mask:0xf bound_ctrl:1
	s_nop 1
	v_add_f32_dpp v183, v183, v183 quad_perm:[2,3,0,1] row_mask:0xf bank_mask:0xf bound_ctrl:1
	s_nop 1
	v_add_f32_dpp v183, v183, v183 row_half_mirror row_mask:0xf bank_mask:0xf bound_ctrl:1
	s_nop 1
	v_add_f32_dpp v183, v183, v183 row_mirror row_mask:0xf bank_mask:0xf bound_ctrl:1
	s_nop 1
	v_readlane_b32 s98, v183, 0
	v_readlane_b32 s99, v183, 16
	v_readlane_b32 s100, v183, 32
	v_readlane_b32 s101, v183, 48
	s_nop 1
	v_mov_b32_e32 v183, s98
	v_add_f32_e32 v183, s99, v183
	v_add_f32_e32 v183, s100, v183
	v_add_f32_e32 v183, s101, v183
	v_fmamk_f32 v183, v183, 0x3a800000, v182
	v_cmp_gt_f32_e32 vcc, 0x800000, v183
	v_mul_f32_e32 v181, 0x4b800000, v183
	s_nop 1
	v_cndmask_b32_e32 v183, v183, v181, vcc
	v_rsq_f32_e32 v183, v183
	s_nop 0
	v_mul_f32_e32 v181, 0x45800000, v183
	v_cndmask_b32_e32 v184, v183, v181, vcc
	v_mov_b32_e32 v185, v184
	v_pk_mul_f32 v[160:161], v[160:161], v[184:185]
	v_pk_mul_f32 v[162:163], v[162:163], v[184:185]
	v_pk_mul_f32 v[164:165], v[164:165], v[184:185]
	v_pk_mul_f32 v[166:167], v[166:167], v[184:185]
	v_pk_mul_f32 v[168:169], v[168:169], v[184:185]
	v_pk_mul_f32 v[170:171], v[170:171], v[184:185]
	v_pk_mul_f32 v[172:173], v[172:173], v[184:185]
	v_pk_mul_f32 v[174:175], v[174:175], v[184:185]
	v_pk_fma_f32 v[144:145], v[160:161], v[128:129], v[144:145]
	v_pk_fma_f32 v[146:147], v[162:163], v[130:131], v[146:147]
	v_pk_fma_f32 v[148:149], v[164:165], v[132:133], v[148:149]
	v_pk_fma_f32 v[150:151], v[166:167], v[134:135], v[150:151]
	v_pk_fma_f32 v[152:153], v[168:169], v[136:137], v[152:153]
	v_pk_fma_f32 v[154:155], v[170:171], v[138:139], v[154:155]
	v_pk_fma_f32 v[156:157], v[172:173], v[140:141], v[156:157]
	v_pk_fma_f32 v[158:159], v[174:175], v[142:143], v[158:159]
	v_pk_mul_f32 v[252:253], v[144:145], v[144:145]
	v_pk_mul_f32 v[254:255], v[146:147], v[146:147]
	v_pk_fma_f32 v[252:253], v[148:149], v[148:149], v[252:253]
	v_pk_fma_f32 v[254:255], v[150:151], v[150:151], v[254:255]
	v_pk_fma_f32 v[252:253], v[152:153], v[152:153], v[252:253]
	v_pk_fma_f32 v[254:255], v[154:155], v[154:155], v[254:255]
	v_pk_fma_f32 v[252:253], v[156:157], v[156:157], v[252:253]
	v_pk_fma_f32 v[254:255], v[158:159], v[158:159], v[254:255]
	v_pk_add_f32 v[252:253], v[252:253], v[254:255]
	s_nop 0
	v_add_f32_e32 v183, v252, v253
	s_nop 1
	v_add_f32_dpp v183, v183, v183 quad_perm:[1,0,3,2] row_mask:0xf bank_mask:0xf bound_ctrl:1
	s_nop 1
	v_add_f32_dpp v183, v183, v183 quad_perm:[2,3,0,1] row_mask:0xf bank_mask:0xf bound_ctrl:1
	s_nop 1
	v_add_f32_dpp v183, v183, v183 row_half_mirror row_mask:0xf bank_mask:0xf bound_ctrl:1
	s_nop 1
	v_add_f32_dpp v183, v183, v183 row_mirror row_mask:0xf bank_mask:0xf bound_ctrl:1
	s_nop 1
	v_readlane_b32 s98, v183, 0
	v_readlane_b32 s99, v183, 16
	v_readlane_b32 s100, v183, 32
	v_readlane_b32 s101, v183, 48
	s_nop 1
	v_mov_b32_e32 v183, s98
	v_add_f32_e32 v183, s99, v183
	v_add_f32_e32 v183, s100, v183
	v_add_f32_e32 v183, s101, v183
	v_fmamk_f32 v183, v183, 0x3a800000, v182
	v_cmp_gt_f32_e32 vcc, 0x800000, v183
	v_mul_f32_e32 v181, 0x4b800000, v183
	s_nop 1
	v_cndmask_b32_e32 v183, v183, v181, vcc
	v_rsq_f32_e32 v183, v183
	s_nop 0
	v_mul_f32_e32 v181, 0x45800000, v183
	v_cndmask_b32_e32 v184, v183, v181, vcc
	v_mov_b32_e32 v185, v184
	v_cvt_pk_bf16_f32 v48, v144, v145
	v_cvt_pk_bf16_f32 v49, v146, v147
	v_cvt_pk_bf16_f32 v50, v148, v149
	v_cvt_pk_bf16_f32 v51, v150, v151
	v_cvt_pk_bf16_f32 v52, v152, v153
	v_cvt_pk_bf16_f32 v53, v154, v155
	v_cvt_pk_bf16_f32 v54, v156, v157
	v_cvt_pk_bf16_f32 v55, v158, v159
	v_add_u32_e32 v181, 0x1980000, v177
	global_store_dwordx4 v181, v[48:51], s[78:79]
	global_store_dwordx4 v181, v[52:55], s[78:79] offset:1024
	v_add_u32_e32 v236, 0xc00, v237
	s_mov_b64 exec, 1
	global_store_dword v236, v184, s[78:79]
	s_mov_b64 exec, -1
	s_waitcnt vmcnt(12)
	v_lshlrev_b32_e32 v144, 16, v64
	v_and_b32_e32 v145, 0xffff0000, v64
	v_lshlrev_b32_e32 v146, 16, v65
	v_and_b32_e32 v147, 0xffff0000, v65
	v_lshlrev_b32_e32 v148, 16, v66
	v_and_b32_e32 v149, 0xffff0000, v66
	v_lshlrev_b32_e32 v150, 16, v67
	v_and_b32_e32 v151, 0xffff0000, v67
	v_lshlrev_b32_e32 v152, 16, v68
	v_and_b32_e32 v153, 0xffff0000, v68
	v_lshlrev_b32_e32 v154, 16, v69
	v_and_b32_e32 v155, 0xffff0000, v69
	v_lshlrev_b32_e32 v156, 16, v70
	v_and_b32_e32 v157, 0xffff0000, v70
	v_lshlrev_b32_e32 v158, 16, v71
	v_and_b32_e32 v159, 0xffff0000, v71
	v_lshlrev_b32_e32 v160, 16, v72
	v_and_b32_e32 v161, 0xffff0000, v72
	v_lshlrev_b32_e32 v162, 16, v73
	v_and_b32_e32 v163, 0xffff0000, v73
	v_lshlrev_b32_e32 v164, 16, v74
	v_and_b32_e32 v165, 0xffff0000, v74
	v_lshlrev_b32_e32 v166, 16, v75
	v_and_b32_e32 v167, 0xffff0000, v75
	v_lshlrev_b32_e32 v168, 16, v76
	v_and_b32_e32 v169, 0xffff0000, v76
	v_lshlrev_b32_e32 v170, 16, v77
	v_and_b32_e32 v171, 0xffff0000, v77
	v_lshlrev_b32_e32 v172, 16, v78
	v_and_b32_e32 v173, 0xffff0000, v78
	v_lshlrev_b32_e32 v174, 16, v79
	v_and_b32_e32 v175, 0xffff0000, v79
	v_pk_mul_f32 v[252:253], v[160:161], v[160:161]
	v_pk_mul_f32 v[254:255], v[162:163], v[162:163]
	v_pk_fma_f32 v[252:253], v[164:165], v[164:165], v[252:253]
	v_pk_fma_f32 v[254:255], v[166:167], v[166:167], v[254:255]
	v_pk_fma_f32 v[252:253], v[168:169], v[168:169], v[252:253]
	v_pk_fma_f32 v[254:255], v[170:171], v[170:171], v[254:255]
	v_pk_fma_f32 v[252:253], v[172:173], v[172:173], v[252:253]
	v_pk_fma_f32 v[254:255], v[174:175], v[174:175], v[254:255]
	v_pk_add_f32 v[252:253], v[252:253], v[254:255]
	s_nop 0
	v_add_f32_e32 v183, v252, v253
	s_nop 1
	v_add_f32_dpp v183, v183, v183 quad_perm:[1,0,3,2] row_mask:0xf bank_mask:0xf bound_ctrl:1
	s_nop 1
	v_add_f32_dpp v183, v183, v183 quad_perm:[2,3,0,1] row_mask:0xf bank_mask:0xf bound_ctrl:1
	s_nop 1
	v_add_f32_dpp v183, v183, v183 row_half_mirror row_mask:0xf bank_mask:0xf bound_ctrl:1
	s_nop 1
	v_add_f32_dpp v183, v183, v183 row_mirror row_mask:0xf bank_mask:0xf bound_ctrl:1
	s_nop 1
	v_readlane_b32 s98, v183, 0
	v_readlane_b32 s99, v183, 16
	v_readlane_b32 s100, v183, 32
	v_readlane_b32 s101, v183, 48
	s_nop 1
	v_mov_b32_e32 v183, s98
	v_add_f32_e32 v183, s99, v183
	v_add_f32_e32 v183, s100, v183
	v_add_f32_e32 v183, s101, v183
	v_fmamk_f32 v183, v183, 0x3a800000, v182
	v_cmp_gt_f32_e32 vcc, 0x800000, v183
	v_mul_f32_e32 v181, 0x4b800000, v183
	s_nop 1
	v_cndmask_b32_e32 v183, v183, v181, vcc
	v_rsq_f32_e32 v183, v183
	s_nop 0
	v_mul_f32_e32 v181, 0x45800000, v183
	v_cndmask_b32_e32 v184, v183, v181, vcc
	v_mov_b32_e32 v185, v184
	v_pk_mul_f32 v[160:161], v[160:161], v[184:185]
	v_pk_mul_f32 v[162:163], v[162:163], v[184:185]
	v_pk_mul_f32 v[164:165], v[164:165], v[184:185]
	v_pk_mul_f32 v[166:167], v[166:167], v[184:185]
	v_pk_mul_f32 v[168:169], v[168:169], v[184:185]
	v_pk_mul_f32 v[170:171], v[170:171], v[184:185]
	v_pk_mul_f32 v[172:173], v[172:173], v[184:185]
	v_pk_mul_f32 v[174:175], v[174:175], v[184:185]
	v_pk_fma_f32 v[144:145], v[160:161], v[128:129], v[144:145]
	v_pk_fma_f32 v[146:147], v[162:163], v[130:131], v[146:147]
	v_pk_fma_f32 v[148:149], v[164:165], v[132:133], v[148:149]
	v_pk_fma_f32 v[150:151], v[166:167], v[134:135], v[150:151]
	v_pk_fma_f32 v[152:153], v[168:169], v[136:137], v[152:153]
	v_pk_fma_f32 v[154:155], v[170:171], v[138:139], v[154:155]
	v_pk_fma_f32 v[156:157], v[172:173], v[140:141], v[156:157]
	v_pk_fma_f32 v[158:159], v[174:175], v[142:143], v[158:159]
	v_pk_mul_f32 v[252:253], v[144:145], v[144:145]
	v_pk_mul_f32 v[254:255], v[146:147], v[146:147]
	v_pk_fma_f32 v[252:253], v[148:149], v[148:149], v[252:253]
	v_pk_fma_f32 v[254:255], v[150:151], v[150:151], v[254:255]
	v_pk_fma_f32 v[252:253], v[152:153], v[152:153], v[252:253]
	v_pk_fma_f32 v[254:255], v[154:155], v[154:155], v[254:255]
	v_pk_fma_f32 v[252:253], v[156:157], v[156:157], v[252:253]
	v_pk_fma_f32 v[254:255], v[158:159], v[158:159], v[254:255]
	v_pk_add_f32 v[252:253], v[252:253], v[254:255]
	s_nop 0
	v_add_f32_e32 v183, v252, v253
	s_nop 1
	v_add_f32_dpp v183, v183, v183 quad_perm:[1,0,3,2] row_mask:0xf bank_mask:0xf bound_ctrl:1
	s_nop 1
	v_add_f32_dpp v183, v183, v183 quad_perm:[2,3,0,1] row_mask:0xf bank_mask:0xf bound_ctrl:1
	s_nop 1
	v_add_f32_dpp v183, v183, v183 row_half_mirror row_mask:0xf bank_mask:0xf bound_ctrl:1
	s_nop 1
	v_add_f32_dpp v183, v183, v183 row_mirror row_mask:0xf bank_mask:0xf bound_ctrl:1
	s_nop 1
	v_readlane_b32 s98, v183, 0
	v_readlane_b32 s99, v183, 16
	v_readlane_b32 s100, v183, 32
	v_readlane_b32 s101, v183, 48
	s_nop 1
	v_mov_b32_e32 v183, s98
	v_add_f32_e32 v183, s99, v183
	v_add_f32_e32 v183, s100, v183
	v_add_f32_e32 v183, s101, v183
	v_fmamk_f32 v183, v183, 0x3a800000, v182
	v_cmp_gt_f32_e32 vcc, 0x800000, v183
	v_mul_f32_e32 v181, 0x4b800000, v183
	s_nop 1
	v_cndmask_b32_e32 v183, v183, v181, vcc
	v_rsq_f32_e32 v183, v183
	s_nop 0
	v_mul_f32_e32 v181, 0x45800000, v183
	v_cndmask_b32_e32 v184, v183, v181, vcc
	v_mov_b32_e32 v185, v184
	v_cvt_pk_bf16_f32 v64, v144, v145
	v_cvt_pk_bf16_f32 v65, v146, v147
	v_cvt_pk_bf16_f32 v66, v148, v149
	v_cvt_pk_bf16_f32 v67, v150, v151
	v_cvt_pk_bf16_f32 v68, v152, v153
	v_cvt_pk_bf16_f32 v69, v154, v155
	v_cvt_pk_bf16_f32 v70, v156, v157
	v_cvt_pk_bf16_f32 v71, v158, v159
	v_add_u32_e32 v181, 0x1a00000, v177
	global_store_dwordx4 v181, v[64:67], s[78:79]
	global_store_dwordx4 v181, v[68:71], s[78:79] offset:1024
	v_add_u32_e32 v236, 0x1000, v237
	s_mov_b64 exec, 1
	global_store_dword v236, v184, s[78:79]
	s_mov_b64 exec, -1
	s_waitcnt vmcnt(8)
	v_lshlrev_b32_e32 v144, 16, v80
	v_and_b32_e32 v145, 0xffff0000, v80
	v_lshlrev_b32_e32 v146, 16, v81
	v_and_b32_e32 v147, 0xffff0000, v81
	v_lshlrev_b32_e32 v148, 16, v82
	v_and_b32_e32 v149, 0xffff0000, v82
	v_lshlrev_b32_e32 v150, 16, v83
	v_and_b32_e32 v151, 0xffff0000, v83
	v_lshlrev_b32_e32 v152, 16, v84
	v_and_b32_e32 v153, 0xffff0000, v84
	v_lshlrev_b32_e32 v154, 16, v85
	v_and_b32_e32 v155, 0xffff0000, v85
	v_lshlrev_b32_e32 v156, 16, v86
	v_and_b32_e32 v157, 0xffff0000, v86
	v_lshlrev_b32_e32 v158, 16, v87
	v_and_b32_e32 v159, 0xffff0000, v87
	v_lshlrev_b32_e32 v160, 16, v88
	v_and_b32_e32 v161, 0xffff0000, v88
	v_lshlrev_b32_e32 v162, 16, v89
	v_and_b32_e32 v163, 0xffff0000, v89
	v_lshlrev_b32_e32 v164, 16, v90
	v_and_b32_e32 v165, 0xffff0000, v90
	v_lshlrev_b32_e32 v166, 16, v91
	v_and_b32_e32 v167, 0xffff0000, v91
	v_lshlrev_b32_e32 v168, 16, v92
	v_and_b32_e32 v169, 0xffff0000, v92
	v_lshlrev_b32_e32 v170, 16, v93
	v_and_b32_e32 v171, 0xffff0000, v93
	v_lshlrev_b32_e32 v172, 16, v94
	v_and_b32_e32 v173, 0xffff0000, v94
	v_lshlrev_b32_e32 v174, 16, v95
	v_and_b32_e32 v175, 0xffff0000, v95
	v_pk_mul_f32 v[252:253], v[160:161], v[160:161]
	v_pk_mul_f32 v[254:255], v[162:163], v[162:163]
	v_pk_fma_f32 v[252:253], v[164:165], v[164:165], v[252:253]
	v_pk_fma_f32 v[254:255], v[166:167], v[166:167], v[254:255]
	v_pk_fma_f32 v[252:253], v[168:169], v[168:169], v[252:253]
	v_pk_fma_f32 v[254:255], v[170:171], v[170:171], v[254:255]
	v_pk_fma_f32 v[252:253], v[172:173], v[172:173], v[252:253]
	v_pk_fma_f32 v[254:255], v[174:175], v[174:175], v[254:255]
	v_pk_add_f32 v[252:253], v[252:253], v[254:255]
	s_nop 0
	v_add_f32_e32 v183, v252, v253
	s_nop 1
	v_add_f32_dpp v183, v183, v183 quad_perm:[1,0,3,2] row_mask:0xf bank_mask:0xf bound_ctrl:1
	s_nop 1
	v_add_f32_dpp v183, v183, v183 quad_perm:[2,3,0,1] row_mask:0xf bank_mask:0xf bound_ctrl:1
	s_nop 1
	v_add_f32_dpp v183, v183, v183 row_half_mirror row_mask:0xf bank_mask:0xf bound_ctrl:1
	s_nop 1
	v_add_f32_dpp v183, v183, v183 row_mirror row_mask:0xf bank_mask:0xf bound_ctrl:1
	s_nop 1
	v_readlane_b32 s98, v183, 0
	v_readlane_b32 s99, v183, 16
	v_readlane_b32 s100, v183, 32
	v_readlane_b32 s101, v183, 48
	s_nop 1
	v_mov_b32_e32 v183, s98
	v_add_f32_e32 v183, s99, v183
	v_add_f32_e32 v183, s100, v183
	v_add_f32_e32 v183, s101, v183
	v_fmamk_f32 v183, v183, 0x3a800000, v182
	v_cmp_gt_f32_e32 vcc, 0x800000, v183
	v_mul_f32_e32 v181, 0x4b800000, v183
	s_nop 1
	v_cndmask_b32_e32 v183, v183, v181, vcc
	v_rsq_f32_e32 v183, v183
	s_nop 0
	v_mul_f32_e32 v181, 0x45800000, v183
	v_cndmask_b32_e32 v184, v183, v181, vcc
	v_mov_b32_e32 v185, v184
	v_pk_mul_f32 v[160:161], v[160:161], v[184:185]
	v_pk_mul_f32 v[162:163], v[162:163], v[184:185]
	v_pk_mul_f32 v[164:165], v[164:165], v[184:185]
	v_pk_mul_f32 v[166:167], v[166:167], v[184:185]
	v_pk_mul_f32 v[168:169], v[168:169], v[184:185]
	v_pk_mul_f32 v[170:171], v[170:171], v[184:185]
	v_pk_mul_f32 v[172:173], v[172:173], v[184:185]
	v_pk_mul_f32 v[174:175], v[174:175], v[184:185]
	v_pk_fma_f32 v[144:145], v[160:161], v[128:129], v[144:145]
	v_pk_fma_f32 v[146:147], v[162:163], v[130:131], v[146:147]
	v_pk_fma_f32 v[148:149], v[164:165], v[132:133], v[148:149]
	v_pk_fma_f32 v[150:151], v[166:167], v[134:135], v[150:151]
	v_pk_fma_f32 v[152:153], v[168:169], v[136:137], v[152:153]
	v_pk_fma_f32 v[154:155], v[170:171], v[138:139], v[154:155]
	v_pk_fma_f32 v[156:157], v[172:173], v[140:141], v[156:157]
	v_pk_fma_f32 v[158:159], v[174:175], v[142:143], v[158:159]
	v_pk_mul_f32 v[252:253], v[144:145], v[144:145]
	v_pk_mul_f32 v[254:255], v[146:147], v[146:147]
	v_pk_fma_f32 v[252:253], v[148:149], v[148:149], v[252:253]
	v_pk_fma_f32 v[254:255], v[150:151], v[150:151], v[254:255]
	v_pk_fma_f32 v[252:253], v[152:153], v[152:153], v[252:253]
	v_pk_fma_f32 v[254:255], v[154:155], v[154:155], v[254:255]
	v_pk_fma_f32 v[252:253], v[156:157], v[156:157], v[252:253]
	v_pk_fma_f32 v[254:255], v[158:159], v[158:159], v[254:255]
	v_pk_add_f32 v[252:253], v[252:253], v[254:255]
	s_nop 0
	v_add_f32_e32 v183, v252, v253
	s_nop 1
	v_add_f32_dpp v183, v183, v183 quad_perm:[1,0,3,2] row_mask:0xf bank_mask:0xf bound_ctrl:1
	s_nop 1
	v_add_f32_dpp v183, v183, v183 quad_perm:[2,3,0,1] row_mask:0xf bank_mask:0xf bound_ctrl:1
	s_nop 1
	v_add_f32_dpp v183, v183, v183 row_half_mirror row_mask:0xf bank_mask:0xf bound_ctrl:1
	s_nop 1
	v_add_f32_dpp v183, v183, v183 row_mirror row_mask:0xf bank_mask:0xf bound_ctrl:1
	s_nop 1
	v_readlane_b32 s98, v183, 0
	v_readlane_b32 s99, v183, 16
	v_readlane_b32 s100, v183, 32
	v_readlane_b32 s101, v183, 48
	s_nop 1
	v_mov_b32_e32 v183, s98
	v_add_f32_e32 v183, s99, v183
	v_add_f32_e32 v183, s100, v183
	v_add_f32_e32 v183, s101, v183
	v_fmamk_f32 v183, v183, 0x3a800000, v182
	v_cmp_gt_f32_e32 vcc, 0x800000, v183
	v_mul_f32_e32 v181, 0x4b800000, v183
	s_nop 1
	v_cndmask_b32_e32 v183, v183, v181, vcc
	v_rsq_f32_e32 v183, v183
	s_nop 0
	v_mul_f32_e32 v181, 0x45800000, v183
	v_cndmask_b32_e32 v184, v183, v181, vcc
	v_mov_b32_e32 v185, v184
	v_cvt_pk_bf16_f32 v80, v144, v145
	v_cvt_pk_bf16_f32 v81, v146, v147
	v_cvt_pk_bf16_f32 v82, v148, v149
	v_cvt_pk_bf16_f32 v83, v150, v151
	v_cvt_pk_bf16_f32 v84, v152, v153
	v_cvt_pk_bf16_f32 v85, v154, v155
	v_cvt_pk_bf16_f32 v86, v156, v157
	v_cvt_pk_bf16_f32 v87, v158, v159
	v_add_u32_e32 v181, 0x1a80000, v177
	global_store_dwordx4 v181, v[80:83], s[78:79]
	global_store_dwordx4 v181, v[84:87], s[78:79] offset:1024
	v_add_u32_e32 v236, 0x1400, v237
	s_mov_b64 exec, 1
	global_store_dword v236, v184, s[78:79]
	s_mov_b64 exec, -1
	s_waitcnt vmcnt(4)
	v_lshlrev_b32_e32 v144, 16, v96
	v_and_b32_e32 v145, 0xffff0000, v96
	v_lshlrev_b32_e32 v146, 16, v97
	v_and_b32_e32 v147, 0xffff0000, v97
	v_lshlrev_b32_e32 v148, 16, v98
	v_and_b32_e32 v149, 0xffff0000, v98
	v_lshlrev_b32_e32 v150, 16, v99
	v_and_b32_e32 v151, 0xffff0000, v99
	v_lshlrev_b32_e32 v152, 16, v100
	v_and_b32_e32 v153, 0xffff0000, v100
	v_lshlrev_b32_e32 v154, 16, v101
	v_and_b32_e32 v155, 0xffff0000, v101
	v_lshlrev_b32_e32 v156, 16, v102
	v_and_b32_e32 v157, 0xffff0000, v102
	v_lshlrev_b32_e32 v158, 16, v103
	v_and_b32_e32 v159, 0xffff0000, v103
	v_lshlrev_b32_e32 v160, 16, v104
	v_and_b32_e32 v161, 0xffff0000, v104
	v_lshlrev_b32_e32 v162, 16, v105
	v_and_b32_e32 v163, 0xffff0000, v105
	v_lshlrev_b32_e32 v164, 16, v106
	v_and_b32_e32 v165, 0xffff0000, v106
	v_lshlrev_b32_e32 v166, 16, v107
	v_and_b32_e32 v167, 0xffff0000, v107
	v_lshlrev_b32_e32 v168, 16, v108
	v_and_b32_e32 v169, 0xffff0000, v108
	v_lshlrev_b32_e32 v170, 16, v109
	v_and_b32_e32 v171, 0xffff0000, v109
	v_lshlrev_b32_e32 v172, 16, v110
	v_and_b32_e32 v173, 0xffff0000, v110
	v_lshlrev_b32_e32 v174, 16, v111
	v_and_b32_e32 v175, 0xffff0000, v111
	v_pk_mul_f32 v[252:253], v[160:161], v[160:161]
	v_pk_mul_f32 v[254:255], v[162:163], v[162:163]
	v_pk_fma_f32 v[252:253], v[164:165], v[164:165], v[252:253]
	v_pk_fma_f32 v[254:255], v[166:167], v[166:167], v[254:255]
	v_pk_fma_f32 v[252:253], v[168:169], v[168:169], v[252:253]
	v_pk_fma_f32 v[254:255], v[170:171], v[170:171], v[254:255]
	v_pk_fma_f32 v[252:253], v[172:173], v[172:173], v[252:253]
	v_pk_fma_f32 v[254:255], v[174:175], v[174:175], v[254:255]
	v_pk_add_f32 v[252:253], v[252:253], v[254:255]
	s_nop 0
	v_add_f32_e32 v183, v252, v253
	s_nop 1
	v_add_f32_dpp v183, v183, v183 quad_perm:[1,0,3,2] row_mask:0xf bank_mask:0xf bound_ctrl:1
	s_nop 1
	v_add_f32_dpp v183, v183, v183 quad_perm:[2,3,0,1] row_mask:0xf bank_mask:0xf bound_ctrl:1
	s_nop 1
	v_add_f32_dpp v183, v183, v183 row_half_mirror row_mask:0xf bank_mask:0xf bound_ctrl:1
	s_nop 1
	v_add_f32_dpp v183, v183, v183 row_mirror row_mask:0xf bank_mask:0xf bound_ctrl:1
	s_nop 1
	v_readlane_b32 s98, v183, 0
	v_readlane_b32 s99, v183, 16
	v_readlane_b32 s100, v183, 32
	v_readlane_b32 s101, v183, 48
	s_nop 1
	v_mov_b32_e32 v183, s98
	v_add_f32_e32 v183, s99, v183
	v_add_f32_e32 v183, s100, v183
	v_add_f32_e32 v183, s101, v183
	v_fmamk_f32 v183, v183, 0x3a800000, v182
	v_cmp_gt_f32_e32 vcc, 0x800000, v183
	v_mul_f32_e32 v181, 0x4b800000, v183
	s_nop 1
	v_cndmask_b32_e32 v183, v183, v181, vcc
	v_rsq_f32_e32 v183, v183
	s_nop 0
	v_mul_f32_e32 v181, 0x45800000, v183
	v_cndmask_b32_e32 v184, v183, v181, vcc
	v_mov_b32_e32 v185, v184
	v_pk_mul_f32 v[160:161], v[160:161], v[184:185]
	v_pk_mul_f32 v[162:163], v[162:163], v[184:185]
	v_pk_mul_f32 v[164:165], v[164:165], v[184:185]
	v_pk_mul_f32 v[166:167], v[166:167], v[184:185]
	v_pk_mul_f32 v[168:169], v[168:169], v[184:185]
	v_pk_mul_f32 v[170:171], v[170:171], v[184:185]
	v_pk_mul_f32 v[172:173], v[172:173], v[184:185]
	v_pk_mul_f32 v[174:175], v[174:175], v[184:185]
	v_pk_fma_f32 v[144:145], v[160:161], v[128:129], v[144:145]
	v_pk_fma_f32 v[146:147], v[162:163], v[130:131], v[146:147]
	v_pk_fma_f32 v[148:149], v[164:165], v[132:133], v[148:149]
	v_pk_fma_f32 v[150:151], v[166:167], v[134:135], v[150:151]
	v_pk_fma_f32 v[152:153], v[168:169], v[136:137], v[152:153]
	v_pk_fma_f32 v[154:155], v[170:171], v[138:139], v[154:155]
	v_pk_fma_f32 v[156:157], v[172:173], v[140:141], v[156:157]
	v_pk_fma_f32 v[158:159], v[174:175], v[142:143], v[158:159]
	v_pk_mul_f32 v[252:253], v[144:145], v[144:145]
	v_pk_mul_f32 v[254:255], v[146:147], v[146:147]
	v_pk_fma_f32 v[252:253], v[148:149], v[148:149], v[252:253]
	v_pk_fma_f32 v[254:255], v[150:151], v[150:151], v[254:255]
	v_pk_fma_f32 v[252:253], v[152:153], v[152:153], v[252:253]
	v_pk_fma_f32 v[254:255], v[154:155], v[154:155], v[254:255]
	v_pk_fma_f32 v[252:253], v[156:157], v[156:157], v[252:253]
	v_pk_fma_f32 v[254:255], v[158:159], v[158:159], v[254:255]
	v_pk_add_f32 v[252:253], v[252:253], v[254:255]
	s_nop 0
	v_add_f32_e32 v183, v252, v253
	s_nop 1
	v_add_f32_dpp v183, v183, v183 quad_perm:[1,0,3,2] row_mask:0xf bank_mask:0xf bound_ctrl:1
	s_nop 1
	v_add_f32_dpp v183, v183, v183 quad_perm:[2,3,0,1] row_mask:0xf bank_mask:0xf bound_ctrl:1
	s_nop 1
	v_add_f32_dpp v183, v183, v183 row_half_mirror row_mask:0xf bank_mask:0xf bound_ctrl:1
	s_nop 1
	v_add_f32_dpp v183, v183, v183 row_mirror row_mask:0xf bank_mask:0xf bound_ctrl:1
	s_nop 1
	v_readlane_b32 s98, v183, 0
	v_readlane_b32 s99, v183, 16
	v_readlane_b32 s100, v183, 32
	v_readlane_b32 s101, v183, 48
	s_nop 1
	v_mov_b32_e32 v183, s98
	v_add_f32_e32 v183, s99, v183
	v_add_f32_e32 v183, s100, v183
	v_add_f32_e32 v183, s101, v183
	v_fmamk_f32 v183, v183, 0x3a800000, v182
	v_cmp_gt_f32_e32 vcc, 0x800000, v183
	v_mul_f32_e32 v181, 0x4b800000, v183
	s_nop 1
	v_cndmask_b32_e32 v183, v183, v181, vcc
	v_rsq_f32_e32 v183, v183
	s_nop 0
	v_mul_f32_e32 v181, 0x45800000, v183
	v_cndmask_b32_e32 v184, v183, v181, vcc
	v_mov_b32_e32 v185, v184
	v_cvt_pk_bf16_f32 v96, v144, v145
	v_cvt_pk_bf16_f32 v97, v146, v147
	v_cvt_pk_bf16_f32 v98, v148, v149
	v_cvt_pk_bf16_f32 v99, v150, v151
	v_cvt_pk_bf16_f32 v100, v152, v153
	v_cvt_pk_bf16_f32 v101, v154, v155
	v_cvt_pk_bf16_f32 v102, v156, v157
	v_cvt_pk_bf16_f32 v103, v158, v159
	v_add_u32_e32 v181, 0x1b00000, v177
	global_store_dwordx4 v181, v[96:99], s[78:79]
	global_store_dwordx4 v181, v[100:103], s[78:79] offset:1024
	v_add_u32_e32 v236, 0x1800, v237
	s_mov_b64 exec, 1
	global_store_dword v236, v184, s[78:79]
	s_mov_b64 exec, -1
	s_waitcnt vmcnt(0)
	v_lshlrev_b32_e32 v144, 16, v112
	v_and_b32_e32 v145, 0xffff0000, v112
	v_lshlrev_b32_e32 v146, 16, v113
	v_and_b32_e32 v147, 0xffff0000, v113
	v_lshlrev_b32_e32 v148, 16, v114
	v_and_b32_e32 v149, 0xffff0000, v114
	v_lshlrev_b32_e32 v150, 16, v115
	v_and_b32_e32 v151, 0xffff0000, v115
	v_lshlrev_b32_e32 v152, 16, v116
	v_and_b32_e32 v153, 0xffff0000, v116
	v_lshlrev_b32_e32 v154, 16, v117
	v_and_b32_e32 v155, 0xffff0000, v117
	v_lshlrev_b32_e32 v156, 16, v118
	v_and_b32_e32 v157, 0xffff0000, v118
	v_lshlrev_b32_e32 v158, 16, v119
	v_and_b32_e32 v159, 0xffff0000, v119
	v_lshlrev_b32_e32 v160, 16, v120
	v_and_b32_e32 v161, 0xffff0000, v120
	v_lshlrev_b32_e32 v162, 16, v121
	v_and_b32_e32 v163, 0xffff0000, v121
	v_lshlrev_b32_e32 v164, 16, v122
	v_and_b32_e32 v165, 0xffff0000, v122
	v_lshlrev_b32_e32 v166, 16, v123
	v_and_b32_e32 v167, 0xffff0000, v123
	v_lshlrev_b32_e32 v168, 16, v124
	v_and_b32_e32 v169, 0xffff0000, v124
	v_lshlrev_b32_e32 v170, 16, v125
	v_and_b32_e32 v171, 0xffff0000, v125
	v_lshlrev_b32_e32 v172, 16, v126
	v_and_b32_e32 v173, 0xffff0000, v126
	v_lshlrev_b32_e32 v174, 16, v127
	v_and_b32_e32 v175, 0xffff0000, v127
	v_pk_mul_f32 v[252:253], v[160:161], v[160:161]
	v_pk_mul_f32 v[254:255], v[162:163], v[162:163]
	v_pk_fma_f32 v[252:253], v[164:165], v[164:165], v[252:253]
	v_pk_fma_f32 v[254:255], v[166:167], v[166:167], v[254:255]
	v_pk_fma_f32 v[252:253], v[168:169], v[168:169], v[252:253]
	v_pk_fma_f32 v[254:255], v[170:171], v[170:171], v[254:255]
	v_pk_fma_f32 v[252:253], v[172:173], v[172:173], v[252:253]
	v_pk_fma_f32 v[254:255], v[174:175], v[174:175], v[254:255]
	v_pk_add_f32 v[252:253], v[252:253], v[254:255]
	s_nop 0
	v_add_f32_e32 v183, v252, v253
	s_nop 1
	v_add_f32_dpp v183, v183, v183 quad_perm:[1,0,3,2] row_mask:0xf bank_mask:0xf bound_ctrl:1
	s_nop 1
	v_add_f32_dpp v183, v183, v183 quad_perm:[2,3,0,1] row_mask:0xf bank_mask:0xf bound_ctrl:1
	s_nop 1
	v_add_f32_dpp v183, v183, v183 row_half_mirror row_mask:0xf bank_mask:0xf bound_ctrl:1
	s_nop 1
	v_add_f32_dpp v183, v183, v183 row_mirror row_mask:0xf bank_mask:0xf bound_ctrl:1
	s_nop 1
	v_readlane_b32 s98, v183, 0
	v_readlane_b32 s99, v183, 16
	v_readlane_b32 s100, v183, 32
	v_readlane_b32 s101, v183, 48
	s_nop 1
	v_mov_b32_e32 v183, s98
	v_add_f32_e32 v183, s99, v183
	v_add_f32_e32 v183, s100, v183
	v_add_f32_e32 v183, s101, v183
	v_fmamk_f32 v183, v183, 0x3a800000, v182
	v_cmp_gt_f32_e32 vcc, 0x800000, v183
	v_mul_f32_e32 v181, 0x4b800000, v183
	s_nop 1
	v_cndmask_b32_e32 v183, v183, v181, vcc
	v_rsq_f32_e32 v183, v183
	s_nop 0
	v_mul_f32_e32 v181, 0x45800000, v183
	v_cndmask_b32_e32 v184, v183, v181, vcc
	v_mov_b32_e32 v185, v184
	v_pk_mul_f32 v[160:161], v[160:161], v[184:185]
	v_pk_mul_f32 v[162:163], v[162:163], v[184:185]
	v_pk_mul_f32 v[164:165], v[164:165], v[184:185]
	v_pk_mul_f32 v[166:167], v[166:167], v[184:185]
	v_pk_mul_f32 v[168:169], v[168:169], v[184:185]
	v_pk_mul_f32 v[170:171], v[170:171], v[184:185]
	v_pk_mul_f32 v[172:173], v[172:173], v[184:185]
	v_pk_mul_f32 v[174:175], v[174:175], v[184:185]
	v_pk_fma_f32 v[144:145], v[160:161], v[128:129], v[144:145]
	v_pk_fma_f32 v[146:147], v[162:163], v[130:131], v[146:147]
	v_pk_fma_f32 v[148:149], v[164:165], v[132:133], v[148:149]
	v_pk_fma_f32 v[150:151], v[166:167], v[134:135], v[150:151]
	v_pk_fma_f32 v[152:153], v[168:169], v[136:137], v[152:153]
	v_pk_fma_f32 v[154:155], v[170:171], v[138:139], v[154:155]
	v_pk_fma_f32 v[156:157], v[172:173], v[140:141], v[156:157]
	v_pk_fma_f32 v[158:159], v[174:175], v[142:143], v[158:159]
	v_pk_mul_f32 v[252:253], v[144:145], v[144:145]
	v_pk_mul_f32 v[254:255], v[146:147], v[146:147]
	v_pk_fma_f32 v[252:253], v[148:149], v[148:149], v[252:253]
	v_pk_fma_f32 v[254:255], v[150:151], v[150:151], v[254:255]
	v_pk_fma_f32 v[252:253], v[152:153], v[152:153], v[252:253]
	v_pk_fma_f32 v[254:255], v[154:155], v[154:155], v[254:255]
	v_pk_fma_f32 v[252:253], v[156:157], v[156:157], v[252:253]
	v_pk_fma_f32 v[254:255], v[158:159], v[158:159], v[254:255]
	v_pk_add_f32 v[252:253], v[252:253], v[254:255]
	s_nop 0
	v_add_f32_e32 v183, v252, v253
	s_nop 1
	v_add_f32_dpp v183, v183, v183 quad_perm:[1,0,3,2] row_mask:0xf bank_mask:0xf bound_ctrl:1
	s_nop 1
	v_add_f32_dpp v183, v183, v183 quad_perm:[2,3,0,1] row_mask:0xf bank_mask:0xf bound_ctrl:1
	s_nop 1
	v_add_f32_dpp v183, v183, v183 row_half_mirror row_mask:0xf bank_mask:0xf bound_ctrl:1
	s_nop 1
	v_add_f32_dpp v183, v183, v183 row_mirror row_mask:0xf bank_mask:0xf bound_ctrl:1
	s_nop 1
	v_readlane_b32 s98, v183, 0
	v_readlane_b32 s99, v183, 16
	v_readlane_b32 s100, v183, 32
	v_readlane_b32 s101, v183, 48
	s_nop 1
	v_mov_b32_e32 v183, s98
	v_add_f32_e32 v183, s99, v183
	v_add_f32_e32 v183, s100, v183
	v_add_f32_e32 v183, s101, v183
	v_fmamk_f32 v183, v183, 0x3a800000, v182
	v_cmp_gt_f32_e32 vcc, 0x800000, v183
	v_mul_f32_e32 v181, 0x4b800000, v183
	s_nop 1
	v_cndmask_b32_e32 v183, v183, v181, vcc
	v_rsq_f32_e32 v183, v183
	s_nop 0
	v_mul_f32_e32 v181, 0x45800000, v183
	v_cndmask_b32_e32 v184, v183, v181, vcc
	v_mov_b32_e32 v185, v184
	v_cvt_pk_bf16_f32 v112, v144, v145
	v_cvt_pk_bf16_f32 v113, v146, v147
	v_cvt_pk_bf16_f32 v114, v148, v149
	v_cvt_pk_bf16_f32 v115, v150, v151
	v_cvt_pk_bf16_f32 v116, v152, v153
	v_cvt_pk_bf16_f32 v117, v154, v155
	v_cvt_pk_bf16_f32 v118, v156, v157
	v_cvt_pk_bf16_f32 v119, v158, v159
	v_add_u32_e32 v181, 0x1b80000, v177
	global_store_dwordx4 v181, v[112:115], s[78:79]
	global_store_dwordx4 v181, v[116:119], s[78:79] offset:1024
	v_add_u32_e32 v236, 0x1c00, v237
	s_mov_b64 exec, 1
	global_store_dword v236, v184, s[78:79]
	s_mov_b64 exec, -1
	v_readfirstlane_b32 s98, v179
	s_nop 3
	s_cmp_ge_u32 s98, 512
	s_cbranch_scc1 .Lmyxupd_done_6
	v_lshlrev_b32_e32 v177, 4, v176
	v_lshl_add_u32 v177, v179, 11, v177
	v_lshlrev_b32_e32 v237, 2, v179
	v_add_u32_e32 v237, 0x10000, v237
	v_add_u32_e32 v181, 0x3800000, v177
	global_load_dwordx4 v[0:3], v181, s[78:79]
	global_load_dwordx4 v[4:7], v181, s[78:79] offset:1024
	v_lshl_add_u32 v183, v179, 12, v180
	v_add_u32_e32 v183, 0xbf00000, v183
	v_add_u32_e32 v181, 0x0, v183
	global_load_dwordx4 v[8:11], v181, s[78:79]
	global_load_dwordx4 v[12:15], v181, s[78:79] offset:16
	global_load_dwordx4 v[16:19], v181, s[78:79] offset:2048
	global_load_dwordx4 v[20:23], v181, s[78:79] offset:2064
	v_add_u32_e32 v181, 0x200000, v183
	global_load_dwordx4 v[24:27], v181, s[78:79]
	global_load_dwordx4 v[28:31], v181, s[78:79] offset:16
	global_load_dwordx4 v[32:35], v181, s[78:79] offset:2048
	global_load_dwordx4 v[36:39], v181, s[78:79] offset:2064
	v_add_u32_e32 v181, 0x400000, v183
	global_load_dwordx4 v[40:43], v181, s[78:79]
	global_load_dwordx4 v[44:47], v181, s[78:79] offset:16
	global_load_dwordx4 v[48:51], v181, s[78:79] offset:2048
	global_load_dwordx4 v[52:55], v181, s[78:79] offset:2064
	v_add_u32_e32 v181, 0x600000, v183
	global_load_dwordx4 v[56:59], v181, s[78:79]
	global_load_dwordx4 v[60:63], v181, s[78:79] offset:16
	global_load_dwordx4 v[64:67], v181, s[78:79] offset:2048
	global_load_dwordx4 v[68:71], v181, s[78:79] offset:2064
	v_add_u32_e32 v181, 0x800000, v183
	global_load_dwordx4 v[72:75], v181, s[78:79]
	global_load_dwordx4 v[76:79], v181, s[78:79] offset:16
	global_load_dwordx4 v[80:83], v181, s[78:79] offset:2048
	global_load_dwordx4 v[84:87], v181, s[78:79] offset:2064
	v_add_u32_e32 v181, 0xa00000, v183
	global_load_dwordx4 v[88:91], v181, s[78:79]
	global_load_dwordx4 v[92:95], v181, s[78:79] offset:16
	global_load_dwordx4 v[96:99], v181, s[78:79] offset:2048
	global_load_dwordx4 v[100:103], v181, s[78:79] offset:2064
	s_waitcnt vmcnt(20)
	v_pk_add_f32 v[160:161], v[8:9], 0 op_sel_hi:[1,0]
	v_pk_add_f32 v[162:163], v[10:11], 0 op_sel_hi:[1,0]
	v_pk_add_f32 v[164:165], v[12:13], 0 op_sel_hi:[1,0]
	v_pk_add_f32 v[166:167], v[14:15], 0 op_sel_hi:[1,0]
	v_pk_add_f32 v[168:169], v[16:17], 0 op_sel_hi:[1,0]
	v_pk_add_f32 v[170:171], v[18:19], 0 op_sel_hi:[1,0]
	v_pk_add_f32 v[172:173], v[20:21], 0 op_sel_hi:[1,0]
	v_pk_add_f32 v[174:175], v[22:23], 0 op_sel_hi:[1,0]
	s_waitcnt vmcnt(16)
	v_pk_add_f32 v[160:161], v[160:161], v[24:25]
	v_pk_add_f32 v[162:163], v[162:163], v[26:27]
	v_pk_add_f32 v[164:165], v[164:165], v[28:29]
	v_pk_add_f32 v[166:167], v[166:167], v[30:31]
	v_pk_add_f32 v[168:169], v[168:169], v[32:33]
	v_pk_add_f32 v[170:171], v[170:171], v[34:35]
	v_pk_add_f32 v[172:173], v[172:173], v[36:37]
	v_pk_add_f32 v[174:175], v[174:175], v[38:39]
	s_waitcnt vmcnt(12)
	v_pk_add_f32 v[160:161], v[160:161], v[40:41]
	v_pk_add_f32 v[162:163], v[162:163], v[42:43]
	v_pk_add_f32 v[164:165], v[164:165], v[44:45]
	v_pk_add_f32 v[166:167], v[166:167], v[46:47]
	v_pk_add_f32 v[168:169], v[168:169], v[48:49]
	v_pk_add_f32 v[170:171], v[170:171], v[50:51]
	v_pk_add_f32 v[172:173], v[172:173], v[52:53]
	v_pk_add_f32 v[174:175], v[174:175], v[54:55]
	s_waitcnt vmcnt(8)
	v_pk_add_f32 v[160:161], v[160:161], v[56:57]
	v_pk_add_f32 v[162:163], v[162:163], v[58:59]
	v_pk_add_f32 v[164:165], v[164:165], v[60:61]
	v_pk_add_f32 v[166:167], v[166:167], v[62:63]
	v_pk_add_f32 v[168:169], v[168:169], v[64:65]
	v_pk_add_f32 v[170:171], v[170:171], v[66:67]
	v_pk_add_f32 v[172:173], v[172:173], v[68:69]
	v_pk_add_f32 v[174:175], v[174:175], v[70:71]
	s_waitcnt vmcnt(4)
	v_pk_add_f32 v[160:161], v[160:161], v[72:73]
	v_pk_add_f32 v[162:163], v[162:163], v[74:75]
	v_pk_add_f32 v[164:165], v[164:165], v[76:77]
	v_pk_add_f32 v[166:167], v[166:167], v[78:79]
	v_pk_add_f32 v[168:169], v[168:169], v[80:81]
	v_pk_add_f32 v[170:171], v[170:171], v[82:83]
	v_pk_add_f32 v[172:173], v[172:173], v[84:85]
	v_pk_add_f32 v[174:175], v[174:175], v[86:87]
	s_waitcnt vmcnt(0)
	v_pk_add_f32 v[160:161], v[160:161], v[88:89]
	v_pk_add_f32 v[162:163], v[162:163], v[90:91]
	v_pk_add_f32 v[164:165], v[164:165], v[92:93]
	v_pk_add_f32 v[166:167], v[166:167], v[94:95]
	v_pk_add_f32 v[168:169], v[168:169], v[96:97]
	v_pk_add_f32 v[170:171], v[170:171], v[98:99]
	v_pk_add_f32 v[172:173], v[172:173], v[100:101]
	v_pk_add_f32 v[174:175], v[174:175], v[102:103]
	v_lshlrev_b32_e32 v144, 16, v0
	v_and_b32_e32 v145, 0xffff0000, v0
	v_lshlrev_b32_e32 v146, 16, v1
	v_and_b32_e32 v147, 0xffff0000, v1
	v_lshlrev_b32_e32 v148, 16, v2
	v_and_b32_e32 v149, 0xffff0000, v2
	v_lshlrev_b32_e32 v150, 16, v3
	v_and_b32_e32 v151, 0xffff0000, v3
	v_lshlrev_b32_e32 v152, 16, v4
	v_and_b32_e32 v153, 0xffff0000, v4
	v_lshlrev_b32_e32 v154, 16, v5
	v_and_b32_e32 v155, 0xffff0000, v5
	v_lshlrev_b32_e32 v156, 16, v6
	v_and_b32_e32 v157, 0xffff0000, v6
	v_lshlrev_b32_e32 v158, 16, v7
	v_and_b32_e32 v159, 0xffff0000, v7
	v_add_u32_e32 v181, 0xc00000, v183
	global_load_dwordx4 v[8:11], v181, s[78:79]
	global_load_dwordx4 v[12:15], v181, s[78:79] offset:16
	global_load_dwordx4 v[16:19], v181, s[78:79] offset:2048
	global_load_dwordx4 v[20:23], v181, s[78:79] offset:2064
	v_add_u32_e32 v181, 0xe00000, v183
	global_load_dwordx4 v[24:27], v181, s[78:79]
	global_load_dwordx4 v[28:31], v181, s[78:79] offset:16
	global_load_dwordx4 v[32:35], v181, s[78:79] offset:2048
	global_load_dwordx4 v[36:39], v181, s[78:79] offset:2064
	s_waitcnt vmcnt(4)
	v_pk_add_f32 v[160:161], v[160:161], v[8:9]
	v_pk_add_f32 v[162:163], v[162:163], v[10:11]
	v_pk_add_f32 v[164:165], v[164:165], v[12:13]
	v_pk_add_f32 v[166:167], v[166:167], v[14:15]
	v_pk_add_f32 v[168:169], v[168:169], v[16:17]
	v_pk_add_f32 v[170:171], v[170:171], v[18:19]
	v_pk_add_f32 v[172:173], v[172:173], v[20:21]
	v_pk_add_f32 v[174:175], v[174:175], v[22:23]
	s_waitcnt vmcnt(0)
	v_pk_add_f32 v[160:161], v[160:161], v[24:25]
	v_pk_add_f32 v[162:163], v[162:163], v[26:27]
	v_pk_add_f32 v[164:165], v[164:165], v[28:29]
	v_pk_add_f32 v[166:167], v[166:167], v[30:31]
	v_pk_add_f32 v[168:169], v[168:169], v[32:33]
	v_pk_add_f32 v[170:171], v[170:171], v[34:35]
	v_pk_add_f32 v[172:173], v[172:173], v[36:37]
	v_pk_add_f32 v[174:175], v[174:175], v[38:39]
	v_pk_mul_f32 v[252:253], v[160:161], v[160:161]
	v_pk_mul_f32 v[254:255], v[162:163], v[162:163]
	v_pk_fma_f32 v[252:253], v[164:165], v[164:165], v[252:253]
	v_pk_fma_f32 v[254:255], v[166:167], v[166:167], v[254:255]
	v_pk_fma_f32 v[252:253], v[168:169], v[168:169], v[252:253]
	v_pk_fma_f32 v[254:255], v[170:171], v[170:171], v[254:255]
	v_pk_fma_f32 v[252:253], v[172:173], v[172:173], v[252:253]
	v_pk_fma_f32 v[254:255], v[174:175], v[174:175], v[254:255]
	v_pk_add_f32 v[252:253], v[252:253], v[254:255]
	s_nop 0
	v_add_f32_e32 v183, v252, v253
	s_nop 1
	v_add_f32_dpp v183, v183, v183 quad_perm:[1,0,3,2] row_mask:0xf bank_mask:0xf bound_ctrl:1
	s_nop 1
	v_add_f32_dpp v183, v183, v183 quad_perm:[2,3,0,1] row_mask:0xf bank_mask:0xf bound_ctrl:1
	s_nop 1
	v_add_f32_dpp v183, v183, v183 row_half_mirror row_mask:0xf bank_mask:0xf bound_ctrl:1
	s_nop 1
	v_add_f32_dpp v183, v183, v183 row_mirror row_mask:0xf bank_mask:0xf bound_ctrl:1
	s_nop 1
	v_readlane_b32 s98, v183, 0
	v_readlane_b32 s99, v183, 16
	v_readlane_b32 s100, v183, 32
	v_readlane_b32 s101, v183, 48
	s_nop 1
	v_mov_b32_e32 v183, s98
	v_add_f32_e32 v183, s99, v183
	v_add_f32_e32 v183, s100, v183
	v_add_f32_e32 v183, s101, v183
	v_fmamk_f32 v183, v183, 0x3a800000, v182
	v_cmp_gt_f32_e32 vcc, 0x800000, v183
	v_mul_f32_e32 v181, 0x4b800000, v183
	s_nop 1
	v_cndmask_b32_e32 v183, v183, v181, vcc
	v_rsq_f32_e32 v183, v183
	s_nop 0
	v_mul_f32_e32 v181, 0x45800000, v183
	v_cndmask_b32_e32 v184, v183, v181, vcc
	v_mov_b32_e32 v185, v184
	v_pk_mul_f32 v[160:161], v[160:161], v[184:185]
	v_pk_mul_f32 v[162:163], v[162:163], v[184:185]
	v_pk_mul_f32 v[164:165], v[164:165], v[184:185]
	v_pk_mul_f32 v[166:167], v[166:167], v[184:185]
	v_pk_mul_f32 v[168:169], v[168:169], v[184:185]
	v_pk_mul_f32 v[170:171], v[170:171], v[184:185]
	v_pk_mul_f32 v[172:173], v[172:173], v[184:185]
	v_pk_mul_f32 v[174:175], v[174:175], v[184:185]
	v_pk_fma_f32 v[144:145], v[160:161], v[128:129], v[144:145]
	v_pk_fma_f32 v[146:147], v[162:163], v[130:131], v[146:147]
	v_pk_fma_f32 v[148:149], v[164:165], v[132:133], v[148:149]
	v_pk_fma_f32 v[150:151], v[166:167], v[134:135], v[150:151]
	v_pk_fma_f32 v[152:153], v[168:169], v[136:137], v[152:153]
	v_pk_fma_f32 v[154:155], v[170:171], v[138:139], v[154:155]
	v_pk_fma_f32 v[156:157], v[172:173], v[140:141], v[156:157]
	v_pk_fma_f32 v[158:159], v[174:175], v[142:143], v[158:159]
	v_pk_mul_f32 v[252:253], v[144:145], v[144:145]
	v_pk_mul_f32 v[254:255], v[146:147], v[146:147]
	v_pk_fma_f32 v[252:253], v[148:149], v[148:149], v[252:253]
	v_pk_fma_f32 v[254:255], v[150:151], v[150:151], v[254:255]
	v_pk_fma_f32 v[252:253], v[152:153], v[152:153], v[252:253]
	v_pk_fma_f32 v[254:255], v[154:155], v[154:155], v[254:255]
	v_pk_fma_f32 v[252:253], v[156:157], v[156:157], v[252:253]
	v_pk_fma_f32 v[254:255], v[158:159], v[158:159], v[254:255]
	v_pk_add_f32 v[252:253], v[252:253], v[254:255]
	s_nop 0
	v_add_f32_e32 v183, v252, v253
	s_nop 1
	v_add_f32_dpp v183, v183, v183 quad_perm:[1,0,3,2] row_mask:0xf bank_mask:0xf bound_ctrl:1
	s_nop 1
	v_add_f32_dpp v183, v183, v183 quad_perm:[2,3,0,1] row_mask:0xf bank_mask:0xf bound_ctrl:1
	s_nop 1
	v_add_f32_dpp v183, v183, v183 row_half_mirror row_mask:0xf bank_mask:0xf bound_ctrl:1
	s_nop 1
	v_add_f32_dpp v183, v183, v183 row_mirror row_mask:0xf bank_mask:0xf bound_ctrl:1
	s_nop 1
	v_readlane_b32 s98, v183, 0
	v_readlane_b32 s99, v183, 16
	v_readlane_b32 s100, v183, 32
	v_readlane_b32 s101, v183, 48
	s_nop 1
	v_mov_b32_e32 v183, s98
	v_add_f32_e32 v183, s99, v183
	v_add_f32_e32 v183, s100, v183
	v_add_f32_e32 v183, s101, v183
	v_fmamk_f32 v183, v183, 0x3a800000, v182
	v_cmp_gt_f32_e32 vcc, 0x800000, v183
	v_mul_f32_e32 v181, 0x4b800000, v183
	s_nop 1
	v_cndmask_b32_e32 v183, v183, v181, vcc
	v_rsq_f32_e32 v183, v183
	s_nop 0
	v_mul_f32_e32 v181, 0x45800000, v183
	v_cndmask_b32_e32 v184, v183, v181, vcc
	v_mov_b32_e32 v185, v184
	v_cvt_pk_bf16_f32 v0, v144, v145
	v_cvt_pk_bf16_f32 v1, v146, v147
	v_cvt_pk_bf16_f32 v2, v148, v149
	v_cvt_pk_bf16_f32 v3, v150, v151
	v_cvt_pk_bf16_f32 v4, v152, v153
	v_cvt_pk_bf16_f32 v5, v154, v155
	v_cvt_pk_bf16_f32 v6, v156, v157
	v_cvt_pk_bf16_f32 v7, v158, v159
	v_add_u32_e32 v181, 0x3800000, v177
	global_store_dwordx4 v181, v[0:3], s[78:79]
	global_store_dwordx4 v181, v[4:7], s[78:79] offset:1024
	v_add_u32_e32 v236, 0x10000, v237
	s_mov_b64 exec, 1
	global_store_dword v236, v184, s[78:79]
	s_mov_b64 exec, -1

.LBB0_2849:
	v_readlane_b32 s0, v235, 52
	v_readlane_b32 s1, v235, 53
	s_and_b64 vcc, exec, s[0:1]
	s_waitcnt lgkmcnt(0)
	s_barrier
	v_mbcnt_lo_u32_b32 v0, -1, 0
	v_mbcnt_hi_u32_b32 v0, -1, v0
	s_cbranch_vccnz .LBB0_2864
	v_lshlrev_b32_e32 v0, 3, v0
	v_ashrrev_i32_e32 v1, 31, v0
	v_readlane_b32 s0, v235, 4
	v_lshlrev_b64 v[2:3], 1, v[0:1]
	v_lshlrev_b64 v[0:1], 2, v[0:1]
	v_readlane_b32 s1, v235, 5
	v_readlane_b32 s14, v235, 18
	v_readlane_b32 s15, v235, 19
	s_mov_b64 s[0:1], 0x3000
	v_readlane_b32 s2, v235, 6
	v_lshl_add_u64 v[4:5], s[14:15], 0, v[0:1]
	v_readlane_b32 s4, v235, 8
	v_readlane_b32 s5, v235, 9
	v_lshl_add_u64 v[50:51], v[4:5], 0, s[0:1]
	v_readlane_b32 s0, v235, 0
	s_ashr_i32 s25, s24, 31
	s_lshl_b32 s0, s0, 4
	s_add_i32 s2, s24, 0xffffc000
	s_lshl_b64 s[4:5], s[24:25], 11
	s_add_u32 s4, s78, s4
	v_readlane_b32 s1, v235, 1
	s_addc_u32 s5, s79, s5
	v_lshl_add_u64 v[44:45], s[86:87], 0, v[2:3]
	v_lshl_add_u64 v[48:49], s[54:55], 0, v[2:3]
	v_readlane_b32 s6, v235, 10
	v_readlane_b32 s7, v235, 11
	v_lshl_add_u64 v[2:3], s[4:5], 0, v[2:3]
	s_mov_b64 s[4:5], 0x9e00000
	s_ashr_i32 s1, s0, 31
	v_lshl_add_u64 v[56:57], v[2:3], 0, s[4:5]
	s_lshl_b64 s[4:5], s[0:1], 11
	s_lshl_b64 s[6:7], s[24:25], 12
	s_add_u32 s6, s76, s6
	s_addc_u32 s7, s77, s7
	v_lshl_add_u64 v[46:47], s[90:91], 0, v[0:1]
	v_readlane_b32 s3, v235, 7
	v_readlane_b32 s8, v235, 12
	v_readlane_b32 s9, v235, 13
	v_readlane_b32 s10, v235, 14
	v_readlane_b32 s11, v235, 15
	v_readlane_b32 s12, v235, 16
	v_readlane_b32 s13, v235, 17
	v_lshl_add_u64 v[52:53], s[74:75], 0, v[0:1]
	v_lshl_add_u64 v[54:55], s[76:77], 0, v[0:1]
	v_lshl_add_u64 v[0:1], s[6:7], 0, v[0:1]
	s_mov_b64 s[6:7], 0x810
	v_lshl_add_u64 v[58:59], v[0:1], 0, s[6:7]
	s_lshl_b64 s[6:7], s[0:1], 12
	s_mov_b32 s3, 0
	s_mov_b64 s[8:9], 0x200000
	s_mov_b64 s[10:11], 0x200800
	s_mov_b64 s[12:13], 0x400000
	s_mov_b64 s[14:15], 0x400800
	s_mov_b64 s[16:17], 0x600000
	s_mov_b64 s[18:19], 0x600800
	s_mov_b64 s[20:21], 0x800000
	s_mov_b32 s1, 0x800000
	s_mov_b64 s[22:23], 0x800800
	s_mov_b64 s[24:25], 0xa00000
	s_mov_b64 s[26:27], 0xa00800
	s_mov_b64 s[28:29], 0xc00000
	s_mov_b64 s[30:31], 0xc00800
	s_mov_b64 s[34:35], 0xe00000
	s_mov_b64 s[36:37], 0xe00800
	s_mov_b64 s[38:39], 0x1000000
	s_mov_b32 s60, 0x1000000
	s_mov_b64 s[40:41], 0x1000800
	s_mov_b64 s[42:43], 0x1200000
	s_mov_b32 s61, 0x1200000
	s_mov_b64 s[44:45], 0x1200800
	s_mov_b64 s[46:47], 0x1400000
	s_mov_b32 s62, 0x1400000
	s_mov_b64 s[48:49], 0x1400800
	v_mov_b32_e32 v100, 0x358637bd
	v_mbcnt_lo_u32_b32 v176, -1, 0
	v_mbcnt_hi_u32_b32 v176, -1, v176
	v_readlane_b32 s98, v235, 49
	v_readlane_b32 s99, v235, 20
	v_readlane_b32 s100, v235, 18
	v_readlane_b32 s101, v235, 19
	s_nop 3
	s_lshr_b32 vcc_lo, s98, 3
	s_and_b32 vcc_hi, vcc_lo, 7
	s_lshr_b32 vcc_lo, vcc_lo, 3
	s_lshl_b32 vcc_lo, vcc_lo, 3
	s_add_i32 vcc_lo, vcc_lo, s99
	s_lshl_b32 s98, vcc_hi, 8
	s_add_i32 s98, s98, vcc_lo
	s_lshl_b32 s99, vcc_hi, 11
	s_add_i32 s99, s99, vcc_lo
	v_mov_b32_e32 v183, s99
	v_lshlrev_b32_e32 v177, 4, v176
	s_lshl_b32 s99, s99, 11
	v_add_u32_e32 v177, s99, v177
	v_add_u32_e32 v178, 0x1800000, v177
	v_add_u32_e32 v179, 0x9e00000, v177
	v_lshlrev_b32_e32 v180, 5, v176
	v_add_u32_e32 v181, 0x3000, v180
	global_load_dwordx4 v[128:131], v181, s[100:101]
	global_load_dwordx4 v[132:135], v181, s[100:101] offset:16
	global_load_dwordx4 v[136:139], v181, s[100:101] offset:2048
	global_load_dwordx4 v[140:143], v181, s[100:101] offset:2064
	global_load_dwordx4 v[236:239], v180, s[74:75]
	global_load_dwordx4 v[240:243], v180, s[74:75] offset:16
	global_load_dwordx4 v[244:247], v180, s[74:75] offset:2048
	global_load_dwordx4 v[248:251], v180, s[74:75] offset:2064
	v_mov_b32_e32 v182, 0x358637bd
	global_load_dwordx4 v[0:3], v178, s[78:79]
	global_load_dwordx4 v[4:7], v178, s[78:79] offset:1024
	global_load_dwordx4 v[8:11], v179, s[78:79]
	global_load_dwordx4 v[12:15], v179, s[78:79] offset:1024
	v_add_u32_e32 v178, 0x80000, v178
	v_add_u32_e32 v179, 0x80000, v179
	global_load_dwordx4 v[16:19], v178, s[78:79]
	global_load_dwordx4 v[20:23], v178, s[78:79] offset:1024
	global_load_dwordx4 v[24:27], v179, s[78:79]
	global_load_dwordx4 v[28:31], v179, s[78:79] offset:1024
	v_add_u32_e32 v178, 0x80000, v178
	v_add_u32_e32 v179, 0x80000, v179
	global_load_dwordx4 v[32:35], v178, s[78:79]
	global_load_dwordx4 v[36:39], v178, s[78:79] offset:1024
	global_load_dwordx4 v[40:43], v179, s[78:79]
	global_load_dwordx4 v[44:47], v179, s[78:79] offset:1024
	v_add_u32_e32 v178, 0x80000, v178
	v_add_u32_e32 v179, 0x80000, v179
	global_load_dwordx4 v[48:51], v178, s[78:79]
	global_load_dwordx4 v[52:55], v178, s[78:79] offset:1024
	global_load_dwordx4 v[56:59], v179, s[78:79]
	global_load_dwordx4 v[60:63], v179, s[78:79] offset:1024
	v_add_u32_e32 v178, 0x80000, v178
	v_add_u32_e32 v179, 0x80000, v179
	global_load_dwordx4 v[64:67], v178, s[78:79]
	global_load_dwordx4 v[68:71], v178, s[78:79] offset:1024
	global_load_dwordx4 v[72:75], v179, s[78:79]
	global_load_dwordx4 v[76:79], v179, s[78:79] offset:1024
	v_add_u32_e32 v178, 0x80000, v178
	v_add_u32_e32 v179, 0x80000, v179
	global_load_dwordx4 v[80:83], v178, s[78:79]
	global_load_dwordx4 v[84:87], v178, s[78:79] offset:1024
	global_load_dwordx4 v[88:91], v179, s[78:79]
	global_load_dwordx4 v[92:95], v179, s[78:79] offset:1024
	v_add_u32_e32 v178, 0x80000, v178
	v_add_u32_e32 v179, 0x80000, v179
	global_load_dwordx4 v[96:99], v178, s[78:79]
	global_load_dwordx4 v[100:103], v178, s[78:79] offset:1024
	global_load_dwordx4 v[104:107], v179, s[78:79]
	global_load_dwordx4 v[108:111], v179, s[78:79] offset:1024
	v_add_u32_e32 v178, 0x80000, v178
	v_add_u32_e32 v179, 0x80000, v179
	global_load_dwordx4 v[112:115], v178, s[78:79]
	global_load_dwordx4 v[116:119], v178, s[78:79] offset:1024
	global_load_dwordx4 v[120:123], v179, s[78:79]
	global_load_dwordx4 v[124:127], v179, s[78:79] offset:1024
	v_lshl_add_u32 v178, v183, 12, v180
	v_mov_b32_e32 v179, s98
	s_waitcnt vmcnt(28)
	v_lshlrev_b32_e32 v144, 16, v0
	v_and_b32_e32 v145, 0xffff0000, v0
	v_lshlrev_b32_e32 v146, 16, v1
	v_and_b32_e32 v147, 0xffff0000, v1
	v_lshlrev_b32_e32 v148, 16, v2
	v_and_b32_e32 v149, 0xffff0000, v2
	v_lshlrev_b32_e32 v150, 16, v3
	v_and_b32_e32 v151, 0xffff0000, v3
	v_lshlrev_b32_e32 v152, 16, v4
	v_and_b32_e32 v153, 0xffff0000, v4
	v_lshlrev_b32_e32 v154, 16, v5
	v_and_b32_e32 v155, 0xffff0000, v5
	v_lshlrev_b32_e32 v156, 16, v6
	v_and_b32_e32 v157, 0xffff0000, v6
	v_lshlrev_b32_e32 v158, 16, v7
	v_and_b32_e32 v159, 0xffff0000, v7
	v_lshlrev_b32_e32 v160, 16, v8
	v_and_b32_e32 v161, 0xffff0000, v8
	v_lshlrev_b32_e32 v162, 16, v9
	v_and_b32_e32 v163, 0xffff0000, v9
	v_lshlrev_b32_e32 v164, 16, v10
	v_and_b32_e32 v165, 0xffff0000, v10
	v_lshlrev_b32_e32 v166, 16, v11
	v_and_b32_e32 v167, 0xffff0000, v11
	v_lshlrev_b32_e32 v168, 16, v12
	v_and_b32_e32 v169, 0xffff0000, v12
	v_lshlrev_b32_e32 v170, 16, v13
	v_and_b32_e32 v171, 0xffff0000, v13
	v_lshlrev_b32_e32 v172, 16, v14
	v_and_b32_e32 v173, 0xffff0000, v14
	v_lshlrev_b32_e32 v174, 16, v15
	v_and_b32_e32 v175, 0xffff0000, v15
	v_pk_mul_f32 v[252:253], v[160:161], v[160:161]
	v_pk_mul_f32 v[254:255], v[162:163], v[162:163]
	v_pk_fma_f32 v[252:253], v[164:165], v[164:165], v[252:253]
	v_pk_fma_f32 v[254:255], v[166:167], v[166:167], v[254:255]
	v_pk_fma_f32 v[252:253], v[168:169], v[168:169], v[252:253]
	v_pk_fma_f32 v[254:255], v[170:171], v[170:171], v[254:255]
	v_pk_fma_f32 v[252:253], v[172:173], v[172:173], v[252:253]
	v_pk_fma_f32 v[254:255], v[174:175], v[174:175], v[254:255]
	v_pk_add_f32 v[252:253], v[252:253], v[254:255]
	s_nop 0
	v_add_f32_e32 v183, v252, v253
	s_nop 1
	v_add_f32_dpp v183, v183, v183 quad_perm:[1,0,3,2] row_mask:0xf bank_mask:0xf bound_ctrl:1
	s_nop 1
	v_add_f32_dpp v183, v183, v183 quad_perm:[2,3,0,1] row_mask:0xf bank_mask:0xf bound_ctrl:1
	s_nop 1
	v_add_f32_dpp v183, v183, v183 row_half_mirror row_mask:0xf bank_mask:0xf bound_ctrl:1
	s_nop 1
	v_add_f32_dpp v183, v183, v183 row_mirror row_mask:0xf bank_mask:0xf bound_ctrl:1
	s_nop 1
	v_readlane_b32 s98, v183, 0
	v_readlane_b32 s99, v183, 16
	v_readlane_b32 s100, v183, 32
	v_readlane_b32 s101, v183, 48
	s_nop 1
	v_mov_b32_e32 v183, s98
	v_add_f32_e32 v183, s99, v183
	v_add_f32_e32 v183, s100, v183
	v_add_f32_e32 v183, s101, v183
	v_fmamk_f32 v183, v183, 0x3a800000, v182
	v_cmp_gt_f32_e32 vcc, 0x800000, v183
	v_mul_f32_e32 v181, 0x4b800000, v183
	s_nop 1
	v_cndmask_b32_e32 v183, v183, v181, vcc
	v_rsq_f32_e32 v183, v183
	s_nop 0
	v_mul_f32_e32 v181, 0x45800000, v183
	v_cndmask_b32_e32 v184, v183, v181, vcc
	v_mov_b32_e32 v185, v184
	v_pk_mul_f32 v[160:161], v[160:161], v[184:185]
	v_pk_mul_f32 v[162:163], v[162:163], v[184:185]
	v_pk_mul_f32 v[164:165], v[164:165], v[184:185]
	v_pk_mul_f32 v[166:167], v[166:167], v[184:185]
	v_pk_mul_f32 v[168:169], v[168:169], v[184:185]
	v_pk_mul_f32 v[170:171], v[170:171], v[184:185]
	v_pk_mul_f32 v[172:173], v[172:173], v[184:185]
	v_pk_mul_f32 v[174:175], v[174:175], v[184:185]
	v_pk_fma_f32 v[144:145], v[160:161], v[128:129], v[144:145]
	v_pk_fma_f32 v[146:147], v[162:163], v[130:131], v[146:147]
	v_pk_fma_f32 v[148:149], v[164:165], v[132:133], v[148:149]
	v_pk_fma_f32 v[150:151], v[166:167], v[134:135], v[150:151]
	v_pk_fma_f32 v[152:153], v[168:169], v[136:137], v[152:153]
	v_pk_fma_f32 v[154:155], v[170:171], v[138:139], v[154:155]
	v_pk_fma_f32 v[156:157], v[172:173], v[140:141], v[156:157]
	v_pk_fma_f32 v[158:159], v[174:175], v[142:143], v[158:159]
	v_pk_mul_f32 v[252:253], v[144:145], v[144:145]
	v_pk_mul_f32 v[254:255], v[146:147], v[146:147]
	v_pk_fma_f32 v[252:253], v[148:149], v[148:149], v[252:253]
	v_pk_fma_f32 v[254:255], v[150:151], v[150:151], v[254:255]
	v_pk_fma_f32 v[252:253], v[152:153], v[152:153], v[252:253]
	v_pk_fma_f32 v[254:255], v[154:155], v[154:155], v[254:255]
	v_pk_fma_f32 v[252:253], v[156:157], v[156:157], v[252:253]
	v_pk_fma_f32 v[254:255], v[158:159], v[158:159], v[254:255]
	v_pk_add_f32 v[252:253], v[252:253], v[254:255]
	s_nop 0
	v_add_f32_e32 v183, v252, v253
	s_nop 1
	v_add_f32_dpp v183, v183, v183 quad_perm:[1,0,3,2] row_mask:0xf bank_mask:0xf bound_ctrl:1
	s_nop 1
	v_add_f32_dpp v183, v183, v183 quad_perm:[2,3,0,1] row_mask:0xf bank_mask:0xf bound_ctrl:1
	s_nop 1
	v_add_f32_dpp v183, v183, v183 row_half_mirror row_mask:0xf bank_mask:0xf bound_ctrl:1
	s_nop 1
	v_add_f32_dpp v183, v183, v183 row_mirror row_mask:0xf bank_mask:0xf bound_ctrl:1
	s_nop 1
	v_readlane_b32 s98, v183, 0
	v_readlane_b32 s99, v183, 16
	v_readlane_b32 s100, v183, 32
	v_readlane_b32 s101, v183, 48
	s_nop 1
	v_mov_b32_e32 v183, s98
	v_add_f32_e32 v183, s99, v183
	v_add_f32_e32 v183, s100, v183
	v_add_f32_e32 v183, s101, v183
	v_fmamk_f32 v183, v183, 0x3a800000, v182
	v_cmp_gt_f32_e32 vcc, 0x800000, v183
	v_mul_f32_e32 v181, 0x4b800000, v183
	s_nop 1
	v_cndmask_b32_e32 v183, v183, v181, vcc
	v_rsq_f32_e32 v183, v183
	s_nop 0
	v_mul_f32_e32 v181, 0x45800000, v183
	v_cndmask_b32_e32 v184, v183, v181, vcc
	v_mov_b32_e32 v185, v184
	v_pk_mul_f32 v[144:145], v[144:145], v[184:185]
	v_pk_mul_f32 v[146:147], v[146:147], v[184:185]
	v_pk_mul_f32 v[148:149], v[148:149], v[184:185]
	v_pk_mul_f32 v[150:151], v[150:151], v[184:185]
	v_pk_mul_f32 v[152:153], v[152:153], v[184:185]
	v_pk_mul_f32 v[154:155], v[154:155], v[184:185]
	v_pk_mul_f32 v[156:157], v[156:157], v[184:185]
	v_pk_mul_f32 v[158:159], v[158:159], v[184:185]
	v_pk_mul_f32 v[144:145], v[144:145], v[236:237]
	v_pk_mul_f32 v[146:147], v[146:147], v[238:239]
	v_pk_mul_f32 v[148:149], v[148:149], v[240:241]
	v_pk_mul_f32 v[150:151], v[150:151], v[242:243]
	v_pk_mul_f32 v[152:153], v[152:153], v[244:245]
	v_pk_mul_f32 v[154:155], v[154:155], v[246:247]
	v_pk_mul_f32 v[156:157], v[156:157], v[248:249]
	v_pk_mul_f32 v[158:159], v[158:159], v[250:251]
	v_add_u32_e32 v181, 0x0, v178
	global_store_dwordx4 v181, v[144:147], s[76:77]
	global_store_dwordx4 v181, v[148:151], s[76:77] offset:16
	global_store_dwordx4 v181, v[152:155], s[76:77] offset:2048
	global_store_dwordx4 v181, v[156:159], s[76:77] offset:2064
	s_nop 1
	s_waitcnt vmcnt(24)
	v_lshlrev_b32_e32 v144, 16, v16
	v_and_b32_e32 v145, 0xffff0000, v16
	v_lshlrev_b32_e32 v146, 16, v17
	v_and_b32_e32 v147, 0xffff0000, v17
	v_lshlrev_b32_e32 v148, 16, v18
	v_and_b32_e32 v149, 0xffff0000, v18
	v_lshlrev_b32_e32 v150, 16, v19
	v_and_b32_e32 v151, 0xffff0000, v19
	v_lshlrev_b32_e32 v152, 16, v20
	v_and_b32_e32 v153, 0xffff0000, v20
	v_lshlrev_b32_e32 v154, 16, v21
	v_and_b32_e32 v155, 0xffff0000, v21
	v_lshlrev_b32_e32 v156, 16, v22
	v_and_b32_e32 v157, 0xffff0000, v22
	v_lshlrev_b32_e32 v158, 16, v23
	v_and_b32_e32 v159, 0xffff0000, v23
	v_lshlrev_b32_e32 v160, 16, v24
	v_and_b32_e32 v161, 0xffff0000, v24
	v_lshlrev_b32_e32 v162, 16, v25
	v_and_b32_e32 v163, 0xffff0000, v25
	v_lshlrev_b32_e32 v164, 16, v26
	v_and_b32_e32 v165, 0xffff0000, v26
	v_lshlrev_b32_e32 v166, 16, v27
	v_and_b32_e32 v167, 0xffff0000, v27
	v_lshlrev_b32_e32 v168, 16, v28
	v_and_b32_e32 v169, 0xffff0000, v28
	v_lshlrev_b32_e32 v170, 16, v29
	v_and_b32_e32 v171, 0xffff0000, v29
	v_lshlrev_b32_e32 v172, 16, v30
	v_and_b32_e32 v173, 0xffff0000, v30
	v_lshlrev_b32_e32 v174, 16, v31
	v_and_b32_e32 v175, 0xffff0000, v31
	v_pk_mul_f32 v[252:253], v[160:161], v[160:161]
	v_pk_mul_f32 v[254:255], v[162:163], v[162:163]
	v_pk_fma_f32 v[252:253], v[164:165], v[164:165], v[252:253]
	v_pk_fma_f32 v[254:255], v[166:167], v[166:167], v[254:255]
	v_pk_fma_f32 v[252:253], v[168:169], v[168:169], v[252:253]
	v_pk_fma_f32 v[254:255], v[170:171], v[170:171], v[254:255]
	v_pk_fma_f32 v[252:253], v[172:173], v[172:173], v[252:253]
	v_pk_fma_f32 v[254:255], v[174:175], v[174:175], v[254:255]
	v_pk_add_f32 v[252:253], v[252:253], v[254:255]
	s_nop 0
	v_add_f32_e32 v183, v252, v253
	s_nop 1
	v_add_f32_dpp v183, v183, v183 quad_perm:[1,0,3,2] row_mask:0xf bank_mask:0xf bound_ctrl:1
	s_nop 1
	v_add_f32_dpp v183, v183, v183 quad_perm:[2,3,0,1] row_mask:0xf bank_mask:0xf bound_ctrl:1
	s_nop 1
	v_add_f32_dpp v183, v183, v183 row_half_mirror row_mask:0xf bank_mask:0xf bound_ctrl:1
	s_nop 1
	v_add_f32_dpp v183, v183, v183 row_mirror row_mask:0xf bank_mask:0xf bound_ctrl:1
	s_nop 1
	v_readlane_b32 s98, v183, 0
	v_readlane_b32 s99, v183, 16
	v_readlane_b32 s100, v183, 32
	v_readlane_b32 s101, v183, 48
	s_nop 1
	v_mov_b32_e32 v183, s98
	v_add_f32_e32 v183, s99, v183
	v_add_f32_e32 v183, s100, v183
	v_add_f32_e32 v183, s101, v183
	v_fmamk_f32 v183, v183, 0x3a800000, v182
	v_cmp_gt_f32_e32 vcc, 0x800000, v183
	v_mul_f32_e32 v181, 0x4b800000, v183
	s_nop 1
	v_cndmask_b32_e32 v183, v183, v181, vcc
	v_rsq_f32_e32 v183, v183
	s_nop 0
	v_mul_f32_e32 v181, 0x45800000, v183
	v_cndmask_b32_e32 v184, v183, v181, vcc
	v_mov_b32_e32 v185, v184
	v_pk_mul_f32 v[160:161], v[160:161], v[184:185]
	v_pk_mul_f32 v[162:163], v[162:163], v[184:185]
	v_pk_mul_f32 v[164:165], v[164:165], v[184:185]
	v_pk_mul_f32 v[166:167], v[166:167], v[184:185]
	v_pk_mul_f32 v[168:169], v[168:169], v[184:185]
	v_pk_mul_f32 v[170:171], v[170:171], v[184:185]
	v_pk_mul_f32 v[172:173], v[172:173], v[184:185]
	v_pk_mul_f32 v[174:175], v[174:175], v[184:185]
	v_pk_fma_f32 v[144:145], v[160:161], v[128:129], v[144:145]
	v_pk_fma_f32 v[146:147], v[162:163], v[130:131], v[146:147]
	v_pk_fma_f32 v[148:149], v[164:165], v[132:133], v[148:149]
	v_pk_fma_f32 v[150:151], v[166:167], v[134:135], v[150:151]
	v_pk_fma_f32 v[152:153], v[168:169], v[136:137], v[152:153]
	v_pk_fma_f32 v[154:155], v[170:171], v[138:139], v[154:155]
	v_pk_fma_f32 v[156:157], v[172:173], v[140:141], v[156:157]
	v_pk_fma_f32 v[158:159], v[174:175], v[142:143], v[158:159]
	v_pk_mul_f32 v[252:253], v[144:145], v[144:145]
	v_pk_mul_f32 v[254:255], v[146:147], v[146:147]
	v_pk_fma_f32 v[252:253], v[148:149], v[148:149], v[252:253]
	v_pk_fma_f32 v[254:255], v[150:151], v[150:151], v[254:255]
	v_pk_fma_f32 v[252:253], v[152:153], v[152:153], v[252:253]
	v_pk_fma_f32 v[254:255], v[154:155], v[154:155], v[254:255]
	v_pk_fma_f32 v[252:253], v[156:157], v[156:157], v[252:253]
	v_pk_fma_f32 v[254:255], v[158:159], v[158:159], v[254:255]
	v_pk_add_f32 v[252:253], v[252:253], v[254:255]
	s_nop 0
	v_add_f32_e32 v183, v252, v253
	s_nop 1
	v_add_f32_dpp v183, v183, v183 quad_perm:[1,0,3,2] row_mask:0xf bank_mask:0xf bound_ctrl:1
	s_nop 1
	v_add_f32_dpp v183, v183, v183 quad_perm:[2,3,0,1] row_mask:0xf bank_mask:0xf bound_ctrl:1
	s_nop 1
	v_add_f32_dpp v183, v183, v183 row_half_mirror row_mask:0xf bank_mask:0xf bound_ctrl:1
	s_nop 1
	v_add_f32_dpp v183, v183, v183 row_mirror row_mask:0xf bank_mask:0xf bound_ctrl:1
	s_nop 1
	v_readlane_b32 s98, v183, 0
	v_readlane_b32 s99, v183, 16
	v_readlane_b32 s100, v183, 32
	v_readlane_b32 s101, v183, 48
	s_nop 1
	v_mov_b32_e32 v183, s98
	v_add_f32_e32 v183, s99, v183
	v_add_f32_e32 v183, s100, v183
	v_add_f32_e32 v183, s101, v183
	v_fmamk_f32 v183, v183, 0x3a800000, v182
	v_cmp_gt_f32_e32 vcc, 0x800000, v183
	v_mul_f32_e32 v181, 0x4b800000, v183
	s_nop 1
	v_cndmask_b32_e32 v183, v183, v181, vcc
	v_rsq_f32_e32 v183, v183
	s_nop 0
	v_mul_f32_e32 v181, 0x45800000, v183
	v_cndmask_b32_e32 v184, v183, v181, vcc
	v_mov_b32_e32 v185, v184
	v_pk_mul_f32 v[144:145], v[144:145], v[184:185]
	v_pk_mul_f32 v[146:147], v[146:147], v[184:185]
	v_pk_mul_f32 v[148:149], v[148:149], v[184:185]
	v_pk_mul_f32 v[150:151], v[150:151], v[184:185]
	v_pk_mul_f32 v[152:153], v[152:153], v[184:185]
	v_pk_mul_f32 v[154:155], v[154:155], v[184:185]
	v_pk_mul_f32 v[156:157], v[156:157], v[184:185]
	v_pk_mul_f32 v[158:159], v[158:159], v[184:185]
	v_pk_mul_f32 v[144:145], v[144:145], v[236:237]
	v_pk_mul_f32 v[146:147], v[146:147], v[238:239]
	v_pk_mul_f32 v[148:149], v[148:149], v[240:241]
	v_pk_mul_f32 v[150:151], v[150:151], v[242:243]
	v_pk_mul_f32 v[152:153], v[152:153], v[244:245]
	v_pk_mul_f32 v[154:155], v[154:155], v[246:247]
	v_pk_mul_f32 v[156:157], v[156:157], v[248:249]
	v_pk_mul_f32 v[158:159], v[158:159], v[250:251]
	v_add_u32_e32 v181, 0x100000, v178
	global_store_dwordx4 v181, v[144:147], s[76:77]
	global_store_dwordx4 v181, v[148:151], s[76:77] offset:16
	global_store_dwordx4 v181, v[152:155], s[76:77] offset:2048
	global_store_dwordx4 v181, v[156:159], s[76:77] offset:2064
	s_nop 1
	s_waitcnt vmcnt(20)
	v_lshlrev_b32_e32 v144, 16, v32
	v_and_b32_e32 v145, 0xffff0000, v32
	v_lshlrev_b32_e32 v146, 16, v33
	v_and_b32_e32 v147, 0xffff0000, v33
	v_lshlrev_b32_e32 v148, 16, v34
	v_and_b32_e32 v149, 0xffff0000, v34
	v_lshlrev_b32_e32 v150, 16, v35
	v_and_b32_e32 v151, 0xffff0000, v35
	v_lshlrev_b32_e32 v152, 16, v36
	v_and_b32_e32 v153, 0xffff0000, v36
	v_lshlrev_b32_e32 v154, 16, v37
	v_and_b32_e32 v155, 0xffff0000, v37
	v_lshlrev_b32_e32 v156, 16, v38
	v_and_b32_e32 v157, 0xffff0000, v38
	v_lshlrev_b32_e32 v158, 16, v39
	v_and_b32_e32 v159, 0xffff0000, v39
	v_lshlrev_b32_e32 v160, 16, v40
	v_and_b32_e32 v161, 0xffff0000, v40
	v_lshlrev_b32_e32 v162, 16, v41
	v_and_b32_e32 v163, 0xffff0000, v41
	v_lshlrev_b32_e32 v164, 16, v42
	v_and_b32_e32 v165, 0xffff0000, v42
	v_lshlrev_b32_e32 v166, 16, v43
	v_and_b32_e32 v167, 0xffff0000, v43
	v_lshlrev_b32_e32 v168, 16, v44
	v_and_b32_e32 v169, 0xffff0000, v44
	v_lshlrev_b32_e32 v170, 16, v45
	v_and_b32_e32 v171, 0xffff0000, v45
	v_lshlrev_b32_e32 v172, 16, v46
	v_and_b32_e32 v173, 0xffff0000, v46
	v_lshlrev_b32_e32 v174, 16, v47
	v_and_b32_e32 v175, 0xffff0000, v47
	v_pk_mul_f32 v[252:253], v[160:161], v[160:161]
	v_pk_mul_f32 v[254:255], v[162:163], v[162:163]
	v_pk_fma_f32 v[252:253], v[164:165], v[164:165], v[252:253]
	v_pk_fma_f32 v[254:255], v[166:167], v[166:167], v[254:255]
	v_pk_fma_f32 v[252:253], v[168:169], v[168:169], v[252:253]
	v_pk_fma_f32 v[254:255], v[170:171], v[170:171], v[254:255]
	v_pk_fma_f32 v[252:253], v[172:173], v[172:173], v[252:253]
	v_pk_fma_f32 v[254:255], v[174:175], v[174:175], v[254:255]
	v_pk_add_f32 v[252:253], v[252:253], v[254:255]
	s_nop 0
	v_add_f32_e32 v183, v252, v253
	s_nop 1
	v_add_f32_dpp v183, v183, v183 quad_perm:[1,0,3,2] row_mask:0xf bank_mask:0xf bound_ctrl:1
	s_nop 1
	v_add_f32_dpp v183, v183, v183 quad_perm:[2,3,0,1] row_mask:0xf bank_mask:0xf bound_ctrl:1
	s_nop 1
	v_add_f32_dpp v183, v183, v183 row_half_mirror row_mask:0xf bank_mask:0xf bound_ctrl:1
	s_nop 1
	v_add_f32_dpp v183, v183, v183 row_mirror row_mask:0xf bank_mask:0xf bound_ctrl:1
	s_nop 1
	v_readlane_b32 s98, v183, 0
	v_readlane_b32 s99, v183, 16
	v_readlane_b32 s100, v183, 32
	v_readlane_b32 s101, v183, 48
	s_nop 1
	v_mov_b32_e32 v183, s98
	v_add_f32_e32 v183, s99, v183
	v_add_f32_e32 v183, s100, v183
	v_add_f32_e32 v183, s101, v183
	v_fmamk_f32 v183, v183, 0x3a800000, v182
	v_cmp_gt_f32_e32 vcc, 0x800000, v183
	v_mul_f32_e32 v181, 0x4b800000, v183
	s_nop 1
	v_cndmask_b32_e32 v183, v183, v181, vcc
	v_rsq_f32_e32 v183, v183
	s_nop 0
	v_mul_f32_e32 v181, 0x45800000, v183
	v_cndmask_b32_e32 v184, v183, v181, vcc
	v_mov_b32_e32 v185, v184
	v_pk_mul_f32 v[160:161], v[160:161], v[184:185]
	v_pk_mul_f32 v[162:163], v[162:163], v[184:185]
	v_pk_mul_f32 v[164:165], v[164:165], v[184:185]
	v_pk_mul_f32 v[166:167], v[166:167], v[184:185]
	v_pk_mul_f32 v[168:169], v[168:169], v[184:185]
	v_pk_mul_f32 v[170:171], v[170:171], v[184:185]
	v_pk_mul_f32 v[172:173], v[172:173], v[184:185]
	v_pk_mul_f32 v[174:175], v[174:175], v[184:185]
	v_pk_fma_f32 v[144:145], v[160:161], v[128:129], v[144:145]
	v_pk_fma_f32 v[146:147], v[162:163], v[130:131], v[146:147]
	v_pk_fma_f32 v[148:149], v[164:165], v[132:133], v[148:149]
	v_pk_fma_f32 v[150:151], v[166:167], v[134:135], v[150:151]
	v_pk_fma_f32 v[152:153], v[168:169], v[136:137], v[152:153]
	v_pk_fma_f32 v[154:155], v[170:171], v[138:139], v[154:155]
	v_pk_fma_f32 v[156:157], v[172:173], v[140:141], v[156:157]
	v_pk_fma_f32 v[158:159], v[174:175], v[142:143], v[158:159]
	v_pk_mul_f32 v[252:253], v[144:145], v[144:145]
	v_pk_mul_f32 v[254:255], v[146:147], v[146:147]
	v_pk_fma_f32 v[252:253], v[148:149], v[148:149], v[252:253]
	v_pk_fma_f32 v[254:255], v[150:151], v[150:151], v[254:255]
	v_pk_fma_f32 v[252:253], v[152:153], v[152:153], v[252:253]
	v_pk_fma_f32 v[254:255], v[154:155], v[154:155], v[254:255]
	v_pk_fma_f32 v[252:253], v[156:157], v[156:157], v[252:253]
	v_pk_fma_f32 v[254:255], v[158:159], v[158:159], v[254:255]
	v_pk_add_f32 v[252:253], v[252:253], v[254:255]
	s_nop 0
	v_add_f32_e32 v183, v252, v253
	s_nop 1
	v_add_f32_dpp v183, v183, v183 quad_perm:[1,0,3,2] row_mask:0xf bank_mask:0xf bound_ctrl:1
	s_nop 1
	v_add_f32_dpp v183, v183, v183 quad_perm:[2,3,0,1] row_mask:0xf bank_mask:0xf bound_ctrl:1
	s_nop 1
	v_add_f32_dpp v183, v183, v183 row_half_mirror row_mask:0xf bank_mask:0xf bound_ctrl:1
	s_nop 1
	v_add_f32_dpp v183, v183, v183 row_mirror row_mask:0xf bank_mask:0xf bound_ctrl:1
	s_nop 1
	v_readlane_b32 s98, v183, 0
	v_readlane_b32 s99, v183, 16
	v_readlane_b32 s100, v183, 32
	v_readlane_b32 s101, v183, 48
	s_nop 1
	v_mov_b32_e32 v183, s98
	v_add_f32_e32 v183, s99, v183
	v_add_f32_e32 v183, s100, v183
	v_add_f32_e32 v183, s101, v183
	v_fmamk_f32 v183, v183, 0x3a800000, v182
	v_cmp_gt_f32_e32 vcc, 0x800000, v183
	v_mul_f32_e32 v181, 0x4b800000, v183
	s_nop 1
	v_cndmask_b32_e32 v183, v183, v181, vcc
	v_rsq_f32_e32 v183, v183
	s_nop 0
	v_mul_f32_e32 v181, 0x45800000, v183
	v_cndmask_b32_e32 v184, v183, v181, vcc
	v_mov_b32_e32 v185, v184
	v_pk_mul_f32 v[144:145], v[144:145], v[184:185]
	v_pk_mul_f32 v[146:147], v[146:147], v[184:185]
	v_pk_mul_f32 v[148:149], v[148:149], v[184:185]
	v_pk_mul_f32 v[150:151], v[150:151], v[184:185]
	v_pk_mul_f32 v[152:153], v[152:153], v[184:185]
	v_pk_mul_f32 v[154:155], v[154:155], v[184:185]
	v_pk_mul_f32 v[156:157], v[156:157], v[184:185]
	v_pk_mul_f32 v[158:159], v[158:159], v[184:185]
	v_pk_mul_f32 v[144:145], v[144:145], v[236:237]
	v_pk_mul_f32 v[146:147], v[146:147], v[238:239]
	v_pk_mul_f32 v[148:149], v[148:149], v[240:241]
	v_pk_mul_f32 v[150:151], v[150:151], v[242:243]
	v_pk_mul_f32 v[152:153], v[152:153], v[244:245]
	v_pk_mul_f32 v[154:155], v[154:155], v[246:247]
	v_pk_mul_f32 v[156:157], v[156:157], v[248:249]
	v_pk_mul_f32 v[158:159], v[158:159], v[250:251]
	v_add_u32_e32 v181, 0x200000, v178
	global_store_dwordx4 v181, v[144:147], s[76:77]
	global_store_dwordx4 v181, v[148:151], s[76:77] offset:16
	global_store_dwordx4 v181, v[152:155], s[76:77] offset:2048
	global_store_dwordx4 v181, v[156:159], s[76:77] offset:2064
	s_nop 1
	s_waitcnt vmcnt(16)
	v_lshlrev_b32_e32 v144, 16, v48
	v_and_b32_e32 v145, 0xffff0000, v48
	v_lshlrev_b32_e32 v146, 16, v49
	v_and_b32_e32 v147, 0xffff0000, v49
	v_lshlrev_b32_e32 v148, 16, v50
	v_and_b32_e32 v149, 0xffff0000, v50
	v_lshlrev_b32_e32 v150, 16, v51
	v_and_b32_e32 v151, 0xffff0000, v51
	v_lshlrev_b32_e32 v152, 16, v52
	v_and_b32_e32 v153, 0xffff0000, v52
	v_lshlrev_b32_e32 v154, 16, v53
	v_and_b32_e32 v155, 0xffff0000, v53
	v_lshlrev_b32_e32 v156, 16, v54
	v_and_b32_e32 v157, 0xffff0000, v54
	v_lshlrev_b32_e32 v158, 16, v55
	v_and_b32_e32 v159, 0xffff0000, v55
	v_lshlrev_b32_e32 v160, 16, v56
	v_and_b32_e32 v161, 0xffff0000, v56
	v_lshlrev_b32_e32 v162, 16, v57
	v_and_b32_e32 v163, 0xffff0000, v57
	v_lshlrev_b32_e32 v164, 16, v58
	v_and_b32_e32 v165, 0xffff0000, v58
	v_lshlrev_b32_e32 v166, 16, v59
	v_and_b32_e32 v167, 0xffff0000, v59
	v_lshlrev_b32_e32 v168, 16, v60
	v_and_b32_e32 v169, 0xffff0000, v60
	v_lshlrev_b32_e32 v170, 16, v61
	v_and_b32_e32 v171, 0xffff0000, v61
	v_lshlrev_b32_e32 v172, 16, v62
	v_and_b32_e32 v173, 0xffff0000, v62
	v_lshlrev_b32_e32 v174, 16, v63
	v_and_b32_e32 v175, 0xffff0000, v63
	v_pk_mul_f32 v[252:253], v[160:161], v[160:161]
	v_pk_mul_f32 v[254:255], v[162:163], v[162:163]
	v_pk_fma_f32 v[252:253], v[164:165], v[164:165], v[252:253]
	v_pk_fma_f32 v[254:255], v[166:167], v[166:167], v[254:255]
	v_pk_fma_f32 v[252:253], v[168:169], v[168:169], v[252:253]
	v_pk_fma_f32 v[254:255], v[170:171], v[170:171], v[254:255]
	v_pk_fma_f32 v[252:253], v[172:173], v[172:173], v[252:253]
	v_pk_fma_f32 v[254:255], v[174:175], v[174:175], v[254:255]
	v_pk_add_f32 v[252:253], v[252:253], v[254:255]
	s_nop 0
	v_add_f32_e32 v183, v252, v253
	s_nop 1
	v_add_f32_dpp v183, v183, v183 quad_perm:[1,0,3,2] row_mask:0xf bank_mask:0xf bound_ctrl:1
	s_nop 1
	v_add_f32_dpp v183, v183, v183 quad_perm:[2,3,0,1] row_mask:0xf bank_mask:0xf bound_ctrl:1
	s_nop 1
	v_add_f32_dpp v183, v183, v183 row_half_mirror row_mask:0xf bank_mask:0xf bound_ctrl:1
	s_nop 1
	v_add_f32_dpp v183, v183, v183 row_mirror row_mask:0xf bank_mask:0xf bound_ctrl:1
	s_nop 1
	v_readlane_b32 s98, v183, 0
	v_readlane_b32 s99, v183, 16
	v_readlane_b32 s100, v183, 32
	v_readlane_b32 s101, v183, 48
	s_nop 1
	v_mov_b32_e32 v183, s98
	v_add_f32_e32 v183, s99, v183
	v_add_f32_e32 v183, s100, v183
	v_add_f32_e32 v183, s101, v183
	v_fmamk_f32 v183, v183, 0x3a800000, v182
	v_cmp_gt_f32_e32 vcc, 0x800000, v183
	v_mul_f32_e32 v181, 0x4b800000, v183
	s_nop 1
	v_cndmask_b32_e32 v183, v183, v181, vcc
	v_rsq_f32_e32 v183, v183
	s_nop 0
	v_mul_f32_e32 v181, 0x45800000, v183
	v_cndmask_b32_e32 v184, v183, v181, vcc
	v_mov_b32_e32 v185, v184
	v_pk_mul_f32 v[160:161], v[160:161], v[184:185]
	v_pk_mul_f32 v[162:163], v[162:163], v[184:185]
	v_pk_mul_f32 v[164:165], v[164:165], v[184:185]
	v_pk_mul_f32 v[166:167], v[166:167], v[184:185]
	v_pk_mul_f32 v[168:169], v[168:169], v[184:185]
	v_pk_mul_f32 v[170:171], v[170:171], v[184:185]
	v_pk_mul_f32 v[172:173], v[172:173], v[184:185]
	v_pk_mul_f32 v[174:175], v[174:175], v[184:185]
	v_pk_fma_f32 v[144:145], v[160:161], v[128:129], v[144:145]
	v_pk_fma_f32 v[146:147], v[162:163], v[130:131], v[146:147]
	v_pk_fma_f32 v[148:149], v[164:165], v[132:133], v[148:149]
	v_pk_fma_f32 v[150:151], v[166:167], v[134:135], v[150:151]
	v_pk_fma_f32 v[152:153], v[168:169], v[136:137], v[152:153]
	v_pk_fma_f32 v[154:155], v[170:171], v[138:139], v[154:155]
	v_pk_fma_f32 v[156:157], v[172:173], v[140:141], v[156:157]
	v_pk_fma_f32 v[158:159], v[174:175], v[142:143], v[158:159]
	v_pk_mul_f32 v[252:253], v[144:145], v[144:145]
	v_pk_mul_f32 v[254:255], v[146:147], v[146:147]
	v_pk_fma_f32 v[252:253], v[148:149], v[148:149], v[252:253]
	v_pk_fma_f32 v[254:255], v[150:151], v[150:151], v[254:255]
	v_pk_fma_f32 v[252:253], v[152:153], v[152:153], v[252:253]
	v_pk_fma_f32 v[254:255], v[154:155], v[154:155], v[254:255]
	v_pk_fma_f32 v[252:253], v[156:157], v[156:157], v[252:253]
	v_pk_fma_f32 v[254:255], v[158:159], v[158:159], v[254:255]
	v_pk_add_f32 v[252:253], v[252:253], v[254:255]
	s_nop 0
	v_add_f32_e32 v183, v252, v253
	s_nop 1
	v_add_f32_dpp v183, v183, v183 quad_perm:[1,0,3,2] row_mask:0xf bank_mask:0xf bound_ctrl:1
	s_nop 1
	v_add_f32_dpp v183, v183, v183 quad_perm:[2,3,0,1] row_mask:0xf bank_mask:0xf bound_ctrl:1
	s_nop 1
	v_add_f32_dpp v183, v183, v183 row_half_mirror row_mask:0xf bank_mask:0xf bound_ctrl:1
	s_nop 1
	v_add_f32_dpp v183, v183, v183 row_mirror row_mask:0xf bank_mask:0xf bound_ctrl:1
	s_nop 1
	v_readlane_b32 s98, v183, 0
	v_readlane_b32 s99, v183, 16
	v_readlane_b32 s100, v183, 32
	v_readlane_b32 s101, v183, 48
	s_nop 1
	v_mov_b32_e32 v183, s98
	v_add_f32_e32 v183, s99, v183
	v_add_f32_e32 v183, s100, v183
	v_add_f32_e32 v183, s101, v183
	v_fmamk_f32 v183, v183, 0x3a800000, v182
	v_cmp_gt_f32_e32 vcc, 0x800000, v183
	v_mul_f32_e32 v181, 0x4b800000, v183
	s_nop 1
	v_cndmask_b32_e32 v183, v183, v181, vcc
	v_rsq_f32_e32 v183, v183
	s_nop 0
	v_mul_f32_e32 v181, 0x45800000, v183
	v_cndmask_b32_e32 v184, v183, v181, vcc
	v_mov_b32_e32 v185, v184
	v_pk_mul_f32 v[144:145], v[144:145], v[184:185]
	v_pk_mul_f32 v[146:147], v[146:147], v[184:185]
	v_pk_mul_f32 v[148:149], v[148:149], v[184:185]
	v_pk_mul_f32 v[150:151], v[150:151], v[184:185]
	v_pk_mul_f32 v[152:153], v[152:153], v[184:185]
	v_pk_mul_f32 v[154:155], v[154:155], v[184:185]
	v_pk_mul_f32 v[156:157], v[156:157], v[184:185]
	v_pk_mul_f32 v[158:159], v[158:159], v[184:185]
	v_pk_mul_f32 v[144:145], v[144:145], v[236:237]
	v_pk_mul_f32 v[146:147], v[146:147], v[238:239]
	v_pk_mul_f32 v[148:149], v[148:149], v[240:241]
	v_pk_mul_f32 v[150:151], v[150:151], v[242:243]
	v_pk_mul_f32 v[152:153], v[152:153], v[244:245]
	v_pk_mul_f32 v[154:155], v[154:155], v[246:247]
	v_pk_mul_f32 v[156:157], v[156:157], v[248:249]
	v_pk_mul_f32 v[158:159], v[158:159], v[250:251]
	v_add_u32_e32 v181, 0x300000, v178
	global_store_dwordx4 v181, v[144:147], s[76:77]
	global_store_dwordx4 v181, v[148:151], s[76:77] offset:16
	global_store_dwordx4 v181, v[152:155], s[76:77] offset:2048
	global_store_dwordx4 v181, v[156:159], s[76:77] offset:2064
	s_nop 1
	s_waitcnt vmcnt(12)
	v_lshlrev_b32_e32 v144, 16, v64
	v_and_b32_e32 v145, 0xffff0000, v64
	v_lshlrev_b32_e32 v146, 16, v65
	v_and_b32_e32 v147, 0xffff0000, v65
	v_lshlrev_b32_e32 v148, 16, v66
	v_and_b32_e32 v149, 0xffff0000, v66
	v_lshlrev_b32_e32 v150, 16, v67
	v_and_b32_e32 v151, 0xffff0000, v67
	v_lshlrev_b32_e32 v152, 16, v68
	v_and_b32_e32 v153, 0xffff0000, v68
	v_lshlrev_b32_e32 v154, 16, v69
	v_and_b32_e32 v155, 0xffff0000, v69
	v_lshlrev_b32_e32 v156, 16, v70
	v_and_b32_e32 v157, 0xffff0000, v70
	v_lshlrev_b32_e32 v158, 16, v71
	v_and_b32_e32 v159, 0xffff0000, v71
	v_lshlrev_b32_e32 v160, 16, v72
	v_and_b32_e32 v161, 0xffff0000, v72
	v_lshlrev_b32_e32 v162, 16, v73
	v_and_b32_e32 v163, 0xffff0000, v73
	v_lshlrev_b32_e32 v164, 16, v74
	v_and_b32_e32 v165, 0xffff0000, v74
	v_lshlrev_b32_e32 v166, 16, v75
	v_and_b32_e32 v167, 0xffff0000, v75
	v_lshlrev_b32_e32 v168, 16, v76
	v_and_b32_e32 v169, 0xffff0000, v76
	v_lshlrev_b32_e32 v170, 16, v77
	v_and_b32_e32 v171, 0xffff0000, v77
	v_lshlrev_b32_e32 v172, 16, v78
	v_and_b32_e32 v173, 0xffff0000, v78
	v_lshlrev_b32_e32 v174, 16, v79
	v_and_b32_e32 v175, 0xffff0000, v79
	v_pk_mul_f32 v[252:253], v[160:161], v[160:161]
	v_pk_mul_f32 v[254:255], v[162:163], v[162:163]
	v_pk_fma_f32 v[252:253], v[164:165], v[164:165], v[252:253]
	v_pk_fma_f32 v[254:255], v[166:167], v[166:167], v[254:255]
	v_pk_fma_f32 v[252:253], v[168:169], v[168:169], v[252:253]
	v_pk_fma_f32 v[254:255], v[170:171], v[170:171], v[254:255]
	v_pk_fma_f32 v[252:253], v[172:173], v[172:173], v[252:253]
	v_pk_fma_f32 v[254:255], v[174:175], v[174:175], v[254:255]
	v_pk_add_f32 v[252:253], v[252:253], v[254:255]
	s_nop 0
	v_add_f32_e32 v183, v252, v253
	s_nop 1
	v_add_f32_dpp v183, v183, v183 quad_perm:[1,0,3,2] row_mask:0xf bank_mask:0xf bound_ctrl:1
	s_nop 1
	v_add_f32_dpp v183, v183, v183 quad_perm:[2,3,0,1] row_mask:0xf bank_mask:0xf bound_ctrl:1
	s_nop 1
	v_add_f32_dpp v183, v183, v183 row_half_mirror row_mask:0xf bank_mask:0xf bound_ctrl:1
	s_nop 1
	v_add_f32_dpp v183, v183, v183 row_mirror row_mask:0xf bank_mask:0xf bound_ctrl:1
	s_nop 1
	v_readlane_b32 s98, v183, 0
	v_readlane_b32 s99, v183, 16
	v_readlane_b32 s100, v183, 32
	v_readlane_b32 s101, v183, 48
	s_nop 1
	v_mov_b32_e32 v183, s98
	v_add_f32_e32 v183, s99, v183
	v_add_f32_e32 v183, s100, v183
	v_add_f32_e32 v183, s101, v183
	v_fmamk_f32 v183, v183, 0x3a800000, v182
	v_cmp_gt_f32_e32 vcc, 0x800000, v183
	v_mul_f32_e32 v181, 0x4b800000, v183
	s_nop 1
	v_cndmask_b32_e32 v183, v183, v181, vcc
	v_rsq_f32_e32 v183, v183
	s_nop 0
	v_mul_f32_e32 v181, 0x45800000, v183
	v_cndmask_b32_e32 v184, v183, v181, vcc
	v_mov_b32_e32 v185, v184
	v_pk_mul_f32 v[160:161], v[160:161], v[184:185]
	v_pk_mul_f32 v[162:163], v[162:163], v[184:185]
	v_pk_mul_f32 v[164:165], v[164:165], v[184:185]
	v_pk_mul_f32 v[166:167], v[166:167], v[184:185]
	v_pk_mul_f32 v[168:169], v[168:169], v[184:185]
	v_pk_mul_f32 v[170:171], v[170:171], v[184:185]
	v_pk_mul_f32 v[172:173], v[172:173], v[184:185]
	v_pk_mul_f32 v[174:175], v[174:175], v[184:185]
	v_pk_fma_f32 v[144:145], v[160:161], v[128:129], v[144:145]
	v_pk_fma_f32 v[146:147], v[162:163], v[130:131], v[146:147]
	v_pk_fma_f32 v[148:149], v[164:165], v[132:133], v[148:149]
	v_pk_fma_f32 v[150:151], v[166:167], v[134:135], v[150:151]
	v_pk_fma_f32 v[152:153], v[168:169], v[136:137], v[152:153]
	v_pk_fma_f32 v[154:155], v[170:171], v[138:139], v[154:155]
	v_pk_fma_f32 v[156:157], v[172:173], v[140:141], v[156:157]
	v_pk_fma_f32 v[158:159], v[174:175], v[142:143], v[158:159]
	v_pk_mul_f32 v[252:253], v[144:145], v[144:145]
	v_pk_mul_f32 v[254:255], v[146:147], v[146:147]
	v_pk_fma_f32 v[252:253], v[148:149], v[148:149], v[252:253]
	v_pk_fma_f32 v[254:255], v[150:151], v[150:151], v[254:255]
	v_pk_fma_f32 v[252:253], v[152:153], v[152:153], v[252:253]
	v_pk_fma_f32 v[254:255], v[154:155], v[154:155], v[254:255]
	v_pk_fma_f32 v[252:253], v[156:157], v[156:157], v[252:253]
	v_pk_fma_f32 v[254:255], v[158:159], v[158:159], v[254:255]
	v_pk_add_f32 v[252:253], v[252:253], v[254:255]
	s_nop 0
	v_add_f32_e32 v183, v252, v253
	s_nop 1
	v_add_f32_dpp v183, v183, v183 quad_perm:[1,0,3,2] row_mask:0xf bank_mask:0xf bound_ctrl:1
	s_nop 1
	v_add_f32_dpp v183, v183, v183 quad_perm:[2,3,0,1] row_mask:0xf bank_mask:0xf bound_ctrl:1
	s_nop 1
	v_add_f32_dpp v183, v183, v183 row_half_mirror row_mask:0xf bank_mask:0xf bound_ctrl:1
	s_nop 1
	v_add_f32_dpp v183, v183, v183 row_mirror row_mask:0xf bank_mask:0xf bound_ctrl:1
	s_nop 1
	v_readlane_b32 s98, v183, 0
	v_readlane_b32 s99, v183, 16
	v_readlane_b32 s100, v183, 32
	v_readlane_b32 s101, v183, 48
	s_nop 1
	v_mov_b32_e32 v183, s98
	v_add_f32_e32 v183, s99, v183
	v_add_f32_e32 v183, s100, v183
	v_add_f32_e32 v183, s101, v183
	v_fmamk_f32 v183, v183, 0x3a800000, v182
	v_cmp_gt_f32_e32 vcc, 0x800000, v183
	v_mul_f32_e32 v181, 0x4b800000, v183
	s_nop 1
	v_cndmask_b32_e32 v183, v183, v181, vcc
	v_rsq_f32_e32 v183, v183
	s_nop 0
	v_mul_f32_e32 v181, 0x45800000, v183
	v_cndmask_b32_e32 v184, v183, v181, vcc
	v_mov_b32_e32 v185, v184
	v_pk_mul_f32 v[144:145], v[144:145], v[184:185]
	v_pk_mul_f32 v[146:147], v[146:147], v[184:185]
	v_pk_mul_f32 v[148:149], v[148:149], v[184:185]
	v_pk_mul_f32 v[150:151], v[150:151], v[184:185]
	v_pk_mul_f32 v[152:153], v[152:153], v[184:185]
	v_pk_mul_f32 v[154:155], v[154:155], v[184:185]
	v_pk_mul_f32 v[156:157], v[156:157], v[184:185]
	v_pk_mul_f32 v[158:159], v[158:159], v[184:185]
	v_pk_mul_f32 v[144:145], v[144:145], v[236:237]
	v_pk_mul_f32 v[146:147], v[146:147], v[238:239]
	v_pk_mul_f32 v[148:149], v[148:149], v[240:241]
	v_pk_mul_f32 v[150:151], v[150:151], v[242:243]
	v_pk_mul_f32 v[152:153], v[152:153], v[244:245]
	v_pk_mul_f32 v[154:155], v[154:155], v[246:247]
	v_pk_mul_f32 v[156:157], v[156:157], v[248:249]
	v_pk_mul_f32 v[158:159], v[158:159], v[250:251]
	v_add_u32_e32 v181, 0x400000, v178
	global_store_dwordx4 v181, v[144:147], s[76:77]
	global_store_dwordx4 v181, v[148:151], s[76:77] offset:16
	global_store_dwordx4 v181, v[152:155], s[76:77] offset:2048
	global_store_dwordx4 v181, v[156:159], s[76:77] offset:2064
	s_nop 1
	s_waitcnt vmcnt(8)
	v_lshlrev_b32_e32 v144, 16, v80
	v_and_b32_e32 v145, 0xffff0000, v80
	v_lshlrev_b32_e32 v146, 16, v81
	v_and_b32_e32 v147, 0xffff0000, v81
	v_lshlrev_b32_e32 v148, 16, v82
	v_and_b32_e32 v149, 0xffff0000, v82
	v_lshlrev_b32_e32 v150, 16, v83
	v_and_b32_e32 v151, 0xffff0000, v83
	v_lshlrev_b32_e32 v152, 16, v84
	v_and_b32_e32 v153, 0xffff0000, v84
	v_lshlrev_b32_e32 v154, 16, v85
	v_and_b32_e32 v155, 0xffff0000, v85
	v_lshlrev_b32_e32 v156, 16, v86
	v_and_b32_e32 v157, 0xffff0000, v86
	v_lshlrev_b32_e32 v158, 16, v87
	v_and_b32_e32 v159, 0xffff0000, v87
	v_lshlrev_b32_e32 v160, 16, v88
	v_and_b32_e32 v161, 0xffff0000, v88
	v_lshlrev_b32_e32 v162, 16, v89
	v_and_b32_e32 v163, 0xffff0000, v89
	v_lshlrev_b32_e32 v164, 16, v90
	v_and_b32_e32 v165, 0xffff0000, v90
	v_lshlrev_b32_e32 v166, 16, v91
	v_and_b32_e32 v167, 0xffff0000, v91
	v_lshlrev_b32_e32 v168, 16, v92
	v_and_b32_e32 v169, 0xffff0000, v92
	v_lshlrev_b32_e32 v170, 16, v93
	v_and_b32_e32 v171, 0xffff0000, v93
	v_lshlrev_b32_e32 v172, 16, v94
	v_and_b32_e32 v173, 0xffff0000, v94
	v_lshlrev_b32_e32 v174, 16, v95
	v_and_b32_e32 v175, 0xffff0000, v95
	v_pk_mul_f32 v[252:253], v[160:161], v[160:161]
	v_pk_mul_f32 v[254:255], v[162:163], v[162:163]
	v_pk_fma_f32 v[252:253], v[164:165], v[164:165], v[252:253]
	v_pk_fma_f32 v[254:255], v[166:167], v[166:167], v[254:255]
	v_pk_fma_f32 v[252:253], v[168:169], v[168:169], v[252:253]
	v_pk_fma_f32 v[254:255], v[170:171], v[170:171], v[254:255]
	v_pk_fma_f32 v[252:253], v[172:173], v[172:173], v[252:253]
	v_pk_fma_f32 v[254:255], v[174:175], v[174:175], v[254:255]
	v_pk_add_f32 v[252:253], v[252:253], v[254:255]
	s_nop 0
	v_add_f32_e32 v183, v252, v253
	s_nop 1
	v_add_f32_dpp v183, v183, v183 quad_perm:[1,0,3,2] row_mask:0xf bank_mask:0xf bound_ctrl:1
	s_nop 1
	v_add_f32_dpp v183, v183, v183 quad_perm:[2,3,0,1] row_mask:0xf bank_mask:0xf bound_ctrl:1
	s_nop 1
	v_add_f32_dpp v183, v183, v183 row_half_mirror row_mask:0xf bank_mask:0xf bound_ctrl:1
	s_nop 1
	v_add_f32_dpp v183, v183, v183 row_mirror row_mask:0xf bank_mask:0xf bound_ctrl:1
	s_nop 1
	v_readlane_b32 s98, v183, 0
	v_readlane_b32 s99, v183, 16
	v_readlane_b32 s100, v183, 32
	v_readlane_b32 s101, v183, 48
	s_nop 1
	v_mov_b32_e32 v183, s98
	v_add_f32_e32 v183, s99, v183
	v_add_f32_e32 v183, s100, v183
	v_add_f32_e32 v183, s101, v183
	v_fmamk_f32 v183, v183, 0x3a800000, v182
	v_cmp_gt_f32_e32 vcc, 0x800000, v183
	v_mul_f32_e32 v181, 0x4b800000, v183
	s_nop 1
	v_cndmask_b32_e32 v183, v183, v181, vcc
	v_rsq_f32_e32 v183, v183
	s_nop 0
	v_mul_f32_e32 v181, 0x45800000, v183
	v_cndmask_b32_e32 v184, v183, v181, vcc
	v_mov_b32_e32 v185, v184
	v_pk_mul_f32 v[160:161], v[160:161], v[184:185]
	v_pk_mul_f32 v[162:163], v[162:163], v[184:185]
	v_pk_mul_f32 v[164:165], v[164:165], v[184:185]
	v_pk_mul_f32 v[166:167], v[166:167], v[184:185]
	v_pk_mul_f32 v[168:169], v[168:169], v[184:185]
	v_pk_mul_f32 v[170:171], v[170:171], v[184:185]
	v_pk_mul_f32 v[172:173], v[172:173], v[184:185]
	v_pk_mul_f32 v[174:175], v[174:175], v[184:185]
	v_pk_fma_f32 v[144:145], v[160:161], v[128:129], v[144:145]
	v_pk_fma_f32 v[146:147], v[162:163], v[130:131], v[146:147]
	v_pk_fma_f32 v[148:149], v[164:165], v[132:133], v[148:149]
	v_pk_fma_f32 v[150:151], v[166:167], v[134:135], v[150:151]
	v_pk_fma_f32 v[152:153], v[168:169], v[136:137], v[152:153]
	v_pk_fma_f32 v[154:155], v[170:171], v[138:139], v[154:155]
	v_pk_fma_f32 v[156:157], v[172:173], v[140:141], v[156:157]
	v_pk_fma_f32 v[158:159], v[174:175], v[142:143], v[158:159]
	v_pk_mul_f32 v[252:253], v[144:145], v[144:145]
	v_pk_mul_f32 v[254:255], v[146:147], v[146:147]
	v_pk_fma_f32 v[252:253], v[148:149], v[148:149], v[252:253]
	v_pk_fma_f32 v[254:255], v[150:151], v[150:151], v[254:255]
	v_pk_fma_f32 v[252:253], v[152:153], v[152:153], v[252:253]
	v_pk_fma_f32 v[254:255], v[154:155], v[154:155], v[254:255]
	v_pk_fma_f32 v[252:253], v[156:157], v[156:157], v[252:253]
	v_pk_fma_f32 v[254:255], v[158:159], v[158:159], v[254:255]
	v_pk_add_f32 v[252:253], v[252:253], v[254:255]
	s_nop 0
	v_add_f32_e32 v183, v252, v253
	s_nop 1
	v_add_f32_dpp v183, v183, v183 quad_perm:[1,0,3,2] row_mask:0xf bank_mask:0xf bound_ctrl:1
	s_nop 1
	v_add_f32_dpp v183, v183, v183 quad_perm:[2,3,0,1] row_mask:0xf bank_mask:0xf bound_ctrl:1
	s_nop 1
	v_add_f32_dpp v183, v183, v183 row_half_mirror row_mask:0xf bank_mask:0xf bound_ctrl:1
	s_nop 1
	v_add_f32_dpp v183, v183, v183 row_mirror row_mask:0xf bank_mask:0xf bound_ctrl:1
	s_nop 1
	v_readlane_b32 s98, v183, 0
	v_readlane_b32 s99, v183, 16
	v_readlane_b32 s100, v183, 32
	v_readlane_b32 s101, v183, 48
	s_nop 1
	v_mov_b32_e32 v183, s98
	v_add_f32_e32 v183, s99, v183
	v_add_f32_e32 v183, s100, v183
	v_add_f32_e32 v183, s101, v183
	v_fmamk_f32 v183, v183, 0x3a800000, v182
	v_cmp_gt_f32_e32 vcc, 0x800000, v183
	v_mul_f32_e32 v181, 0x4b800000, v183
	s_nop 1
	v_cndmask_b32_e32 v183, v183, v181, vcc
	v_rsq_f32_e32 v183, v183
	s_nop 0
	v_mul_f32_e32 v181, 0x45800000, v183
	v_cndmask_b32_e32 v184, v183, v181, vcc
	v_mov_b32_e32 v185, v184
	v_pk_mul_f32 v[144:145], v[144:145], v[184:185]
	v_pk_mul_f32 v[146:147], v[146:147], v[184:185]
	v_pk_mul_f32 v[148:149], v[148:149], v[184:185]
	v_pk_mul_f32 v[150:151], v[150:151], v[184:185]
	v_pk_mul_f32 v[152:153], v[152:153], v[184:185]
	v_pk_mul_f32 v[154:155], v[154:155], v[184:185]
	v_pk_mul_f32 v[156:157], v[156:157], v[184:185]
	v_pk_mul_f32 v[158:159], v[158:159], v[184:185]
	v_pk_mul_f32 v[144:145], v[144:145], v[236:237]
	v_pk_mul_f32 v[146:147], v[146:147], v[238:239]
	v_pk_mul_f32 v[148:149], v[148:149], v[240:241]
	v_pk_mul_f32 v[150:151], v[150:151], v[242:243]
	v_pk_mul_f32 v[152:153], v[152:153], v[244:245]
	v_pk_mul_f32 v[154:155], v[154:155], v[246:247]
	v_pk_mul_f32 v[156:157], v[156:157], v[248:249]
	v_pk_mul_f32 v[158:159], v[158:159], v[250:251]
	v_add_u32_e32 v181, 0x500000, v178
	global_store_dwordx4 v181, v[144:147], s[76:77]
	global_store_dwordx4 v181, v[148:151], s[76:77] offset:16
	global_store_dwordx4 v181, v[152:155], s[76:77] offset:2048
	global_store_dwordx4 v181, v[156:159], s[76:77] offset:2064
	s_nop 1
	s_waitcnt vmcnt(4)
	v_lshlrev_b32_e32 v144, 16, v96
	v_and_b32_e32 v145, 0xffff0000, v96
	v_lshlrev_b32_e32 v146, 16, v97
	v_and_b32_e32 v147, 0xffff0000, v97
	v_lshlrev_b32_e32 v148, 16, v98
	v_and_b32_e32 v149, 0xffff0000, v98
	v_lshlrev_b32_e32 v150, 16, v99
	v_and_b32_e32 v151, 0xffff0000, v99
	v_lshlrev_b32_e32 v152, 16, v100
	v_and_b32_e32 v153, 0xffff0000, v100
	v_lshlrev_b32_e32 v154, 16, v101
	v_and_b32_e32 v155, 0xffff0000, v101
	v_lshlrev_b32_e32 v156, 16, v102
	v_and_b32_e32 v157, 0xffff0000, v102
	v_lshlrev_b32_e32 v158, 16, v103
	v_and_b32_e32 v159, 0xffff0000, v103
	v_lshlrev_b32_e32 v160, 16, v104
	v_and_b32_e32 v161, 0xffff0000, v104
	v_lshlrev_b32_e32 v162, 16, v105
	v_and_b32_e32 v163, 0xffff0000, v105
	v_lshlrev_b32_e32 v164, 16, v106
	v_and_b32_e32 v165, 0xffff0000, v106
	v_lshlrev_b32_e32 v166, 16, v107
	v_and_b32_e32 v167, 0xffff0000, v107
	v_lshlrev_b32_e32 v168, 16, v108
	v_and_b32_e32 v169, 0xffff0000, v108
	v_lshlrev_b32_e32 v170, 16, v109
	v_and_b32_e32 v171, 0xffff0000, v109
	v_lshlrev_b32_e32 v172, 16, v110
	v_and_b32_e32 v173, 0xffff0000, v110
	v_lshlrev_b32_e32 v174, 16, v111
	v_and_b32_e32 v175, 0xffff0000, v111
	v_pk_mul_f32 v[252:253], v[160:161], v[160:161]
	v_pk_mul_f32 v[254:255], v[162:163], v[162:163]
	v_pk_fma_f32 v[252:253], v[164:165], v[164:165], v[252:253]
	v_pk_fma_f32 v[254:255], v[166:167], v[166:167], v[254:255]
	v_pk_fma_f32 v[252:253], v[168:169], v[168:169], v[252:253]
	v_pk_fma_f32 v[254:255], v[170:171], v[170:171], v[254:255]
	v_pk_fma_f32 v[252:253], v[172:173], v[172:173], v[252:253]
	v_pk_fma_f32 v[254:255], v[174:175], v[174:175], v[254:255]
	v_pk_add_f32 v[252:253], v[252:253], v[254:255]
	s_nop 0
	v_add_f32_e32 v183, v252, v253
	s_nop 1
	v_add_f32_dpp v183, v183, v183 quad_perm:[1,0,3,2] row_mask:0xf bank_mask:0xf bound_ctrl:1
	s_nop 1
	v_add_f32_dpp v183, v183, v183 quad_perm:[2,3,0,1] row_mask:0xf bank_mask:0xf bound_ctrl:1
	s_nop 1
	v_add_f32_dpp v183, v183, v183 row_half_mirror row_mask:0xf bank_mask:0xf bound_ctrl:1
	s_nop 1
	v_add_f32_dpp v183, v183, v183 row_mirror row_mask:0xf bank_mask:0xf bound_ctrl:1
	s_nop 1
	v_readlane_b32 s98, v183, 0
	v_readlane_b32 s99, v183, 16
	v_readlane_b32 s100, v183, 32
	v_readlane_b32 s101, v183, 48
	s_nop 1
	v_mov_b32_e32 v183, s98
	v_add_f32_e32 v183, s99, v183
	v_add_f32_e32 v183, s100, v183
	v_add_f32_e32 v183, s101, v183
	v_fmamk_f32 v183, v183, 0x3a800000, v182
	v_cmp_gt_f32_e32 vcc, 0x800000, v183
	v_mul_f32_e32 v181, 0x4b800000, v183
	s_nop 1
	v_cndmask_b32_e32 v183, v183, v181, vcc
	v_rsq_f32_e32 v183, v183
	s_nop 0
	v_mul_f32_e32 v181, 0x45800000, v183
	v_cndmask_b32_e32 v184, v183, v181, vcc
	v_mov_b32_e32 v185, v184
	v_pk_mul_f32 v[160:161], v[160:161], v[184:185]
	v_pk_mul_f32 v[162:163], v[162:163], v[184:185]
	v_pk_mul_f32 v[164:165], v[164:165], v[184:185]
	v_pk_mul_f32 v[166:167], v[166:167], v[184:185]
	v_pk_mul_f32 v[168:169], v[168:169], v[184:185]
	v_pk_mul_f32 v[170:171], v[170:171], v[184:185]
	v_pk_mul_f32 v[172:173], v[172:173], v[184:185]
	v_pk_mul_f32 v[174:175], v[174:175], v[184:185]
	v_pk_fma_f32 v[144:145], v[160:161], v[128:129], v[144:145]
	v_pk_fma_f32 v[146:147], v[162:163], v[130:131], v[146:147]
	v_pk_fma_f32 v[148:149], v[164:165], v[132:133], v[148:149]
	v_pk_fma_f32 v[150:151], v[166:167], v[134:135], v[150:151]
	v_pk_fma_f32 v[152:153], v[168:169], v[136:137], v[152:153]
	v_pk_fma_f32 v[154:155], v[170:171], v[138:139], v[154:155]
	v_pk_fma_f32 v[156:157], v[172:173], v[140:141], v[156:157]
	v_pk_fma_f32 v[158:159], v[174:175], v[142:143], v[158:159]
	v_pk_mul_f32 v[252:253], v[144:145], v[144:145]
	v_pk_mul_f32 v[254:255], v[146:147], v[146:147]
	v_pk_fma_f32 v[252:253], v[148:149], v[148:149], v[252:253]
	v_pk_fma_f32 v[254:255], v[150:151], v[150:151], v[254:255]
	v_pk_fma_f32 v[252:253], v[152:153], v[152:153], v[252:253]
	v_pk_fma_f32 v[254:255], v[154:155], v[154:155], v[254:255]
	v_pk_fma_f32 v[252:253], v[156:157], v[156:157], v[252:253]
	v_pk_fma_f32 v[254:255], v[158:159], v[158:159], v[254:255]
	v_pk_add_f32 v[252:253], v[252:253], v[254:255]
	s_nop 0
	v_add_f32_e32 v183, v252, v253
	s_nop 1
	v_add_f32_dpp v183, v183, v183 quad_perm:[1,0,3,2] row_mask:0xf bank_mask:0xf bound_ctrl:1
	s_nop 1
	v_add_f32_dpp v183, v183, v183 quad_perm:[2,3,0,1] row_mask:0xf bank_mask:0xf bound_ctrl:1
	s_nop 1
	v_add_f32_dpp v183, v183, v183 row_half_mirror row_mask:0xf bank_mask:0xf bound_ctrl:1
	s_nop 1
	v_add_f32_dpp v183, v183, v183 row_mirror row_mask:0xf bank_mask:0xf bound_ctrl:1
	s_nop 1
	v_readlane_b32 s98, v183, 0
	v_readlane_b32 s99, v183, 16
	v_readlane_b32 s100, v183, 32
	v_readlane_b32 s101, v183, 48
	s_nop 1
	v_mov_b32_e32 v183, s98
	v_add_f32_e32 v183, s99, v183
	v_add_f32_e32 v183, s100, v183
	v_add_f32_e32 v183, s101, v183
	v_fmamk_f32 v183, v183, 0x3a800000, v182
	v_cmp_gt_f32_e32 vcc, 0x800000, v183
	v_mul_f32_e32 v181, 0x4b800000, v183
	s_nop 1
	v_cndmask_b32_e32 v183, v183, v181, vcc
	v_rsq_f32_e32 v183, v183
	s_nop 0
	v_mul_f32_e32 v181, 0x45800000, v183
	v_cndmask_b32_e32 v184, v183, v181, vcc
	v_mov_b32_e32 v185, v184
	v_pk_mul_f32 v[144:145], v[144:145], v[184:185]
	v_pk_mul_f32 v[146:147], v[146:147], v[184:185]
	v_pk_mul_f32 v[148:149], v[148:149], v[184:185]
	v_pk_mul_f32 v[150:151], v[150:151], v[184:185]
	v_pk_mul_f32 v[152:153], v[152:153], v[184:185]
	v_pk_mul_f32 v[154:155], v[154:155], v[184:185]
	v_pk_mul_f32 v[156:157], v[156:157], v[184:185]
	v_pk_mul_f32 v[158:159], v[158:159], v[184:185]
	v_pk_mul_f32 v[144:145], v[144:145], v[236:237]
	v_pk_mul_f32 v[146:147], v[146:147], v[238:239]
	v_pk_mul_f32 v[148:149], v[148:149], v[240:241]
	v_pk_mul_f32 v[150:151], v[150:151], v[242:243]
	v_pk_mul_f32 v[152:153], v[152:153], v[244:245]
	v_pk_mul_f32 v[154:155], v[154:155], v[246:247]
	v_pk_mul_f32 v[156:157], v[156:157], v[248:249]
	v_pk_mul_f32 v[158:159], v[158:159], v[250:251]
	v_add_u32_e32 v181, 0x600000, v178
	global_store_dwordx4 v181, v[144:147], s[76:77]
	global_store_dwordx4 v181, v[148:151], s[76:77] offset:16
	global_store_dwordx4 v181, v[152:155], s[76:77] offset:2048
	global_store_dwordx4 v181, v[156:159], s[76:77] offset:2064
	s_nop 1
	s_waitcnt vmcnt(0)
	v_lshlrev_b32_e32 v144, 16, v112
	v_and_b32_e32 v145, 0xffff0000, v112
	v_lshlrev_b32_e32 v146, 16, v113
	v_and_b32_e32 v147, 0xffff0000, v113
	v_lshlrev_b32_e32 v148, 16, v114
	v_and_b32_e32 v149, 0xffff0000, v114
	v_lshlrev_b32_e32 v150, 16, v115
	v_and_b32_e32 v151, 0xffff0000, v115
	v_lshlrev_b32_e32 v152, 16, v116
	v_and_b32_e32 v153, 0xffff0000, v116
	v_lshlrev_b32_e32 v154, 16, v117
	v_and_b32_e32 v155, 0xffff0000, v117
	v_lshlrev_b32_e32 v156, 16, v118
	v_and_b32_e32 v157, 0xffff0000, v118
	v_lshlrev_b32_e32 v158, 16, v119
	v_and_b32_e32 v159, 0xffff0000, v119
	v_lshlrev_b32_e32 v160, 16, v120
	v_and_b32_e32 v161, 0xffff0000, v120
	v_lshlrev_b32_e32 v162, 16, v121
	v_and_b32_e32 v163, 0xffff0000, v121
	v_lshlrev_b32_e32 v164, 16, v122
	v_and_b32_e32 v165, 0xffff0000, v122
	v_lshlrev_b32_e32 v166, 16, v123
	v_and_b32_e32 v167, 0xffff0000, v123
	v_lshlrev_b32_e32 v168, 16, v124
	v_and_b32_e32 v169, 0xffff0000, v124
	v_lshlrev_b32_e32 v170, 16, v125
	v_and_b32_e32 v171, 0xffff0000, v125
	v_lshlrev_b32_e32 v172, 16, v126
	v_and_b32_e32 v173, 0xffff0000, v126
	v_lshlrev_b32_e32 v174, 16, v127
	v_and_b32_e32 v175, 0xffff0000, v127
	v_pk_mul_f32 v[252:253], v[160:161], v[160:161]
	v_pk_mul_f32 v[254:255], v[162:163], v[162:163]
	v_pk_fma_f32 v[252:253], v[164:165], v[164:165], v[252:253]
	v_pk_fma_f32 v[254:255], v[166:167], v[166:167], v[254:255]
	v_pk_fma_f32 v[252:253], v[168:169], v[168:169], v[252:253]
	v_pk_fma_f32 v[254:255], v[170:171], v[170:171], v[254:255]
	v_pk_fma_f32 v[252:253], v[172:173], v[172:173], v[252:253]
	v_pk_fma_f32 v[254:255], v[174:175], v[174:175], v[254:255]
	v_pk_add_f32 v[252:253], v[252:253], v[254:255]
	s_nop 0
	v_add_f32_e32 v183, v252, v253
	s_nop 1
	v_add_f32_dpp v183, v183, v183 quad_perm:[1,0,3,2] row_mask:0xf bank_mask:0xf bound_ctrl:1
	s_nop 1
	v_add_f32_dpp v183, v183, v183 quad_perm:[2,3,0,1] row_mask:0xf bank_mask:0xf bound_ctrl:1
	s_nop 1
	v_add_f32_dpp v183, v183, v183 row_half_mirror row_mask:0xf bank_mask:0xf bound_ctrl:1
	s_nop 1
	v_add_f32_dpp v183, v183, v183 row_mirror row_mask:0xf bank_mask:0xf bound_ctrl:1
	s_nop 1
	v_readlane_b32 s98, v183, 0
	v_readlane_b32 s99, v183, 16
	v_readlane_b32 s100, v183, 32
	v_readlane_b32 s101, v183, 48
	s_nop 1
	v_mov_b32_e32 v183, s98
	v_add_f32_e32 v183, s99, v183
	v_add_f32_e32 v183, s100, v183
	v_add_f32_e32 v183, s101, v183
	v_fmamk_f32 v183, v183, 0x3a800000, v182
	v_cmp_gt_f32_e32 vcc, 0x800000, v183
	v_mul_f32_e32 v181, 0x4b800000, v183
	s_nop 1
	v_cndmask_b32_e32 v183, v183, v181, vcc
	v_rsq_f32_e32 v183, v183
	s_nop 0
	v_mul_f32_e32 v181, 0x45800000, v183
	v_cndmask_b32_e32 v184, v183, v181, vcc
	v_mov_b32_e32 v185, v184
	v_pk_mul_f32 v[160:161], v[160:161], v[184:185]
	v_pk_mul_f32 v[162:163], v[162:163], v[184:185]
	v_pk_mul_f32 v[164:165], v[164:165], v[184:185]
	v_pk_mul_f32 v[166:167], v[166:167], v[184:185]
	v_pk_mul_f32 v[168:169], v[168:169], v[184:185]
	v_pk_mul_f32 v[170:171], v[170:171], v[184:185]
	v_pk_mul_f32 v[172:173], v[172:173], v[184:185]
	v_pk_mul_f32 v[174:175], v[174:175], v[184:185]
	v_pk_fma_f32 v[144:145], v[160:161], v[128:129], v[144:145]
	v_pk_fma_f32 v[146:147], v[162:163], v[130:131], v[146:147]
	v_pk_fma_f32 v[148:149], v[164:165], v[132:133], v[148:149]
	v_pk_fma_f32 v[150:151], v[166:167], v[134:135], v[150:151]
	v_pk_fma_f32 v[152:153], v[168:169], v[136:137], v[152:153]
	v_pk_fma_f32 v[154:155], v[170:171], v[138:139], v[154:155]
	v_pk_fma_f32 v[156:157], v[172:173], v[140:141], v[156:157]
	v_pk_fma_f32 v[158:159], v[174:175], v[142:143], v[158:159]
	v_pk_mul_f32 v[252:253], v[144:145], v[144:145]
	v_pk_mul_f32 v[254:255], v[146:147], v[146:147]
	v_pk_fma_f32 v[252:253], v[148:149], v[148:149], v[252:253]
	v_pk_fma_f32 v[254:255], v[150:151], v[150:151], v[254:255]
	v_pk_fma_f32 v[252:253], v[152:153], v[152:153], v[252:253]
	v_pk_fma_f32 v[254:255], v[154:155], v[154:155], v[254:255]
	v_pk_fma_f32 v[252:253], v[156:157], v[156:157], v[252:253]
	v_pk_fma_f32 v[254:255], v[158:159], v[158:159], v[254:255]
	v_pk_add_f32 v[252:253], v[252:253], v[254:255]
	s_nop 0
	v_add_f32_e32 v183, v252, v253
	s_nop 1
	v_add_f32_dpp v183, v183, v183 quad_perm:[1,0,3,2] row_mask:0xf bank_mask:0xf bound_ctrl:1
	s_nop 1
	v_add_f32_dpp v183, v183, v183 quad_perm:[2,3,0,1] row_mask:0xf bank_mask:0xf bound_ctrl:1
	s_nop 1
	v_add_f32_dpp v183, v183, v183 row_half_mirror row_mask:0xf bank_mask:0xf bound_ctrl:1
	s_nop 1
	v_add_f32_dpp v183, v183, v183 row_mirror row_mask:0xf bank_mask:0xf bound_ctrl:1
	s_nop 1
	v_readlane_b32 s98, v183, 0
	v_readlane_b32 s99, v183, 16
	v_readlane_b32 s100, v183, 32
	v_readlane_b32 s101, v183, 48
	s_nop 1
	v_mov_b32_e32 v183, s98
	v_add_f32_e32 v183, s99, v183
	v_add_f32_e32 v183, s100, v183
	v_add_f32_e32 v183, s101, v183
	v_fmamk_f32 v183, v183, 0x3a800000, v182
	v_cmp_gt_f32_e32 vcc, 0x800000, v183
	v_mul_f32_e32 v181, 0x4b800000, v183
	s_nop 1
	v_cndmask_b32_e32 v183, v183, v181, vcc
	v_rsq_f32_e32 v183, v183
	s_nop 0
	v_mul_f32_e32 v181, 0x45800000, v183
	v_cndmask_b32_e32 v184, v183, v181, vcc
	v_mov_b32_e32 v185, v184
	v_pk_mul_f32 v[144:145], v[144:145], v[184:185]
	v_pk_mul_f32 v[146:147], v[146:147], v[184:185]
	v_pk_mul_f32 v[148:149], v[148:149], v[184:185]
	v_pk_mul_f32 v[150:151], v[150:151], v[184:185]
	v_pk_mul_f32 v[152:153], v[152:153], v[184:185]
	v_pk_mul_f32 v[154:155], v[154:155], v[184:185]
	v_pk_mul_f32 v[156:157], v[156:157], v[184:185]
	v_pk_mul_f32 v[158:159], v[158:159], v[184:185]
	v_pk_mul_f32 v[144:145], v[144:145], v[236:237]
	v_pk_mul_f32 v[146:147], v[146:147], v[238:239]
	v_pk_mul_f32 v[148:149], v[148:149], v[240:241]
	v_pk_mul_f32 v[150:151], v[150:151], v[242:243]
	v_pk_mul_f32 v[152:153], v[152:153], v[244:245]
	v_pk_mul_f32 v[154:155], v[154:155], v[246:247]
	v_pk_mul_f32 v[156:157], v[156:157], v[248:249]
	v_pk_mul_f32 v[158:159], v[158:159], v[250:251]
	v_add_u32_e32 v181, 0x700000, v178
	global_store_dwordx4 v181, v[144:147], s[76:77]
	global_store_dwordx4 v181, v[148:151], s[76:77] offset:16
	global_store_dwordx4 v181, v[152:155], s[76:77] offset:2048
	global_store_dwordx4 v181, v[156:159], s[76:77] offset:2064
	s_nop 1
	v_readfirstlane_b32 s98, v179
	s_nop 3
	s_cmp_ge_u32 s98, 512
	s_cbranch_scc1 .Lmyxupd_done_7
	v_lshlrev_b32_e32 v177, 4, v176
	v_lshl_add_u32 v177, v179, 11, v177
	v_lshl_add_u32 v178, v179, 12, v180
	v_add_u32_e32 v181, 0x3800000, v177
	global_load_dwordx4 v[0:3], v181, s[78:79]
	global_load_dwordx4 v[4:7], v181, s[78:79] offset:1024
	v_lshl_add_u32 v183, v179, 12, v180
	v_add_u32_e32 v183, 0xbf00000, v183
	v_add_u32_e32 v181, 0x0, v183
	global_load_dwordx4 v[8:11], v181, s[78:79]
	global_load_dwordx4 v[12:15], v181, s[78:79] offset:16
	global_load_dwordx4 v[16:19], v181, s[78:79] offset:2048
	global_load_dwordx4 v[20:23], v181, s[78:79] offset:2064
	v_add_u32_e32 v181, 0x200000, v183
	global_load_dwordx4 v[24:27], v181, s[78:79]
	global_load_dwordx4 v[28:31], v181, s[78:79] offset:16
	global_load_dwordx4 v[32:35], v181, s[78:79] offset:2048
	global_load_dwordx4 v[36:39], v181, s[78:79] offset:2064
	v_add_u32_e32 v181, 0x400000, v183
	global_load_dwordx4 v[40:43], v181, s[78:79]
	global_load_dwordx4 v[44:47], v181, s[78:79] offset:16
	global_load_dwordx4 v[48:51], v181, s[78:79] offset:2048
	global_load_dwordx4 v[52:55], v181, s[78:79] offset:2064
	v_add_u32_e32 v181, 0x600000, v183
	global_load_dwordx4 v[56:59], v181, s[78:79]
	global_load_dwordx4 v[60:63], v181, s[78:79] offset:16
	global_load_dwordx4 v[64:67], v181, s[78:79] offset:2048
	global_load_dwordx4 v[68:71], v181, s[78:79] offset:2064
	v_add_u32_e32 v181, 0x800000, v183
	global_load_dwordx4 v[72:75], v181, s[78:79]
	global_load_dwordx4 v[76:79], v181, s[78:79] offset:16
	global_load_dwordx4 v[80:83], v181, s[78:79] offset:2048
	global_load_dwordx4 v[84:87], v181, s[78:79] offset:2064
	v_add_u32_e32 v181, 0xa00000, v183
	global_load_dwordx4 v[88:91], v181, s[78:79]
	global_load_dwordx4 v[92:95], v181, s[78:79] offset:16
	global_load_dwordx4 v[96:99], v181, s[78:79] offset:2048
	global_load_dwordx4 v[100:103], v181, s[78:79] offset:2064
	s_waitcnt vmcnt(20)
	v_pk_add_f32 v[160:161], v[8:9], 0 op_sel_hi:[1,0]
	v_pk_add_f32 v[162:163], v[10:11], 0 op_sel_hi:[1,0]
	v_pk_add_f32 v[164:165], v[12:13], 0 op_sel_hi:[1,0]
	v_pk_add_f32 v[166:167], v[14:15], 0 op_sel_hi:[1,0]
	v_pk_add_f32 v[168:169], v[16:17], 0 op_sel_hi:[1,0]
	v_pk_add_f32 v[170:171], v[18:19], 0 op_sel_hi:[1,0]
	v_pk_add_f32 v[172:173], v[20:21], 0 op_sel_hi:[1,0]
	v_pk_add_f32 v[174:175], v[22:23], 0 op_sel_hi:[1,0]
	s_waitcnt vmcnt(16)
	v_pk_add_f32 v[160:161], v[160:161], v[24:25]
	v_pk_add_f32 v[162:163], v[162:163], v[26:27]
	v_pk_add_f32 v[164:165], v[164:165], v[28:29]
	v_pk_add_f32 v[166:167], v[166:167], v[30:31]
	v_pk_add_f32 v[168:169], v[168:169], v[32:33]
	v_pk_add_f32 v[170:171], v[170:171], v[34:35]
	v_pk_add_f32 v[172:173], v[172:173], v[36:37]
	v_pk_add_f32 v[174:175], v[174:175], v[38:39]
	s_waitcnt vmcnt(12)
	v_pk_add_f32 v[160:161], v[160:161], v[40:41]
	v_pk_add_f32 v[162:163], v[162:163], v[42:43]
	v_pk_add_f32 v[164:165], v[164:165], v[44:45]
	v_pk_add_f32 v[166:167], v[166:167], v[46:47]
	v_pk_add_f32 v[168:169], v[168:169], v[48:49]
	v_pk_add_f32 v[170:171], v[170:171], v[50:51]
	v_pk_add_f32 v[172:173], v[172:173], v[52:53]
	v_pk_add_f32 v[174:175], v[174:175], v[54:55]
	s_waitcnt vmcnt(8)
	v_pk_add_f32 v[160:161], v[160:161], v[56:57]
	v_pk_add_f32 v[162:163], v[162:163], v[58:59]
	v_pk_add_f32 v[164:165], v[164:165], v[60:61]
	v_pk_add_f32 v[166:167], v[166:167], v[62:63]
	v_pk_add_f32 v[168:169], v[168:169], v[64:65]
	v_pk_add_f32 v[170:171], v[170:171], v[66:67]
	v_pk_add_f32 v[172:173], v[172:173], v[68:69]
	v_pk_add_f32 v[174:175], v[174:175], v[70:71]
	s_waitcnt vmcnt(4)
	v_pk_add_f32 v[160:161], v[160:161], v[72:73]
	v_pk_add_f32 v[162:163], v[162:163], v[74:75]
	v_pk_add_f32 v[164:165], v[164:165], v[76:77]
	v_pk_add_f32 v[166:167], v[166:167], v[78:79]
	v_pk_add_f32 v[168:169], v[168:169], v[80:81]
	v_pk_add_f32 v[170:171], v[170:171], v[82:83]
	v_pk_add_f32 v[172:173], v[172:173], v[84:85]
	v_pk_add_f32 v[174:175], v[174:175], v[86:87]
	s_waitcnt vmcnt(0)
	v_pk_add_f32 v[160:161], v[160:161], v[88:89]
	v_pk_add_f32 v[162:163], v[162:163], v[90:91]
	v_pk_add_f32 v[164:165], v[164:165], v[92:93]
	v_pk_add_f32 v[166:167], v[166:167], v[94:95]
	v_pk_add_f32 v[168:169], v[168:169], v[96:97]
	v_pk_add_f32 v[170:171], v[170:171], v[98:99]
	v_pk_add_f32 v[172:173], v[172:173], v[100:101]
	v_pk_add_f32 v[174:175], v[174:175], v[102:103]
	v_lshlrev_b32_e32 v144, 16, v0
	v_and_b32_e32 v145, 0xffff0000, v0
	v_lshlrev_b32_e32 v146, 16, v1
	v_and_b32_e32 v147, 0xffff0000, v1
	v_lshlrev_b32_e32 v148, 16, v2
	v_and_b32_e32 v149, 0xffff0000, v2
	v_lshlrev_b32_e32 v150, 16, v3
	v_and_b32_e32 v151, 0xffff0000, v3
	v_lshlrev_b32_e32 v152, 16, v4
	v_and_b32_e32 v153, 0xffff0000, v4
	v_lshlrev_b32_e32 v154, 16, v5
	v_and_b32_e32 v155, 0xffff0000, v5
	v_lshlrev_b32_e32 v156, 16, v6
	v_and_b32_e32 v157, 0xffff0000, v6
	v_lshlrev_b32_e32 v158, 16, v7
	v_and_b32_e32 v159, 0xffff0000, v7
	v_add_u32_e32 v181, 0xc00000, v183
	global_load_dwordx4 v[8:11], v181, s[78:79]
	global_load_dwordx4 v[12:15], v181, s[78:79] offset:16
	global_load_dwordx4 v[16:19], v181, s[78:79] offset:2048
	global_load_dwordx4 v[20:23], v181, s[78:79] offset:2064
	v_add_u32_e32 v181, 0xe00000, v183
	global_load_dwordx4 v[24:27], v181, s[78:79]
	global_load_dwordx4 v[28:31], v181, s[78:79] offset:16
	global_load_dwordx4 v[32:35], v181, s[78:79] offset:2048
	global_load_dwordx4 v[36:39], v181, s[78:79] offset:2064
	v_add_u32_e32 v181, 0x1000000, v183
	global_load_dwordx4 v[40:43], v181, s[78:79]
	global_load_dwordx4 v[44:47], v181, s[78:79] offset:16
	global_load_dwordx4 v[48:51], v181, s[78:79] offset:2048
	global_load_dwordx4 v[52:55], v181, s[78:79] offset:2064
	v_add_u32_e32 v181, 0x1200000, v183
	global_load_dwordx4 v[56:59], v181, s[78:79]
	global_load_dwordx4 v[60:63], v181, s[78:79] offset:16
	global_load_dwordx4 v[64:67], v181, s[78:79] offset:2048
	global_load_dwordx4 v[68:71], v181, s[78:79] offset:2064
	v_add_u32_e32 v181, 0x1400000, v183
	global_load_dwordx4 v[72:75], v181, s[78:79]
	global_load_dwordx4 v[76:79], v181, s[78:79] offset:16
	global_load_dwordx4 v[80:83], v181, s[78:79] offset:2048
	global_load_dwordx4 v[84:87], v181, s[78:79] offset:2064
	s_waitcnt vmcnt(16)
	v_pk_add_f32 v[160:161], v[160:161], v[8:9]
	v_pk_add_f32 v[162:163], v[162:163], v[10:11]
	v_pk_add_f32 v[164:165], v[164:165], v[12:13]
	v_pk_add_f32 v[166:167], v[166:167], v[14:15]
	v_pk_add_f32 v[168:169], v[168:169], v[16:17]
	v_pk_add_f32 v[170:171], v[170:171], v[18:19]
	v_pk_add_f32 v[172:173], v[172:173], v[20:21]
	v_pk_add_f32 v[174:175], v[174:175], v[22:23]
	s_waitcnt vmcnt(12)
	v_pk_add_f32 v[160:161], v[160:161], v[24:25]
	v_pk_add_f32 v[162:163], v[162:163], v[26:27]
	v_pk_add_f32 v[164:165], v[164:165], v[28:29]
	v_pk_add_f32 v[166:167], v[166:167], v[30:31]
	v_pk_add_f32 v[168:169], v[168:169], v[32:33]
	v_pk_add_f32 v[170:171], v[170:171], v[34:35]
	v_pk_add_f32 v[172:173], v[172:173], v[36:37]
	v_pk_add_f32 v[174:175], v[174:175], v[38:39]
	s_waitcnt vmcnt(8)
	v_pk_add_f32 v[160:161], v[160:161], v[40:41]
	v_pk_add_f32 v[162:163], v[162:163], v[42:43]
	v_pk_add_f32 v[164:165], v[164:165], v[44:45]
	v_pk_add_f32 v[166:167], v[166:167], v[46:47]
	v_pk_add_f32 v[168:169], v[168:169], v[48:49]
	v_pk_add_f32 v[170:171], v[170:171], v[50:51]
	v_pk_add_f32 v[172:173], v[172:173], v[52:53]
	v_pk_add_f32 v[174:175], v[174:175], v[54:55]
	s_waitcnt vmcnt(4)
	v_pk_add_f32 v[160:161], v[160:161], v[56:57]
	v_pk_add_f32 v[162:163], v[162:163], v[58:59]
	v_pk_add_f32 v[164:165], v[164:165], v[60:61]
	v_pk_add_f32 v[166:167], v[166:167], v[62:63]
	v_pk_add_f32 v[168:169], v[168:169], v[64:65]
	v_pk_add_f32 v[170:171], v[170:171], v[66:67]
	v_pk_add_f32 v[172:173], v[172:173], v[68:69]
	v_pk_add_f32 v[174:175], v[174:175], v[70:71]
	s_waitcnt vmcnt(0)
	v_pk_add_f32 v[160:161], v[160:161], v[72:73]
	v_pk_add_f32 v[162:163], v[162:163], v[74:75]
	v_pk_add_f32 v[164:165], v[164:165], v[76:77]
	v_pk_add_f32 v[166:167], v[166:167], v[78:79]
	v_pk_add_f32 v[168:169], v[168:169], v[80:81]
	v_pk_add_f32 v[170:171], v[170:171], v[82:83]
	v_pk_add_f32 v[172:173], v[172:173], v[84:85]
	v_pk_add_f32 v[174:175], v[174:175], v[86:87]
	v_pk_mul_f32 v[252:253], v[160:161], v[160:161]
	v_pk_mul_f32 v[254:255], v[162:163], v[162:163]
	v_pk_fma_f32 v[252:253], v[164:165], v[164:165], v[252:253]
	v_pk_fma_f32 v[254:255], v[166:167], v[166:167], v[254:255]
	v_pk_fma_f32 v[252:253], v[168:169], v[168:169], v[252:253]
	v_pk_fma_f32 v[254:255], v[170:171], v[170:171], v[254:255]
	v_pk_fma_f32 v[252:253], v[172:173], v[172:173], v[252:253]
	v_pk_fma_f32 v[254:255], v[174:175], v[174:175], v[254:255]
	v_pk_add_f32 v[252:253], v[252:253], v[254:255]
	s_nop 0
	v_add_f32_e32 v183, v252, v253
	s_nop 1
	v_add_f32_dpp v183, v183, v183 quad_perm:[1,0,3,2] row_mask:0xf bank_mask:0xf bound_ctrl:1
	s_nop 1
	v_add_f32_dpp v183, v183, v183 quad_perm:[2,3,0,1] row_mask:0xf bank_mask:0xf bound_ctrl:1
	s_nop 1
	v_add_f32_dpp v183, v183, v183 row_half_mirror row_mask:0xf bank_mask:0xf bound_ctrl:1
	s_nop 1
	v_add_f32_dpp v183, v183, v183 row_mirror row_mask:0xf bank_mask:0xf bound_ctrl:1
	s_nop 1
	v_readlane_b32 s98, v183, 0
	v_readlane_b32 s99, v183, 16
	v_readlane_b32 s100, v183, 32
	v_readlane_b32 s101, v183, 48
	s_nop 1
	v_mov_b32_e32 v183, s98
	v_add_f32_e32 v183, s99, v183
	v_add_f32_e32 v183, s100, v183
	v_add_f32_e32 v183, s101, v183
	v_fmamk_f32 v183, v183, 0x3a800000, v182
	v_cmp_gt_f32_e32 vcc, 0x800000, v183
	v_mul_f32_e32 v181, 0x4b800000, v183
	s_nop 1
	v_cndmask_b32_e32 v183, v183, v181, vcc
	v_rsq_f32_e32 v183, v183
	s_nop 0
	v_mul_f32_e32 v181, 0x45800000, v183
	v_cndmask_b32_e32 v184, v183, v181, vcc
	v_mov_b32_e32 v185, v184
	v_pk_mul_f32 v[160:161], v[160:161], v[184:185]
	v_pk_mul_f32 v[162:163], v[162:163], v[184:185]
	v_pk_mul_f32 v[164:165], v[164:165], v[184:185]
	v_pk_mul_f32 v[166:167], v[166:167], v[184:185]
	v_pk_mul_f32 v[168:169], v[168:169], v[184:185]
	v_pk_mul_f32 v[170:171], v[170:171], v[184:185]
	v_pk_mul_f32 v[172:173], v[172:173], v[184:185]
	v_pk_mul_f32 v[174:175], v[174:175], v[184:185]
	v_pk_fma_f32 v[144:145], v[160:161], v[128:129], v[144:145]
	v_pk_fma_f32 v[146:147], v[162:163], v[130:131], v[146:147]
	v_pk_fma_f32 v[148:149], v[164:165], v[132:133], v[148:149]
	v_pk_fma_f32 v[150:151], v[166:167], v[134:135], v[150:151]
	v_pk_fma_f32 v[152:153], v[168:169], v[136:137], v[152:153]
	v_pk_fma_f32 v[154:155], v[170:171], v[138:139], v[154:155]
	v_pk_fma_f32 v[156:157], v[172:173], v[140:141], v[156:157]
	v_pk_fma_f32 v[158:159], v[174:175], v[142:143], v[158:159]
	v_pk_mul_f32 v[252:253], v[144:145], v[144:145]
	v_pk_mul_f32 v[254:255], v[146:147], v[146:147]
	v_pk_fma_f32 v[252:253], v[148:149], v[148:149], v[252:253]
	v_pk_fma_f32 v[254:255], v[150:151], v[150:151], v[254:255]
	v_pk_fma_f32 v[252:253], v[152:153], v[152:153], v[252:253]
	v_pk_fma_f32 v[254:255], v[154:155], v[154:155], v[254:255]
	v_pk_fma_f32 v[252:253], v[156:157], v[156:157], v[252:253]
	v_pk_fma_f32 v[254:255], v[158:159], v[158:159], v[254:255]
	v_pk_add_f32 v[252:253], v[252:253], v[254:255]
	s_nop 0
	v_add_f32_e32 v183, v252, v253
	s_nop 1
	v_add_f32_dpp v183, v183, v183 quad_perm:[1,0,3,2] row_mask:0xf bank_mask:0xf bound_ctrl:1
	s_nop 1
	v_add_f32_dpp v183, v183, v183 quad_perm:[2,3,0,1] row_mask:0xf bank_mask:0xf bound_ctrl:1
	s_nop 1
	v_add_f32_dpp v183, v183, v183 row_half_mirror row_mask:0xf bank_mask:0xf bound_ctrl:1
	s_nop 1
	v_add_f32_dpp v183, v183, v183 row_mirror row_mask:0xf bank_mask:0xf bound_ctrl:1
	s_nop 1
	v_readlane_b32 s98, v183, 0
	v_readlane_b32 s99, v183, 16
	v_readlane_b32 s100, v183, 32
	v_readlane_b32 s101, v183, 48
	s_nop 1
	v_mov_b32_e32 v183, s98
	v_add_f32_e32 v183, s99, v183
	v_add_f32_e32 v183, s100, v183
	v_add_f32_e32 v183, s101, v183
	v_fmamk_f32 v183, v183, 0x3a800000, v182
	v_cmp_gt_f32_e32 vcc, 0x800000, v183
	v_mul_f32_e32 v181, 0x4b800000, v183
	s_nop 1
	v_cndmask_b32_e32 v183, v183, v181, vcc
	v_rsq_f32_e32 v183, v183
	s_nop 0
	v_mul_f32_e32 v181, 0x45800000, v183
	v_cndmask_b32_e32 v184, v183, v181, vcc
	v_mov_b32_e32 v185, v184
	v_pk_mul_f32 v[144:145], v[144:145], v[184:185]
	v_pk_mul_f32 v[146:147], v[146:147], v[184:185]
	v_pk_mul_f32 v[148:149], v[148:149], v[184:185]
	v_pk_mul_f32 v[150:151], v[150:151], v[184:185]
	v_pk_mul_f32 v[152:153], v[152:153], v[184:185]
	v_pk_mul_f32 v[154:155], v[154:155], v[184:185]
	v_pk_mul_f32 v[156:157], v[156:157], v[184:185]
	v_pk_mul_f32 v[158:159], v[158:159], v[184:185]
	v_pk_mul_f32 v[144:145], v[144:145], v[236:237]
	v_pk_mul_f32 v[146:147], v[146:147], v[238:239]
	v_pk_mul_f32 v[148:149], v[148:149], v[240:241]
	v_pk_mul_f32 v[150:151], v[150:151], v[242:243]
	v_pk_mul_f32 v[152:153], v[152:153], v[244:245]
	v_pk_mul_f32 v[154:155], v[154:155], v[246:247]
	v_pk_mul_f32 v[156:157], v[156:157], v[248:249]
	v_pk_mul_f32 v[158:159], v[158:159], v[250:251]
	v_add_u32_e32 v181, 0x4000000, v178
	global_store_dwordx4 v181, v[144:147], s[76:77]
	global_store_dwordx4 v181, v[148:151], s[76:77] offset:16
	global_store_dwordx4 v181, v[152:155], s[76:77] offset:2048
	global_store_dwordx4 v181, v[156:159], s[76:77] offset:2064
	s_nop 1
